# ssd_intra and ctx attention units: LDS fragment reads renamed into free registers and issued several MFMAs ahead, lgkmcnt waits recomputed
# speedup vs baseline: 1.0204x; 1.0005x over previous
.LBB0_150:
	s_and_b64 vcc, exec, s[4:5]
	s_cbranch_vccz .LBB0_152
	s_add_i32 s0, s25, 0xfffff900
	s_lshr_b32 s8, s0, 4
	s_bfe_u32 s9, s25, 0x20002
	s_lshl_b32 s10, s8, 8
	s_mul_i32 s0, s8, 0x302000
	v_readlane_b32 s12, v254, 4
	s_mul_hi_u32 s4, s10, 0x3020
	v_readlane_b32 s13, v254, 5
	s_add_u32 s5, s12, s0
	s_addc_u32 s4, s13, s4
	s_lshl_b32 s0, s9, 8
	s_add_u32 s5, s5, s0
	s_addc_u32 s4, s4, 0
	s_add_u32 s6, s5, 0x2420
	s_addc_u32 s7, s4, 0
	s_lshl_b32 s8, s8, 2
	s_or_b32 s8, s8, s9
	s_mov_b32 s9, s1
	v_mov_b32_e32 v2, v171
	s_lshl_b64 s[8:9], s[8:9], 16
	v_readlane_b32 s11, v254, 8
	s_add_u32 s8, s11, s8
	v_readlane_b32 s11, v254, 9
	v_ashrrev_i32_e32 v100, 3, v2
	s_addc_u32 s9, s11, s9
	s_lshl_b32 s11, s25, 6
	v_lshlrev_b32_e32 v18, 4, v2
	v_ashrrev_i32_e32 v101, 31, v100
	s_and_b32 s11, s11, 0xc0
	v_and_b32_e32 v84, 0xf0, v18
	v_and_b32_e32 v102, 0x70, v18
	v_lshlrev_b64 v[18:19], 9, v[100:101]
	v_and_b32_e32 v107, 15, v2
	v_ashrrev_i32_e32 v0, 2, v2
	s_or_b32 s10, s11, s10
	v_ashrrev_i32_e32 v8, 4, v2
	v_mov_b32_e32 v103, v169
	v_lshl_add_u64 v[18:19], s[8:9], 0, v[18:19]
	v_and_b32_e32 v0, -16, v0
	v_or_b32_e32 v1, s10, v107
	v_mov_b64_e32 v[10:11], s[6:7]
	s_movk_i32 s10, 0x3020
	v_add_u32_e32 v9, 16, v8
	v_add_u32_e32 v97, 32, v8
	v_add_u32_e32 v95, 48, v8
	v_lshl_add_u64 v[86:87], v[18:19], 0, v[102:103]
	v_bfe_u32 v94, v2, 4, 2
	v_add_u32_e32 v174, v1, v0
	v_mad_i64_i32 v[0:1], s[6:7], v8, s10, v[10:11]
	v_mov_b32_e32 v85, v169
	v_mad_i64_i32 v[2:3], s[6:7], v9, s10, v[10:11]
	s_waitcnt vmcnt(0)
	v_mad_i64_i32 v[12:13], s[6:7], v97, s10, v[10:11]
	v_mad_i64_i32 v[10:11], s[6:7], v95, s10, v[10:11]
	v_add_co_u32_e32 v24, vcc, s97, v86
	s_mov_b64 s[2:3], 0x8000
	v_lshl_add_u64 v[0:1], v[0:1], 0, v[84:85]
	v_lshl_add_u64 v[4:5], v[2:3], 0, v[84:85]
	v_lshl_add_u64 v[12:13], v[12:13], 0, v[84:85]
	v_lshl_add_u64 v[14:15], v[10:11], 0, v[84:85]
	v_addc_co_u32_e32 v25, vcc, 0, v87, vcc
	v_lshl_add_u64 v[90:91], v[86:87], 0, s[2:3]
	s_mov_b32 s3, 0x8000
	s_barrier
	global_load_dwordx4 v[0:3], v[0:1], off
	s_nop 0
	global_load_dwordx4 v[4:7], v[4:5], off
	s_nop 0
	global_load_dwordx4 v[10:13], v[12:13], off
	s_nop 0
	global_load_dwordx4 v[14:17], v[14:15], off
	s_add_u32 s6, s5, 0xc2c20
	global_load_dwordx4 v[18:21], v[86:87], off
	global_load_dwordx4 v[40:43], v[24:25], off
	v_add_co_u32_e32 v24, vcc, s3, v86
	s_mov_b64 s[2:3], 0xc000
	s_nop 0
	v_addc_co_u32_e32 v25, vcc, 0, v87, vcc
	v_lshl_add_u64 v[98:99], v[86:87], 0, s[2:3]
	s_mov_b32 s3, 0xc000
	global_load_dwordx4 v[44:47], v[24:25], off
	v_add_co_u32_e32 v24, vcc, s3, v86
	s_addc_u32 s7, s4, 0
	s_nop 0
	v_addc_co_u32_e32 v25, vcc, 0, v87, vcc
	global_load_dwordx4 v[48:51], v[24:25], off
	v_mov_b64_e32 v[24:25], s[6:7]
	v_mad_i64_i32 v[26:27], s[6:7], v8, s10, v[24:25]
	v_lshl_add_u64 v[26:27], v[26:27], 0, v[84:85]
	v_mad_i64_i32 v[28:29], s[6:7], v9, s10, v[24:25]
	v_lshl_add_u64 v[28:29], v[28:29], 0, v[84:85]
	global_load_dwordx4 v[52:55], v[26:27], off
	global_load_dwordx4 v[56:59], v[28:29], off
	v_mad_i64_i32 v[26:27], s[6:7], v97, s10, v[24:25]
	v_mov_b64_e32 v[22:23], s[12:13]
	v_lshl_add_u64 v[26:27], v[26:27], 0, v[84:85]
	v_mad_i64_i32 v[24:25], s[6:7], v95, s10, v[24:25]
	v_lshl_add_u64 v[88:89], v[86:87], 0, s[84:85]
	v_lshl_add_u64 v[24:25], v[24:25], 0, v[84:85]
	global_load_dwordx4 v[60:63], v[26:27], off
	global_load_dwordx4 v[64:67], v[24:25], off
	global_load_dwordx4 v[68:71], v[86:87], off offset:128
	global_load_dwordx4 v[72:75], v[88:89], off offset:128
	global_load_dwordx4 v[76:79], v[90:91], off offset:128
	global_load_dwordx4 v[80:83], v[98:99], off offset:128
	v_mad_i64_i32 v[22:23], s[6:7], v174, s10, v[22:23]
	v_lshlrev_b32_e32 v104, 4, v94
	v_mov_b32_e32 v105, v169
	v_lshl_add_u64 v[176:177], v[22:23], 0, s[0:1]
	v_lshl_add_u64 v[22:23], v[176:177], 0, v[104:105]
	v_add_co_u32_e32 v24, vcc, s33, v22
	s_mov_b64 s[2:3], 0x2020
	s_nop 0
	v_addc_co_u32_e32 v25, vcc, 0, v23, vcc
	global_load_dwordx4 v[36:39], v[24:25], off offset:32
	v_lshl_add_u64 v[22:23], v[22:23], 0, s[2:3]
	global_load_dwordx4 v[32:35], v[22:23], off offset:64
	global_load_dwordx4 v[28:31], v[22:23], off offset:128
	global_load_dwordx4 v[24:27], v[22:23], off offset:192
	s_movk_i32 s3, 0x110
	s_movk_i32 s8, 0x90
	v_mad_u64_u32 v[92:93], s[6:7], v8, s3, v[84:85]
	v_mad_u64_u32 v[22:23], s[6:7], v100, s8, v[102:103]
	v_add_u32_e32 v93, 0x8800, v22
	s_waitcnt vmcnt(19)
	ds_write_b128 v92, v[0:3]
	s_waitcnt vmcnt(18)
	ds_write_b128 v92, v[4:7] offset:4352
	s_waitcnt vmcnt(17)
	ds_write_b128 v92, v[10:13] offset:8704
	s_waitcnt vmcnt(16)
	ds_write_b128 v92, v[14:17] offset:13056
	s_waitcnt vmcnt(15)
	ds_write_b128 v22, v[18:21] offset:34816
	s_waitcnt vmcnt(14)
	ds_write_b128 v22, v[40:43] offset:39424
	s_waitcnt vmcnt(13)
	ds_write_b128 v22, v[44:47] offset:44032
	s_waitcnt vmcnt(12)
	ds_write_b128 v22, v[48:51] offset:48640
	s_waitcnt lgkmcnt(0)
	s_barrier
	s_waitcnt vmcnt(11)
	ds_write_b128 v92, v[52:55] offset:17408
	s_waitcnt vmcnt(10)
	ds_write_b128 v92, v[56:59] offset:21760
	s_waitcnt vmcnt(9)
	ds_write_b128 v92, v[60:63] offset:26112
	s_waitcnt vmcnt(8)
	ds_write_b128 v92, v[64:67] offset:30464
	s_waitcnt vmcnt(7)
	ds_write_b128 v22, v[68:71] offset:53248
	s_waitcnt vmcnt(6)
	ds_write_b128 v22, v[72:75] offset:57856
	s_waitcnt vmcnt(5)
	ds_write_b128 v22, v[76:79] offset:62464
	s_waitcnt vmcnt(4)
	ds_write_b128 v93, v[80:83] offset:32256
	v_mad_u32_u24 v129, v107, s3, v104
	ds_read_b128 v[230:233], v129
	ds_read_b128 v[234:237], v129 offset:64
	ds_read_b128 v[238:241], v129 offset:128
	ds_read_b128 v[242:245], v129 offset:4480
	ds_read_b128 v[246:249], v129 offset:4544
	s_nop 0
	s_nop 0
	s_waitcnt lgkmcnt(13)
	s_waitcnt vmcnt(3)
	s_waitcnt lgkmcnt(4)
	v_mfma_f32_16x16x32_f16 v[0:3], v[230:233], v[36:39], 0
	ds_read_b128 v[230:233], v129 offset:192
	s_nop 0
	s_nop 0
	s_nop 0
	s_waitcnt vmcnt(2)
	s_waitcnt lgkmcnt(4)
	v_mfma_f32_16x16x32_f16 v[0:3], v[234:237], v[32:35], v[0:3]
	ds_read_b128 v[234:237], v129 offset:4352
	s_nop 0
	v_mbcnt_hi_u32_b32 v23, -1, v214
	v_xor_b32_e32 v40, 16, v23
	s_waitcnt vmcnt(1)
	s_waitcnt lgkmcnt(4)
	v_mfma_f32_16x16x32_f16 v[0:3], v[238:241], v[28:31], v[0:3]
	ds_read_b128 v[238:241], v129 offset:4416
	s_nop 0
	s_add_u32 s6, s5, 0x183420
	s_addc_u32 s7, s4, 0
	s_waitcnt vmcnt(0)
	s_waitcnt lgkmcnt(2)
	v_mfma_f32_16x16x32_f16 v[0:3], v[230:233], v[24:27], v[0:3]
	ds_read_b128 v[230:233], v129 offset:8704
	s_nop 0
	v_mov_b64_e32 v[52:53], s[6:7]
	ds_read_b128 v[44:47], v129 offset:13248
	s_nop 0
	s_waitcnt lgkmcnt(3)
	v_mfma_f32_16x16x32_f16 v[10:13], v[234:237], v[36:39], 0
	ds_read_b128 v[234:237], v129 offset:8768
	s_mov_b32 s11, 0xf149f2ca
	v_mad_i64_i32 v[50:51], s[6:7], v9, s10, v[52:53]
	s_nop 0
	s_waitcnt lgkmcnt(3)
	v_mfma_f32_16x16x32_f16 v[4:7], v[238:241], v[32:35], v[10:13]
	ds_read_b128 v[238:241], v129 offset:8832
	v_lshl_add_u64 v[50:51], v[50:51], 0, v[84:85]
	s_mov_b32 s9, 0x3db504f3
	v_lshlrev_b32_e32 v168, 3, v94
	s_nop 0
	v_and_b32_e32 v10, 64, v23
	v_add_u32_e32 v41, 64, v10
	s_nop 0
	v_mfma_f32_16x16x32_f16 v[4:7], v[242:245], v[28:31], v[4:7]
	ds_read_b128 v[242:245], v129 offset:13056
	s_nop 0
	v_cmp_lt_i32_e32 vcc, v40, v41
	v_lshl_add_u64 v[176:177], v[176:177], 0, v[168:169]
	v_mfma_f32_16x16x32_f16 v[18:21], v[246:249], v[24:27], v[4:7]
	ds_read_b128 v[246:249], v129 offset:13120
	v_cndmask_b32_e32 v40, v23, v40, vcc
	v_lshlrev_b32_e32 v173, 2, v40
	v_xor_b32_e32 v40, 32, v23
	s_nop 0
	s_nop 0
	s_nop 0
	s_waitcnt lgkmcnt(5)
	v_mfma_f32_16x16x32_f16 v[10:13], v[230:233], v[36:39], 0
	v_cmp_lt_i32_e32 vcc, v40, v41
	v_ashrrev_i32_e32 v175, 31, v174
	v_lshlrev_b64 v[174:175], 12, v[174:175]
	v_cndmask_b32_e32 v23, v23, v40, vcc
	ds_read_b128 v[40:43], v129 offset:8896
	s_nop 0
	s_waitcnt lgkmcnt(4)
	v_mfma_f32_16x16x32_f16 v[10:13], v[234:237], v[32:35], v[10:13]
	v_lshlrev_b32_e32 v225, 2, v23
	v_sub_u32_e32 v23, v104, v168
	v_mad_u32_u24 v100, v107, s8, v23
	s_nop 0
	s_waitcnt lgkmcnt(3)
	v_mfma_f32_16x16x32_f16 v[4:7], v[238:241], v[28:31], v[10:13]
	v_add_u32_e32 v131, 0x9800, v100
	v_add_u32_e32 v132, 0xa000, v100
	v_add_u32_e32 v133, 0xa800, v100
	s_nop 0
	s_nop 0
	s_waitcnt lgkmcnt(0)
	v_mfma_f32_16x16x32_f16 v[14:17], v[40:43], v[24:27], v[4:7]
	v_mad_i64_i32 v[40:41], s[6:7], v8, s10, v[52:53]
	v_lshl_add_u64 v[48:49], v[40:41], 0, v[84:85]
	s_nop 0
	s_nop 0
	ds_read_b128 v[40:43], v129 offset:13184
	s_nop 0
	v_mfma_f32_16x16x32_f16 v[10:13], v[242:245], v[36:39], 0
	v_add_u32_e32 v134, 0xb000, v100
	v_add_u32_e32 v135, 0xb800, v100
	v_add_u32_e32 v23, 0x8800, v100
	s_nop 0
	v_mfma_f32_16x16x32_f16 v[10:13], v[246:249], v[32:35], v[10:13]
	global_load_dwordx4 v[4:7], v[48:49], off
	s_nop 0
	global_load_dwordx4 v[48:51], v[50:51], off
	v_add_u32_e32 v136, 0xc000, v100
	v_add_u32_e32 v130, 0x9000, v100
	s_nop 0
	s_waitcnt lgkmcnt(0)
	v_mfma_f32_16x16x32_f16 v[10:13], v[40:43], v[28:31], v[10:13]
	v_mul_f32_e32 v42, 0x3db504f3, v0
	v_mul_f32_e32 v43, 0x3db504f3, v1
	v_max3_f32 v42, v42, s11, v43
	v_mfma_f32_16x16x32_f16 v[10:13], v[44:47], v[24:27], v[10:13]
	v_mul_f32_e32 v43, 0x3db504f3, v2
	v_mul_f32_e32 v44, 0x3db504f3, v3
	v_max3_f32 v42, v42, v43, v44
	v_mul_f32_e32 v43, 0x3db504f3, v18
	v_mul_f32_e32 v44, 0x3db504f3, v19
	v_max3_f32 v42, v42, v43, v44
	v_mul_f32_e32 v43, 0x3db504f3, v20
	v_mul_f32_e32 v44, 0x3db504f3, v21
	v_max3_f32 v42, v42, v43, v44
	v_mul_f32_e32 v43, 0x3db504f3, v14
	v_mul_f32_e32 v44, 0x3db504f3, v15
	v_max3_f32 v42, v42, v43, v44
	v_mul_f32_e32 v43, 0x3db504f3, v16
	v_mul_f32_e32 v44, 0x3db504f3, v17
	v_max3_f32 v42, v42, v43, v44
	v_mul_f32_e32 v43, 0x3db504f3, v10
	v_mul_f32_e32 v44, 0x3db504f3, v11
	v_max3_f32 v42, v42, v43, v44
	v_mul_f32_e32 v43, 0x3db504f3, v12
	v_mul_f32_e32 v44, 0x3db504f3, v13
	v_max3_f32 v44, v42, v43, v44
	ds_bpermute_b32 v45, v173, v44
	v_mad_i64_i32 v[40:41], s[6:7], v97, s10, v[52:53]
	v_lshl_add_u64 v[40:41], v[40:41], 0, v[84:85]
	v_mad_i64_i32 v[42:43], s[6:7], v95, s10, v[52:53]
	v_lshl_add_u64 v[42:43], v[42:43], 0, v[84:85]
	global_load_dwordx4 v[60:63], v[40:41], off
	global_load_dwordx4 v[64:67], v[42:43], off
	s_nop 0
	s_waitcnt lgkmcnt(0)
	v_max_f32_e32 v40, v45, v45
	v_max_f32_e32 v40, v44, v40
	ds_bpermute_b32 v41, v225, v40
	ds_read2_b64 v[230:233], v131 offset0:64 offset1:68
	ds_read2_b64 v[234:237], v132 offset0:96 offset1:100
	ds_read2_b64 v[238:241], v130 offset0:32 offset1:36
	ds_read2_b64 v[242:245], v133 offset0:128 offset1:132
	ds_read2_b64 v[246:249], v134 offset0:160 offset1:164
	global_load_dwordx4 v[68:71], v[86:87], off offset:256
	global_load_dwordx4 v[72:75], v[88:89], off offset:256
	global_load_dwordx4 v[76:79], v[90:91], off offset:256
	global_load_dwordx4 v[80:83], v[98:99], off offset:256
	s_nop 0
	s_nop 0
	s_nop 0
	s_nop 0
	s_waitcnt lgkmcnt(5)
	v_max3_f32 v101, v40, v41, s11
	v_fma_f32 v0, v0, s9, -v101
	v_mul_f32_e32 v0, 0x3fb8aa3b, v0
	v_exp_f32_e32 v137, v0
	v_fma_f32 v0, v1, s9, -v101
	v_mul_f32_e32 v0, 0x3fb8aa3b, v0
	v_exp_f32_e32 v138, v0
	v_fma_f32 v0, v2, s9, -v101
	v_mul_f32_e32 v0, 0x3fb8aa3b, v0
	v_exp_f32_e32 v96, v0
	v_fma_f32 v0, v3, s9, -v101
	v_mul_f32_e32 v0, 0x3fb8aa3b, v0
	v_exp_f32_e32 v94, v0
	v_fma_f32 v0, v18, s9, -v101
	v_mul_f32_e32 v0, 0x3fb8aa3b, v0
	v_exp_f32_e32 v108, v0
	v_fma_f32 v0, v19, s9, -v101
	v_mul_f32_e32 v0, 0x3fb8aa3b, v0
	v_exp_f32_e32 v104, v0
	v_fma_f32 v0, v20, s9, -v101
	v_mul_f32_e32 v0, 0x3fb8aa3b, v0
	v_exp_f32_e32 v110, v0
	v_fma_f32 v0, v21, s9, -v101
	v_mul_f32_e32 v0, 0x3fb8aa3b, v0
	v_sub_f32_e32 v40, 0xf149f2ca, v101
	v_exp_f32_e32 v106, v0
	v_fma_f32 v0, v14, s9, -v101
	v_mul_f32_e32 v40, 0x3fb8aa3b, v40
	v_mul_f32_e32 v0, 0x3fb8aa3b, v0
	v_exp_f32_e32 v112, v0
	v_exp_f32_e32 v0, v40
	v_fma_f32 v1, v15, s9, -v101
	v_fma_f32 v14, v16, s9, -v101
	v_mul_f32_e32 v1, 0x3fb8aa3b, v1
	v_mul_f32_e32 v0, 0, v0
	v_mul_f32_e32 v14, 0x3fb8aa3b, v14
	v_exp_f32_e32 v114, v1
	v_mov_b32_e32 v1, v0
	v_mov_b32_e32 v2, v0
	v_mov_b32_e32 v3, v0
	v_cvt_pk_f16_f32 v43, v110, v106
	v_cvt_pk_f16_f32 v42, v108, v104
	v_cvt_pk_f16_f32 v41, v96, v94
	v_cvt_pk_f16_f32 v40, v137, v138
	v_exp_f32_e32 v116, v14
	v_fma_f32 v14, v17, s9, -v101
	v_mul_f32_e32 v102, 0x3fb8aa3b, v14
	s_nop 0
	s_waitcnt lgkmcnt(4)
	v_mfma_f32_16x16x32_f16 v[14:17], v[230:233], v[40:43], v[0:3]
	ds_read2_b64 v[230:233], v23 offset1:4
	s_nop 0
	v_fma_f32 v10, v10, s9, -v101
	v_mul_f32_e32 v10, 0x3fb8aa3b, v10
	s_nop 0
	s_waitcnt lgkmcnt(4)
	v_mfma_f32_16x16x32_f16 v[140:143], v[234:237], v[40:43], v[0:3]
	ds_read2_b64 v[234:237], v135 offset0:192 offset1:196
	s_nop 0
	s_nop 0
	v_exp_f32_e32 v120, v10
	s_nop 0
	s_waitcnt lgkmcnt(3)
	v_mfma_f32_16x16x32_f16 v[144:147], v[242:245], v[40:43], v[0:3]
	ds_read2_b64 v[242:245], v136 offset0:224 offset1:228
	s_nop 0
	v_fma_f32 v10, v11, s9, -v101
	v_mul_f32_e32 v103, 0x3fb8aa3b, v10
	v_fma_f32 v10, v12, s9, -v101
	v_mul_f32_e32 v10, 0x3fb8aa3b, v10
	v_exp_f32_e32 v118, v10
	v_fma_f32 v10, v13, s9, -v101
	s_nop 0
	s_waitcnt lgkmcnt(3)
	v_mfma_f32_16x16x32_f16 v[148:151], v[246:249], v[40:43], v[0:3]
	ds_read2_b64 v[246:249], v23 offset0:8 offset1:12
	s_nop 0
	v_mul_f32_e32 v105, 0x3fb8aa3b, v10
	v_exp_f32_e32 v122, v105
	s_nop 0
	s_waitcnt lgkmcnt(2)
	v_mfma_f32_16x16x32_f16 v[10:13], v[234:237], v[40:43], v[0:3]
	ds_read2_b64 v[234:237], v130 offset0:40 offset1:44
	s_nop 0
	v_exp_f32_e32 v124, v103
	v_exp_f32_e32 v126, v102
	v_mfma_f32_16x16x32_f16 v[18:21], v[230:233], v[40:43], v[0:3]
	ds_read2_b64 v[230:233], v131 offset0:72 offset1:76
	v_cvt_pk_f16_f32 v159, v118, v122
	v_cvt_pk_f16_f32 v158, v120, v124
	v_cvt_pk_f16_f32 v157, v116, v126
	v_cvt_pk_f16_f32 v156, v112, v114
	s_nop 0
	s_waitcnt lgkmcnt(3)
	v_mfma_f32_16x16x32_f16 v[152:155], v[242:245], v[40:43], v[0:3]
	ds_read2_b64 v[242:245], v132 offset0:104 offset1:108
	s_add_u32 s6, s5, 0x243c20
	s_addc_u32 s7, s4, 0
	v_add_u32_e32 v189, 0xf800, v100
	s_nop 0
	s_waitcnt lgkmcnt(3)
	v_mfma_f32_16x16x32_f16 v[56:59], v[246:249], v[156:159], v[18:21]
	ds_read2_b64 v[246:249], v133 offset0:136 offset1:140
	v_add_u32_e32 v187, 0xf000, v100
	v_add_co_u32_e32 v222, vcc, s33, v176
	s_nop 0
	s_nop 0
	v_mfma_f32_16x16x32_f16 v[44:47], v[238:241], v[40:43], v[0:3]
	ds_read2_b64 v[238:241], v135 offset0:200 offset1:204
	v_addc_co_u32_e32 v223, vcc, 0, v177, vcc
	v_lshl_add_u64 v[174:175], s[20:21], 0, v[174:175]
	s_nop 0
	s_waitcnt lgkmcnt(4)
	v_mfma_f32_16x16x32_f16 v[52:55], v[234:237], v[156:159], v[44:47]
	s_nop 0
	v_lshl_add_u64 v[174:175], v[174:175], 0, s[0:1]
	s_mov_b32 s0, 0x4800000
	s_nop 0
	s_waitcnt lgkmcnt(3)
	v_mfma_f32_16x16x32_f16 v[44:47], v[230:233], v[156:159], v[14:17]
	s_nop 2
	s_nop 0
	s_movk_i32 s3, 0x3020
	s_mov_b32 s2, 0xf149f2ca
	s_nop 0
	s_waitcnt lgkmcnt(2)
	v_mfma_f32_16x16x32_f16 v[40:43], v[242:245], v[156:159], v[140:143]
	s_nop 0
	s_nop 1
	s_nop 0
	s_nop 0
	s_waitcnt lgkmcnt(1)
	v_mfma_f32_16x16x32_f16 v[18:21], v[246:249], v[156:159], v[144:147]
	ds_read2_b64 v[14:17], v134 offset0:168 offset1:172
	s_nop 0
	s_waitcnt lgkmcnt(1)
	v_mfma_f32_16x16x32_f16 v[10:13], v[238:241], v[156:159], v[10:13]
	ds_read2_b64 v[140:143], v136 offset0:232 offset1:236
	s_nop 0
	s_waitcnt lgkmcnt(0)
	s_barrier
	s_waitcnt vmcnt(7)
	ds_write_b128 v92, v[4:7]
	s_waitcnt vmcnt(6)
	ds_write_b128 v92, v[48:51] offset:4352
	s_waitcnt vmcnt(5)
	ds_write_b128 v92, v[60:63] offset:8704
	s_waitcnt vmcnt(4)
	ds_write_b128 v92, v[64:67] offset:13056
	s_waitcnt vmcnt(3)
	ds_write_b128 v22, v[68:71] offset:34816
	s_waitcnt vmcnt(2)
	ds_write_b128 v22, v[72:75] offset:39424
	s_waitcnt vmcnt(1)
	ds_write_b128 v22, v[76:79] offset:44032
	s_waitcnt vmcnt(0)
	ds_write_b128 v22, v[80:83] offset:48640
	ds_read_b128 v[230:233], v129 offset:17408
	ds_read_b128 v[234:237], v129 offset:17472
	ds_read_b128 v[238:241], v129 offset:17536
	ds_read_b128 v[242:245], v129 offset:30656
	ds_read_b128 v[246:249], v129 offset:17600
	s_nop 0
	s_nop 0
	s_waitcnt lgkmcnt(13)
	s_waitcnt lgkmcnt(4)
	v_mfma_f32_16x16x32_f16 v[2:5], v[230:233], v[36:39], 0
	ds_read_b128 v[230:233], v129 offset:21760
	s_nop 0
	s_nop 0
	v_mov_b64_e32 v[72:73], s[6:7]
	s_nop 0
	s_waitcnt lgkmcnt(4)
	v_mfma_f32_16x16x32_f16 v[2:5], v[234:237], v[32:35], v[2:5]
	ds_read_b128 v[234:237], v129 offset:21824
	s_nop 0
	v_mad_i64_i32 v[6:7], s[4:5], v8, s10, v[72:73]
	s_nop 0
	s_waitcnt lgkmcnt(4)
	v_mfma_f32_16x16x32_f16 v[2:5], v[238:241], v[28:31], v[2:5]
	ds_read_b128 v[238:241], v129 offset:21888
	s_nop 0
	v_mad_i64_i32 v[8:9], s[4:5], v9, s10, v[72:73]
	s_nop 0
	s_waitcnt lgkmcnt(3)
	v_mfma_f32_16x16x32_f16 v[80:83], v[246:249], v[24:27], v[2:5]
	ds_read_b128 v[246:249], v129 offset:21952
	v_lshl_add_u64 v[6:7], v[6:7], 0, v[84:85]
	v_lshl_add_u64 v[8:9], v[8:9], 0, v[84:85]
	s_nop 1
	s_nop 0
	s_nop 0
	s_waitcnt lgkmcnt(3)
	v_mfma_f32_16x16x32_f16 v[60:63], v[230:233], v[36:39], 0
	ds_read_b128 v[230:233], v129 offset:26112
	s_nop 0
	v_mul_f32_e32 v1, 0x3db504f3, v80
	s_nop 0
	s_waitcnt lgkmcnt(3)
	v_mfma_f32_16x16x32_f16 v[2:5], v[234:237], v[32:35], v[60:63]
	ds_read_b128 v[234:237], v129 offset:26176
	s_nop 3
	s_nop 0
	s_nop 0
	s_waitcnt lgkmcnt(3)
	v_mfma_f32_16x16x32_f16 v[2:5], v[238:241], v[28:31], v[2:5]
	ds_read_b128 v[238:241], v129 offset:26240
	s_nop 0
	v_mfma_f32_16x16x32_f16 v[48:51], v[140:143], v[156:159], v[152:155]
	s_nop 0
	s_waitcnt lgkmcnt(3)
	v_mfma_f32_16x16x32_f16 v[140:143], v[246:249], v[24:27], v[2:5]
	ds_read_b128 v[246:249], v129 offset:26304
	s_nop 3
	s_nop 0
	s_nop 0
	s_waitcnt lgkmcnt(3)
	v_mfma_f32_16x16x32_f16 v[60:63], v[230:233], v[36:39], 0
	ds_read_b128 v[230:233], v129 offset:30464
	s_nop 0
	s_nop 0
	s_waitcnt lgkmcnt(3)
	v_mfma_f32_16x16x32_f16 v[2:5], v[234:237], v[32:35], v[60:63]
	ds_read_b128 v[234:237], v129 offset:30592
	s_nop 4
	s_nop 0
	s_nop 0
	s_waitcnt lgkmcnt(3)
	v_mfma_f32_16x16x32_f16 v[2:5], v[238:241], v[28:31], v[2:5]
	ds_read_b128 v[238:241], v129 offset:30528
	s_nop 0
	s_nop 0
	s_waitcnt lgkmcnt(3)
	v_mfma_f32_16x16x32_f16 v[144:147], v[246:249], v[24:27], v[2:5]
	s_nop 0
	s_nop 3
	s_nop 0
	s_nop 0
	s_waitcnt lgkmcnt(2)
	v_mfma_f32_16x16x32_f16 v[64:67], v[230:233], v[36:39], 0
	s_nop 0
	s_waitcnt lgkmcnt(0)
	v_mfma_f32_16x16x32_f16 v[64:67], v[238:241], v[32:35], v[64:67]
	global_load_dwordx4 v[2:5], v[6:7], off
	s_nop 0
	global_load_dwordx4 v[6:9], v[8:9], off
	v_mfma_f32_16x16x32_f16 v[60:63], v[234:237], v[28:31], v[64:67]
	v_mfma_f32_16x16x32_f16 v[68:71], v[242:245], v[24:27], v[60:63]
	s_nop 2
	v_mad_i64_i32 v[64:65], s[4:5], v97, s10, v[72:73]
	v_lshl_add_u64 v[64:65], v[64:65], 0, v[84:85]
	s_nop 1
	v_mul_f32_e32 v60, 0x3db504f3, v81
	v_max3_f32 v1, v1, s11, v60
	v_mul_f32_e32 v60, 0x3db504f3, v82
	v_mul_f32_e32 v61, 0x3db504f3, v83
	v_max3_f32 v1, v1, v60, v61
	v_mul_f32_e32 v60, 0x3db504f3, v140
	v_mul_f32_e32 v61, 0x3db504f3, v141
	v_max3_f32 v1, v1, v60, v61
	v_mul_f32_e32 v60, 0x3db504f3, v142
	v_mul_f32_e32 v61, 0x3db504f3, v143
	v_max3_f32 v1, v1, v60, v61
	v_mul_f32_e32 v60, 0x3db504f3, v144
	v_mul_f32_e32 v61, 0x3db504f3, v145
	v_max3_f32 v1, v1, v60, v61
	v_mul_f32_e32 v60, 0x3db504f3, v146
	v_mul_f32_e32 v61, 0x3db504f3, v147
	v_max3_f32 v1, v1, v60, v61
	v_mul_f32_e32 v60, 0x3db504f3, v68
	v_mul_f32_e32 v61, 0x3db504f3, v69
	v_max3_f32 v1, v1, v60, v61
	v_mul_f32_e32 v60, 0x3db504f3, v70
	v_mul_f32_e32 v61, 0x3db504f3, v71
	v_max3_f32 v1, v1, v60, v61
	ds_bpermute_b32 v74, v173, v1
	v_mad_i64_i32 v[60:61], s[4:5], v95, s10, v[72:73]
	v_lshl_add_u64 v[66:67], v[60:61], 0, v[84:85]
	global_load_dwordx4 v[60:63], v[64:65], off
	s_nop 0
	global_load_dwordx4 v[64:67], v[66:67], off
	s_nop 0
	s_waitcnt lgkmcnt(0)
	v_max_f32_e32 v72, v74, v74
	v_max_f32_e32 v1, v1, v72
	ds_bpermute_b32 v95, v225, v1
	global_load_dwordx4 v[72:75], v[86:87], off offset:384
	global_load_dwordx4 v[76:79], v[88:89], off offset:384
	s_nop 0
	global_load_dwordx4 v[84:87], v[90:91], off offset:384
	s_nop 0
	global_load_dwordx4 v[88:91], v[98:99], off offset:384
	v_mfma_f32_16x16x32_f16 v[14:17], v[14:17], v[156:159], v[148:151]
	s_nop 0
	s_waitcnt lgkmcnt(0)
	v_max3_f32 v139, v101, v1, v95
	v_fma_f32 v80, v80, s9, -v139
	v_mul_f32_e32 v80, 0x3fb8aa3b, v80
	v_exp_f32_e32 v97, v80
	v_fma_f32 v80, v81, s9, -v139
	v_mul_f32_e32 v80, 0x3fb8aa3b, v80
	v_exp_f32_e32 v95, v80
	v_fma_f32 v80, v82, s9, -v139
	v_mul_f32_e32 v80, 0x3fb8aa3b, v80
	v_exp_f32_e32 v109, v80
	v_fma_f32 v80, v83, s9, -v139
	v_mul_f32_e32 v80, 0x3fb8aa3b, v80
	v_exp_f32_e32 v105, v80
	v_fma_f32 v80, v140, s9, -v139
	v_mul_f32_e32 v80, 0x3fb8aa3b, v80
	v_exp_f32_e32 v111, v80
	v_fma_f32 v80, v141, s9, -v139
	v_mul_f32_e32 v80, 0x3fb8aa3b, v80
	v_exp_f32_e32 v107, v80
	v_fma_f32 v80, v142, s9, -v139
	v_mul_f32_e32 v80, 0x3fb8aa3b, v80
	v_exp_f32_e32 v113, v80
	v_fma_f32 v80, v143, s9, -v139
	v_mul_f32_e32 v80, 0x3fb8aa3b, v80
	v_exp_f32_e32 v115, v80
	v_fma_f32 v80, v144, s9, -v139
	v_mul_f32_e32 v80, 0x3fb8aa3b, v80
	v_exp_f32_e32 v117, v80
	v_fma_f32 v80, v145, s9, -v139
	v_mul_f32_e32 v80, 0x3fb8aa3b, v80
	v_exp_f32_e32 v127, v80
	v_fma_f32 v80, v146, s9, -v139
	v_mul_f32_e32 v80, 0x3fb8aa3b, v80
	v_exp_f32_e32 v121, v80
	v_fma_f32 v80, v147, s9, -v139
	v_mul_f32_e32 v80, 0x3fb8aa3b, v80
	v_add_u32_e32 v140, 0xd000, v100
	ds_read2_b64 v[246:249], v140 offset1:4
	v_exp_f32_e32 v125, v80
	s_nop 0
	v_sub_f32_e32 v1, v101, v139
	v_mul_f32_e32 v1, 0x3fb8aa3b, v1
	v_exp_f32_e32 v128, v1
	v_add_u32_e32 v141, 0xd800, v100
	ds_read2_b64 v[230:233], v141 offset0:32 offset1:36
	s_nop 0
	v_cvt_pk_f16_f32 v147, v113, v115
	v_pk_mul_f32 v[58:59], v[58:59], v[128:129] op_sel_hi:[1,0]
	v_pk_mul_f32 v[56:57], v[56:57], v[128:129] op_sel_hi:[1,0]
	v_cvt_pk_f16_f32 v146, v111, v107
	v_cvt_pk_f16_f32 v145, v109, v105
	v_cvt_pk_f16_f32 v144, v97, v95
	v_add_u32_e32 v142, 0xe000, v100
	ds_read2_b64 v[238:241], v142 offset0:64 offset1:68
	ds_read2_b64 v[234:237], v189 offset0:160 offset1:164
	v_fma_f32 v68, v68, s9, -v139
	s_nop 0
	s_waitcnt lgkmcnt(3)
	v_mfma_f32_16x16x32_f16 v[56:59], v[246:249], v[144:147], v[56:59]
	s_nop 0
	v_mul_f32_e32 v68, 0x3fb8aa3b, v68
	v_exp_f32_e32 v119, v68
	v_fma_f32 v68, v69, s9, -v139
	v_mul_f32_e32 v68, 0x3fb8aa3b, v68
	v_exp_f32_e32 v123, v68
	v_fma_f32 v68, v70, s9, -v139
	v_pk_mul_f32 v[54:55], v[54:55], v[128:129] op_sel_hi:[1,0]
	v_pk_mul_f32 v[52:53], v[52:53], v[128:129] op_sel_hi:[1,0]
	v_add_u32_e32 v143, 0xe800, v100
	ds_read2_b64 v[242:245], v143 offset0:96 offset1:100
	s_nop 0
	v_add_u32_e32 v191, 0x3000, v140
	ds_read2_b64 v[246:249], v191 offset0:192 offset1:196
	v_mul_f32_e32 v1, 0x3fb8aa3b, v68
	s_nop 0
	s_waitcnt lgkmcnt(4)
	v_mfma_f32_16x16x32_f16 v[52:55], v[230:233], v[144:147], v[52:55]
	ds_read2_b64 v[230:233], v140 offset0:8 offset1:12
	s_nop 0
	v_fma_f32 v102, v71, s9, -v139
	s_nop 0
	v_pk_mul_f32 v[46:47], v[46:47], v[128:129] op_sel_hi:[1,0]
	v_pk_mul_f32 v[44:45], v[44:45], v[128:129] op_sel_hi:[1,0]
	v_pk_mul_f32 v[16:17], v[16:17], v[128:129] op_sel_hi:[1,0]
	v_pk_mul_f32 v[14:15], v[14:15], v[128:129] op_sel_hi:[1,0]
	s_nop 0
	s_waitcnt lgkmcnt(4)
	v_mfma_f32_16x16x32_f16 v[44:47], v[238:241], v[144:147], v[44:47]
	ds_read2_b64 v[238:241], v141 offset0:40 offset1:44
	ds_read2_b64 v[80:83], v187 offset0:128 offset1:132
	v_add_u32_e32 v193, 0x3800, v140
	v_pk_mul_f32 v[42:43], v[42:43], v[128:129] op_sel_hi:[1,0]
	v_pk_mul_f32 v[40:41], v[40:41], v[128:129] op_sel_hi:[1,0]
	s_nop 0
	s_waitcnt lgkmcnt(5)
	v_mfma_f32_16x16x32_f16 v[98:101], v[234:237], v[144:147], v[14:17]
	ds_read2_b64 v[234:237], v142 offset0:72 offset1:76
	v_mul_f32_e64 v12, v12, v128
	v_mul_f32_e64 v13, v13, v128
	v_pk_mul_f32 v[10:11], v[10:11], v[128:129] op_sel_hi:[1,0]
	v_pk_mul_f32 v[20:21], v[20:21], v[128:129] op_sel_hi:[1,0]
	ds_read2_b64 v[14:17], v193 offset0:224 offset1:228
	s_nop 0
	s_waitcnt lgkmcnt(6)
	v_mfma_f32_16x16x32_f16 v[40:43], v[242:245], v[144:147], v[40:43]
	ds_read2_b64 v[242:245], v143 offset0:104 offset1:108
	v_mul_f32_e64 v18, v18, v128
	v_mul_f32_e64 v19, v19, v128
	v_exp_f32_e32 v1, v1
	v_pk_mul_f32 v[50:51], v[50:51], v[128:129] op_sel_hi:[1,0]
	s_nop 0
	s_waitcnt lgkmcnt(6)
	v_mfma_f32_16x16x32_f16 v[148:151], v[246:249], v[144:147], v[10:13]
	ds_read2_b64 v[246:249], v187 offset0:136 offset1:140
	v_mul_f32_e64 v48, v48, v128
	v_mul_f32_e64 v49, v49, v128
	s_nop 0
	s_nop 0
	s_nop 0
	s_waitcnt lgkmcnt(4)
	v_mfma_f32_16x16x32_f16 v[18:21], v[80:83], v[144:147], v[18:21]
	v_mul_f32_e32 v80, 0x3fb8aa3b, v102
	v_exp_f32_e32 v152, v80
	s_nop 0
	s_waitcnt lgkmcnt(2)
	v_mfma_f32_16x16x32_f16 v[48:51], v[14:17], v[144:147], v[48:51]
	v_cvt_pk_f16_f32 v146, v119, v123
	v_cvt_pk_f16_f32 v147, v1, v152
	v_cvt_pk_f16_f32 v145, v121, v125
	v_cvt_pk_f16_f32 v144, v117, v127
	s_nop 0
	s_nop 0
	v_mfma_f32_16x16x32_f16 v[80:83], v[230:233], v[144:147], v[56:59]
	s_nop 0
	s_nop 0
	v_mfma_f32_16x16x32_f16 v[68:71], v[238:241], v[144:147], v[52:55]
	s_nop 0
	s_nop 0
	v_mfma_f32_16x16x32_f16 v[56:59], v[234:237], v[144:147], v[44:47]
	s_nop 0
	s_nop 0
	s_waitcnt lgkmcnt(1)
	v_mfma_f32_16x16x32_f16 v[44:47], v[242:245], v[144:147], v[40:43]
	s_nop 0
	s_nop 0
	s_waitcnt lgkmcnt(0)
	v_mfma_f32_16x16x32_f16 v[16:19], v[246:249], v[144:147], v[18:21]
	ds_read2_b64 v[10:13], v189 offset0:168 offset1:172
	ds_read2_b64 v[40:43], v191 offset0:200 offset1:204
	ds_read2_b64 v[52:55], v193 offset0:232 offset1:236
	s_nop 0
	s_waitcnt lgkmcnt(0)
	s_barrier
	s_waitcnt vmcnt(7)
	ds_write_b128 v92, v[2:5] offset:17408
	s_waitcnt vmcnt(6)
	ds_write_b128 v92, v[6:9] offset:21760
	s_waitcnt vmcnt(5)
	ds_write_b128 v92, v[60:63] offset:26112
	s_waitcnt vmcnt(4)
	ds_write_b128 v92, v[64:67] offset:30464
	s_waitcnt vmcnt(3)
	ds_write_b128 v22, v[72:75] offset:53248
	s_waitcnt vmcnt(2)
	ds_write_b128 v22, v[76:79] offset:57856
	s_waitcnt vmcnt(1)
	ds_write_b128 v22, v[84:87] offset:62464
	s_waitcnt vmcnt(0)
	ds_write_b128 v93, v[88:91] offset:32256
	ds_read_b128 v[230:233], v129
	ds_read_b128 v[234:237], v129 offset:64
	ds_read_b128 v[238:241], v129 offset:128
	ds_read_b128 v[242:245], v129 offset:4480
	ds_read_b128 v[246:249], v129 offset:8896
	s_nop 0
	v_mfma_f32_16x16x32_f16 v[8:11], v[10:13], v[144:147], v[98:101]
	s_nop 0
	s_nop 0
	s_nop 0
	s_waitcnt lgkmcnt(13)
	s_waitcnt lgkmcnt(4)
	v_mfma_f32_16x16x32_f16 v[2:5], v[230:233], v[36:39], 0
	ds_read_b128 v[230:233], v129 offset:192
	s_nop 0
	v_add_f32_e32 v6, 0, v137
	v_add_f32_e32 v6, v138, v6
	s_nop 0
	s_waitcnt lgkmcnt(4)
	v_mfma_f32_16x16x32_f16 v[2:5], v[234:237], v[32:35], v[2:5]
	ds_read_b128 v[234:237], v129 offset:4352
	s_nop 0
	v_mov_b32_e32 v7, v169
	v_pk_add_f32 v[6:7], v[96:97], v[6:7]
	s_nop 0
	s_waitcnt lgkmcnt(4)
	v_mfma_f32_16x16x32_f16 v[2:5], v[238:241], v[28:31], v[2:5]
	ds_read_b128 v[238:241], v129 offset:4416
	s_nop 0
	s_nop 0
	s_waitcnt lgkmcnt(2)
	v_mfma_f32_16x16x32_f16 v[12:15], v[230:233], v[24:27], v[2:5]
	ds_read_b128 v[230:233], v129 offset:4544
	s_nop 4
	s_nop 0
	s_nop 0
	s_waitcnt lgkmcnt(2)
	v_mfma_f32_16x16x32_f16 v[60:63], v[234:237], v[36:39], 0
	ds_read_b128 v[234:237], v129 offset:8704
	s_nop 0
	s_waitcnt lgkmcnt(2)
	v_mfma_f32_16x16x32_f16 v[2:5], v[238:241], v[32:35], v[60:63]
	ds_read_b128 v[238:241], v129 offset:8768
	s_nop 5
	s_nop 0
	v_mfma_f32_16x16x32_f16 v[2:5], v[242:245], v[28:31], v[2:5]
	ds_read_b128 v[242:245], v129 offset:8832
	s_nop 0
	s_nop 0
	s_waitcnt lgkmcnt(3)
	v_mfma_f32_16x16x32_f16 v[100:103], v[230:233], v[24:27], v[2:5]
	ds_read_b128 v[230:233], v129 offset:13056
	s_nop 4
	s_nop 0
	s_nop 0
	s_waitcnt lgkmcnt(3)
	v_mfma_f32_16x16x32_f16 v[60:63], v[234:237], v[36:39], 0
	ds_read_b128 v[234:237], v129 offset:13120
	s_nop 0
	s_nop 0
	s_waitcnt lgkmcnt(3)
	v_mfma_f32_16x16x32_f16 v[2:5], v[238:241], v[32:35], v[60:63]
	ds_read_b128 v[238:241], v129 offset:13248
	s_nop 4
	s_nop 0
	s_nop 0
	s_waitcnt lgkmcnt(3)
	v_mfma_f32_16x16x32_f16 v[2:5], v[242:245], v[28:31], v[2:5]
	ds_read_b128 v[242:245], v129 offset:13184
	s_nop 0
	v_mfma_f32_16x16x32_f16 v[96:99], v[246:249], v[24:27], v[2:5]
	s_nop 0
	s_nop 4
	v_pk_add_f32 v[2:3], v[94:95], v[6:7]
	s_nop 0
	s_waitcnt lgkmcnt(3)
	v_mfma_f32_16x16x32_f16 v[60:63], v[230:233], v[36:39], 0
	v_add_f32_e64 v6, v108, v2
	v_add_f32_e64 v7, v109, v3
	s_nop 0
	v_pk_add_f32 v[6:7], v[104:105], v[6:7]
	s_nop 0
	s_waitcnt lgkmcnt(2)
	v_mfma_f32_16x16x32_f16 v[60:63], v[234:237], v[32:35], v[60:63]
	v_add_f32_e64 v6, v110, v6
	v_add_f32_e64 v7, v111, v7
	v_pk_add_f32 v[6:7], v[106:107], v[6:7]
	s_nop 0
	s_waitcnt lgkmcnt(0)
	v_mfma_f32_16x16x32_f16 v[2:5], v[242:245], v[28:31], v[60:63]
	v_add_f32_e64 v6, v112, v6
	v_add_f32_e64 v7, v113, v7
	v_pk_add_f32 v[6:7], v[114:115], v[6:7]
	v_mfma_f32_16x16x32_f16 v[88:91], v[238:241], v[24:27], v[2:5]
	v_add_f32_e64 v6, v116, v6
	v_add_f32_e64 v7, v117, v7
	v_pk_add_f32 v[6:7], v[126:127], v[6:7]
	s_nop 0
	v_mul_f32_e32 v2, 0x3db504f3, v12
	v_mul_f32_e32 v3, 0x3db504f3, v13
	v_max3_f32 v2, v2, s11, v3
	v_mul_f32_e32 v3, 0x3db504f3, v14
	v_mul_f32_e32 v4, 0x3db504f3, v15
	v_max3_f32 v2, v2, v3, v4
	v_mul_f32_e32 v3, 0x3db504f3, v100
	v_mul_f32_e32 v4, 0x3db504f3, v101
	v_max3_f32 v2, v2, v3, v4
	v_mul_f32_e32 v3, 0x3db504f3, v102
	v_mul_f32_e32 v4, 0x3db504f3, v103
	v_max3_f32 v2, v2, v3, v4
	v_mul_f32_e32 v3, 0x3db504f3, v96
	v_mul_f32_e32 v4, 0x3db504f3, v97
	v_max3_f32 v2, v2, v3, v4
	v_mul_f32_e32 v3, 0x3db504f3, v98
	v_mul_f32_e32 v4, 0x3db504f3, v99
	v_max3_f32 v2, v2, v3, v4
	v_mul_f32_e32 v3, 0x3db504f3, v88
	v_mul_f32_e32 v4, 0x3db504f3, v89
	v_max3_f32 v2, v2, v3, v4
	v_mul_f32_e32 v3, 0x3db504f3, v90
	v_mul_f32_e32 v4, 0x3db504f3, v91
	v_max3_f32 v20, v2, v3, v4
	ds_bpermute_b32 v21, v173, v20
	v_pk_add_f32 v[6:7], v[120:121], v[6:7]
	s_nop 0
	s_waitcnt lgkmcnt(0)
	v_max_f32_e32 v21, v21, v21
	v_max_f32_e32 v22, v20, v21
	v_pk_add_f32 v[2:3], v[124:125], v[6:7]
	v_mfma_f32_16x16x32_f16 v[4:7], v[40:43], v[144:147], v[148:151]
	ds_bpermute_b32 v40, v225, v22
	v_pk_add_f32 v[2:3], v[118:119], v[2:3]
	s_nop 0
	s_waitcnt lgkmcnt(0)
	v_max3_f32 v114, v139, v22, v40
	v_fma_f32 v12, v12, s9, -v114
	v_pk_add_f32 v[2:3], v[122:123], v[2:3]
	v_mul_f32_e32 v12, 0x3fb8aa3b, v12
	v_pk_add_f32 v[20:21], v[0:1], v[2:3]
	v_exp_f32_e32 v115, v12
	v_fma_f32 v12, v13, s9, -v114
	v_add_f32_e32 v113, v21, v152
	v_mul_f32_e32 v12, 0x3fb8aa3b, v12
	v_fmac_f32_e32 v113, v20, v128
	v_exp_f32_e32 v128, v12
	v_sub_f32_e32 v12, v139, v114
	v_mul_f32_e32 v138, 0x3fb8aa3b, v12
	v_add_f32_e32 v12, 0, v115
	v_add_f32_e32 v112, v128, v12
	v_fma_f32 v12, v14, s9, -v114
	v_mul_f32_e32 v12, 0x3fb8aa3b, v12
	v_exp_f32_e32 v178, v12
	v_fma_f32 v12, v15, s9, -v114
	v_mul_f32_e32 v12, 0x3fb8aa3b, v12
	v_exp_f32_e32 v180, v12
	v_fma_f32 v12, v100, s9, -v114
	v_mul_f32_e32 v12, 0x3fb8aa3b, v12
	v_mfma_f32_16x16x32_f16 v[0:3], v[52:55], v[144:147], v[48:51]
	v_exp_f32_e32 v182, v12
	ds_read2_b64 v[104:107], v23 offset1:4
	ds_read2_b64 v[116:119], v130 offset0:32 offset1:36
	ds_read2_b64 v[92:95], v131 offset0:64 offset1:68
	ds_read2_b64 v[76:79], v132 offset0:96 offset1:100
	ds_read2_b64 v[64:67], v133 offset0:128 offset1:132
	ds_read2_b64 v[52:55], v134 offset0:160 offset1:164
	ds_read2_b64 v[40:43], v135 offset0:192 offset1:196
	ds_read2_b64 v[12:15], v136 offset0:224 offset1:228
	ds_read2_b64 v[120:123], v23 offset0:8 offset1:12
	ds_read2_b64 v[124:127], v130 offset0:40 offset1:44
	ds_read2_b64 v[108:111], v131 offset0:72 offset1:76
	ds_read2_b64 v[84:87], v132 offset0:104 offset1:108
	ds_read2_b64 v[72:75], v133 offset0:136 offset1:140
	ds_read2_b64 v[60:63], v134 offset0:168 offset1:172
	ds_read2_b64 v[48:51], v135 offset0:200 offset1:204
	s_waitcnt lgkmcnt(14)
	ds_read2_b64 v[20:23], v136 offset0:232 offset1:236
	s_nop 0
	s_waitcnt lgkmcnt(0)
	s_barrier
	ds_read_b128 v[230:233], v129 offset:17408
	ds_read_b128 v[234:237], v129 offset:17472
	ds_read_b128 v[238:241], v129 offset:17536
	ds_read_b128 v[242:245], v129 offset:17600
	ds_read_b128 v[246:249], v129 offset:21760
	s_nop 0
	s_nop 0
	v_fma_f32 v100, v101, s9, -v114
	v_mul_f32_e32 v100, 0x3fb8aa3b, v100
	v_exp_f32_e32 v184, v100
	v_fma_f32 v100, v102, s9, -v114
	v_mul_f32_e32 v100, 0x3fb8aa3b, v100
	v_exp_f32_e32 v186, v100
	v_fma_f32 v139, v103, s9, -v114
	s_nop 0
	s_nop 0
	s_waitcnt lgkmcnt(5)
	s_waitcnt lgkmcnt(4)
	v_mfma_f32_16x16x32_f16 v[130:133], v[230:233], v[36:39], 0
	ds_read_b128 v[230:233], v129 offset:21824
	v_fma_f32 v96, v96, s9, -v114
	v_mul_f32_e32 v96, 0x3fb8aa3b, v96
	v_exp_f32_e32 v190, v96
	s_nop 0
	s_waitcnt lgkmcnt(4)
	v_mfma_f32_16x16x32_f16 v[130:133], v[234:237], v[32:35], v[130:133]
	ds_read_b128 v[234:237], v129 offset:21952
	s_nop 0
	v_fma_f32 v96, v97, s9, -v114
	v_mul_f32_e32 v96, 0x3fb8aa3b, v96
	s_nop 0
	s_waitcnt lgkmcnt(4)
	v_mfma_f32_16x16x32_f16 v[100:103], v[238:241], v[28:31], v[130:133]
	ds_read_b128 v[238:241], v129 offset:26112
	v_mul_f32_e32 v139, 0x3fb8aa3b, v139
	v_exp_f32_e32 v194, v96
	v_fma_f32 v96, v98, s9, -v114
	s_nop 0
	s_nop 0
	s_waitcnt lgkmcnt(4)
	v_mfma_f32_16x16x32_f16 v[144:147], v[242:245], v[24:27], v[100:103]
	ds_read_b128 v[242:245], v129 offset:26176
	v_exp_f32_e32 v188, v139
	v_mul_f32_e32 v96, 0x3fb8aa3b, v96
	v_fma_f32 v139, v99, s9, -v114
	ds_read_b128 v[100:103], v129 offset:21888
	s_nop 0
	s_nop 0
	s_waitcnt lgkmcnt(5)
	v_mfma_f32_16x16x32_f16 v[134:137], v[246:249], v[36:39], 0
	ds_read_b128 v[246:249], v129 offset:26240
	v_exp_f32_e32 v192, v96
	v_fma_f32 v88, v88, s9, -v114
	v_mul_f32_e32 v88, 0x3fb8aa3b, v88
	s_nop 0
	s_waitcnt lgkmcnt(5)
	v_mfma_f32_16x16x32_f16 v[130:133], v[230:233], v[32:35], v[134:137]
	ds_read_b128 v[230:233], v129 offset:30592
	v_exp_f32_e32 v198, v88
	v_fma_f32 v88, v89, s9, -v114
	v_mul_f32_e32 v88, 0x3fb8aa3b, v88
	s_nop 0
	s_nop 0
	s_waitcnt lgkmcnt(2)
	v_mfma_f32_16x16x32_f16 v[96:99], v[100:103], v[28:31], v[130:133]
	v_mul_f32_e32 v100, 0x3fb8aa3b, v139
	v_exp_f32_e32 v196, v100
	s_nop 0
	s_nop 0
	s_nop 0
	v_mfma_f32_16x16x32_f16 v[134:137], v[238:241], v[36:39], 0
	ds_read_b128 v[238:241], v129 offset:30464
	v_exp_f32_e32 v200, v88
	v_fma_f32 v88, v90, s9, -v114
	v_mul_f32_e32 v88, 0x3fb8aa3b, v88
	s_nop 0
	v_mfma_f32_16x16x32_f16 v[100:103], v[242:245], v[32:35], v[134:137]
	ds_read_b128 v[242:245], v129 offset:26304
	v_exp_f32_e32 v202, v88
	v_fma_f32 v139, v91, s9, -v114
	s_nop 0
	s_nop 0
	v_mfma_f32_16x16x32_f16 v[96:99], v[234:237], v[24:27], v[96:99]
	ds_read_b128 v[234:237], v129 offset:30656
	s_nop 0
	s_nop 0
	s_waitcnt lgkmcnt(4)
	v_mfma_f32_16x16x32_f16 v[100:103], v[246:249], v[28:31], v[100:103]
	ds_read_b128 v[130:133], v129 offset:30528
	s_nop 0
	s_waitcnt lgkmcnt(3)
	v_mfma_f32_16x16x32_f16 v[134:137], v[238:241], v[36:39], 0
	v_exp_f32_e32 v38, v138
	v_mul_f32_e32 v36, 0x3fb8aa3b, v139
	v_exp_f32_e32 v204, v36
	s_nop 0
	s_waitcnt lgkmcnt(2)
	v_mfma_f32_16x16x32_f16 v[100:103], v[242:245], v[24:27], v[100:103]
	s_nop 0
	v_pk_mul_f32 v[36:37], v[82:83], v[38:39] op_sel_hi:[1,0]
	v_mul_f32_e32 v206, v113, v38
	s_nop 0
	s_waitcnt lgkmcnt(0)
	v_mfma_f32_16x16x32_f16 v[32:35], v[130:133], v[32:35], v[134:137]
	v_mov_b32_e32 v113, v169
	v_mfma_f32_16x16x32_f16 v[30:33], v[230:233], v[28:31], v[32:35]
	v_cvt_pk_f16_f32 v29, v186, v188
	v_cvt_pk_f16_f32 v28, v182, v184
	s_nop 0
	v_mfma_f32_16x16x32_f16 v[152:155], v[234:237], v[24:27], v[30:33]
	v_mul_f32_e32 v24, 0x3db504f3, v144
	v_mul_f32_e32 v25, 0x3db504f3, v145
	v_max3_f32 v24, v24, s11, v25
	v_mul_f32_e32 v25, 0x3db504f3, v146
	v_mul_f32_e32 v26, 0x3db504f3, v147
	v_max3_f32 v24, v24, v25, v26
	v_mul_f32_e32 v25, 0x3db504f3, v96
	v_mul_f32_e32 v26, 0x3db504f3, v97
	v_max3_f32 v24, v24, v25, v26
	v_mul_f32_e32 v25, 0x3db504f3, v98
	v_mul_f32_e32 v26, 0x3db504f3, v99
	v_max3_f32 v24, v24, v25, v26
	v_mul_f32_e32 v25, 0x3db504f3, v100
	v_mul_f32_e32 v26, 0x3db504f3, v101
	v_max3_f32 v24, v24, v25, v26
	v_mul_f32_e32 v25, 0x3db504f3, v102
	v_mul_f32_e32 v26, 0x3db504f3, v103
	v_max3_f32 v24, v24, v25, v26
	v_mul_f32_e32 v25, 0x3db504f3, v152
	v_mul_f32_e32 v26, 0x3db504f3, v153
	v_max3_f32 v24, v24, v25, v26
	v_mul_f32_e32 v25, 0x3db504f3, v154
	v_mul_f32_e32 v26, 0x3db504f3, v155
	v_max3_f32 v24, v24, v25, v26
	ds_bpermute_b32 v25, v173, v24
	v_pk_mul_f32 v[34:35], v[80:81], v[38:39] op_sel_hi:[1,0]
	v_cvt_pk_f16_f32 v27, v178, v180
	v_cvt_pk_f16_f32 v26, v115, v128
	v_cvt_pk_f16_f32 v33, v202, v204
	s_nop 0
	s_waitcnt lgkmcnt(0)
	v_max_f32_e32 v25, v25, v25
	v_max_f32_e32 v24, v24, v25
	ds_bpermute_b32 v25, v225, v24
	v_mfma_f32_16x16x32_f16 v[34:37], v[104:107], v[26:29], v[34:37]
	v_cvt_pk_f16_f32 v32, v198, v200
	v_cvt_pk_f16_f32 v31, v192, v196
	v_cvt_pk_f16_f32 v30, v190, v194
	s_nop 0
	s_waitcnt lgkmcnt(0)
	v_max3_f32 v39, v114, v24, v25
	v_sub_f32_e32 v24, v114, v39
	v_mul_f32_e32 v224, 0x3fb8aa3b, v24
	v_fma_f32 v24, v144, s9, -v39
	v_mul_f32_e32 v24, 0x3fb8aa3b, v24
	v_exp_f32_e32 v179, v24
	v_fma_f32 v24, v145, s9, -v39
	v_mul_f32_e32 v24, 0x3fb8aa3b, v24
	v_exp_f32_e32 v181, v24
	v_fma_f32 v24, v146, s9, -v39
	v_mul_f32_e32 v24, 0x3fb8aa3b, v24
	v_exp_f32_e32 v183, v24
	v_fma_f32 v24, v147, s9, -v39
	v_mul_f32_e32 v24, 0x3fb8aa3b, v24
	v_mfma_f32_16x16x32_f16 v[156:159], v[120:123], v[30:33], v[34:37]
	v_exp_f32_e32 v185, v24
	v_pk_add_f32 v[24:25], v[178:179], v[112:113]
	ds_read2_b64 v[210:213], v140 offset1:4
	ds_read2_b64 v[160:163], v141 offset0:32 offset1:36
	ds_read2_b64 v[144:147], v142 offset0:64 offset1:68
	ds_read2_b64 v[136:139], v143 offset0:96 offset1:100
	ds_read2_b64 v[128:131], v187 offset0:128 offset1:132
	ds_read2_b64 v[112:115], v189 offset0:160 offset1:164
	ds_read2_b64 v[88:91], v191 offset0:192 offset1:196
	ds_read2_b64 v[34:37], v193 offset0:224 offset1:228
	ds_read2_b64 v[226:229], v140 offset0:8 offset1:12
	ds_read2_b64 v[164:167], v141 offset0:40 offset1:44
	ds_read2_b64 v[148:151], v142 offset0:72 offset1:76
	ds_read2_b64 v[140:143], v143 offset0:104 offset1:108
	ds_read2_b64 v[132:135], v187 offset0:136 offset1:140
	ds_read2_b64 v[120:123], v189 offset0:168 offset1:172
	ds_read2_b64 v[104:107], v191 offset0:200 offset1:204
	s_waitcnt lgkmcnt(14)
	ds_read2_b64 v[80:83], v193 offset0:232 offset1:236
	s_nop 0
	s_waitcnt lgkmcnt(0)
	s_barrier
	global_load_dwordx2 v[222:223], v[222:223], off offset:3104
	v_fma_f32 v96, v96, s9, -v39
	v_mul_f32_e32 v96, 0x3fb8aa3b, v96
	v_exp_f32_e32 v187, v96
	v_fma_f32 v96, v97, s9, -v39
	v_mul_f32_e32 v96, 0x3fb8aa3b, v96
	v_exp_f32_e32 v189, v96
	v_fma_f32 v96, v98, s9, -v39
	v_mul_f32_e32 v96, 0x3fb8aa3b, v96
	v_exp_f32_e32 v191, v96
	v_fma_f32 v96, v99, s9, -v39
	v_mul_f32_e32 v96, 0x3fb8aa3b, v96
	v_exp_f32_e32 v195, v96
	v_fma_f32 v96, v100, s9, -v39
	v_mul_f32_e32 v96, 0x3fb8aa3b, v96
	v_exp_f32_e32 v193, v96
	v_fma_f32 v96, v101, s9, -v39
	v_mul_f32_e32 v96, 0x3fb8aa3b, v96
	v_exp_f32_e32 v197, v96
	v_fma_f32 v96, v102, s9, -v39
	v_pk_add_f32 v[24:25], v[180:181], v[24:25]
	v_mul_f32_e32 v96, 0x3fb8aa3b, v96
	v_pk_add_f32 v[24:25], v[182:183], v[24:25]
	v_exp_f32_e32 v199, v96
	v_fma_f32 v96, v103, s9, -v39
	v_pk_add_f32 v[24:25], v[184:185], v[24:25]
	v_mul_f32_e32 v96, 0x3fb8aa3b, v96
	v_exp_f32_e32 v201, v96
	v_fma_f32 v96, v152, s9, -v39
	v_pk_add_f32 v[24:25], v[186:187], v[24:25]
	v_mul_f32_e32 v96, 0x3fb8aa3b, v96
	v_pk_add_f32 v[24:25], v[188:189], v[24:25]
	v_exp_f32_e32 v203, v96
	v_fma_f32 v96, v153, s9, -v39
	v_pk_add_f32 v[24:25], v[190:191], v[24:25]
	v_mul_f32_e32 v96, 0x3fb8aa3b, v96
	v_pk_add_f32 v[24:25], v[194:195], v[24:25]
	v_exp_f32_e32 v205, v96
	v_fma_f32 v96, v154, s9, -v39
	v_pk_add_f32 v[24:25], v[192:193], v[24:25]
	v_mul_f32_e32 v96, 0x3fb8aa3b, v96
	v_fma_f32 v39, v155, s9, -v39
	v_pk_add_f32 v[24:25], v[196:197], v[24:25]
	v_exp_f32_e32 v207, v96
	v_mul_f32_e32 v39, 0x3fb8aa3b, v39
	v_pk_add_f32 v[24:25], v[198:199], v[24:25]
	v_exp_f32_e32 v39, v39
	v_pk_add_f32 v[24:25], v[200:201], v[24:25]
	v_exp_f32_e32 v152, v224
	v_pk_add_f32 v[24:25], v[202:203], v[24:25]
	v_cvt_pk_f16_f32 v99, v191, v195
	v_pk_add_f32 v[24:25], v[204:205], v[24:25]
	v_pk_mul_f32 v[102:103], v[158:159], v[152:153] op_sel_hi:[1,0]
	v_pk_add_f32 v[24:25], v[206:207], v[24:25]
	v_pk_mul_f32 v[100:101], v[156:157], v[152:153] op_sel_hi:[1,0]
	v_add_f32_e32 v25, v25, v39
	v_fmac_f32_e32 v25, v24, v152
	ds_bpermute_b32 v24, v173, v25
	v_cvt_pk_f16_f32 v98, v187, v189
	v_cvt_pk_f16_f32 v97, v183, v185
	v_cvt_pk_f16_f32 v96, v179, v181
	s_waitcnt lgkmcnt(0)
	v_add_f32_e32 v24, v25, v24
	ds_bpermute_b32 v25, v225, v24
	v_mfma_f32_16x16x32_f16 v[154:157], v[210:213], v[96:99], v[100:103]
	s_waitcnt lgkmcnt(0)
	v_add_f32_e32 v24, v24, v25
	v_div_scale_f32 v25, s[4:5], v24, v24, 1.0
	v_cvt_pk_f16_f32 v103, v207, v39
	v_rcp_f32_e32 v39, v25
	v_cvt_pk_f16_f32 v102, v203, v205
	v_cvt_pk_f16_f32 v101, v199, v201
	v_cvt_pk_f16_f32 v100, v193, v197
	v_fma_f32 v153, -v25, v39, 1.0
	v_fmac_f32_e32 v39, v153, v39
	v_div_scale_f32 v153, vcc, 1.0, v24, 1.0
	v_mfma_f32_16x16x32_f16 v[156:159], v[226:229], v[100:103], v[154:157]
	s_waitcnt vmcnt(0)
	v_cvt_f32_f16_sdwa v173, v222 dst_sel:DWORD dst_unused:UNUSED_PAD src0_sel:WORD_1
	v_cvt_f32_f16_e32 v183, v223
	v_mul_f32_e32 v154, v153, v39
	v_fma_f32 v155, -v25, v154, v153
	v_fmac_f32_e32 v154, v155, v39
	v_fma_f32 v25, -v25, v154, v153
	v_cvt_f32_f16_e32 v153, v222
	v_div_fmas_f32 v25, v25, v39, v154
	v_div_fixup_f32 v24, v25, v24, 1.0
	v_mul_f32_e32 v39, 0xbfb8aa3b, v153
	v_exp_f32_e32 v154, v39
	v_mul_f32_e32 v39, 0xbfb8aa3b, v173
	v_exp_f32_e32 v155, v39
	s_nop 0
	v_pk_add_f32 v[178:179], v[154:155], 1.0 op_sel_hi:[1,0]
	s_nop 0
	v_div_scale_f32 v25, s[4:5], v179, v179, v173
	v_rcp_f32_e32 v39, v25
	s_mov_b64 s[4:5], 0x2c20
	v_lshl_add_u64 v[154:155], v[176:177], 0, s[4:5]
	v_pk_mul_f32 v[156:157], v[156:157], v[24:25] op_sel_hi:[1,0]
	v_fma_f32 v176, -v25, v39, 1.0
	v_fmac_f32_e32 v39, v176, v39
	v_div_scale_f32 v176, vcc, v173, v179, v173
	v_mul_f32_e32 v177, v176, v39
	v_fma_f32 v180, -v25, v177, v176
	v_fmac_f32_e32 v177, v180, v39
	v_fma_f32 v25, -v25, v177, v176
	v_div_scale_f32 v176, s[4:5], v178, v178, v153
	v_rcp_f32_e32 v182, v176
	v_div_fmas_f32 v25, v25, v39, v177
	v_div_fixup_f32 v177, v25, v179, v173
	v_fma_f32 v25, -v176, v182, 1.0
	v_fmac_f32_e32 v182, v25, v182
	v_div_scale_f32 v25, vcc, v153, v178, v153
	v_mul_f32_e32 v39, v25, v182
	v_fma_f32 v173, -v176, v39, v25
	v_fmac_f32_e32 v39, v173, v182
	v_cvt_f32_f16_sdwa v173, v223 dst_sel:DWORD dst_unused:UNUSED_PAD src0_sel:WORD_1
	v_fma_f32 v25, -v176, v39, v25
	v_mul_f32_e32 v176, 0xbfb8aa3b, v183
	v_exp_f32_e32 v180, v176
	v_mul_f32_e32 v176, 0xbfb8aa3b, v173
	v_exp_f32_e32 v181, v176
	v_div_fmas_f32 v25, v25, v182, v39
	v_div_fixup_f32 v176, v25, v178, v153
	v_pk_mul_f32 v[156:157], v[156:157], v[176:177]
	v_pk_add_f32 v[178:179], v[180:181], 1.0 op_sel_hi:[1,0]
	v_cvt_pk_f16_f32 v156, v156, v157
	v_div_scale_f32 v25, s[4:5], v179, v179, v173
	v_rcp_f32_e32 v39, v25
	v_pk_mul_f32 v[158:159], v[158:159], v[24:25] op_sel_hi:[1,0]
	v_fma_f32 v153, -v25, v39, 1.0
	v_fmac_f32_e32 v39, v153, v39
	v_div_scale_f32 v153, vcc, v173, v179, v173
	v_mul_f32_e32 v157, v153, v39
	v_fma_f32 v176, -v25, v157, v153
	v_fmac_f32_e32 v157, v176, v39
	v_fma_f32 v25, -v25, v157, v153
	v_div_scale_f32 v153, s[4:5], v178, v178, v183
	v_rcp_f32_e32 v176, v153
	v_div_fmas_f32 v25, v25, v39, v157
	v_div_fixup_f32 v177, v25, v179, v173
	v_fma_f32 v25, -v153, v176, 1.0
	v_fmac_f32_e32 v176, v25, v176
	v_div_scale_f32 v25, vcc, v183, v178, v183
	v_mul_f32_e32 v39, v25, v176
	v_fma_f32 v157, -v153, v39, v25
	v_fmac_f32_e32 v39, v157, v176
	v_fma_f32 v25, -v153, v39, v25
	v_div_fmas_f32 v25, v25, v176, v39
	v_div_fixup_f32 v176, v25, v178, v183
	v_pk_mul_f32 v[158:159], v[158:159], v[176:177]
	v_pk_mul_f32 v[70:71], v[70:71], v[38:39] op_sel_hi:[1,0]
	v_cvt_pk_f16_f32 v157, v158, v159
	v_lshl_add_u64 v[158:159], v[174:175], 0, v[168:169]
	v_add_co_u32_e32 v174, vcc, s0, v158
	v_pk_mul_f32 v[68:69], v[68:69], v[38:39] op_sel_hi:[1,0]
	s_nop 0
	v_addc_co_u32_e32 v175, vcc, 0, v159, vcc
	global_load_dwordx2 v[176:177], v[154:155], off offset:32
	global_load_dwordx2 v[178:179], v[154:155], off offset:64
	global_load_dwordx2 v[180:181], v[154:155], off offset:96
	global_load_dwordx2 v[182:183], v[154:155], off offset:128
	global_load_dwordx2 v[184:185], v[154:155], off offset:160
	global_load_dwordx2 v[186:187], v[154:155], off offset:192
	global_load_dwordx2 v[188:189], v[154:155], off offset:224
	global_store_dwordx2 v[174:175], v[156:157], off offset:768
	v_mfma_f32_16x16x32_f16 v[68:71], v[116:119], v[26:29], v[68:71]
	s_waitcnt vmcnt(7)
	v_cvt_f32_f16_e32 v25, v176
	v_cvt_f32_f16_sdwa v39, v176 dst_sel:DWORD dst_unused:UNUSED_PAD src0_sel:WORD_1
	v_mfma_f32_16x16x32_f16 v[68:71], v[124:127], v[30:33], v[68:71]
	v_cvt_f32_f16_e32 v156, v177
	v_mul_f32_e32 v116, 0xbfb8aa3b, v25
	v_mul_f32_e32 v117, 0xbfb8aa3b, v39
	v_exp_f32_e32 v116, v116
	v_exp_f32_e32 v117, v117
	s_nop 2
	v_pk_mul_f32 v[70:71], v[70:71], v[152:153] op_sel_hi:[1,0]
	v_pk_mul_f32 v[68:69], v[68:69], v[152:153] op_sel_hi:[1,0]
	v_cvt_f32_f16_sdwa v157, v177 dst_sel:DWORD dst_unused:UNUSED_PAD src0_sel:WORD_1
	v_pk_add_f32 v[124:125], v[116:117], 1.0 op_sel_hi:[1,0]
	v_mfma_f32_16x16x32_f16 v[68:71], v[160:163], v[96:99], v[68:71]
	v_div_scale_f32 v126, s[4:5], v125, v125, v39
	v_rcp_f32_e32 v127, v126
	v_mfma_f32_16x16x32_f16 v[116:119], v[164:167], v[100:103], v[68:71]
	s_mov_b64 s[4:5], 0x4800300
	s_nop 3
	v_lshl_add_u64 v[68:69], v[158:159], 0, s[4:5]
	s_nop 1
	v_pk_mul_f32 v[70:71], v[116:117], v[24:25] op_sel_hi:[1,0]
	v_fma_f32 v116, -v126, v127, 1.0
	v_fmac_f32_e32 v127, v116, v127
	v_div_scale_f32 v116, vcc, v39, v125, v39
	v_mul_f32_e32 v117, v116, v127
	v_fma_f32 v153, -v126, v117, v116
	v_fmac_f32_e32 v117, v153, v127
	v_fma_f32 v116, -v126, v117, v116
	v_div_scale_f32 v126, s[4:5], v124, v124, v25
	v_rcp_f32_e32 v153, v126
	v_div_fmas_f32 v116, v116, v127, v117
	v_div_fixup_f32 v117, v116, v125, v39
	v_fma_f32 v39, -v126, v153, 1.0
	v_fmac_f32_e32 v153, v39, v153
	v_div_scale_f32 v39, vcc, v25, v124, v25
	v_mul_f32_e32 v116, v39, v153
	v_fma_f32 v125, -v126, v116, v39
	v_fmac_f32_e32 v116, v125, v153
	v_mul_f32_e32 v125, 0xbfb8aa3b, v156
	v_fma_f32 v39, -v126, v116, v39
	v_exp_f32_e32 v126, v125
	v_mul_f32_e32 v125, 0xbfb8aa3b, v157
	v_exp_f32_e32 v127, v125
	v_div_fmas_f32 v39, v39, v153, v116
	v_div_fixup_f32 v116, v39, v124, v25
	v_pk_mul_f32 v[70:71], v[70:71], v[116:117]
	v_pk_add_f32 v[124:125], v[126:127], 1.0 op_sel_hi:[1,0]
	v_cvt_pk_f16_f32 v70, v70, v71
	v_div_scale_f32 v25, s[4:5], v125, v125, v157
	v_rcp_f32_e32 v39, v25
	v_pk_mul_f32 v[116:117], v[118:119], v[24:25] op_sel_hi:[1,0]
	v_fma_f32 v71, -v25, v39, 1.0
	v_fmac_f32_e32 v39, v71, v39
	v_div_scale_f32 v71, vcc, v157, v125, v157
	v_mul_f32_e32 v118, v71, v39
	v_fma_f32 v119, -v25, v118, v71
	v_fmac_f32_e32 v118, v119, v39
	v_fma_f32 v25, -v25, v118, v71
	v_div_scale_f32 v71, s[4:5], v124, v124, v156
	v_rcp_f32_e32 v126, v71
	v_div_fmas_f32 v25, v25, v39, v118
	v_div_fixup_f32 v119, v25, v125, v157
	v_fma_f32 v25, -v71, v126, 1.0
	v_fmac_f32_e32 v126, v25, v126
	v_div_scale_f32 v25, vcc, v156, v124, v156
	v_mul_f32_e32 v39, v25, v126
	v_fma_f32 v118, -v71, v39, v25
	v_fmac_f32_e32 v39, v118, v126
	v_fma_f32 v25, -v71, v39, v25
	v_div_fmas_f32 v25, v25, v126, v39
	v_div_fixup_f32 v118, v25, v124, v156
	v_pk_mul_f32 v[116:117], v[116:117], v[118:119]
	v_pk_mul_f32 v[58:59], v[58:59], v[38:39] op_sel_hi:[1,0]
	v_cvt_pk_f16_f32 v71, v116, v117
	global_store_dwordx2 v[68:69], v[70:71], off offset:32
	v_pk_mul_f32 v[56:57], v[56:57], v[38:39] op_sel_hi:[1,0]
	s_waitcnt vmcnt(7)
	v_cvt_f32_f16_e32 v25, v178
	v_cvt_f32_f16_sdwa v39, v178 dst_sel:DWORD dst_unused:UNUSED_PAD src0_sel:WORD_1
	v_mfma_f32_16x16x32_f16 v[56:59], v[92:95], v[26:29], v[56:59]
	v_mul_f32_e32 v70, 0xbfb8aa3b, v25
	v_exp_f32_e32 v92, v70
	v_mul_f32_e32 v70, 0xbfb8aa3b, v39
	v_exp_f32_e32 v93, v70
	v_mfma_f32_16x16x32_f16 v[56:59], v[108:111], v[30:33], v[56:59]
	v_cvt_f32_f16_sdwa v110, v179 dst_sel:DWORD dst_unused:UNUSED_PAD src0_sel:WORD_1
	v_pk_add_f32 v[92:93], v[92:93], 1.0 op_sel_hi:[1,0]
	s_nop 0
	v_div_scale_f32 v70, s[4:5], v93, v93, v39
	v_rcp_f32_e32 v94, v70
	s_nop 2
	v_pk_mul_f32 v[58:59], v[58:59], v[152:153] op_sel_hi:[1,0]
	v_pk_mul_f32 v[56:57], v[56:57], v[152:153] op_sel_hi:[1,0]
	v_fma_f32 v95, -v70, v94, 1.0
	v_fmac_f32_e32 v94, v95, v94
	v_div_scale_f32 v95, vcc, v39, v93, v39
	v_mul_f32_e32 v108, v95, v94
	v_fma_f32 v109, -v70, v108, v95
	v_fmac_f32_e32 v108, v109, v94
	v_fma_f32 v70, -v70, v108, v95
	v_div_scale_f32 v95, s[4:5], v92, v92, v25
	v_rcp_f32_e32 v109, v95
	v_div_fmas_f32 v70, v70, v94, v108
	v_div_fixup_f32 v93, v70, v93, v39
	v_cvt_f32_f16_e32 v108, v179
	v_fma_f32 v39, -v95, v109, 1.0
	v_fmac_f32_e32 v109, v39, v109
	v_div_scale_f32 v39, vcc, v25, v92, v25
	v_mfma_f32_16x16x32_f16 v[56:59], v[144:147], v[96:99], v[56:59]
	v_mul_f32_e32 v94, v39, v109
	v_fma_f32 v70, -v95, v94, v39
	v_fmac_f32_e32 v94, v70, v109
	v_mul_f32_e32 v70, 0xbfb8aa3b, v108
	v_mul_f32_e32 v71, 0xbfb8aa3b, v110
	v_exp_f32_e32 v70, v70
	v_exp_f32_e32 v71, v71
	v_mfma_f32_16x16x32_f16 v[56:59], v[148:151], v[100:103], v[56:59]
	v_fma_f32 v39, -v95, v94, v39
	v_div_fmas_f32 v39, v39, v109, v94
	v_pk_add_f32 v[70:71], v[70:71], 1.0 op_sel_hi:[1,0]
	v_div_fixup_f32 v92, v39, v92, v25
	s_nop 3
	v_pk_mul_f32 v[56:57], v[56:57], v[24:25] op_sel_hi:[1,0]
	v_div_scale_f32 v25, s[4:5], v71, v71, v110
	v_rcp_f32_e32 v39, v25
	v_pk_mul_f32 v[56:57], v[56:57], v[92:93]
	v_pk_mul_f32 v[58:59], v[58:59], v[24:25] op_sel_hi:[1,0]
	v_cvt_pk_f16_f32 v56, v56, v57
	v_fma_f32 v57, -v25, v39, 1.0
	v_fmac_f32_e32 v39, v57, v39
	v_div_scale_f32 v57, vcc, v110, v71, v110
	v_mul_f32_e32 v92, v57, v39
	v_fma_f32 v93, -v25, v92, v57
	v_fmac_f32_e32 v92, v93, v39
	v_fma_f32 v25, -v25, v92, v57
	v_div_scale_f32 v57, s[4:5], v70, v70, v108
	v_rcp_f32_e32 v93, v57
	v_div_fmas_f32 v25, v25, v39, v92
	v_div_fixup_f32 v71, v25, v71, v110
	v_fma_f32 v25, -v57, v93, 1.0
	v_fmac_f32_e32 v93, v25, v93
	v_div_scale_f32 v25, vcc, v108, v70, v108
	v_mul_f32_e32 v39, v25, v93
	v_fma_f32 v92, -v57, v39, v25
	v_fmac_f32_e32 v39, v92, v93
	v_fma_f32 v25, -v57, v39, v25
	v_div_fmas_f32 v25, v25, v93, v39
	v_div_fixup_f32 v70, v25, v70, v108
	v_pk_mul_f32 v[58:59], v[58:59], v[70:71]
	v_pk_mul_f32 v[46:47], v[46:47], v[38:39] op_sel_hi:[1,0]
	v_cvt_pk_f16_f32 v57, v58, v59
	global_store_dwordx2 v[68:69], v[56:57], off offset:64
	v_pk_mul_f32 v[44:45], v[44:45], v[38:39] op_sel_hi:[1,0]
	s_waitcnt vmcnt(7)
	v_cvt_f32_f16_e32 v25, v180
	v_cvt_f32_f16_sdwa v39, v180 dst_sel:DWORD dst_unused:UNUSED_PAD src0_sel:WORD_1
	v_mfma_f32_16x16x32_f16 v[44:47], v[76:79], v[26:29], v[44:47]
	v_cvt_f32_f16_sdwa v78, v181 dst_sel:DWORD dst_unused:UNUSED_PAD src0_sel:WORD_1
	v_mul_f32_e32 v56, 0xbfb8aa3b, v25
	v_exp_f32_e32 v58, v56
	v_mul_f32_e32 v56, 0xbfb8aa3b, v39
	v_exp_f32_e32 v59, v56
	v_mfma_f32_16x16x32_f16 v[44:47], v[84:87], v[30:33], v[44:47]
	v_add_f32_e64 v58, v58, 1.0
	v_add_f32_e64 v59, v59, 1.0
	v_div_scale_f32 v56, s[4:5], v59, v59, v39
	v_rcp_f32_e32 v70, v56
	s_nop 3
	v_pk_mul_f32 v[46:47], v[46:47], v[152:153] op_sel_hi:[1,0]
	v_pk_mul_f32 v[44:45], v[44:45], v[152:153] op_sel_hi:[1,0]
	v_fma_f32 v71, -v56, v70, 1.0
	v_fmac_f32_e32 v70, v71, v70
	v_div_scale_f32 v71, vcc, v39, v59, v39
	v_mul_f32_e32 v76, v71, v70
	v_fma_f32 v77, -v56, v76, v71
	v_fmac_f32_e32 v76, v77, v70
	v_fma_f32 v56, -v56, v76, v71
	v_div_scale_f32 v71, s[4:5], v58, v58, v25
	v_rcp_f32_e32 v77, v71
	v_div_fmas_f32 v56, v56, v70, v76
	v_div_fixup_f32 v59, v56, v59, v39
	v_cvt_f32_f16_e32 v76, v181
	v_fma_f32 v39, -v71, v77, 1.0
	v_fmac_f32_e32 v77, v39, v77
	v_div_scale_f32 v39, vcc, v25, v58, v25
	v_mfma_f32_16x16x32_f16 v[44:47], v[136:139], v[96:99], v[44:47]
	v_mul_f32_e32 v70, v39, v77
	v_fma_f32 v56, -v71, v70, v39
	v_fmac_f32_e32 v70, v56, v77
	v_mul_f32_e32 v56, 0xbfb8aa3b, v76
	v_mul_f32_e32 v57, 0xbfb8aa3b, v78
	v_exp_f32_e32 v56, v56
	v_exp_f32_e32 v57, v57
	v_mfma_f32_16x16x32_f16 v[44:47], v[140:143], v[100:103], v[44:47]
	v_fma_f32 v39, -v71, v70, v39
	v_div_fmas_f32 v39, v39, v77, v70
	v_pk_add_f32 v[56:57], v[56:57], 1.0 op_sel_hi:[1,0]
	v_div_fixup_f32 v58, v39, v58, v25
	s_nop 3
	v_pk_mul_f32 v[44:45], v[44:45], v[24:25] op_sel_hi:[1,0]
	v_div_scale_f32 v25, s[4:5], v57, v57, v78
	v_rcp_f32_e32 v39, v25
	v_pk_mul_f32 v[44:45], v[44:45], v[58:59]
	v_pk_mul_f32 v[46:47], v[46:47], v[24:25] op_sel_hi:[1,0]
	v_cvt_pk_f16_f32 v44, v44, v45
	v_fma_f32 v45, -v25, v39, 1.0
	v_fmac_f32_e32 v39, v45, v39
	v_div_scale_f32 v45, vcc, v78, v57, v78
	v_mul_f32_e32 v58, v45, v39
	v_fma_f32 v59, -v25, v58, v45
	v_fmac_f32_e32 v58, v59, v39
	v_fma_f32 v25, -v25, v58, v45
	v_div_scale_f32 v45, s[4:5], v56, v56, v76
	v_rcp_f32_e32 v59, v45
	v_div_fmas_f32 v25, v25, v39, v58
	v_div_fixup_f32 v57, v25, v57, v78
	v_fma_f32 v25, -v45, v59, 1.0
	v_fmac_f32_e32 v59, v25, v59
	v_div_scale_f32 v25, vcc, v76, v56, v76
	v_mul_f32_e32 v39, v25, v59
	v_fma_f32 v58, -v45, v39, v25
	v_fmac_f32_e32 v39, v58, v59
	v_fma_f32 v25, -v45, v39, v25
	v_div_fmas_f32 v25, v25, v59, v39
	v_div_fixup_f32 v56, v25, v56, v76
	v_pk_mul_f32 v[46:47], v[46:47], v[56:57]
	v_pk_mul_f32 v[18:19], v[18:19], v[38:39] op_sel_hi:[1,0]
	v_cvt_pk_f16_f32 v45, v46, v47
	global_store_dwordx2 v[68:69], v[44:45], off offset:96
	v_pk_mul_f32 v[16:17], v[16:17], v[38:39] op_sel_hi:[1,0]
	s_waitcnt vmcnt(7)
	v_cvt_f32_f16_e32 v25, v182
	v_cvt_f32_f16_sdwa v39, v182 dst_sel:DWORD dst_unused:UNUSED_PAD src0_sel:WORD_1
	v_mfma_f32_16x16x32_f16 v[16:19], v[64:67], v[26:29], v[16:19]
	v_cvt_f32_f16_sdwa v64, v183 dst_sel:DWORD dst_unused:UNUSED_PAD src0_sel:WORD_1
	v_mul_f32_e32 v44, 0xbfb8aa3b, v25
	v_exp_f32_e32 v46, v44
	v_mul_f32_e32 v44, 0xbfb8aa3b, v39
	v_exp_f32_e32 v47, v44
	v_mfma_f32_16x16x32_f16 v[16:19], v[72:75], v[30:33], v[16:19]
	v_add_f32_e64 v46, v46, 1.0
	v_add_f32_e64 v47, v47, 1.0
	v_div_scale_f32 v44, s[4:5], v47, v47, v39
	v_rcp_f32_e32 v56, v44
	s_nop 3
	v_pk_mul_f32 v[18:19], v[18:19], v[152:153] op_sel_hi:[1,0]
	v_pk_mul_f32 v[16:17], v[16:17], v[152:153] op_sel_hi:[1,0]
	v_fma_f32 v57, -v44, v56, 1.0
	v_fmac_f32_e32 v56, v57, v56
	v_div_scale_f32 v57, vcc, v39, v47, v39
	v_mul_f32_e32 v58, v57, v56
	v_fma_f32 v59, -v44, v58, v57
	v_fmac_f32_e32 v58, v59, v56
	v_fma_f32 v44, -v44, v58, v57
	v_div_scale_f32 v57, s[4:5], v46, v46, v25
	v_rcp_f32_e32 v59, v57
	v_div_fmas_f32 v44, v44, v56, v58
	v_div_fixup_f32 v47, v44, v47, v39
	v_cvt_f32_f16_e32 v58, v183
	v_fma_f32 v39, -v57, v59, 1.0
	v_fmac_f32_e32 v59, v39, v59
	v_div_scale_f32 v39, vcc, v25, v46, v25
	v_mfma_f32_16x16x32_f16 v[16:19], v[128:131], v[96:99], v[16:19]
	v_mul_f32_e32 v56, v39, v59
	v_fma_f32 v44, -v57, v56, v39
	v_fmac_f32_e32 v56, v44, v59
	v_mul_f32_e32 v44, 0xbfb8aa3b, v58
	v_mul_f32_e32 v45, 0xbfb8aa3b, v64
	v_exp_f32_e32 v44, v44
	v_exp_f32_e32 v45, v45
	v_mfma_f32_16x16x32_f16 v[16:19], v[132:135], v[100:103], v[16:19]
	v_fma_f32 v39, -v57, v56, v39
	v_div_fmas_f32 v39, v39, v59, v56
	v_pk_add_f32 v[44:45], v[44:45], 1.0 op_sel_hi:[1,0]
	v_div_fixup_f32 v46, v39, v46, v25
	s_nop 3
	v_pk_mul_f32 v[16:17], v[16:17], v[24:25] op_sel_hi:[1,0]
	v_div_scale_f32 v25, s[4:5], v45, v45, v64
	v_rcp_f32_e32 v39, v25
	v_pk_mul_f32 v[16:17], v[16:17], v[46:47]
	v_pk_mul_f32 v[18:19], v[18:19], v[24:25] op_sel_hi:[1,0]
	v_cvt_pk_f16_f32 v16, v16, v17
	v_fma_f32 v17, -v25, v39, 1.0
	v_fmac_f32_e32 v39, v17, v39
	v_div_scale_f32 v17, vcc, v64, v45, v64
	v_mul_f32_e32 v46, v17, v39
	v_fma_f32 v47, -v25, v46, v17
	v_fmac_f32_e32 v46, v47, v39
	v_fma_f32 v17, -v25, v46, v17
	v_div_scale_f32 v25, s[4:5], v44, v44, v58
	v_rcp_f32_e32 v47, v25
	v_div_fmas_f32 v17, v17, v39, v46
	v_div_fixup_f32 v45, v17, v45, v64
	v_fma_f32 v17, -v25, v47, 1.0
	v_fmac_f32_e32 v47, v17, v47
	v_div_scale_f32 v17, vcc, v58, v44, v58
	v_mul_f32_e32 v39, v17, v47
	v_fma_f32 v46, -v25, v39, v17
	v_fmac_f32_e32 v39, v46, v47
	v_fma_f32 v17, -v25, v39, v17
	v_div_fmas_f32 v17, v17, v47, v39
	v_div_fixup_f32 v44, v17, v44, v58
	v_pk_mul_f32 v[18:19], v[18:19], v[44:45]
	v_pk_mul_f32 v[10:11], v[10:11], v[38:39] op_sel_hi:[1,0]
	v_cvt_pk_f16_f32 v17, v18, v19
	global_store_dwordx2 v[68:69], v[16:17], off offset:128
	v_pk_mul_f32 v[8:9], v[8:9], v[38:39] op_sel_hi:[1,0]
	s_waitcnt vmcnt(7)
	v_cvt_f32_f16_e32 v25, v184
	v_cvt_f32_f16_sdwa v16, v184 dst_sel:DWORD dst_unused:UNUSED_PAD src0_sel:WORD_1
	v_mfma_f32_16x16x32_f16 v[8:11], v[52:55], v[26:29], v[8:11]
	v_mul_f32_e32 v18, 0xbfb8aa3b, v25
	v_mul_f32_e32 v19, 0xbfb8aa3b, v16
	v_exp_f32_e32 v18, v18
	v_exp_f32_e32 v19, v19
	v_mfma_f32_16x16x32_f16 v[8:11], v[60:63], v[30:33], v[8:11]
	v_add_f32_e64 v18, v18, 1.0
	v_add_f32_e64 v19, v19, 1.0
	v_div_scale_f32 v39, s[4:5], v19, v19, v16
	v_rcp_f32_e32 v44, v39
	s_nop 3
	v_pk_mul_f32 v[10:11], v[10:11], v[152:153] op_sel_hi:[1,0]
	v_pk_mul_f32 v[8:9], v[8:9], v[152:153] op_sel_hi:[1,0]
	v_fma_f32 v45, -v39, v44, 1.0
	v_fmac_f32_e32 v44, v45, v44
	v_div_scale_f32 v45, vcc, v16, v19, v16
	v_mul_f32_e32 v46, v45, v44
	v_fma_f32 v47, -v39, v46, v45
	v_fmac_f32_e32 v46, v47, v44
	v_fma_f32 v39, -v39, v46, v45
	v_div_scale_f32 v45, s[4:5], v18, v18, v25
	v_rcp_f32_e32 v47, v45
	v_div_fmas_f32 v39, v39, v44, v46
	v_div_fixup_f32 v19, v39, v19, v16
	v_cvt_f32_f16_e32 v46, v185
	v_fma_f32 v16, -v45, v47, 1.0
	v_fmac_f32_e32 v47, v16, v47
	v_div_scale_f32 v16, vcc, v25, v18, v25
	v_mul_f32_e32 v39, v16, v47
	v_fma_f32 v44, -v45, v39, v16
	v_fmac_f32_e32 v39, v44, v47
	v_cvt_f32_f16_sdwa v44, v185 dst_sel:DWORD dst_unused:UNUSED_PAD src0_sel:WORD_1
	v_mfma_f32_16x16x32_f16 v[8:11], v[112:115], v[96:99], v[8:11]
	v_fma_f32 v45, -v45, v39, v16
	v_mul_f32_e32 v16, 0xbfb8aa3b, v46
	v_mul_f32_e32 v17, 0xbfb8aa3b, v44
	v_exp_f32_e32 v16, v16
	v_exp_f32_e32 v17, v17
	v_mfma_f32_16x16x32_f16 v[8:11], v[120:123], v[100:103], v[8:11]
	v_div_fmas_f32 v39, v45, v47, v39
	v_div_fixup_f32 v18, v39, v18, v25
	v_pk_add_f32 v[16:17], v[16:17], 1.0 op_sel_hi:[1,0]
	s_nop 4
	v_pk_mul_f32 v[8:9], v[8:9], v[24:25] op_sel_hi:[1,0]
	v_div_scale_f32 v25, s[4:5], v17, v17, v44
	v_rcp_f32_e32 v39, v25
	v_pk_mul_f32 v[8:9], v[8:9], v[18:19]
	v_pk_mul_f32 v[10:11], v[10:11], v[24:25] op_sel_hi:[1,0]
	v_cvt_pk_f16_f32 v8, v8, v9
	v_fma_f32 v9, -v25, v39, 1.0
	v_fmac_f32_e32 v39, v9, v39
	v_div_scale_f32 v9, vcc, v44, v17, v44
	v_mul_f32_e32 v18, v9, v39
	v_fma_f32 v19, -v25, v18, v9
	v_fmac_f32_e32 v18, v19, v39
	v_div_scale_f32 v19, s[4:5], v16, v16, v46
	v_fma_f32 v9, -v25, v18, v9
	v_rcp_f32_e32 v25, v19
	v_div_fmas_f32 v9, v9, v39, v18
	v_div_fixup_f32 v17, v9, v17, v44
	v_fma_f32 v9, -v19, v25, 1.0
	v_fmac_f32_e32 v25, v9, v25
	v_div_scale_f32 v9, vcc, v46, v16, v46
	v_mul_f32_e32 v18, v9, v25
	v_fma_f32 v39, -v19, v18, v9
	v_fmac_f32_e32 v18, v39, v25
	v_fma_f32 v9, -v19, v18, v9
	v_div_fmas_f32 v9, v9, v25, v18
	v_div_fixup_f32 v16, v9, v16, v46
	v_pk_mul_f32 v[10:11], v[10:11], v[16:17]
	v_pk_mul_f32 v[6:7], v[6:7], v[38:39] op_sel_hi:[1,0]
	v_cvt_pk_f16_f32 v9, v10, v11
	global_store_dwordx2 v[68:69], v[8:9], off offset:160
	v_pk_mul_f32 v[4:5], v[4:5], v[38:39] op_sel_hi:[1,0]
	s_waitcnt vmcnt(7)
	v_cvt_f32_f16_e32 v16, v186
	v_mfma_f32_16x16x32_f16 v[4:7], v[40:43], v[26:29], v[4:7]
	v_cvt_f32_f16_sdwa v8, v186 dst_sel:DWORD dst_unused:UNUSED_PAD src0_sel:WORD_1
	v_mul_f32_e32 v10, 0xbfb8aa3b, v16
	v_mfma_f32_16x16x32_f16 v[4:7], v[48:51], v[30:33], v[4:7]
	v_mul_f32_e32 v11, 0xbfb8aa3b, v8
	v_exp_f32_e32 v10, v10
	v_exp_f32_e32 v11, v11
	s_nop 0
	v_pk_add_f32 v[10:11], v[10:11], 1.0 op_sel_hi:[1,0]
	s_nop 2
	v_pk_mul_f32 v[6:7], v[6:7], v[152:153] op_sel_hi:[1,0]
	v_pk_mul_f32 v[4:5], v[4:5], v[152:153] op_sel_hi:[1,0]
	v_div_scale_f32 v17, s[4:5], v11, v11, v8
	s_nop 0
	v_mfma_f32_16x16x32_f16 v[4:7], v[88:91], v[96:99], v[4:7]
	v_rcp_f32_e32 v18, v17
	s_nop 0
	v_fma_f32 v19, -v17, v18, 1.0
	v_mfma_f32_16x16x32_f16 v[4:7], v[104:107], v[100:103], v[4:7]
	v_fmac_f32_e32 v18, v19, v18
	v_div_scale_f32 v19, vcc, v8, v11, v8
	s_nop 5
	v_pk_mul_f32 v[4:5], v[4:5], v[24:25] op_sel_hi:[1,0]
	v_mul_f32_e32 v25, v19, v18
	v_fma_f32 v39, -v17, v25, v19
	v_fmac_f32_e32 v25, v39, v18
	v_fma_f32 v17, -v17, v25, v19
	v_div_scale_f32 v19, s[4:5], v10, v10, v16
	v_rcp_f32_e32 v39, v19
	v_div_fmas_f32 v17, v17, v18, v25
	v_div_fixup_f32 v11, v17, v11, v8
	v_cvt_f32_f16_e32 v25, v187
	v_fma_f32 v8, -v19, v39, 1.0
	v_fmac_f32_e32 v39, v8, v39
	v_div_scale_f32 v8, vcc, v16, v10, v16
	v_mul_f32_e32 v17, v8, v39
	v_fma_f32 v18, -v19, v17, v8
	v_fmac_f32_e32 v17, v18, v39
	v_cvt_f32_f16_sdwa v18, v187 dst_sel:DWORD dst_unused:UNUSED_PAD src0_sel:WORD_1
	v_fma_f32 v19, -v19, v17, v8
	v_mul_f32_e32 v8, 0xbfb8aa3b, v25
	v_exp_f32_e32 v8, v8
	v_mul_f32_e32 v9, 0xbfb8aa3b, v18
	v_exp_f32_e32 v9, v9
	v_div_fmas_f32 v17, v19, v39, v17
	v_div_fixup_f32 v10, v17, v10, v16
	v_pk_mul_f32 v[4:5], v[4:5], v[10:11]
	v_pk_add_f32 v[8:9], v[8:9], 1.0 op_sel_hi:[1,0]
	v_cvt_pk_f16_f32 v4, v4, v5
	v_div_scale_f32 v16, s[4:5], v9, v9, v18
	v_rcp_f32_e32 v17, v16
	v_pk_mul_f32 v[6:7], v[6:7], v[24:25] op_sel_hi:[1,0]
	v_pk_mul_f32 v[2:3], v[2:3], v[38:39] op_sel_hi:[1,0]
	v_pk_mul_f32 v[0:1], v[0:1], v[38:39] op_sel_hi:[1,0]
	v_fma_f32 v5, -v16, v17, 1.0
	v_fmac_f32_e32 v17, v5, v17
	v_div_scale_f32 v5, vcc, v18, v9, v18
	v_mul_f32_e32 v10, v5, v17
	v_fma_f32 v11, -v16, v10, v5
	v_fmac_f32_e32 v10, v11, v17
	v_div_scale_f32 v11, s[4:5], v8, v8, v25
	v_fma_f32 v5, -v16, v10, v5
	v_rcp_f32_e32 v16, v11
	v_div_fmas_f32 v5, v5, v17, v10
	v_div_fixup_f32 v9, v5, v9, v18
	v_mfma_f32_16x16x32_f16 v[0:3], v[12:15], v[26:29], v[0:3]
	v_fma_f32 v5, -v11, v16, 1.0
	v_fmac_f32_e32 v16, v5, v16
	v_div_scale_f32 v5, vcc, v25, v8, v25
	v_mul_f32_e32 v10, v5, v16
	v_fma_f32 v17, -v11, v10, v5
	v_fmac_f32_e32 v10, v17, v16
	v_fma_f32 v5, -v11, v10, v5
	v_div_fmas_f32 v5, v5, v16, v10
	v_div_fixup_f32 v8, v5, v8, v25
	v_pk_mul_f32 v[6:7], v[6:7], v[8:9]
	v_mfma_f32_16x16x32_f16 v[0:3], v[20:23], v[30:33], v[0:3]
	v_cvt_pk_f16_f32 v5, v6, v7
	global_store_dwordx2 v[68:69], v[4:5], off offset:192
	s_waitcnt vmcnt(7)
	v_cvt_f32_f16_e32 v8, v188
	v_cvt_f32_f16_sdwa v4, v188 dst_sel:DWORD dst_unused:UNUSED_PAD src0_sel:WORD_1
	s_nop 1
	v_pk_mul_f32 v[2:3], v[2:3], v[152:153] op_sel_hi:[1,0]
	v_pk_mul_f32 v[0:1], v[0:1], v[152:153] op_sel_hi:[1,0]
	v_mul_f32_e32 v6, 0xbfb8aa3b, v8
	v_mul_f32_e32 v7, 0xbfb8aa3b, v4
	v_exp_f32_e32 v6, v6
	v_exp_f32_e32 v7, v7
	v_mfma_f32_16x16x32_f16 v[0:3], v[34:37], v[96:99], v[0:3]
	v_add_f32_e64 v6, v6, 1.0
	v_add_f32_e64 v7, v7, 1.0
	v_div_scale_f32 v9, s[4:5], v7, v7, v4
	v_rcp_f32_e32 v10, v9
	v_mfma_f32_16x16x32_f16 v[0:3], v[80:83], v[100:103], v[0:3]
	v_fma_f32 v11, -v9, v10, 1.0
	v_fmac_f32_e32 v10, v11, v10
	v_div_scale_f32 v11, vcc, v4, v7, v4
	v_mul_f32_e32 v12, v11, v10
	v_fma_f32 v13, -v9, v12, v11
	v_fmac_f32_e32 v12, v13, v10
	v_fma_f32 v9, -v9, v12, v11
	v_div_scale_f32 v11, s[4:5], v6, v6, v8
	v_rcp_f32_e32 v13, v11
	v_div_fmas_f32 v9, v9, v10, v12
	v_div_fixup_f32 v7, v9, v7, v4
	v_cvt_f32_f16_e32 v12, v189
	v_fma_f32 v4, -v11, v13, 1.0
	v_fmac_f32_e32 v13, v4, v13
	v_div_scale_f32 v4, vcc, v8, v6, v8
	v_mul_f32_e32 v9, v4, v13
	v_fma_f32 v10, -v11, v9, v4
	v_fmac_f32_e32 v9, v10, v13
	v_cvt_f32_f16_sdwa v10, v189 dst_sel:DWORD dst_unused:UNUSED_PAD src0_sel:WORD_1
	v_fma_f32 v11, -v11, v9, v4
	v_mul_f32_e32 v4, 0xbfb8aa3b, v12
	v_exp_f32_e32 v4, v4
	v_mul_f32_e32 v5, 0xbfb8aa3b, v10
	v_exp_f32_e32 v5, v5
	v_div_fmas_f32 v9, v11, v13, v9
	v_div_fixup_f32 v6, v9, v6, v8
	v_pk_mul_f32 v[0:1], v[0:1], v[24:25] op_sel_hi:[1,0]
	v_pk_add_f32 v[4:5], v[4:5], 1.0 op_sel_hi:[1,0]
	v_pk_mul_f32 v[0:1], v[0:1], v[6:7]
	v_div_scale_f32 v8, s[4:5], v5, v5, v10
	v_rcp_f32_e32 v9, v8
	v_cvt_pk_f16_f32 v0, v0, v1
	v_pk_mul_f32 v[2:3], v[2:3], v[24:25] op_sel_hi:[1,0]
	v_fma_f32 v1, -v8, v9, 1.0
	v_fmac_f32_e32 v9, v1, v9
	v_div_scale_f32 v1, vcc, v10, v5, v10
	v_mul_f32_e32 v6, v1, v9
	v_fma_f32 v7, -v8, v6, v1
	v_fmac_f32_e32 v6, v7, v9
	v_div_scale_f32 v7, s[4:5], v4, v4, v12
	v_fma_f32 v1, -v8, v6, v1
	v_rcp_f32_e32 v8, v7
	v_div_fmas_f32 v1, v1, v9, v6
	v_div_fixup_f32 v5, v1, v5, v10
	v_fma_f32 v1, -v7, v8, 1.0
	v_fmac_f32_e32 v8, v1, v8
	v_div_scale_f32 v1, vcc, v12, v4, v12
	v_mul_f32_e32 v6, v1, v8
	v_fma_f32 v9, -v7, v6, v1
	v_fmac_f32_e32 v6, v9, v8
	v_fma_f32 v1, -v7, v6, v1
	v_div_fmas_f32 v1, v1, v8, v6
	v_div_fixup_f32 v4, v1, v4, v12
	v_pk_mul_f32 v[2:3], v[2:3], v[4:5]
	s_nop 0
	v_cvt_pk_f16_f32 v1, v2, v3
	global_store_dwordx2 v[68:69], v[0:1], off offset:224

.LBB0_153:
	s_andn2_b64 vcc, exec, s[4:5]
	s_cbranch_vccnz .LBB0_155
	s_add_i32 s0, s25, 0xfffffb00
	s_lshr_b32 s0, s0, 4
	s_lshr_b32 s4, s25, 2
	s_bfe_u32 s8, s25, 0x20002
	s_lshl_b32 s9, s0, 8
	s_bfe_u32 s6, s4, 0x10001
	s_mul_i32 s4, s0, 0x302000
	v_readlane_b32 s10, v254, 4
	s_mul_hi_u32 s5, s9, 0x3020
	v_readlane_b32 s11, v254, 5
	s_add_u32 s4, s10, s4
	s_addc_u32 s5, s11, s5
	s_lshl_b32 s7, s6, 8
	s_add_u32 s4, s4, s7
	s_addc_u32 s5, s5, 0
	s_lshl_b32 s0, s0, 1
	s_or_b32 s0, s0, s6
	s_lshl_b64 s[6:7], s[0:1], 16
	v_readlane_b32 s0, v254, 10
	s_add_u32 s6, s0, s6
	v_readlane_b32 s0, v254, 11
	s_addc_u32 s7, s0, s7
	s_lshl_b32 s0, s25, 6
	s_waitcnt vmcnt(0)
	v_mov_b32_e32 v20, v171
	s_and_b32 s0, s0, 0xc0
	s_or_b32 s0, s0, s9
	v_and_b32_e32 v56, 15, v20
	v_ashrrev_i32_e32 v0, 2, v20
	v_and_b32_e32 v0, -16, v0
	v_or_b32_e32 v1, s0, v56
	v_add_u32_e32 v94, v1, v0
	v_mov_b64_e32 v[0:1], s[10:11]
	s_movk_i32 s9, 0x3020
	v_bfe_u32 v2, v20, 4, 2
	v_mad_i64_i32 v[0:1], s[10:11], v94, s9, v[0:1]
	s_lshl_b32 s0, s8, 8
	v_lshl_add_u64 v[92:93], v[0:1], 0, s[0:1]
	v_lshlrev_b32_e32 v16, 4, v2
	v_mov_b32_e32 v17, v169
	v_ashrrev_i32_e32 v50, 3, v20
	v_lshl_add_u64 v[0:1], v[92:93], 0, v[16:17]
	v_ashrrev_i32_e32 v101, 4, v20
	v_mov_b64_e32 v[30:31], s[4:5]
	v_lshlrev_b32_e32 v17, 4, v20
	v_ashrrev_i32_e32 v51, 31, v50
	v_mad_i64_i32 v[18:19], s[10:11], v101, s9, v[30:31]
	v_and_b32_e32 v84, 0xf0, v17
	v_mov_b32_e32 v85, v169
	v_add_u32_e32 v103, 16, v101
	v_lshlrev_b64 v[34:35], 9, v[50:51]
	v_lshl_add_u64 v[18:19], v[18:19], 0, v[84:85]
	v_mad_i64_i32 v[22:23], s[10:11], v103, s9, v[30:31]
	v_add_u32_e32 v105, 32, v101
	v_and_b32_e32 v52, 0x70, v17
	v_mov_b32_e32 v53, v169
	v_lshl_add_u64 v[34:35], s[6:7], 0, v[34:35]
	s_barrier
	v_lshlrev_b32_e32 v168, 3, v2
	global_load_dwordx4 v[12:15], v[0:1], off
	global_load_dwordx4 v[8:11], v[0:1], off offset:64
	global_load_dwordx4 v[4:7], v[0:1], off offset:128
	s_nop 0
	global_load_dwordx4 v[0:3], v[0:1], off offset:192
	v_lshl_add_u64 v[22:23], v[22:23], 0, v[84:85]
	global_load_dwordx4 v[18:21], v[18:19], off offset:1024
	v_mad_i64_i32 v[26:27], s[10:11], v105, s9, v[30:31]
	v_add_u32_e32 v107, 48, v101
	v_lshl_add_u64 v[86:87], v[34:35], 0, v[52:53]
	global_load_dwordx4 v[22:25], v[22:23], off offset:1024
	v_lshl_add_u64 v[26:27], v[26:27], 0, v[84:85]
	v_mad_i64_i32 v[30:31], s[10:11], v107, s9, v[30:31]
	v_add_co_u32_e32 v38, vcc, s97, v86
	s_mov_b64 s[2:3], 0x8000
	global_load_dwordx4 v[26:29], v[26:27], off offset:1024
	v_lshl_add_u64 v[30:31], v[30:31], 0, v[84:85]
	v_addc_co_u32_e32 v39, vcc, 0, v87, vcc
	v_lshl_add_u64 v[90:91], v[86:87], 0, s[2:3]
	s_mov_b32 s3, 0x8000
	global_load_dwordx4 v[30:33], v[30:31], off offset:1024
	v_add_co_u32_e32 v42, vcc, s3, v86
	s_mov_b64 s[2:3], 0xc000
	global_load_dwordx4 v[34:37], v[86:87], off
	v_addc_co_u32_e32 v43, vcc, 0, v87, vcc
	v_lshl_add_u64 v[112:113], v[86:87], 0, s[2:3]
	s_mov_b32 s3, 0xc000
	global_load_dwordx4 v[38:41], v[38:39], off
	v_add_co_u32_e32 v46, vcc, s3, v86
	global_load_dwordx4 v[42:45], v[42:43], off
	s_nop 0
	v_addc_co_u32_e32 v47, vcc, 0, v87, vcc
	global_load_dwordx4 v[46:49], v[46:47], off
	s_movk_i32 s3, 0x110
	s_movk_i32 s10, 0x90
	v_mad_u64_u32 v[98:99], s[6:7], v101, s3, v[84:85]
	v_mad_u64_u32 v[96:97], s[6:7], v50, s10, v[52:53]
	s_add_u32 s6, s4, 0xc0c00
	s_addc_u32 s7, s5, 0
	s_waitcnt vmcnt(7)
	ds_write_b128 v98, v[18:21]
	s_waitcnt vmcnt(6)
	ds_write_b128 v98, v[22:25] offset:4352
	s_waitcnt vmcnt(5)
	ds_write_b128 v98, v[26:29] offset:8704
	s_waitcnt vmcnt(4)
	ds_write_b128 v98, v[30:33] offset:13056
	s_waitcnt vmcnt(3)
	ds_write_b128 v96, v[34:37] offset:34816
	s_waitcnt vmcnt(2)
	ds_write_b128 v96, v[38:41] offset:39424
	s_waitcnt vmcnt(1)
	ds_write_b128 v96, v[42:45] offset:44032
	s_waitcnt vmcnt(0)
	ds_write_b128 v96, v[46:49] offset:48640
	v_mov_b64_e32 v[30:31], s[6:7]
	v_mad_i64_i32 v[18:19], s[6:7], v101, s9, v[30:31]
	v_mad_i64_i32 v[22:23], s[6:7], v103, s9, v[30:31]
	v_mad_i64_i32 v[26:27], s[6:7], v105, s9, v[30:31]
	v_mad_i64_i32 v[30:31], s[6:7], v107, s9, v[30:31]
	v_lshl_add_u64 v[18:19], v[18:19], 0, v[84:85]
	v_lshl_add_u64 v[22:23], v[22:23], 0, v[84:85]
	v_lshl_add_u64 v[26:27], v[26:27], 0, v[84:85]
	v_lshl_add_u64 v[30:31], v[30:31], 0, v[84:85]
	v_lshl_add_u64 v[88:89], v[86:87], 0, s[84:85]
	global_load_dwordx4 v[18:21], v[18:19], off
	v_mbcnt_hi_u32_b32 v17, -1, v214
	global_load_dwordx4 v[22:25], v[22:23], off
	v_and_b32_e32 v51, 64, v17
	global_load_dwordx4 v[26:29], v[26:27], off
	s_nop 0
	global_load_dwordx4 v[30:33], v[30:31], off
	s_nop 0
	global_load_dwordx4 v[34:37], v[86:87], off offset:128
	global_load_dwordx4 v[38:41], v[88:89], off offset:128
	global_load_dwordx4 v[42:45], v[90:91], off offset:128
	global_load_dwordx4 v[46:49], v[112:113], off offset:128
	v_xor_b32_e32 v50, 16, v17
	v_add_u32_e32 v51, 64, v51
	v_cmp_lt_i32_e32 vcc, v50, v51
	s_add_u32 s6, s4, 0x181400
	s_addc_u32 s7, s5, 0
	v_cndmask_b32_e32 v50, v17, v50, vcc
	v_add_u32_e32 v99, 0x8800, v96
	s_waitcnt lgkmcnt(0)
	s_barrier
	v_lshlrev_b32_e32 v132, 2, v50
	v_xor_b32_e32 v50, 32, v17
	s_waitcnt vmcnt(7)
	ds_write_b128 v98, v[18:21] offset:17408
	s_waitcnt vmcnt(6)
	ds_write_b128 v98, v[22:25] offset:21760
	s_waitcnt vmcnt(5)
	ds_write_b128 v98, v[26:29] offset:26112
	s_waitcnt vmcnt(4)
	ds_write_b128 v98, v[30:33] offset:30464
	s_waitcnt vmcnt(3)
	ds_write_b128 v96, v[34:37] offset:53248
	s_waitcnt vmcnt(2)
	ds_write_b128 v96, v[38:41] offset:57856
	s_waitcnt vmcnt(1)
	ds_write_b128 v96, v[42:45] offset:62464
	s_waitcnt vmcnt(0)
	ds_write_b128 v99, v[46:49] offset:32256
	v_mov_b64_e32 v[18:19], s[6:7]
	v_cmp_lt_i32_e32 vcc, v50, v51
	v_mad_i64_i32 v[20:21], s[6:7], v101, s9, v[18:19]
	v_mad_i64_i32 v[24:25], s[6:7], v103, s9, v[18:19]
	v_mad_i64_i32 v[28:29], s[6:7], v105, s9, v[18:19]
	v_mad_i64_i32 v[18:19], s[6:7], v107, s9, v[18:19]
	v_cndmask_b32_e32 v17, v17, v50, vcc
	v_lshl_add_u64 v[20:21], v[20:21], 0, v[84:85]
	v_lshl_add_u64 v[24:25], v[24:25], 0, v[84:85]
	v_lshl_add_u64 v[28:29], v[28:29], 0, v[84:85]
	v_lshl_add_u64 v[18:19], v[18:19], 0, v[84:85]
	v_mad_u32_u24 v97, v56, s3, v16
	ds_read_b128 v[156:159], v97
	ds_read_b128 v[160:163], v97 offset:64
	ds_read_b128 v[164:167], v97 offset:4416
	ds_read_b128 v[174:177], v97 offset:8768
	ds_read_b128 v[178:181], v97 offset:13120
	ds_read_b128 v[182:185], v97 offset:128
	ds_read_b128 v[186:189], v97 offset:192
	s_waitcnt lgkmcnt(14)
	ds_read_b128 v[190:193], v97 offset:4352
	s_waitcnt lgkmcnt(14)
	ds_read_b128 v[194:197], v97 offset:4480
	s_waitcnt lgkmcnt(14)
	v_lshlrev_b32_e32 v133, 2, v17
	v_sub_u32_e32 v57, v16, v168
	global_load_dwordx4 v[20:23], v[20:21], off
	s_mov_b32 s7, 0xf149f2ca
	global_load_dwordx4 v[24:27], v[24:25], off
	s_mov_b32 s6, 0x3db504f3
	global_load_dwordx4 v[28:31], v[28:29], off
	s_nop 0
	global_load_dwordx4 v[32:35], v[18:19], off
	global_load_dwordx4 v[36:39], v[86:87], off offset:256
	global_load_dwordx4 v[40:43], v[88:89], off offset:256
	global_load_dwordx4 v[44:47], v[90:91], off offset:256
	global_load_dwordx4 v[48:51], v[112:113], off offset:256
	s_nop 0
	s_nop 0
	s_waitcnt lgkmcnt(14)
	s_waitcnt lgkmcnt(8)
	v_mfma_f32_16x16x32_f16 v[16:19], v[156:159], v[12:15], 0
	s_nop 0
	s_nop 0
	s_nop 0
	s_nop 0
	s_waitcnt lgkmcnt(7)
	v_mfma_f32_16x16x32_f16 v[16:19], v[160:163], v[8:11], v[16:19]
	s_nop 0
	v_mad_u32_u24 v142, v56, s10, v57
	v_add_u32_e32 v134, 0x8800, v142
	s_nop 0
	s_waitcnt lgkmcnt(3)
	v_mfma_f32_16x16x32_f16 v[16:19], v[182:185], v[4:7], v[16:19]
	s_nop 0
	v_add_u32_e32 v135, 0x9000, v142
	v_add_u32_e32 v136, 0x9800, v142
	s_nop 0
	s_waitcnt lgkmcnt(2)
	v_mfma_f32_16x16x32_f16 v[16:19], v[186:189], v[0:3], v[16:19]
	s_nop 0
	v_add_u32_e32 v137, 0xa000, v142
	v_add_u32_e32 v138, 0xa800, v142
	ds_read2_b64 v[198:201], v138 offset0:128 offset1:132
	s_nop 0
	s_waitcnt lgkmcnt(2)
	v_mfma_f32_16x16x32_f16 v[52:55], v[190:193], v[12:15], 0
	v_add_u32_e32 v139, 0xb000, v142
	ds_read2_b64 v[202:205], v139 offset0:160 offset1:164
	ds_read_b128 v[210:213], v97 offset:4544
	v_add_u32_e32 v140, 0xb800, v142
	ds_read2_b64 v[156:159], v140 offset0:192 offset1:196
	v_add_u32_e32 v141, 0xc000, v142
	ds_read2_b64 v[160:163], v141 offset0:224 offset1:228
	ds_read_b128 v[182:185], v97 offset:8704
	ds_read_b128 v[186:189], v97 offset:8832
	ds_read_b128 v[190:193], v97 offset:8896
	v_mfma_f32_16x16x32_f16 v[52:55], v[164:167], v[8:11], v[52:55]
	ds_read_b128 v[164:167], v97 offset:13056
	s_nop 0
	s_nop 0
	s_nop 0
	s_nop 0
	s_waitcnt lgkmcnt(9)
	v_mfma_f32_16x16x32_f16 v[52:55], v[194:197], v[4:7], v[52:55]
	ds_read_b128 v[194:197], v97 offset:13184
	s_nop 0
	s_nop 0
	s_nop 0
	s_nop 0
	s_waitcnt lgkmcnt(7)
	v_mfma_f32_16x16x32_f16 v[52:55], v[210:213], v[0:3], v[52:55]
	s_nop 0
	s_add_u32 s4, s4, 0x241c00
	s_addc_u32 s5, s5, 0
	s_nop 0
	s_waitcnt lgkmcnt(4)
	v_mfma_f32_16x16x32_f16 v[58:61], v[182:185], v[12:15], 0
	v_mov_b32_e32 v131, v169
	v_readlane_b32 s44, v253, 32
	v_readlane_b32 s45, v253, 33
	v_mfma_f32_16x16x32_f16 v[58:61], v[174:177], v[8:11], v[58:61]
	s_nop 0
	v_ashrrev_i32_e32 v95, 31, v94
	s_movk_i32 s3, 0x3020
	s_nop 0
	s_waitcnt lgkmcnt(3)
	v_mfma_f32_16x16x32_f16 v[58:61], v[186:189], v[4:7], v[58:61]
	s_nop 0
	s_mov_b32 s2, 0xf149f2ca
	v_readlane_b32 s46, v253, 34
	s_nop 0
	s_waitcnt lgkmcnt(2)
	v_mfma_f32_16x16x32_f16 v[58:61], v[190:193], v[0:3], v[58:61]
	s_nop 0
	v_readlane_b32 s47, v253, 35
	v_readlane_b32 s48, v253, 36
	s_nop 0
	s_waitcnt lgkmcnt(1)
	v_mfma_f32_16x16x32_f16 v[62:65], v[164:167], v[12:15], 0
	v_readlane_b32 s49, v253, 37
	v_readlane_b32 s50, v253, 38
	v_readlane_b32 s51, v253, 39
	v_mfma_f32_16x16x32_f16 v[62:65], v[178:181], v[8:11], v[62:65]
	s_nop 0
	v_readlane_b32 s52, v253, 40
	v_readlane_b32 s53, v253, 41
	s_nop 0
	s_waitcnt lgkmcnt(0)
	v_mfma_f32_16x16x32_f16 v[62:65], v[194:197], v[4:7], v[62:65]
	ds_read_b128 v[66:69], v97 offset:13248
	v_readlane_b32 s54, v253, 42
	v_readlane_b32 s55, v253, 43
	s_nop 0
	s_waitcnt lgkmcnt(0)
	v_mfma_f32_16x16x32_f16 v[62:65], v[66:69], v[0:3], v[62:65]
	v_mul_f32_e32 v66, 0x3db504f3, v16
	v_mul_f32_e32 v67, 0x3db504f3, v17
	v_max3_f32 v66, v66, s7, v67
	v_mul_f32_e32 v67, 0x3db504f3, v18
	v_mul_f32_e32 v68, 0x3db504f3, v19
	v_max3_f32 v66, v66, v67, v68
	v_mul_f32_e32 v67, 0x3db504f3, v52
	v_mul_f32_e32 v68, 0x3db504f3, v53
	v_max3_f32 v66, v66, v67, v68
	v_mul_f32_e32 v67, 0x3db504f3, v54
	v_mul_f32_e32 v68, 0x3db504f3, v55
	v_max3_f32 v66, v66, v67, v68
	v_mul_f32_e32 v67, 0x3db504f3, v58
	v_mul_f32_e32 v68, 0x3db504f3, v59
	v_max3_f32 v66, v66, v67, v68
	v_mul_f32_e32 v67, 0x3db504f3, v60
	v_mul_f32_e32 v68, 0x3db504f3, v61
	v_max3_f32 v66, v66, v67, v68
	v_mul_f32_e32 v67, 0x3db504f3, v62
	v_mul_f32_e32 v68, 0x3db504f3, v63
	v_max3_f32 v66, v66, v67, v68
	v_mul_f32_e32 v67, 0x3db504f3, v64
	v_mul_f32_e32 v68, 0x3db504f3, v65
	v_max3_f32 v66, v66, v67, v68
	ds_bpermute_b32 v67, v132, v66
	v_readlane_b32 s56, v253, 44
	v_readlane_b32 s57, v253, 45
	v_readlane_b32 s58, v253, 46
	v_readlane_b32 s59, v253, 47
	s_nop 0
	s_waitcnt lgkmcnt(0)
	v_max_f32_e32 v67, v67, v67
	v_max_f32_e32 v66, v66, v67
	ds_bpermute_b32 v67, v133, v66
	ds_read2_b64 v[210:213], v134 offset1:4
	ds_read2_b64 v[182:185], v135 offset0:32 offset1:36
	ds_read2_b64 v[174:177], v136 offset0:64 offset1:68
	ds_read2_b64 v[186:189], v137 offset0:96 offset1:100
	ds_read2_b64 v[190:193], v134 offset0:8 offset1:12
	ds_read2_b64 v[164:167], v135 offset0:40 offset1:44
	ds_read2_b64 v[178:181], v136 offset0:72 offset1:76
	ds_read2_b64 v[194:197], v137 offset0:104 offset1:108
	s_nop 0
	s_waitcnt lgkmcnt(8)
	v_max3_f32 v109, v66, v67, s7
	v_fma_f32 v16, v16, s6, -v109
	v_mul_f32_e32 v16, 0x3fb8aa3b, v16
	v_fma_f32 v17, v17, s6, -v109
	v_exp_f32_e32 v67, v16
	v_mul_f32_e32 v17, 0x3fb8aa3b, v17
	v_exp_f32_e32 v68, v17
	v_sub_f32_e32 v66, 0xf149f2ca, v109
	v_add_f32_e32 v16, 0, v67
	v_mul_f32_e32 v66, 0x3fb8aa3b, v66
	v_add_f32_e32 v130, v68, v16
	v_fma_f32 v16, v18, s6, -v109
	v_mul_f32_e32 v16, 0x3fb8aa3b, v16
	v_exp_f32_e32 v114, v16
	v_fma_f32 v16, v19, s6, -v109
	v_mul_f32_e32 v16, 0x3fb8aa3b, v16
	v_exp_f32_e32 v116, v16
	v_fma_f32 v16, v52, s6, -v109
	v_mul_f32_e32 v16, 0x3fb8aa3b, v16
	v_exp_f32_e32 v118, v16
	v_fma_f32 v16, v53, s6, -v109
	v_mul_f32_e32 v16, 0x3fb8aa3b, v16
	v_exp_f32_e32 v120, v16
	v_fma_f32 v16, v54, s6, -v109
	v_mul_f32_e32 v16, 0x3fb8aa3b, v16
	v_exp_f32_e32 v122, v16
	v_fma_f32 v16, v55, s6, -v109
	v_mul_f32_e32 v16, 0x3fb8aa3b, v16
	v_exp_f32_e32 v124, v16
	v_fma_f32 v16, v58, s6, -v109
	v_mul_f32_e32 v16, 0x3fb8aa3b, v16
	v_exp_f32_e32 v126, v16
	v_fma_f32 v16, v59, s6, -v109
	v_mul_f32_e32 v16, 0x3fb8aa3b, v16
	v_exp_f32_e32 v128, v16
	v_fma_f32 v16, v60, s6, -v109
	v_mul_f32_e32 v16, 0x3fb8aa3b, v16
	v_exp_f32_e32 v100, v16
	v_fma_f32 v16, v61, s6, -v109
	v_mul_f32_e32 v16, 0x3fb8aa3b, v16
	v_exp_f32_e32 v102, v16
	v_fma_f32 v16, v62, s6, -v109
	v_mul_f32_e32 v16, 0x3fb8aa3b, v16
	v_exp_f32_e32 v104, v16
	v_fma_f32 v16, v63, s6, -v109
	v_mul_f32_e32 v16, 0x3fb8aa3b, v16
	v_exp_f32_e32 v106, v16
	v_fma_f32 v16, v64, s6, -v109
	v_mul_f32_e32 v16, 0x3fb8aa3b, v16
	v_exp_f32_e32 v108, v16
	v_fma_f32 v16, v65, s6, -v109
	v_mul_f32_e32 v16, 0x3fb8aa3b, v16
	v_exp_f32_e32 v110, v16
	v_exp_f32_e32 v16, v66
	v_cvt_pk_f16_f32 v60, v67, v68
	s_nop 0
	s_nop 0
	s_nop 0
	s_nop 0
	v_mul_f32_e32 v16, 0, v16
	v_mov_b32_e32 v17, v16
	v_mov_b32_e32 v18, v16
	v_mov_b32_e32 v19, v16
	v_cvt_pk_f16_f32 v63, v122, v124
	v_cvt_pk_f16_f32 v62, v118, v120
	v_cvt_pk_f16_f32 v61, v114, v116
	v_cvt_pk_f16_f32 v151, v108, v110
	v_cvt_pk_f16_f32 v150, v104, v106
	s_nop 0
	s_waitcnt lgkmcnt(7)
	v_mfma_f32_16x16x32_f16 v[52:55], v[210:213], v[60:63], v[16:19]
	ds_read2_b64 v[210:213], v138 offset0:136 offset1:140
	v_cvt_pk_f16_f32 v149, v100, v102
	v_cvt_pk_f16_f32 v148, v126, v128
	s_nop 0
	s_waitcnt lgkmcnt(7)
	v_mfma_f32_16x16x32_f16 v[56:59], v[182:185], v[60:63], v[16:19]
	ds_read2_b64 v[182:185], v139 offset0:168 offset1:172
	s_nop 0
	s_waitcnt lgkmcnt(7)
	v_mfma_f32_16x16x32_f16 v[64:67], v[174:177], v[60:63], v[16:19]
	ds_read2_b64 v[174:177], v140 offset0:200 offset1:204
	s_nop 0
	s_waitcnt lgkmcnt(7)
	v_mfma_f32_16x16x32_f16 v[68:71], v[186:189], v[60:63], v[16:19]
	v_mfma_f32_16x16x32_f16 v[72:75], v[198:201], v[60:63], v[16:19]
	v_mfma_f32_16x16x32_f16 v[76:79], v[202:205], v[60:63], v[16:19]
	v_mfma_f32_16x16x32_f16 v[80:83], v[156:159], v[60:63], v[16:19]
	v_mfma_f32_16x16x32_f16 v[144:147], v[160:163], v[60:63], v[16:19]
	s_nop 0
	s_nop 0
	s_waitcnt lgkmcnt(6)
	v_mfma_f32_16x16x32_f16 v[52:55], v[190:193], v[148:151], v[52:55]
	s_nop 0
	s_nop 0
	s_waitcnt lgkmcnt(5)
	v_mfma_f32_16x16x32_f16 v[56:59], v[164:167], v[148:151], v[56:59]
	s_nop 0
	s_nop 0
	s_waitcnt lgkmcnt(4)
	v_mfma_f32_16x16x32_f16 v[60:63], v[178:181], v[148:151], v[64:67]
	s_nop 2
	s_nop 0
	s_nop 0
	s_waitcnt lgkmcnt(3)
	v_mfma_f32_16x16x32_f16 v[64:67], v[194:197], v[148:151], v[68:71]
	s_nop 2
	s_nop 0
	s_nop 0
	s_waitcnt lgkmcnt(2)
	v_mfma_f32_16x16x32_f16 v[68:71], v[210:213], v[148:151], v[72:75]
	s_nop 2
	s_nop 0
	s_nop 0
	s_waitcnt lgkmcnt(1)
	v_mfma_f32_16x16x32_f16 v[72:75], v[182:185], v[148:151], v[76:79]
	s_nop 2
	s_nop 0
	s_nop 0
	s_waitcnt lgkmcnt(0)
	v_mfma_f32_16x16x32_f16 v[76:79], v[174:177], v[148:151], v[80:83]
	s_nop 2
	ds_read2_b64 v[80:83], v141 offset0:232 offset1:236
	s_nop 0
	s_waitcnt lgkmcnt(0)
	s_barrier
	s_waitcnt vmcnt(7)
	ds_write_b128 v98, v[20:23]
	s_waitcnt vmcnt(6)
	ds_write_b128 v98, v[24:27] offset:4352
	s_waitcnt vmcnt(5)
	ds_write_b128 v98, v[28:31] offset:8704
	s_waitcnt vmcnt(4)
	ds_write_b128 v98, v[32:35] offset:13056
	s_waitcnt vmcnt(3)
	ds_write_b128 v96, v[36:39] offset:34816
	s_waitcnt vmcnt(2)
	ds_write_b128 v96, v[40:43] offset:39424
	s_waitcnt vmcnt(1)
	ds_write_b128 v96, v[44:47] offset:44032
	s_waitcnt vmcnt(0)
	ds_write_b128 v96, v[48:51] offset:48640
	ds_read_b128 v[156:159], v97 offset:17408
	ds_read_b128 v[160:163], v97 offset:17472
	ds_read_b128 v[164:167], v97 offset:21824
	ds_read_b128 v[174:177], v97 offset:26176
	ds_read_b128 v[178:181], v97 offset:30528
	ds_read_b128 v[182:185], v97 offset:17536
	ds_read_b128 v[186:189], v97 offset:17600
	s_waitcnt lgkmcnt(14)
	ds_read_b128 v[190:193], v97 offset:21760
	s_waitcnt lgkmcnt(14)
	ds_read_b128 v[194:197], v97 offset:21888
	s_waitcnt lgkmcnt(14)
	ds_read_b128 v[198:201], v97 offset:21952
	s_waitcnt lgkmcnt(14)
	ds_read_b128 v[202:205], v97 offset:26112
	s_waitcnt lgkmcnt(14)
	ds_read_b128 v[210:213], v97 offset:26240
	s_waitcnt lgkmcnt(14)
	v_mov_b64_e32 v[30:31], s[4:5]
	v_mad_i64_i32 v[18:19], s[4:5], v101, s9, v[30:31]
	v_mad_i64_i32 v[22:23], s[4:5], v103, s9, v[30:31]
	v_mad_i64_i32 v[26:27], s[4:5], v105, s9, v[30:31]
	v_mad_i64_i32 v[30:31], s[4:5], v107, s9, v[30:31]
	v_lshl_add_u64 v[18:19], v[18:19], 0, v[84:85]
	v_lshl_add_u64 v[22:23], v[22:23], 0, v[84:85]
	v_lshl_add_u64 v[26:27], v[26:27], 0, v[84:85]
	v_lshl_add_u64 v[30:31], v[30:31], 0, v[84:85]
	global_load_dwordx4 v[18:21], v[18:19], off
	v_mfma_f32_16x16x32_f16 v[80:83], v[80:83], v[148:151], v[144:147]
	global_load_dwordx4 v[22:25], v[22:23], off
	v_readlane_b32 s4, v255, 47
	global_load_dwordx4 v[26:29], v[26:27], off
	s_nop 0
	global_load_dwordx4 v[30:33], v[30:31], off
	s_nop 0
	global_load_dwordx4 v[34:37], v[86:87], off offset:384
	global_load_dwordx4 v[38:41], v[88:89], off offset:384
	global_load_dwordx4 v[42:45], v[90:91], off offset:384
	global_load_dwordx4 v[46:49], v[112:113], off offset:384
	s_nop 0
	s_nop 0
	s_waitcnt lgkmcnt(14)
	s_waitcnt lgkmcnt(11)
	v_mfma_f32_16x16x32_f16 v[84:87], v[156:159], v[12:15], 0
	ds_read_b128 v[156:159], v97 offset:26304
	s_nop 0
	s_nop 0
	s_nop 0
	s_nop 0
	s_waitcnt lgkmcnt(11)
	v_mfma_f32_16x16x32_f16 v[84:87], v[160:163], v[8:11], v[84:87]
	ds_read_b128 v[160:163], v97 offset:30464
	s_nop 0
	s_or_b32 s4, s8, s4
	s_ashr_i32 s5, s4, 31
	s_nop 0
	s_waitcnt lgkmcnt(8)
	v_mfma_f32_16x16x32_f16 v[84:87], v[182:185], v[4:7], v[84:87]
	ds_read_b128 v[182:185], v97 offset:30592
	s_nop 0
	s_lshl_b64 s[4:5], s[4:5], 2
	s_add_u32 s4, s44, s4
	s_nop 0
	s_waitcnt lgkmcnt(8)
	v_mfma_f32_16x16x32_f16 v[84:87], v[186:189], v[0:3], v[84:87]
	s_nop 0
	s_addc_u32 s5, s45, s5
	s_nop 5
	v_mul_f32_e32 v17, 0x3db504f3, v84
	s_nop 0
	s_waitcnt lgkmcnt(7)
	v_mfma_f32_16x16x32_f16 v[88:91], v[190:193], v[12:15], 0
	v_mul_f32_e32 v50, 0x3db504f3, v85
	v_max3_f32 v17, v17, s7, v50
	v_mul_f32_e32 v50, 0x3db504f3, v86
	v_mfma_f32_16x16x32_f16 v[88:91], v[164:167], v[8:11], v[88:91]
	s_nop 0
	v_mul_f32_e32 v51, 0x3db504f3, v87
	v_max3_f32 v17, v17, v50, v51
	s_nop 0
	s_waitcnt lgkmcnt(6)
	v_mfma_f32_16x16x32_f16 v[88:91], v[194:197], v[4:7], v[88:91]
	s_nop 0
	s_nop 0
	s_waitcnt lgkmcnt(5)
	v_mfma_f32_16x16x32_f16 v[88:91], v[198:201], v[0:3], v[88:91]
	s_nop 0
	s_nop 6
	v_mul_f32_e32 v50, 0x3db504f3, v88
	s_nop 0
	s_waitcnt lgkmcnt(4)
	v_mfma_f32_16x16x32_f16 v[144:147], v[202:205], v[12:15], 0
	v_mul_f32_e32 v51, 0x3db504f3, v89
	v_max3_f32 v17, v17, v50, v51
	v_mul_f32_e32 v50, 0x3db504f3, v90
	v_mfma_f32_16x16x32_f16 v[144:147], v[174:177], v[8:11], v[144:147]
	s_nop 0
	v_mul_f32_e32 v51, 0x3db504f3, v91
	v_max3_f32 v17, v17, v50, v51
	s_nop 0
	s_waitcnt lgkmcnt(3)
	v_mfma_f32_16x16x32_f16 v[144:147], v[210:213], v[4:7], v[144:147]
	s_nop 0
	s_nop 0
	s_waitcnt lgkmcnt(2)
	v_mfma_f32_16x16x32_f16 v[144:147], v[156:159], v[0:3], v[144:147]
	s_nop 0
	s_nop 6
	v_mul_f32_e32 v50, 0x3db504f3, v144
	s_nop 0
	s_waitcnt lgkmcnt(1)
	v_mfma_f32_16x16x32_f16 v[148:151], v[160:163], v[12:15], 0
	v_mul_f32_e32 v51, 0x3db504f3, v145
	v_max3_f32 v17, v17, v50, v51
	v_mul_f32_e32 v50, 0x3db504f3, v146
	v_mfma_f32_16x16x32_f16 v[148:151], v[178:181], v[8:11], v[148:151]
	s_nop 0
	v_mul_f32_e32 v51, 0x3db504f3, v147
	v_max3_f32 v17, v17, v50, v51
	s_nop 0
	s_waitcnt lgkmcnt(0)
	v_mfma_f32_16x16x32_f16 v[148:151], v[182:185], v[4:7], v[148:151]
	ds_read_b128 v[152:155], v97 offset:30656
	s_nop 0
	s_waitcnt lgkmcnt(0)
	v_mfma_f32_16x16x32_f16 v[148:151], v[152:155], v[0:3], v[148:151]
	s_nop 7
	v_mul_f32_e32 v50, 0x3db504f3, v148
	v_mul_f32_e32 v51, 0x3db504f3, v149
	v_max3_f32 v17, v17, v50, v51
	v_mul_f32_e32 v50, 0x3db504f3, v150
	v_mul_f32_e32 v51, 0x3db504f3, v151
	v_max3_f32 v17, v17, v50, v51
	ds_bpermute_b32 v50, v132, v17
	s_nop 0
	s_waitcnt lgkmcnt(0)
	v_max_f32_e32 v50, v50, v50
	v_max_f32_e32 v17, v17, v50
	ds_bpermute_b32 v50, v133, v17
	s_nop 0
	s_waitcnt lgkmcnt(0)
	v_max3_f32 v113, v109, v17, v50
	v_sub_f32_e32 v17, v109, v113
	v_mul_f32_e32 v112, 0x3fb8aa3b, v17
	v_fma_f32 v17, v84, s6, -v113
	v_mul_f32_e32 v17, 0x3fb8aa3b, v17
	v_exp_f32_e32 v115, v17
	v_fma_f32 v17, v85, s6, -v113
	v_mul_f32_e32 v17, 0x3fb8aa3b, v17
	v_exp_f32_e32 v117, v17
	v_fma_f32 v17, v86, s6, -v113
	v_mul_f32_e32 v17, 0x3fb8aa3b, v17
	v_exp_f32_e32 v119, v17
	v_fma_f32 v17, v87, s6, -v113
	v_mul_f32_e32 v17, 0x3fb8aa3b, v17
	v_exp_f32_e32 v121, v17
	v_fma_f32 v17, v88, s6, -v113
	v_mul_f32_e32 v17, 0x3fb8aa3b, v17
	v_exp_f32_e32 v123, v17
	v_fma_f32 v17, v89, s6, -v113
	v_mul_f32_e32 v17, 0x3fb8aa3b, v17
	v_exp_f32_e32 v125, v17
	v_fma_f32 v17, v90, s6, -v113
	v_mul_f32_e32 v17, 0x3fb8aa3b, v17
	v_exp_f32_e32 v127, v17
	v_fma_f32 v17, v91, s6, -v113
	v_mul_f32_e32 v17, 0x3fb8aa3b, v17
	v_exp_f32_e32 v129, v17
	v_fma_f32 v17, v144, s6, -v113
	v_mul_f32_e32 v17, 0x3fb8aa3b, v17
	v_exp_f32_e32 v101, v17
	v_fma_f32 v17, v145, s6, -v113
	v_mul_f32_e32 v17, 0x3fb8aa3b, v17
	v_pk_add_f32 v[50:51], v[114:115], v[130:131]
	v_exp_f32_e32 v103, v17
	v_fma_f32 v17, v146, s6, -v113
	v_pk_add_f32 v[50:51], v[116:117], v[50:51]
	v_mul_f32_e32 v17, 0x3fb8aa3b, v17
	v_pk_add_f32 v[50:51], v[118:119], v[50:51]
	v_exp_f32_e32 v105, v17
	v_fma_f32 v17, v147, s6, -v113
	v_pk_add_f32 v[50:51], v[120:121], v[50:51]
	v_mul_f32_e32 v17, 0x3fb8aa3b, v17
	v_exp_f32_e32 v107, v17
	v_fma_f32 v17, v148, s6, -v113
	v_pk_add_f32 v[50:51], v[122:123], v[50:51]
	v_mul_f32_e32 v17, 0x3fb8aa3b, v17
	v_pk_add_f32 v[50:51], v[124:125], v[50:51]
	v_exp_f32_e32 v109, v17
	v_fma_f32 v17, v149, s6, -v113
	v_pk_add_f32 v[50:51], v[126:127], v[50:51]
	v_mul_f32_e32 v17, 0x3fb8aa3b, v17
	v_pk_add_f32 v[50:51], v[128:129], v[50:51]
	v_exp_f32_e32 v111, v17
	v_fma_f32 v17, v150, s6, -v113
	v_pk_add_f32 v[50:51], v[100:101], v[50:51]
	v_mul_f32_e32 v17, 0x3fb8aa3b, v17
	v_pk_add_f32 v[50:51], v[102:103], v[50:51]
	v_exp_f32_e32 v17, v17
	v_exp_f32_e32 v112, v112
	v_pk_add_f32 v[50:51], v[104:105], v[50:51]
	v_add_u32_e32 v120, 0xe000, v142
	ds_read2_b64 v[186:189], v120 offset0:64 offset1:68
	v_pk_add_f32 v[50:51], v[106:107], v[50:51]
	v_pk_mul_f32 v[148:149], v[56:57], v[112:113] op_sel_hi:[1,0]
	v_pk_add_f32 v[50:51], v[108:109], v[50:51]
	v_pk_mul_f32 v[56:57], v[78:79], v[112:113] op_sel_hi:[1,0]
	v_pk_add_f32 v[50:51], v[110:111], v[50:51]
	v_pk_mul_f32 v[146:147], v[54:55], v[112:113] op_sel_hi:[1,0]
	v_pk_add_f32 v[130:131], v[16:17], v[50:51]
	v_pk_mul_f32 v[50:51], v[80:81], v[112:113] op_sel_hi:[1,0]
	s_nop 0
	v_pk_mul_f32 v[90:91], v[62:63], v[112:113] op_sel_hi:[1,0]
	v_pk_mul_f32 v[88:89], v[60:61], v[112:113] op_sel_hi:[1,0]
	v_pk_mul_f32 v[60:61], v[74:75], v[112:113] op_sel_hi:[1,0]
	v_pk_mul_f32 v[54:55], v[76:77], v[112:113] op_sel_hi:[1,0]
	v_cvt_pk_f16_f32 v77, v127, v129
	v_cvt_pk_f16_f32 v76, v123, v125
	v_cvt_pk_f16_f32 v75, v119, v121
	v_cvt_pk_f16_f32 v74, v115, v117
	v_add_u32_e32 v121, 0xe800, v142
	v_fma_f32 v84, v151, s6, -v113
	s_nop 0
	s_waitcnt lgkmcnt(0)
	v_mfma_f32_16x16x32_f16 v[78:81], v[186:189], v[74:77], v[88:91]
	v_mul_f32_e32 v84, 0x3fb8aa3b, v84
	v_exp_f32_e32 v114, v84
	v_pk_mul_f32 v[86:87], v[66:67], v[112:113] op_sel_hi:[1,0]
	ds_read2_b64 v[88:91], v121 offset0:96 offset1:100
	v_pk_mul_f32 v[84:85], v[64:65], v[112:113] op_sel_hi:[1,0]
	v_add_u32_e32 v122, 0xf000, v142
	ds_read2_b64 v[190:193], v122 offset0:128 offset1:132
	v_pk_mul_f32 v[144:145], v[52:53], v[112:113] op_sel_hi:[1,0]
	v_pk_mul_f32 v[52:53], v[82:83], v[112:113] op_sel_hi:[1,0]
	s_nop 0
	s_waitcnt lgkmcnt(1)
	v_mfma_f32_16x16x32_f16 v[82:85], v[88:91], v[74:77], v[84:87]
	s_nop 2
	s_nop 0
	v_pk_mul_f32 v[64:65], v[70:71], v[112:113] op_sel_hi:[1,0]
	v_pk_mul_f32 v[62:63], v[68:69], v[112:113] op_sel_hi:[1,0]
	v_add_u32_e32 v123, 0xf800, v142
	ds_read2_b64 v[164:167], v123 offset0:160 offset1:164
	v_add_u32_e32 v118, 0xd000, v142
	ds_read2_b64 v[194:197], v118 offset1:4
	s_nop 0
	s_waitcnt lgkmcnt(2)
	v_mfma_f32_16x16x32_f16 v[86:89], v[190:193], v[74:77], v[62:65]
	s_nop 2
	s_nop 0
	v_pk_mul_f32 v[150:151], v[58:59], v[112:113] op_sel_hi:[1,0]
	v_pk_mul_f32 v[58:59], v[72:73], v[112:113] op_sel_hi:[1,0]
	v_add_u32_e32 v124, 0x3000, v118
	ds_read2_b64 v[198:201], v124 offset0:192 offset1:196
	s_nop 0
	s_nop 0
	s_waitcnt lgkmcnt(2)
	v_mfma_f32_16x16x32_f16 v[126:129], v[164:167], v[74:77], v[58:61]
	s_nop 2
	s_nop 0
	v_add_u32_e32 v119, 0xd800, v142
	ds_read2_b64 v[202:205], v119 offset0:32 offset1:36
	ds_read2_b64 v[174:177], v120 offset0:72 offset1:76
	v_add_u32_e32 v125, 0x3800, v118
	ds_read2_b64 v[210:213], v125 offset0:224 offset1:228
	ds_read2_b64 v[156:159], v118 offset0:8 offset1:12
	ds_read2_b64 v[160:163], v119 offset0:40 offset1:44
	s_nop 0
	s_waitcnt lgkmcnt(6)
	v_mfma_f32_16x16x32_f16 v[66:69], v[194:197], v[74:77], v[144:147]
	s_nop 0
	v_cvt_pk_f16_f32 v153, v17, v114
	v_cvt_pk_f16_f32 v152, v109, v111
	s_nop 0
	s_waitcnt lgkmcnt(5)
	v_mfma_f32_16x16x32_f16 v[142:145], v[198:201], v[74:77], v[54:57]
	s_nop 0
	s_nop 1
	s_nop 0
	ds_read2_b64 v[62:65], v121 offset0:104 offset1:108
	s_nop 0
	s_waitcnt lgkmcnt(5)
	v_mfma_f32_16x16x32_f16 v[70:73], v[202:205], v[74:77], v[148:151]
	v_mov_b32_e32 v117, v169
	s_nop 0
	s_waitcnt lgkmcnt(3)
	v_mfma_f32_16x16x32_f16 v[146:149], v[210:213], v[74:77], v[50:53]
	s_nop 2
	s_nop 0
	s_nop 0
	v_cvt_pk_f16_f32 v151, v105, v107
	v_cvt_pk_f16_f32 v150, v101, v103
	ds_read2_b64 v[74:77], v124 offset0:200 offset1:204
	s_nop 0
	s_waitcnt lgkmcnt(3)
	v_mfma_f32_16x16x32_f16 v[50:53], v[156:159], v[150:153], v[66:69]
	s_nop 2
	ds_read2_b64 v[66:69], v122 offset0:136 offset1:140
	s_nop 0
	s_waitcnt lgkmcnt(3)
	v_mfma_f32_16x16x32_f16 v[54:57], v[160:163], v[150:153], v[70:73]
	v_mfma_f32_16x16x32_f16 v[58:61], v[174:177], v[150:153], v[78:81]
	s_nop 1
	ds_read2_b64 v[70:73], v123 offset0:168 offset1:172
	ds_read2_b64 v[78:81], v125 offset0:232 offset1:236
	s_nop 0
	s_waitcnt lgkmcnt(0)
	s_barrier
	s_waitcnt vmcnt(7)
	ds_write_b128 v98, v[18:21] offset:17408
	s_waitcnt vmcnt(6)
	ds_write_b128 v98, v[22:25] offset:21760
	s_waitcnt vmcnt(5)
	ds_write_b128 v98, v[26:29] offset:26112
	s_waitcnt vmcnt(4)
	ds_write_b128 v98, v[30:33] offset:30464
	s_waitcnt vmcnt(3)
	ds_write_b128 v96, v[34:37] offset:53248
	s_waitcnt vmcnt(2)
	ds_write_b128 v96, v[38:41] offset:57856
	s_waitcnt vmcnt(1)
	ds_write_b128 v96, v[42:45] offset:62464
	s_waitcnt vmcnt(0)
	ds_write_b128 v99, v[46:49] offset:32256
	ds_read_b128 v[156:159], v97
	ds_read_b128 v[160:163], v97 offset:64
	ds_read_b128 v[164:167], v97 offset:4416
	ds_read_b128 v[174:177], v97 offset:8768
	ds_read_b128 v[178:181], v97 offset:13120
	ds_read_b128 v[182:185], v97 offset:128
	ds_read_b128 v[186:189], v97 offset:192
	s_waitcnt lgkmcnt(14)
	ds_read_b128 v[190:193], v97 offset:4352
	s_waitcnt lgkmcnt(14)
	ds_read_b128 v[194:197], v97 offset:4480
	s_waitcnt lgkmcnt(14)
	ds_read_b128 v[198:201], v97 offset:4544
	s_waitcnt lgkmcnt(14)
	ds_read_b128 v[202:205], v97 offset:8704
	s_waitcnt lgkmcnt(14)
	ds_read_b128 v[210:213], v97 offset:8832
	s_nop 0
	s_nop 0
	s_waitcnt lgkmcnt(15)
	s_waitcnt lgkmcnt(11)
	v_mfma_f32_16x16x32_f16 v[16:19], v[156:159], v[12:15], 0
	ds_read_b128 v[156:159], v97 offset:8896
	s_nop 0
	s_nop 0
	s_nop 0
	s_nop 0
	s_waitcnt lgkmcnt(11)
	v_mfma_f32_16x16x32_f16 v[16:19], v[160:163], v[8:11], v[16:19]
	ds_read_b128 v[160:163], v97 offset:13056
	s_nop 0
	s_nop 0
	s_waitcnt lgkmcnt(8)
	v_mfma_f32_16x16x32_f16 v[16:19], v[182:185], v[4:7], v[16:19]
	ds_read_b128 v[182:185], v97 offset:13184
	s_nop 0
	s_nop 0
	s_waitcnt lgkmcnt(8)
	v_mfma_f32_16x16x32_f16 v[16:19], v[186:189], v[0:3], v[16:19]
	s_nop 0
	s_nop 0
	s_waitcnt lgkmcnt(7)
	v_mfma_f32_16x16x32_f16 v[20:23], v[190:193], v[12:15], 0
	v_mfma_f32_16x16x32_f16 v[20:23], v[164:167], v[8:11], v[20:23]
	s_nop 0
	s_nop 0
	s_waitcnt lgkmcnt(6)
	v_mfma_f32_16x16x32_f16 v[20:23], v[194:197], v[4:7], v[20:23]
	s_nop 0
	s_nop 0
	s_waitcnt lgkmcnt(5)
	v_mfma_f32_16x16x32_f16 v[20:23], v[198:201], v[0:3], v[20:23]
	s_nop 0
	s_nop 0
	s_waitcnt lgkmcnt(4)
	v_mfma_f32_16x16x32_f16 v[24:27], v[202:205], v[12:15], 0
	v_mfma_f32_16x16x32_f16 v[24:27], v[174:177], v[8:11], v[24:27]
	s_nop 0
	s_nop 0
	s_waitcnt lgkmcnt(3)
	v_mfma_f32_16x16x32_f16 v[24:27], v[210:213], v[4:7], v[24:27]
	s_nop 0
	s_nop 0
	s_waitcnt lgkmcnt(2)
	v_mfma_f32_16x16x32_f16 v[24:27], v[156:159], v[0:3], v[24:27]
	s_nop 0
	s_nop 0
	s_waitcnt lgkmcnt(1)
	v_mfma_f32_16x16x32_f16 v[28:31], v[160:163], v[12:15], 0
	v_mfma_f32_16x16x32_f16 v[28:31], v[178:181], v[8:11], v[28:31]
	s_nop 0
	s_nop 0
	s_waitcnt lgkmcnt(0)
	v_mfma_f32_16x16x32_f16 v[28:31], v[182:185], v[4:7], v[28:31]
	ds_read_b128 v[32:35], v97 offset:13248
	s_nop 0
	s_waitcnt lgkmcnt(0)
	v_mfma_f32_16x16x32_f16 v[28:31], v[32:35], v[0:3], v[28:31]
	v_mul_f32_e32 v32, 0x3db504f3, v16
	v_mul_f32_e32 v33, 0x3db504f3, v17
	v_max3_f32 v32, v32, s7, v33
	v_mul_f32_e32 v33, 0x3db504f3, v18
	v_mul_f32_e32 v34, 0x3db504f3, v19
	v_max3_f32 v32, v32, v33, v34
	v_mul_f32_e32 v33, 0x3db504f3, v20
	v_mul_f32_e32 v34, 0x3db504f3, v21
	v_max3_f32 v32, v32, v33, v34
	v_mul_f32_e32 v33, 0x3db504f3, v22
	v_mul_f32_e32 v34, 0x3db504f3, v23
	v_max3_f32 v32, v32, v33, v34
	v_mul_f32_e32 v33, 0x3db504f3, v24
	v_mul_f32_e32 v34, 0x3db504f3, v25
	v_max3_f32 v32, v32, v33, v34
	v_mul_f32_e32 v33, 0x3db504f3, v26
	v_mul_f32_e32 v34, 0x3db504f3, v27
	v_max3_f32 v32, v32, v33, v34
	v_mul_f32_e32 v33, 0x3db504f3, v28
	v_mul_f32_e32 v34, 0x3db504f3, v29
	v_max3_f32 v32, v32, v33, v34
	v_mul_f32_e32 v33, 0x3db504f3, v30
	v_mul_f32_e32 v34, 0x3db504f3, v31
	v_max3_f32 v32, v32, v33, v34
	ds_bpermute_b32 v33, v132, v32
	v_mfma_f32_16x16x32_f16 v[62:65], v[62:65], v[150:153], v[82:85]
	s_nop 0
	s_waitcnt lgkmcnt(0)
	v_max_f32_e32 v33, v33, v33
	v_max_f32_e32 v32, v32, v33
	ds_bpermute_b32 v33, v133, v32
	ds_read2_b64 v[186:189], v135 offset0:32 offset1:36
	ds_read2_b64 v[190:193], v136 offset0:64 offset1:68
	ds_read2_b64 v[164:167], v137 offset0:96 offset1:100
	ds_read2_b64 v[194:197], v138 offset0:128 offset1:132
	ds_read2_b64 v[198:201], v139 offset0:160 offset1:164
	ds_read2_b64 v[202:205], v140 offset0:192 offset1:196
	ds_read2_b64 v[174:177], v137 offset0:104 offset1:108
	ds_read2_b64 v[210:213], v141 offset0:224 offset1:228
	ds_read2_b64 v[156:159], v138 offset0:136 offset1:140
	ds_read2_b64 v[160:163], v135 offset0:40 offset1:44
	ds_read2_b64 v[178:181], v136 offset0:72 offset1:76
	ds_read2_b64 v[182:185], v134 offset0:8 offset1:12
	v_add_f32_e32 v85, v131, v114
	v_fmac_f32_e32 v85, v130, v112
	v_mfma_f32_16x16x32_f16 v[66:69], v[66:69], v[150:153], v[86:89]
	s_nop 0
	s_waitcnt lgkmcnt(12)
	v_max3_f32 v83, v113, v32, v33
	v_fma_f32 v16, v16, s6, -v83
	v_mul_f32_e32 v16, 0x3fb8aa3b, v16
	v_fma_f32 v17, v17, s6, -v83
	v_exp_f32_e32 v48, v16
	v_mul_f32_e32 v17, 0x3fb8aa3b, v17
	v_exp_f32_e32 v49, v17
	v_sub_f32_e32 v32, v113, v83
	v_add_f32_e32 v16, 0, v48
	v_mul_f32_e32 v32, 0x3fb8aa3b, v32
	v_add_f32_e32 v116, v49, v16
	v_fma_f32 v16, v18, s6, -v83
	v_mul_f32_e32 v16, 0x3fb8aa3b, v16
	v_exp_f32_e32 v100, v16
	v_fma_f32 v16, v19, s6, -v83
	v_mul_f32_e32 v16, 0x3fb8aa3b, v16
	v_exp_f32_e32 v102, v16
	v_fma_f32 v16, v20, s6, -v83
	v_mul_f32_e32 v16, 0x3fb8aa3b, v16
	v_exp_f32_e32 v104, v16
	v_fma_f32 v16, v21, s6, -v83
	v_mul_f32_e32 v16, 0x3fb8aa3b, v16
	v_exp_f32_e32 v106, v16
	v_fma_f32 v16, v22, s6, -v83
	v_mul_f32_e32 v16, 0x3fb8aa3b, v16
	v_exp_f32_e32 v108, v16
	v_fma_f32 v16, v23, s6, -v83
	v_mul_f32_e32 v16, 0x3fb8aa3b, v16
	v_exp_f32_e32 v110, v16
	v_fma_f32 v16, v24, s6, -v83
	v_mul_f32_e32 v16, 0x3fb8aa3b, v16
	v_exp_f32_e32 v112, v16
	v_fma_f32 v16, v25, s6, -v83
	v_mul_f32_e32 v16, 0x3fb8aa3b, v16
	v_exp_f32_e32 v114, v16
	v_fma_f32 v16, v26, s6, -v83
	v_mul_f32_e32 v16, 0x3fb8aa3b, v16
	v_exp_f32_e32 v82, v16
	v_fma_f32 v16, v27, s6, -v83
	v_mul_f32_e32 v16, 0x3fb8aa3b, v16
	v_exp_f32_e32 v84, v16
	v_fma_f32 v16, v28, s6, -v83
	v_mul_f32_e32 v16, 0x3fb8aa3b, v16
	v_exp_f32_e32 v86, v16
	v_fma_f32 v16, v29, s6, -v83
	v_mul_f32_e32 v16, 0x3fb8aa3b, v16
	v_exp_f32_e32 v88, v16
	v_fma_f32 v16, v30, s6, -v83
	v_mul_f32_e32 v16, 0x3fb8aa3b, v16
	v_exp_f32_e32 v90, v16
	v_fma_f32 v16, v31, s6, -v83
	v_mul_f32_e32 v16, 0x3fb8aa3b, v16
	v_exp_f32_e32 v96, v16
	v_exp_f32_e32 v16, v32
	v_cvt_pk_f16_f32 v23, v108, v110
	v_cvt_pk_f16_f32 v22, v104, v106
	v_cvt_pk_f16_f32 v21, v100, v102
	v_pk_mul_f32 v[46:47], v[56:57], v[16:17] op_sel_hi:[1,0]
	v_pk_mul_f32 v[44:45], v[54:55], v[16:17] op_sel_hi:[1,0]
	ds_read2_b64 v[54:57], v134 offset1:4
	v_pk_mul_f32 v[52:53], v[52:53], v[16:17] op_sel_hi:[1,0]
	v_pk_mul_f32 v[50:51], v[50:51], v[16:17] op_sel_hi:[1,0]
	v_cvt_pk_f16_f32 v20, v48, v49
	v_pk_mul_f32 v[42:43], v[60:61], v[16:17] op_sel_hi:[1,0]
	v_pk_mul_f32 v[40:41], v[58:59], v[16:17] op_sel_hi:[1,0]
	s_nop 0
	s_waitcnt lgkmcnt(0)
	v_mfma_f32_16x16x32_f16 v[48:51], v[54:57], v[20:23], v[50:53]
	s_nop 2
	s_nop 0
	v_pk_mul_f32 v[38:39], v[64:65], v[16:17] op_sel_hi:[1,0]
	v_pk_mul_f32 v[36:37], v[62:63], v[16:17] op_sel_hi:[1,0]
	s_nop 0
	v_mfma_f32_16x16x32_f16 v[44:47], v[186:189], v[20:23], v[44:47]
	s_nop 0
	v_pk_mul_f32 v[34:35], v[68:69], v[16:17] op_sel_hi:[1,0]
	v_pk_mul_f32 v[32:33], v[66:67], v[16:17] op_sel_hi:[1,0]
	s_nop 0
	v_mfma_f32_16x16x32_f16 v[40:43], v[190:193], v[20:23], v[40:43]
	s_nop 0
	v_cvt_pk_f16_f32 v67, v90, v96
	v_cvt_pk_f16_f32 v66, v86, v88
	s_nop 0
	v_mfma_f32_16x16x32_f16 v[36:39], v[164:167], v[20:23], v[36:39]
	s_nop 0
	v_cvt_pk_f16_f32 v65, v82, v84
	v_cvt_pk_f16_f32 v64, v112, v114
	s_nop 0
	v_mfma_f32_16x16x32_f16 v[32:35], v[194:197], v[20:23], v[32:35]
	s_nop 0
	v_mul_f32_e32 v98, v85, v16
	v_mfma_f32_16x16x32_f16 v[70:73], v[70:73], v[150:153], v[126:129]
	v_mfma_f32_16x16x32_f16 v[74:77], v[74:77], v[150:153], v[142:145]
	v_mfma_f32_16x16x32_f16 v[78:81], v[78:81], v[150:153], v[146:149]
	s_nop 5
	v_mul_f32_e64 v30, v72, v16
	v_mul_f32_e64 v31, v73, v16
	v_pk_mul_f32 v[28:29], v[70:71], v[16:17] op_sel_hi:[1,0]
	v_pk_mul_f32 v[26:27], v[76:77], v[16:17] op_sel_hi:[1,0]
	v_pk_mul_f32 v[24:25], v[74:75], v[16:17] op_sel_hi:[1,0]
	s_nop 0
	v_mfma_f32_16x16x32_f16 v[52:55], v[198:201], v[20:23], v[28:31]
	v_mul_f32_e64 v18, v80, v16
	v_mul_f32_e64 v19, v81, v16
	v_pk_mul_f32 v[16:17], v[78:79], v[16:17] op_sel_hi:[1,0]
	s_nop 0
	s_nop 0
	v_mfma_f32_16x16x32_f16 v[56:59], v[202:205], v[20:23], v[24:27]
	s_nop 0
	s_nop 1
	s_nop 0
	s_nop 0
	v_mfma_f32_16x16x32_f16 v[28:31], v[174:177], v[64:67], v[36:39]
	s_nop 2
	s_nop 0
	s_nop 0
	v_mfma_f32_16x16x32_f16 v[60:63], v[210:213], v[20:23], v[16:19]
	s_nop 0
	s_nop 0
	s_nop 0
	s_nop 0
	s_nop 0
	v_mfma_f32_16x16x32_f16 v[32:35], v[156:159], v[64:67], v[32:35]
	ds_read2_b64 v[36:39], v139 offset0:168 offset1:172
	s_nop 0
	v_mfma_f32_16x16x32_f16 v[16:19], v[182:185], v[64:67], v[48:51]
	v_mfma_f32_16x16x32_f16 v[20:23], v[160:163], v[64:67], v[44:47]
	v_mfma_f32_16x16x32_f16 v[24:27], v[178:181], v[64:67], v[40:43]
	s_nop 1
	ds_read2_b64 v[44:47], v141 offset0:232 offset1:236
	ds_read2_b64 v[40:43], v140 offset0:200 offset1:204
	s_nop 0
	s_waitcnt lgkmcnt(0)
	s_barrier
	ds_read_b128 v[156:159], v97 offset:17408
	ds_read_b128 v[160:163], v97 offset:17472
	ds_read_b128 v[164:167], v97 offset:17536
	ds_read_b128 v[174:177], v97 offset:21824
	ds_read_b128 v[178:181], v97 offset:17600
	ds_read_b128 v[182:185], v97 offset:26176
	ds_read_b128 v[186:189], v97 offset:21760
	ds_read_b128 v[190:193], v97 offset:21888
	ds_read_b128 v[194:197], v97 offset:21952
	ds_read_b128 v[198:201], v97 offset:26112
	ds_read_b128 v[202:205], v97 offset:26240
	ds_read_b128 v[210:213], v97 offset:30464
	s_nop 0
	v_mfma_f32_16x16x32_f16 v[36:39], v[36:39], v[64:67], v[52:55]
	s_nop 2
	s_nop 0
	s_waitcnt lgkmcnt(12)
	s_waitcnt lgkmcnt(11)
	v_mfma_f32_16x16x32_f16 v[48:51], v[156:159], v[12:15], 0
	s_nop 0
	s_waitcnt lgkmcnt(10)
	v_mfma_f32_16x16x32_f16 v[48:51], v[160:163], v[8:11], v[48:51]
	s_nop 0
	v_mfma_f32_16x16x32_f16 v[40:43], v[40:43], v[64:67], v[56:59]
	s_nop 2
	s_nop 0
	s_nop 0
	s_waitcnt lgkmcnt(9)
	v_mfma_f32_16x16x32_f16 v[48:51], v[164:167], v[4:7], v[48:51]
	s_nop 0
	v_mfma_f32_16x16x32_f16 v[44:47], v[44:47], v[64:67], v[60:63]
	s_nop 2
	s_nop 0
	s_nop 0
	s_waitcnt lgkmcnt(7)
	v_mfma_f32_16x16x32_f16 v[48:51], v[178:181], v[0:3], v[48:51]
	s_nop 0
	s_nop 0
	s_waitcnt lgkmcnt(5)
	v_mfma_f32_16x16x32_f16 v[52:55], v[186:189], v[12:15], 0
	v_mfma_f32_16x16x32_f16 v[52:55], v[174:177], v[8:11], v[52:55]
	s_nop 0
	s_nop 0
	s_waitcnt lgkmcnt(4)
	v_mfma_f32_16x16x32_f16 v[52:55], v[190:193], v[4:7], v[52:55]
	s_nop 0
	s_nop 0
	s_waitcnt lgkmcnt(3)
	v_mfma_f32_16x16x32_f16 v[52:55], v[194:197], v[0:3], v[52:55]
	s_nop 0
	s_nop 0
	s_waitcnt lgkmcnt(2)
	v_mfma_f32_16x16x32_f16 v[56:59], v[198:201], v[12:15], 0
	v_mfma_f32_16x16x32_f16 v[56:59], v[182:185], v[8:11], v[56:59]
	s_nop 0
	s_nop 0
	s_waitcnt lgkmcnt(1)
	v_mfma_f32_16x16x32_f16 v[56:59], v[202:205], v[4:7], v[56:59]
	ds_read_b128 v[60:63], v97 offset:26304
	s_nop 0
	s_waitcnt lgkmcnt(0)
	v_mfma_f32_16x16x32_f16 v[58:61], v[60:63], v[0:3], v[56:59]
	s_nop 0
	s_nop 0
	v_mfma_f32_16x16x32_f16 v[12:15], v[210:213], v[12:15], 0
	ds_read_b128 v[62:65], v97 offset:30528
	s_nop 0
	s_waitcnt lgkmcnt(0)
	v_mfma_f32_16x16x32_f16 v[8:11], v[62:65], v[8:11], v[12:15]
	s_nop 4
	ds_read_b128 v[12:15], v97 offset:30592
	s_nop 0
	s_waitcnt lgkmcnt(0)
	v_mfma_f32_16x16x32_f16 v[4:7], v[12:15], v[4:7], v[8:11]
	s_nop 2
	ds_read_b128 v[8:11], v97 offset:30656
	s_nop 0
	s_waitcnt lgkmcnt(0)
	v_mfma_f32_16x16x32_f16 v[0:3], v[8:11], v[0:3], v[4:7]
	s_nop 2
	v_mul_f32_e32 v4, 0x3db504f3, v48
	v_mul_f32_e32 v5, 0x3db504f3, v49
	v_max3_f32 v4, v4, s7, v5
	v_mul_f32_e32 v5, 0x3db504f3, v50
	v_mul_f32_e32 v6, 0x3db504f3, v51
	v_max3_f32 v4, v4, v5, v6
	v_mul_f32_e32 v5, 0x3db504f3, v52
	v_mul_f32_e32 v6, 0x3db504f3, v53
	v_max3_f32 v4, v4, v5, v6
	v_mul_f32_e32 v5, 0x3db504f3, v54
	v_mul_f32_e32 v6, 0x3db504f3, v55
	v_max3_f32 v4, v4, v5, v6
	v_mul_f32_e32 v5, 0x3db504f3, v58
	v_mul_f32_e32 v6, 0x3db504f3, v59
	v_max3_f32 v4, v4, v5, v6
	v_mul_f32_e32 v5, 0x3db504f3, v60
	v_mul_f32_e32 v6, 0x3db504f3, v61
	v_max3_f32 v4, v4, v5, v6
	v_mul_f32_e32 v5, 0x3db504f3, v0
	v_mul_f32_e32 v6, 0x3db504f3, v1
	v_max3_f32 v4, v4, v5, v6
	v_mul_f32_e32 v5, 0x3db504f3, v2
	v_mul_f32_e32 v6, 0x3db504f3, v3
	v_max3_f32 v4, v4, v5, v6
	ds_bpermute_b32 v5, v132, v4
	s_nop 0
	s_waitcnt lgkmcnt(0)
	v_max_f32_e32 v5, v5, v5
	v_max_f32_e32 v4, v4, v5
	ds_bpermute_b32 v5, v133, v4
	ds_read2_b64 v[156:159], v120 offset0:64 offset1:68
	ds_read2_b64 v[160:163], v121 offset0:96 offset1:100
	ds_read2_b64 v[164:167], v122 offset0:128 offset1:132
	ds_read2_b64 v[178:181], v119 offset0:32 offset1:36
	ds_read2_b64 v[186:189], v118 offset1:4
	ds_read2_b64 v[174:177], v123 offset0:160 offset1:164
	ds_read2_b64 v[190:193], v124 offset0:192 offset1:196
	ds_read2_b64 v[194:197], v125 offset0:224 offset1:228
	ds_read2_b64 v[198:201], v118 offset0:8 offset1:12
	ds_read2_b64 v[182:185], v119 offset0:40 offset1:44
	ds_read2_b64 v[202:205], v120 offset0:72 offset1:76
	ds_read2_b64 v[210:213], v121 offset0:104 offset1:108
	s_nop 0
	s_waitcnt lgkmcnt(12)
	v_max3_f32 v57, v83, v4, v5
	v_fma_f32 v7, v52, s6, -v57
	v_mul_f32_e32 v7, 0x3fb8aa3b, v7
	v_sub_f32_e32 v4, v83, v57
	v_exp_f32_e32 v109, v7
	v_fma_f32 v7, v53, s6, -v57
	v_mul_f32_e32 v6, 0x3fb8aa3b, v4
	v_fma_f32 v4, v48, s6, -v57
	v_mul_f32_e32 v7, 0x3fb8aa3b, v7
	v_mul_f32_e32 v4, 0x3fb8aa3b, v4
	v_exp_f32_e32 v111, v7
	v_fma_f32 v7, v54, s6, -v57
	v_exp_f32_e32 v56, v6
	v_exp_f32_e32 v101, v4
	v_fma_f32 v4, v49, s6, -v57
	v_mul_f32_e32 v7, 0x3fb8aa3b, v7
	v_mul_f32_e32 v4, 0x3fb8aa3b, v4
	v_exp_f32_e32 v113, v7
	v_fma_f32 v7, v55, s6, -v57
	v_exp_f32_e32 v103, v4
	v_fma_f32 v4, v50, s6, -v57
	v_mul_f32_e32 v7, 0x3fb8aa3b, v7
	v_mul_f32_e32 v4, 0x3fb8aa3b, v4
	v_exp_f32_e32 v115, v7
	v_fma_f32 v7, v58, s6, -v57
	v_fma_f32 v0, v0, s6, -v57
	v_pk_mul_f32 v[14:15], v[38:39], v[56:57] op_sel_hi:[1,0]
	v_pk_mul_f32 v[12:13], v[36:37], v[56:57] op_sel_hi:[1,0]
	s_nop 0
	v_exp_f32_e32 v105, v4
	v_fma_f32 v4, v51, s6, -v57
	v_mul_f32_e32 v7, 0x3fb8aa3b, v7
	v_mul_f32_e32 v0, 0x3fb8aa3b, v0
	v_mul_f32_e32 v4, 0x3fb8aa3b, v4
	v_exp_f32_e32 v83, v7
	v_fma_f32 v7, v59, s6, -v57
	v_exp_f32_e32 v91, v0
	v_fma_f32 v0, v1, s6, -v57
	v_exp_f32_e32 v107, v4
	v_mul_f32_e32 v7, 0x3fb8aa3b, v7
	v_mul_f32_e32 v0, 0x3fb8aa3b, v0
	v_pk_add_f32 v[4:5], v[100:101], v[116:117]
	v_exp_f32_e32 v85, v7
	v_fma_f32 v7, v60, s6, -v57
	v_exp_f32_e32 v97, v0
	v_fma_f32 v0, v2, s6, -v57
	v_pk_add_f32 v[4:5], v[102:103], v[4:5]
	v_mul_f32_e32 v7, 0x3fb8aa3b, v7
	v_mul_f32_e32 v0, 0x3fb8aa3b, v0
	v_pk_add_f32 v[4:5], v[104:105], v[4:5]
	v_exp_f32_e32 v87, v7
	v_fma_f32 v7, v61, s6, -v57
	v_exp_f32_e32 v99, v0
	v_fma_f32 v0, v3, s6, -v57
	v_pk_add_f32 v[4:5], v[106:107], v[4:5]
	v_mul_f32_e32 v7, 0x3fb8aa3b, v7
	v_mul_f32_e32 v0, 0x3fb8aa3b, v0
	v_exp_f32_e32 v89, v7
	v_exp_f32_e32 v60, v0
	v_pk_add_f32 v[0:1], v[108:109], v[4:5]
	v_pk_mul_f32 v[26:27], v[26:27], v[56:57] op_sel_hi:[1,0]
	v_pk_mul_f32 v[24:25], v[24:25], v[56:57] op_sel_hi:[1,0]
	v_cvt_pk_f16_f32 v7, v113, v115
	v_cvt_pk_f16_f32 v6, v109, v111
	v_cvt_pk_f16_f32 v5, v105, v107
	v_cvt_pk_f16_f32 v4, v101, v103
	v_pk_mul_f32 v[50:51], v[22:23], v[56:57] op_sel_hi:[1,0]
	v_pk_mul_f32 v[48:49], v[20:21], v[56:57] op_sel_hi:[1,0]
	s_nop 0
	s_waitcnt lgkmcnt(11)
	v_mfma_f32_16x16x32_f16 v[36:39], v[156:159], v[4:7], v[24:27]
	ds_read2_b64 v[156:159], v122 offset0:136 offset1:140
	v_mul_f32_e64 v22, v30, v56
	v_mul_f32_e64 v23, v31, v56
	v_pk_mul_f32 v[20:21], v[28:29], v[56:57] op_sel_hi:[1,0]
	v_pk_add_f32 v[0:1], v[110:111], v[0:1]
	s_nop 0
	v_pk_mul_f32 v[10:11], v[42:43], v[56:57] op_sel_hi:[1,0]
	v_pk_mul_f32 v[8:9], v[40:41], v[56:57] op_sel_hi:[1,0]
	s_nop 0
	s_waitcnt lgkmcnt(11)
	v_mfma_f32_16x16x32_f16 v[40:43], v[160:163], v[4:7], v[20:23]
	s_nop 2
	s_nop 0
	v_pk_add_f32 v[0:1], v[112:113], v[0:1]
	v_pk_mul_f32 v[54:55], v[18:19], v[56:57] op_sel_hi:[1,0]
	v_pk_add_f32 v[0:1], v[114:115], v[0:1]
	v_pk_mul_f32 v[52:53], v[16:17], v[56:57] op_sel_hi:[1,0]
	v_pk_add_f32 v[0:1], v[82:83], v[0:1]
	v_pk_mul_f32 v[18:19], v[34:35], v[56:57] op_sel_hi:[1,0]
	v_pk_add_f32 v[0:1], v[84:85], v[0:1]
	v_pk_mul_f32 v[16:17], v[32:33], v[56:57] op_sel_hi:[1,0]
	v_pk_add_f32 v[0:1], v[86:87], v[0:1]
	v_pk_mul_f32 v[2:3], v[46:47], v[56:57] op_sel_hi:[1,0]
	v_pk_add_f32 v[0:1], v[88:89], v[0:1]
	s_nop 0
	v_pk_add_f32 v[0:1], v[90:91], v[0:1]
	s_nop 0
	v_pk_add_f32 v[0:1], v[96:97], v[0:1]
	s_nop 0
	s_waitcnt lgkmcnt(9)
	v_mfma_f32_16x16x32_f16 v[32:35], v[178:181], v[4:7], v[48:51]
	v_add_f32_e64 v58, v98, v0
	v_add_f32_e64 v59, v99, v1
	v_pk_mul_f32 v[0:1], v[44:45], v[56:57] op_sel_hi:[1,0]
	v_cvt_pk_f16_f32 v65, v99, v60
	v_mfma_f32_16x16x32_f16 v[44:47], v[164:167], v[4:7], v[16:19]
	v_cvt_pk_f16_f32 v64, v91, v97
	v_cvt_pk_f16_f32 v63, v87, v89
	v_cvt_pk_f16_f32 v62, v83, v85
	s_nop 0
	s_nop 0
	s_waitcnt lgkmcnt(7)
	v_mfma_f32_16x16x32_f16 v[48:51], v[174:177], v[4:7], v[12:15]
	s_nop 2
	s_nop 0
	v_mfma_f32_16x16x32_f16 v[28:31], v[186:189], v[4:7], v[52:55]
	s_nop 0
	s_waitcnt lgkmcnt(6)
	v_mfma_f32_16x16x32_f16 v[52:55], v[190:193], v[4:7], v[8:11]
	s_nop 2
	s_nop 0
	s_nop 0
	s_waitcnt lgkmcnt(5)
	v_mfma_f32_16x16x32_f16 v[0:3], v[194:197], v[4:7], v[0:3]
	s_nop 0
	s_nop 0
	s_waitcnt lgkmcnt(4)
	v_mfma_f32_16x16x32_f16 v[28:31], v[198:201], v[62:65], v[28:31]
	s_nop 0
	s_nop 0
	s_waitcnt lgkmcnt(3)
	v_mfma_f32_16x16x32_f16 v[24:27], v[182:185], v[62:65], v[32:35]
	s_nop 0
	s_nop 1
	ds_read2_b64 v[32:35], v125 offset0:232 offset1:236
	s_nop 0
	s_waitcnt lgkmcnt(3)
	v_mfma_f32_16x16x32_f16 v[20:23], v[202:205], v[62:65], v[36:39]
	s_nop 0
	s_nop 0
	s_waitcnt lgkmcnt(2)
	v_mfma_f32_16x16x32_f16 v[16:19], v[210:213], v[62:65], v[40:43]
	s_nop 0
	s_waitcnt lgkmcnt(0)
	v_mfma_f32_16x16x32_f16 v[0:3], v[32:35], v[62:65], v[0:3]
	v_add_f32_e32 v32, v59, v60
	v_fmac_f32_e32 v32, v58, v56
	ds_bpermute_b32 v33, v132, v32
	ds_read2_b64 v[160:163], v123 offset0:168 offset1:172
	s_nop 0
	v_mfma_f32_16x16x32_f16 v[12:15], v[156:159], v[62:65], v[44:47]
	s_nop 0
	s_nop 0
	s_waitcnt lgkmcnt(1)
	v_add_f32_e32 v32, v32, v33
	ds_bpermute_b32 v33, v133, v32
	s_nop 0
	s_waitcnt lgkmcnt(1)
	v_mfma_f32_16x16x32_f16 v[8:11], v[160:163], v[62:65], v[48:51]
	ds_read2_b64 v[4:7], v124 offset0:200 offset1:204
	s_nop 0
	s_waitcnt lgkmcnt(0)
	s_barrier
	v_add_f32_e32 v32, v32, v33
	global_load_dword v33, v169, s[4:5]
	v_mfma_f32_16x16x32_f16 v[4:7], v[4:7], v[62:65], v[52:55]
	s_waitcnt vmcnt(0)
	v_sub_f32_e32 v33, v33, v57
	v_mul_f32_e32 v33, 0x3fb8aa3b, v33
	v_exp_f32_e32 v33, v33
	s_nop 0
	v_add_f32_e32 v32, v32, v33
	v_div_scale_f32 v33, s[4:5], v32, v32, 1.0
	v_rcp_f32_e32 v34, v33
	v_readlane_b32 s4, v254, 12
	v_readlane_b32 s5, v254, 13
	v_fma_f32 v35, -v33, v34, 1.0
	v_fmac_f32_e32 v34, v35, v34
	v_div_scale_f32 v35, vcc, 1.0, v32, 1.0
	v_mul_f32_e32 v36, v35, v34
	v_fma_f32 v37, -v33, v36, v35
	v_fmac_f32_e32 v36, v37, v34
	v_fma_f32 v33, -v33, v36, v35
	v_div_fmas_f32 v33, v33, v34, v36
	v_lshlrev_b64 v[34:35], 12, v[94:95]
	v_lshl_add_u64 v[34:35], s[4:5], 0, v[34:35]
	v_lshl_add_u64 v[36:37], v[34:35], 0, s[0:1]
	v_lshl_add_u64 v[34:35], v[92:93], 0, v[168:169]
	global_load_dwordx2 v[60:61], v[34:35], off offset:2048
	global_load_dwordx2 v[62:63], v[34:35], off offset:2080
	global_load_dwordx2 v[64:65], v[34:35], off offset:2112
	global_load_dwordx2 v[66:67], v[34:35], off offset:2144
	global_load_dwordx2 v[68:69], v[34:35], off offset:2176
	global_load_dwordx2 v[70:71], v[34:35], off offset:2208
	global_load_dwordx2 v[72:73], v[34:35], off offset:2240
	global_load_dwordx2 v[74:75], v[34:35], off offset:2272
	v_div_fixup_f32 v32, v33, v32, 1.0
	s_waitcnt vmcnt(7)
	v_cvt_f32_f16_sdwa v33, v60 dst_sel:DWORD dst_unused:UNUSED_PAD src0_sel:WORD_1
	v_cvt_f32_f16_e32 v38, v60
	v_mul_f32_e32 v41, 0xbfb8aa3b, v33
	v_mul_f32_e32 v40, 0xbfb8aa3b, v38
	v_exp_f32_e32 v40, v40
	v_exp_f32_e32 v41, v41
	v_pk_mul_f32 v[28:29], v[28:29], v[32:33] op_sel_hi:[1,0]
	v_pk_add_f32 v[40:41], v[40:41], 1.0 op_sel_hi:[1,0]
	s_nop 0
	v_div_scale_f32 v42, s[4:5], v41, v41, v33
	v_rcp_f32_e32 v43, v42
	s_nop 0
	v_fma_f32 v44, -v42, v43, 1.0
	v_fmac_f32_e32 v43, v44, v43
	v_div_scale_f32 v44, vcc, v33, v41, v33
	v_mul_f32_e32 v45, v44, v43
	v_fma_f32 v46, -v42, v45, v44
	v_fmac_f32_e32 v45, v46, v43
	v_fma_f32 v42, -v42, v45, v44
	v_div_fmas_f32 v42, v42, v43, v45
	v_div_fixup_f32 v41, v42, v41, v33
	v_div_scale_f32 v33, s[4:5], v40, v40, v38
	v_rcp_f32_e32 v42, v33
	s_nop 0
	v_fma_f32 v43, -v33, v42, 1.0
	v_fmac_f32_e32 v42, v43, v42
	v_div_scale_f32 v43, vcc, v38, v40, v38
	v_mul_f32_e32 v44, v43, v42
	v_fma_f32 v45, -v33, v44, v43
	v_fmac_f32_e32 v44, v45, v42
	v_fma_f32 v33, -v33, v44, v43
	v_div_fmas_f32 v33, v33, v42, v44
	v_div_fixup_f32 v40, v33, v40, v38
	v_cvt_f32_f16_sdwa v33, v61 dst_sel:DWORD dst_unused:UNUSED_PAD src0_sel:WORD_1
	v_cvt_f32_f16_e32 v39, v61
	v_pk_mul_f32 v[28:29], v[28:29], v[40:41]
	v_pk_mul_f32 v[30:31], v[30:31], v[32:33] op_sel_hi:[1,0]
	v_cvt_pk_f16_f32 v38, v28, v29
	v_mul_f32_e32 v28, 0xbfb8aa3b, v39
	v_mul_f32_e32 v29, 0xbfb8aa3b, v33
	v_exp_f32_e32 v28, v28
	v_exp_f32_e32 v29, v29
	s_nop 0
	v_pk_add_f32 v[28:29], v[28:29], 1.0 op_sel_hi:[1,0]
	s_nop 0
	v_div_scale_f32 v40, s[4:5], v29, v29, v33
	v_rcp_f32_e32 v41, v40
	s_nop 0
	v_fma_f32 v42, -v40, v41, 1.0
	v_fmac_f32_e32 v41, v42, v41
	v_div_scale_f32 v42, vcc, v33, v29, v33
	v_mul_f32_e32 v43, v42, v41
	v_fma_f32 v44, -v40, v43, v42
	v_fmac_f32_e32 v43, v44, v41
	v_fma_f32 v40, -v40, v43, v42
	v_div_fmas_f32 v40, v40, v41, v43
	v_div_fixup_f32 v29, v40, v29, v33
	v_div_scale_f32 v33, s[4:5], v28, v28, v39
	v_rcp_f32_e32 v40, v33
	s_nop 0
	v_fma_f32 v41, -v33, v40, 1.0
	v_fmac_f32_e32 v40, v41, v40
	v_div_scale_f32 v41, vcc, v39, v28, v39
	v_mul_f32_e32 v42, v41, v40
	v_fma_f32 v43, -v33, v42, v41
	v_fmac_f32_e32 v42, v43, v40
	v_fma_f32 v33, -v33, v42, v41
	v_div_fmas_f32 v33, v33, v40, v42
	v_div_fixup_f32 v28, v33, v28, v39
	v_pk_mul_f32 v[28:29], v[30:31], v[28:29]
	s_nop 0
	v_cvt_pk_f16_f32 v39, v28, v29
	v_lshl_add_u64 v[28:29], v[36:37], 0, v[168:169]
	global_store_dwordx2 v[28:29], v[38:39], off
	s_waitcnt vmcnt(7)
	v_cvt_f32_f16_sdwa v33, v62 dst_sel:DWORD dst_unused:UNUSED_PAD src0_sel:WORD_1
	v_cvt_f32_f16_e32 v30, v62
	v_mul_f32_e32 v37, 0xbfb8aa3b, v33
	v_mul_f32_e32 v36, 0xbfb8aa3b, v30
	v_exp_f32_e32 v36, v36
	v_exp_f32_e32 v37, v37
	v_pk_mul_f32 v[24:25], v[24:25], v[32:33] op_sel_hi:[1,0]
	v_pk_add_f32 v[36:37], v[36:37], 1.0 op_sel_hi:[1,0]
	s_nop 0
	v_div_scale_f32 v38, s[4:5], v37, v37, v33
	v_rcp_f32_e32 v39, v38
	s_nop 0
	v_fma_f32 v40, -v38, v39, 1.0
	v_fmac_f32_e32 v39, v40, v39
	v_div_scale_f32 v40, vcc, v33, v37, v33
	v_mul_f32_e32 v41, v40, v39
	v_fma_f32 v42, -v38, v41, v40
	v_fmac_f32_e32 v41, v42, v39
	v_fma_f32 v38, -v38, v41, v40
	v_div_fmas_f32 v38, v38, v39, v41
	v_div_fixup_f32 v37, v38, v37, v33
	v_div_scale_f32 v33, s[4:5], v36, v36, v30
	v_rcp_f32_e32 v38, v33
	s_nop 0
	v_fma_f32 v39, -v33, v38, 1.0
	v_fmac_f32_e32 v38, v39, v38
	v_div_scale_f32 v39, vcc, v30, v36, v30
	v_mul_f32_e32 v40, v39, v38
	v_fma_f32 v41, -v33, v40, v39
	v_fmac_f32_e32 v40, v41, v38
	v_fma_f32 v33, -v33, v40, v39
	v_div_fmas_f32 v33, v33, v38, v40
	v_div_fixup_f32 v36, v33, v36, v30
	v_pk_mul_f32 v[24:25], v[24:25], v[36:37]
	v_cvt_f32_f16_e32 v33, v63
	v_cvt_pk_f16_f32 v24, v24, v25
	v_cvt_f32_f16_sdwa v25, v63 dst_sel:DWORD dst_unused:UNUSED_PAD src0_sel:WORD_1
	v_mul_f32_e32 v30, 0xbfb8aa3b, v33
	v_exp_f32_e32 v30, v30
	v_mul_f32_e32 v31, 0xbfb8aa3b, v25
	v_exp_f32_e32 v31, v31
	v_pk_mul_f32 v[26:27], v[26:27], v[32:33] op_sel_hi:[1,0]
	v_pk_mul_f32 v[20:21], v[20:21], v[32:33] op_sel_hi:[1,0]
	v_pk_add_f32 v[30:31], v[30:31], 1.0 op_sel_hi:[1,0]
	s_nop 0
	v_div_scale_f32 v36, s[4:5], v31, v31, v25
	v_rcp_f32_e32 v37, v36
	s_nop 0
	v_fma_f32 v38, -v36, v37, 1.0
	v_fmac_f32_e32 v37, v38, v37
	v_div_scale_f32 v38, vcc, v25, v31, v25
	v_mul_f32_e32 v39, v38, v37
	v_fma_f32 v40, -v36, v39, v38
	v_fmac_f32_e32 v39, v40, v37
	v_fma_f32 v36, -v36, v39, v38
	v_div_fmas_f32 v36, v36, v37, v39
	v_div_fixup_f32 v31, v36, v31, v25
	v_div_scale_f32 v25, s[4:5], v30, v30, v33
	v_rcp_f32_e32 v36, v25
	s_nop 0
	v_fma_f32 v37, -v25, v36, 1.0
	v_fmac_f32_e32 v36, v37, v36
	v_div_scale_f32 v37, vcc, v33, v30, v33
	v_mul_f32_e32 v38, v37, v36
	v_fma_f32 v39, -v25, v38, v37
	v_fmac_f32_e32 v38, v39, v36
	v_fma_f32 v25, -v25, v38, v37
	v_div_fmas_f32 v25, v25, v36, v38
	v_div_fixup_f32 v30, v25, v30, v33
	v_pk_mul_f32 v[26:27], v[26:27], v[30:31]
	s_nop 0
	v_cvt_pk_f16_f32 v25, v26, v27
	global_store_dwordx2 v[28:29], v[24:25], off offset:32
	s_waitcnt vmcnt(7)
	v_cvt_f32_f16_sdwa v30, v64 dst_sel:DWORD dst_unused:UNUSED_PAD src0_sel:WORD_1
	v_cvt_f32_f16_e32 v24, v64
	v_mul_f32_e32 v27, 0xbfb8aa3b, v30
	v_mul_f32_e32 v26, 0xbfb8aa3b, v24
	v_exp_f32_e32 v26, v26
	v_exp_f32_e32 v27, v27
	s_nop 0
	v_pk_add_f32 v[26:27], v[26:27], 1.0 op_sel_hi:[1,0]
	s_nop 0
	v_div_scale_f32 v31, s[4:5], v27, v27, v30
	v_rcp_f32_e32 v33, v31
	s_nop 0
	v_fma_f32 v36, -v31, v33, 1.0
	v_fmac_f32_e32 v33, v36, v33
	v_div_scale_f32 v36, vcc, v30, v27, v30
	v_mul_f32_e32 v37, v36, v33
	v_fma_f32 v38, -v31, v37, v36
	v_fmac_f32_e32 v37, v38, v33
	v_fma_f32 v31, -v31, v37, v36
	v_div_fmas_f32 v31, v31, v33, v37
	v_div_fixup_f32 v27, v31, v27, v30
	v_div_scale_f32 v30, s[4:5], v26, v26, v24
	v_rcp_f32_e32 v31, v30
	s_nop 0
	v_fma_f32 v33, -v30, v31, 1.0
	v_fmac_f32_e32 v31, v33, v31
	v_div_scale_f32 v33, vcc, v24, v26, v24
	v_mul_f32_e32 v36, v33, v31
	v_fma_f32 v37, -v30, v36, v33
	v_fmac_f32_e32 v36, v37, v31
	v_fma_f32 v30, -v30, v36, v33
	v_div_fmas_f32 v30, v30, v31, v36
	v_div_fixup_f32 v26, v30, v26, v24
	v_pk_mul_f32 v[20:21], v[20:21], v[26:27]
	v_cvt_f32_f16_e32 v26, v65
	v_cvt_pk_f16_f32 v20, v20, v21
	v_cvt_f32_f16_sdwa v21, v65 dst_sel:DWORD dst_unused:UNUSED_PAD src0_sel:WORD_1
	v_pk_mul_f32 v[22:23], v[22:23], v[32:33] op_sel_hi:[1,0]
	v_mul_f32_e32 v24, 0xbfb8aa3b, v26
	v_exp_f32_e32 v24, v24
	v_mul_f32_e32 v25, 0xbfb8aa3b, v21
	v_exp_f32_e32 v25, v25
	s_nop 0
	v_pk_add_f32 v[24:25], v[24:25], 1.0 op_sel_hi:[1,0]
	s_nop 0
	v_div_scale_f32 v27, s[4:5], v25, v25, v21
	v_rcp_f32_e32 v30, v27
	s_nop 0
	v_fma_f32 v31, -v27, v30, 1.0
	v_fmac_f32_e32 v30, v31, v30
	v_div_scale_f32 v31, vcc, v21, v25, v21
	v_mul_f32_e32 v33, v31, v30
	v_fma_f32 v36, -v27, v33, v31
	v_fmac_f32_e32 v33, v36, v30
	v_fma_f32 v27, -v27, v33, v31
	v_div_fmas_f32 v27, v27, v30, v33
	v_div_fixup_f32 v25, v27, v25, v21
	v_div_scale_f32 v21, s[4:5], v24, v24, v26
	v_rcp_f32_e32 v27, v21
	s_nop 0
	v_fma_f32 v30, -v21, v27, 1.0
	v_fmac_f32_e32 v27, v30, v27
	v_div_scale_f32 v30, vcc, v26, v24, v26
	v_mul_f32_e32 v31, v30, v27
	v_fma_f32 v33, -v21, v31, v30
	v_fmac_f32_e32 v31, v33, v27
	v_fma_f32 v21, -v21, v31, v30
	v_div_fmas_f32 v21, v21, v27, v31
	v_div_fixup_f32 v24, v21, v24, v26
	v_pk_mul_f32 v[22:23], v[22:23], v[24:25]
	v_pk_mul_f32 v[16:17], v[16:17], v[32:33] op_sel_hi:[1,0]
	v_cvt_pk_f16_f32 v21, v22, v23
	global_store_dwordx2 v[28:29], v[20:21], off offset:64
	v_pk_mul_f32 v[18:19], v[18:19], v[32:33] op_sel_hi:[1,0]
	v_pk_mul_f32 v[12:13], v[12:13], v[32:33] op_sel_hi:[1,0]
	v_pk_mul_f32 v[14:15], v[14:15], v[32:33] op_sel_hi:[1,0]
	v_pk_mul_f32 v[8:9], v[8:9], v[32:33] op_sel_hi:[1,0]
	v_pk_mul_f32 v[10:11], v[10:11], v[32:33] op_sel_hi:[1,0]
	v_pk_mul_f32 v[4:5], v[4:5], v[32:33] op_sel_hi:[1,0]
	v_pk_mul_f32 v[6:7], v[6:7], v[32:33] op_sel_hi:[1,0]
	v_pk_mul_f32 v[0:1], v[0:1], v[32:33] op_sel_hi:[1,0]
	v_pk_mul_f32 v[2:3], v[2:3], v[32:33] op_sel_hi:[1,0]
	s_waitcnt vmcnt(7)
	v_cvt_f32_f16_sdwa v24, v66 dst_sel:DWORD dst_unused:UNUSED_PAD src0_sel:WORD_1
	v_cvt_f32_f16_e32 v20, v66
	v_mul_f32_e32 v23, 0xbfb8aa3b, v24
	v_mul_f32_e32 v22, 0xbfb8aa3b, v20
	v_exp_f32_e32 v22, v22
	v_exp_f32_e32 v23, v23
	s_nop 0
	v_pk_add_f32 v[22:23], v[22:23], 1.0 op_sel_hi:[1,0]
	s_nop 0
	v_div_scale_f32 v25, s[4:5], v23, v23, v24
	v_rcp_f32_e32 v26, v25
	s_nop 0
	v_fma_f32 v27, -v25, v26, 1.0
	v_fmac_f32_e32 v26, v27, v26
	v_div_scale_f32 v27, vcc, v24, v23, v24
	v_mul_f32_e32 v30, v27, v26
	v_fma_f32 v31, -v25, v30, v27
	v_fmac_f32_e32 v30, v31, v26
	v_fma_f32 v25, -v25, v30, v27
	v_div_fmas_f32 v25, v25, v26, v30
	v_div_fixup_f32 v23, v25, v23, v24
	v_div_scale_f32 v24, s[4:5], v22, v22, v20
	v_rcp_f32_e32 v25, v24
	s_nop 0
	v_fma_f32 v26, -v24, v25, 1.0
	v_fmac_f32_e32 v25, v26, v25
	v_div_scale_f32 v26, vcc, v20, v22, v20
	v_mul_f32_e32 v27, v26, v25
	v_fma_f32 v30, -v24, v27, v26
	v_fmac_f32_e32 v27, v30, v25
	v_fma_f32 v24, -v24, v27, v26
	v_div_fmas_f32 v24, v24, v25, v27
	v_div_fixup_f32 v22, v24, v22, v20
	v_pk_mul_f32 v[16:17], v[16:17], v[22:23]
	v_cvt_f32_f16_e32 v22, v67
	v_cvt_pk_f16_f32 v16, v16, v17
	v_cvt_f32_f16_sdwa v17, v67 dst_sel:DWORD dst_unused:UNUSED_PAD src0_sel:WORD_1
	v_mul_f32_e32 v20, 0xbfb8aa3b, v22
	v_exp_f32_e32 v20, v20
	v_mul_f32_e32 v21, 0xbfb8aa3b, v17
	v_exp_f32_e32 v21, v21
	s_nop 0
	v_pk_add_f32 v[20:21], v[20:21], 1.0 op_sel_hi:[1,0]
	s_nop 0
	v_div_scale_f32 v23, s[4:5], v21, v21, v17
	v_rcp_f32_e32 v24, v23
	s_nop 0
	v_fma_f32 v25, -v23, v24, 1.0
	v_fmac_f32_e32 v24, v25, v24
	v_div_scale_f32 v25, vcc, v17, v21, v17
	v_mul_f32_e32 v26, v25, v24
	v_fma_f32 v27, -v23, v26, v25
	v_fmac_f32_e32 v26, v27, v24
	v_fma_f32 v23, -v23, v26, v25
	v_div_fmas_f32 v23, v23, v24, v26
	v_div_fixup_f32 v21, v23, v21, v17
	v_div_scale_f32 v17, s[4:5], v20, v20, v22
	v_rcp_f32_e32 v23, v17
	s_nop 0
	v_fma_f32 v24, -v17, v23, 1.0
	v_fmac_f32_e32 v23, v24, v23
	v_div_scale_f32 v24, vcc, v22, v20, v22
	v_mul_f32_e32 v25, v24, v23
	v_fma_f32 v26, -v17, v25, v24
	v_fmac_f32_e32 v25, v26, v23
	v_fma_f32 v17, -v17, v25, v24
	v_div_fmas_f32 v17, v17, v23, v25
	v_div_fixup_f32 v20, v17, v20, v22
	v_pk_mul_f32 v[18:19], v[18:19], v[20:21]
	s_nop 0
	v_cvt_pk_f16_f32 v17, v18, v19
	global_store_dwordx2 v[28:29], v[16:17], off offset:96
	s_waitcnt vmcnt(7)
	v_cvt_f32_f16_sdwa v20, v68 dst_sel:DWORD dst_unused:UNUSED_PAD src0_sel:WORD_1
	v_cvt_f32_f16_e32 v16, v68
	v_mul_f32_e32 v19, 0xbfb8aa3b, v20
	v_mul_f32_e32 v18, 0xbfb8aa3b, v16
	v_exp_f32_e32 v18, v18
	v_exp_f32_e32 v19, v19
	s_nop 0
	v_pk_add_f32 v[18:19], v[18:19], 1.0 op_sel_hi:[1,0]
	s_nop 0
	v_div_scale_f32 v21, s[4:5], v19, v19, v20
	v_rcp_f32_e32 v22, v21
	s_nop 0
	v_fma_f32 v23, -v21, v22, 1.0
	v_fmac_f32_e32 v22, v23, v22
	v_div_scale_f32 v23, vcc, v20, v19, v20
	v_mul_f32_e32 v24, v23, v22
	v_fma_f32 v25, -v21, v24, v23
	v_fmac_f32_e32 v24, v25, v22
	v_fma_f32 v21, -v21, v24, v23
	v_div_fmas_f32 v21, v21, v22, v24
	v_div_fixup_f32 v19, v21, v19, v20
	v_div_scale_f32 v20, s[4:5], v18, v18, v16
	v_rcp_f32_e32 v21, v20
	s_nop 0
	v_fma_f32 v22, -v20, v21, 1.0
	v_fmac_f32_e32 v21, v22, v21
	v_div_scale_f32 v22, vcc, v16, v18, v16
	v_mul_f32_e32 v23, v22, v21
	v_fma_f32 v24, -v20, v23, v22
	v_fmac_f32_e32 v23, v24, v21
	v_fma_f32 v20, -v20, v23, v22
	v_div_fmas_f32 v20, v20, v21, v23
	v_div_fixup_f32 v18, v20, v18, v16
	v_pk_mul_f32 v[12:13], v[12:13], v[18:19]
	v_cvt_f32_f16_e32 v18, v69
	v_cvt_pk_f16_f32 v12, v12, v13
	v_cvt_f32_f16_sdwa v13, v69 dst_sel:DWORD dst_unused:UNUSED_PAD src0_sel:WORD_1
	v_mul_f32_e32 v16, 0xbfb8aa3b, v18
	v_exp_f32_e32 v16, v16
	v_mul_f32_e32 v17, 0xbfb8aa3b, v13
	v_exp_f32_e32 v17, v17
	s_nop 0
	v_pk_add_f32 v[16:17], v[16:17], 1.0 op_sel_hi:[1,0]
	s_nop 0
	v_div_scale_f32 v19, s[4:5], v17, v17, v13
	v_rcp_f32_e32 v20, v19
	s_nop 0
	v_fma_f32 v21, -v19, v20, 1.0
	v_fmac_f32_e32 v20, v21, v20
	v_div_scale_f32 v21, vcc, v13, v17, v13
	v_mul_f32_e32 v22, v21, v20
	v_fma_f32 v23, -v19, v22, v21
	v_fmac_f32_e32 v22, v23, v20
	v_fma_f32 v19, -v19, v22, v21
	v_div_fmas_f32 v19, v19, v20, v22
	v_div_fixup_f32 v17, v19, v17, v13
	v_div_scale_f32 v13, s[4:5], v16, v16, v18
	v_rcp_f32_e32 v19, v13
	s_nop 0
	v_fma_f32 v20, -v13, v19, 1.0
	v_fmac_f32_e32 v19, v20, v19
	v_div_scale_f32 v20, vcc, v18, v16, v18
	v_mul_f32_e32 v21, v20, v19
	v_fma_f32 v22, -v13, v21, v20
	v_fmac_f32_e32 v21, v22, v19
	v_fma_f32 v13, -v13, v21, v20
	v_div_fmas_f32 v13, v13, v19, v21
	v_div_fixup_f32 v16, v13, v16, v18
	v_pk_mul_f32 v[14:15], v[14:15], v[16:17]
	s_nop 0
	v_cvt_pk_f16_f32 v13, v14, v15
	global_store_dwordx2 v[28:29], v[12:13], off offset:128
	s_waitcnt vmcnt(7)
	v_cvt_f32_f16_sdwa v16, v70 dst_sel:DWORD dst_unused:UNUSED_PAD src0_sel:WORD_1
	v_cvt_f32_f16_e32 v12, v70
	v_mul_f32_e32 v15, 0xbfb8aa3b, v16
	v_mul_f32_e32 v14, 0xbfb8aa3b, v12
	v_exp_f32_e32 v14, v14
	v_exp_f32_e32 v15, v15
	s_nop 0
	v_pk_add_f32 v[14:15], v[14:15], 1.0 op_sel_hi:[1,0]
	s_nop 0
	v_div_scale_f32 v17, s[4:5], v15, v15, v16
	v_rcp_f32_e32 v18, v17
	s_nop 0
	v_fma_f32 v19, -v17, v18, 1.0
	v_fmac_f32_e32 v18, v19, v18
	v_div_scale_f32 v19, vcc, v16, v15, v16
	v_mul_f32_e32 v20, v19, v18
	v_fma_f32 v21, -v17, v20, v19
	v_fmac_f32_e32 v20, v21, v18
	v_fma_f32 v17, -v17, v20, v19
	v_div_fmas_f32 v17, v17, v18, v20
	v_div_fixup_f32 v15, v17, v15, v16
	v_div_scale_f32 v16, s[4:5], v14, v14, v12
	v_rcp_f32_e32 v17, v16
	s_nop 0
	v_fma_f32 v18, -v16, v17, 1.0
	v_fmac_f32_e32 v17, v18, v17
	v_div_scale_f32 v18, vcc, v12, v14, v12
	v_mul_f32_e32 v19, v18, v17
	v_fma_f32 v20, -v16, v19, v18
	v_fmac_f32_e32 v19, v20, v17
	v_fma_f32 v16, -v16, v19, v18
	v_div_fmas_f32 v16, v16, v17, v19
	v_div_fixup_f32 v14, v16, v14, v12
	v_pk_mul_f32 v[8:9], v[8:9], v[14:15]
	v_cvt_f32_f16_e32 v14, v71
	v_cvt_pk_f16_f32 v8, v8, v9
	v_cvt_f32_f16_sdwa v9, v71 dst_sel:DWORD dst_unused:UNUSED_PAD src0_sel:WORD_1
	v_mul_f32_e32 v12, 0xbfb8aa3b, v14
	v_exp_f32_e32 v12, v12
	v_mul_f32_e32 v13, 0xbfb8aa3b, v9
	v_exp_f32_e32 v13, v13
	s_nop 0
	v_pk_add_f32 v[12:13], v[12:13], 1.0 op_sel_hi:[1,0]
	s_nop 0
	v_div_scale_f32 v15, s[4:5], v13, v13, v9
	v_rcp_f32_e32 v16, v15
	s_nop 0
	v_fma_f32 v17, -v15, v16, 1.0
	v_fmac_f32_e32 v16, v17, v16
	v_div_scale_f32 v17, vcc, v9, v13, v9
	v_mul_f32_e32 v18, v17, v16
	v_fma_f32 v19, -v15, v18, v17
	v_fmac_f32_e32 v18, v19, v16
	v_fma_f32 v15, -v15, v18, v17
	v_div_fmas_f32 v15, v15, v16, v18
	v_div_fixup_f32 v13, v15, v13, v9
	v_div_scale_f32 v9, s[4:5], v12, v12, v14
	v_rcp_f32_e32 v15, v9
	s_nop 0
	v_fma_f32 v16, -v9, v15, 1.0
	v_fmac_f32_e32 v15, v16, v15
	v_div_scale_f32 v16, vcc, v14, v12, v14
	v_mul_f32_e32 v17, v16, v15
	v_fma_f32 v18, -v9, v17, v16
	v_fmac_f32_e32 v17, v18, v15
	v_fma_f32 v9, -v9, v17, v16
	v_div_fmas_f32 v9, v9, v15, v17
	v_div_fixup_f32 v12, v9, v12, v14
	v_pk_mul_f32 v[10:11], v[10:11], v[12:13]
	s_nop 0
	v_cvt_pk_f16_f32 v9, v10, v11
	global_store_dwordx2 v[28:29], v[8:9], off offset:160
	s_waitcnt vmcnt(7)
	v_cvt_f32_f16_sdwa v12, v72 dst_sel:DWORD dst_unused:UNUSED_PAD src0_sel:WORD_1
	v_cvt_f32_f16_e32 v8, v72
	v_mul_f32_e32 v11, 0xbfb8aa3b, v12
	v_mul_f32_e32 v10, 0xbfb8aa3b, v8
	v_exp_f32_e32 v10, v10
	v_exp_f32_e32 v11, v11
	s_nop 0
	v_pk_add_f32 v[10:11], v[10:11], 1.0 op_sel_hi:[1,0]
	s_nop 0
	v_div_scale_f32 v13, s[4:5], v11, v11, v12
	v_rcp_f32_e32 v14, v13
	s_nop 0
	v_fma_f32 v15, -v13, v14, 1.0
	v_fmac_f32_e32 v14, v15, v14
	v_div_scale_f32 v15, vcc, v12, v11, v12
	v_mul_f32_e32 v16, v15, v14
	v_fma_f32 v17, -v13, v16, v15
	v_fmac_f32_e32 v16, v17, v14
	v_fma_f32 v13, -v13, v16, v15
	v_div_fmas_f32 v13, v13, v14, v16
	v_div_fixup_f32 v11, v13, v11, v12
	v_div_scale_f32 v12, s[4:5], v10, v10, v8
	v_rcp_f32_e32 v13, v12
	s_nop 0
	v_fma_f32 v14, -v12, v13, 1.0
	v_fmac_f32_e32 v13, v14, v13
	v_div_scale_f32 v14, vcc, v8, v10, v8
	v_mul_f32_e32 v15, v14, v13
	v_fma_f32 v16, -v12, v15, v14
	v_fmac_f32_e32 v15, v16, v13
	v_fma_f32 v12, -v12, v15, v14
	v_div_fmas_f32 v12, v12, v13, v15
	v_div_fixup_f32 v10, v12, v10, v8
	v_pk_mul_f32 v[4:5], v[4:5], v[10:11]
	v_cvt_f32_f16_e32 v10, v73
	v_cvt_pk_f16_f32 v4, v4, v5
	v_cvt_f32_f16_sdwa v5, v73 dst_sel:DWORD dst_unused:UNUSED_PAD src0_sel:WORD_1
	v_mul_f32_e32 v8, 0xbfb8aa3b, v10
	v_exp_f32_e32 v8, v8
	v_mul_f32_e32 v9, 0xbfb8aa3b, v5
	v_exp_f32_e32 v9, v9
	s_nop 0
	v_pk_add_f32 v[8:9], v[8:9], 1.0 op_sel_hi:[1,0]
	s_nop 0
	v_div_scale_f32 v11, s[4:5], v9, v9, v5
	v_rcp_f32_e32 v12, v11
	s_nop 0
	v_fma_f32 v13, -v11, v12, 1.0
	v_fmac_f32_e32 v12, v13, v12
	v_div_scale_f32 v13, vcc, v5, v9, v5
	v_mul_f32_e32 v14, v13, v12
	v_fma_f32 v15, -v11, v14, v13
	v_fmac_f32_e32 v14, v15, v12
	v_fma_f32 v11, -v11, v14, v13
	v_div_fmas_f32 v11, v11, v12, v14
	v_div_fixup_f32 v9, v11, v9, v5
	v_div_scale_f32 v5, s[4:5], v8, v8, v10
	v_rcp_f32_e32 v11, v5
	s_nop 0
	v_fma_f32 v12, -v5, v11, 1.0
	v_fmac_f32_e32 v11, v12, v11
	v_div_scale_f32 v12, vcc, v10, v8, v10
	v_mul_f32_e32 v13, v12, v11
	v_fma_f32 v14, -v5, v13, v12
	v_fmac_f32_e32 v13, v14, v11
	v_fma_f32 v5, -v5, v13, v12
	v_div_fmas_f32 v5, v5, v11, v13
	v_div_fixup_f32 v8, v5, v8, v10
	v_pk_mul_f32 v[6:7], v[6:7], v[8:9]
	s_nop 0
	v_cvt_pk_f16_f32 v5, v6, v7
	global_store_dwordx2 v[28:29], v[4:5], off offset:192
	s_waitcnt vmcnt(7)
	v_cvt_f32_f16_sdwa v8, v74 dst_sel:DWORD dst_unused:UNUSED_PAD src0_sel:WORD_1
	v_cvt_f32_f16_e32 v4, v74
	v_mul_f32_e32 v7, 0xbfb8aa3b, v8
	v_mul_f32_e32 v6, 0xbfb8aa3b, v4
	v_exp_f32_e32 v6, v6
	v_exp_f32_e32 v7, v7
	s_nop 0
	v_pk_add_f32 v[6:7], v[6:7], 1.0 op_sel_hi:[1,0]
	s_nop 0
	v_div_scale_f32 v9, s[4:5], v7, v7, v8
	v_rcp_f32_e32 v10, v9
	s_nop 0
	v_fma_f32 v11, -v9, v10, 1.0
	v_fmac_f32_e32 v10, v11, v10
	v_div_scale_f32 v11, vcc, v8, v7, v8
	v_mul_f32_e32 v12, v11, v10
	v_fma_f32 v13, -v9, v12, v11
	v_fmac_f32_e32 v12, v13, v10
	v_fma_f32 v9, -v9, v12, v11
	v_div_fmas_f32 v9, v9, v10, v12
	v_div_fixup_f32 v7, v9, v7, v8
	v_div_scale_f32 v8, s[4:5], v6, v6, v4
	v_rcp_f32_e32 v9, v8
	s_nop 0
	v_fma_f32 v10, -v8, v9, 1.0
	v_fmac_f32_e32 v9, v10, v9
	v_div_scale_f32 v10, vcc, v4, v6, v4
	v_mul_f32_e32 v11, v10, v9
	v_fma_f32 v12, -v8, v11, v10
	v_fmac_f32_e32 v11, v12, v9
	v_fma_f32 v8, -v8, v11, v10
	v_div_fmas_f32 v8, v8, v9, v11
	v_div_fixup_f32 v6, v8, v6, v4
	v_pk_mul_f32 v[0:1], v[0:1], v[6:7]
	v_cvt_f32_f16_e32 v6, v75
	v_cvt_pk_f16_f32 v0, v0, v1
	v_cvt_f32_f16_sdwa v1, v75 dst_sel:DWORD dst_unused:UNUSED_PAD src0_sel:WORD_1
	v_mul_f32_e32 v4, 0xbfb8aa3b, v6
	v_exp_f32_e32 v4, v4
	v_mul_f32_e32 v5, 0xbfb8aa3b, v1
	v_exp_f32_e32 v5, v5
	s_nop 0
	v_pk_add_f32 v[4:5], v[4:5], 1.0 op_sel_hi:[1,0]
	s_nop 0
	v_div_scale_f32 v7, s[4:5], v5, v5, v1
	v_rcp_f32_e32 v8, v7
	s_nop 0
	v_fma_f32 v9, -v7, v8, 1.0
	v_fmac_f32_e32 v8, v9, v8
	v_div_scale_f32 v9, vcc, v1, v5, v1
	v_mul_f32_e32 v10, v9, v8
	v_fma_f32 v11, -v7, v10, v9
	v_fmac_f32_e32 v10, v11, v8
	v_fma_f32 v7, -v7, v10, v9
	v_div_fmas_f32 v7, v7, v8, v10
	v_div_fixup_f32 v5, v7, v5, v1
	v_div_scale_f32 v1, s[4:5], v4, v4, v6
	v_rcp_f32_e32 v7, v1
	s_nop 0
	v_fma_f32 v8, -v1, v7, 1.0
	v_fmac_f32_e32 v7, v8, v7
	v_div_scale_f32 v8, vcc, v6, v4, v6
	v_mul_f32_e32 v9, v8, v7
	v_fma_f32 v10, -v1, v9, v8
	v_fmac_f32_e32 v9, v10, v7
	v_fma_f32 v1, -v1, v9, v8
	v_div_fmas_f32 v1, v1, v7, v9
	v_div_fixup_f32 v4, v1, v4, v6
	v_pk_mul_f32 v[2:3], v[2:3], v[4:5]
	s_nop 0
	v_cvt_pk_f16_f32 v1, v2, v3
	global_store_dwordx2 v[28:29], v[0:1], off offset:224

.LBB0_159:
	s_or_b64 exec, exec, s[6:7]
	s_movk_i32 s12, 0x110
	v_mad_u64_u32 v[132:133], s[6:7], v64, s12, v[168:169]
	v_mad_u64_u32 v[134:135], s[6:7], v70, s12, v[168:169]
	v_mad_u64_u32 v[136:137], s[6:7], v74, s12, v[168:169]
	v_mad_u64_u32 v[138:139], s[6:7], v78, s12, v[168:169]
	v_mad_u64_u32 v[140:141], s[6:7], v66, s12, v[168:169]
	v_mad_u64_u32 v[142:143], s[6:7], v68, s12, v[168:169]
	v_mad_u64_u32 v[144:145], s[6:7], v72, s12, v[168:169]
	v_mad_u64_u32 v[146:147], s[6:7], v76, s12, v[168:169]
	s_mov_b32 s5, s1
	s_lshl_b64 s[6:7], s[4:5], 10
	v_readlane_b32 s0, v254, 18
	s_add_u32 s0, s0, s6
	v_readlane_b32 s6, v254, 19
	s_addc_u32 s6, s6, s7
	s_lshl_b32 s7, s9, 15
	s_add_u32 s0, s0, s7
	s_addc_u32 s7, s6, 0
	s_lshl_b32 s10, s10, 1
	s_add_u32 s6, s0, s10
	s_addc_u32 s7, s7, 0
	s_lshl_b64 s[4:5], s[4:5], 9
	v_readlane_b32 s0, v254, 20
	s_add_u32 s0, s0, s4
	v_readlane_b32 s4, v254, 21
	s_addc_u32 s4, s4, s5
	s_lshl_b32 s5, s11, 9
	s_add_u32 s0, s0, s5
	s_addc_u32 s5, s4, 0
	s_add_u32 s4, s0, s10
	v_bfe_u32 v164, v80, 4, 2
	s_addc_u32 s5, s5, 0
	v_and_b32_e32 v162, 15, v80
	s_waitcnt vmcnt(15)
	ds_write_b128 v132, v[0:3]
	s_waitcnt vmcnt(14)
	ds_write_b128 v132, v[4:7] offset:34816
	s_waitcnt vmcnt(13)
	ds_write_b128 v134, v[8:11]
	s_waitcnt vmcnt(12)
	ds_write_b128 v134, v[12:15] offset:34816
	s_waitcnt vmcnt(11)
	ds_write_b128 v136, v[16:19]
	s_waitcnt vmcnt(10)
	ds_write_b128 v136, v[20:23] offset:34816
	s_waitcnt vmcnt(9)
	ds_write_b128 v138, v[24:27]
	s_waitcnt vmcnt(8)
	ds_write_b128 v138, v[28:31] offset:34816
	s_waitcnt vmcnt(7)
	ds_write_b128 v140, v[32:35]
	s_waitcnt vmcnt(6)
	ds_write_b128 v140, v[36:39] offset:34816
	s_waitcnt vmcnt(5)
	ds_write_b128 v142, v[40:43]
	s_waitcnt vmcnt(4)
	ds_write_b128 v142, v[44:47] offset:34816
	v_lshl_add_u64 v[12:13], s[6:7], 0, v[168:169]
	v_lshlrev_b64 v[16:17], 9, v[64:65]
	v_lshlrev_b64 v[20:21], 9, v[70:71]
	v_lshlrev_b64 v[24:25], 9, v[74:75]
	v_lshlrev_b64 v[28:29], 9, v[78:79]
	v_lshl_add_u64 v[44:45], s[4:5], 0, v[168:169]
	v_lshlrev_b64 v[32:33], 9, v[66:67]
	v_lshlrev_b64 v[36:37], 9, v[68:69]
	v_lshlrev_b64 v[40:41], 9, v[72:73]
	v_lshlrev_b64 v[46:47], 9, v[76:77]
	v_lshlrev_b32_e32 v168, 4, v164
	s_waitcnt vmcnt(3)
	ds_write_b128 v144, v[48:51]
	s_waitcnt vmcnt(2)
	ds_write_b128 v144, v[52:55] offset:34816
	s_waitcnt vmcnt(1)
	ds_write_b128 v146, v[56:59]
	s_waitcnt vmcnt(0)
	ds_write_b128 v146, v[60:63] offset:34816
	v_lshl_add_u64 v[0:1], v[12:13], 0, v[16:17]
	v_lshl_add_u64 v[4:5], v[12:13], 0, v[20:21]
	v_lshl_add_u64 v[8:9], v[12:13], 0, v[24:25]
	v_lshl_add_u64 v[12:13], v[12:13], 0, v[28:29]
	v_lshl_add_u64 v[16:17], v[44:45], 0, v[16:17]
	v_lshl_add_u64 v[20:21], v[44:45], 0, v[20:21]
	v_lshl_add_u64 v[24:25], v[44:45], 0, v[24:25]
	v_lshl_add_u64 v[28:29], v[44:45], 0, v[28:29]
	v_lshl_add_u64 v[32:33], v[44:45], 0, v[32:33]
	v_lshl_add_u64 v[36:37], v[44:45], 0, v[36:37]
	v_lshl_add_u64 v[40:41], v[44:45], 0, v[40:41]
	v_lshl_add_u64 v[44:45], v[44:45], 0, v[46:47]
	v_mad_u32_u24 v60, v162, s12, v168
	v_ashrrev_i32_e32 v163, 6, v80
	global_load_dwordx4 v[0:3], v[0:1], off
	v_lshl_or_b32 v135, v163, 5, v162
	global_load_dwordx4 v[4:7], v[4:5], off
	v_mad_u64_u32 v[56:57], s[4:5], v135, s12, v[168:169]
	global_load_dwordx4 v[8:11], v[8:9], off
	v_or_b32_e32 v133, 16, v135
	global_load_dwordx4 v[12:15], v[12:13], off
	v_lshlrev_b32_e32 v147, 2, v164
	global_load_dwordx4 v[16:19], v[16:17], off
	s_movk_i32 s0, 0xffef
	global_load_dwordx4 v[20:23], v[20:21], off
	s_nop 0
	global_load_dwordx4 v[24:27], v[24:25], off
	s_nop 0
	global_load_dwordx4 v[28:31], v[28:29], off
	s_nop 0
	global_load_dwordx4 v[32:35], v[32:33], off
	s_nop 0
	global_load_dwordx4 v[36:39], v[36:37], off
	s_nop 0
	global_load_dwordx4 v[40:43], v[40:41], off
	s_nop 0
	global_load_dwordx4 v[44:47], v[44:45], off
	s_waitcnt lgkmcnt(0)
	s_barrier
	ds_read_b128 v[198:201], v60 offset:34816
	ds_read_b128 v[202:205], v60 offset:39168
	ds_read_b128 v[210:213], v60 offset:43520
	ds_read_b128 v[222:225], v60 offset:47872
	ds_read_b128 v[226:229], v60 offset:52224
	ds_read_b128 v[230:233], v60 offset:56576
	ds_read_b128 v[234:237], v60 offset:60928
	ds_read_b128 v[238:241], v60 offset:65280
	ds_read_b128 v[242:245], v56
	ds_read_b128 v[246:249], v56 offset:4352
	s_nop 0
	s_nop 0
	s_nop 0
	s_nop 0
	s_nop 0
	s_nop 0
	s_nop 0
	s_nop 0
	s_nop 0
	s_nop 0
	s_waitcnt lgkmcnt(10)
	s_waitcnt lgkmcnt(1)
	v_mfma_f32_16x16x32_f16 v[66:69], v[198:201], v[242:245], 0
	s_nop 0
	s_waitcnt lgkmcnt(0)
	v_mfma_f32_16x16x32_f16 v[62:65], v[198:201], v[246:249], 0
	ds_read_b128 v[198:201], v56 offset:64
	v_mfma_f32_16x16x32_f16 v[74:77], v[202:205], v[242:245], 0
	v_mfma_f32_16x16x32_f16 v[70:73], v[202:205], v[246:249], 0
	ds_read_b128 v[202:205], v56 offset:4416
	v_mfma_f32_16x16x32_f16 v[82:85], v[210:213], v[242:245], 0
	v_mfma_f32_16x16x32_f16 v[78:81], v[210:213], v[246:249], 0
	ds_read_b128 v[210:213], v60 offset:34880
	v_mfma_f32_16x16x32_f16 v[90:93], v[222:225], v[242:245], 0
	v_mfma_f32_16x16x32_f16 v[86:89], v[222:225], v[246:249], 0
	ds_read_b128 v[222:225], v60 offset:39232
	v_mfma_f32_16x16x32_f16 v[98:101], v[226:229], v[242:245], 0
	v_mfma_f32_16x16x32_f16 v[94:97], v[226:229], v[246:249], 0
	ds_read_b128 v[226:229], v60 offset:43584
	v_mfma_f32_16x16x32_f16 v[106:109], v[230:233], v[242:245], 0
	v_mfma_f32_16x16x32_f16 v[102:105], v[230:233], v[246:249], 0
	ds_read_b128 v[230:233], v60 offset:47936
	v_mfma_f32_16x16x32_f16 v[114:117], v[234:237], v[242:245], 0
	v_mfma_f32_16x16x32_f16 v[110:113], v[234:237], v[246:249], 0
	ds_read_b128 v[234:237], v60 offset:52288
	v_mfma_f32_16x16x32_f16 v[48:51], v[238:241], v[242:245], 0
	ds_read_b128 v[242:245], v60 offset:56640
	v_mfma_f32_16x16x32_f16 v[52:55], v[238:241], v[246:249], 0
	ds_read_b128 v[238:241], v60 offset:60992
	ds_read_b128 v[246:249], v60 offset:65344
	s_nop 0
	s_nop 0
	s_nop 0
	s_nop 0
	s_waitcnt lgkmcnt(7)
	v_mfma_f32_16x16x32_f16 v[66:69], v[210:213], v[198:201], v[66:69]
	v_mfma_f32_16x16x32_f16 v[62:65], v[210:213], v[202:205], v[62:65]
	ds_read_b128 v[210:213], v60 offset:34944
	s_nop 0
	s_nop 0
	s_waitcnt lgkmcnt(7)
	v_mfma_f32_16x16x32_f16 v[74:77], v[222:225], v[198:201], v[74:77]
	v_mfma_f32_16x16x32_f16 v[70:73], v[222:225], v[202:205], v[70:73]
	ds_read_b128 v[222:225], v60 offset:39296
	s_nop 0
	s_nop 0
	s_waitcnt lgkmcnt(7)
	v_mfma_f32_16x16x32_f16 v[82:85], v[226:229], v[198:201], v[82:85]
	v_mfma_f32_16x16x32_f16 v[78:81], v[226:229], v[202:205], v[78:81]
	ds_read_b128 v[226:229], v60 offset:43648
	s_nop 0
	s_nop 0
	s_waitcnt lgkmcnt(7)
	v_mfma_f32_16x16x32_f16 v[90:93], v[230:233], v[198:201], v[90:93]
	v_mfma_f32_16x16x32_f16 v[86:89], v[230:233], v[202:205], v[86:89]
	ds_read_b128 v[230:233], v60 offset:48000
	s_nop 0
	s_nop 0
	s_waitcnt lgkmcnt(7)
	v_mfma_f32_16x16x32_f16 v[98:101], v[234:237], v[198:201], v[98:101]
	v_mfma_f32_16x16x32_f16 v[94:97], v[234:237], v[202:205], v[94:97]
	ds_read_b128 v[234:237], v60 offset:52352
	s_nop 0
	s_nop 0
	s_waitcnt lgkmcnt(7)
	v_mfma_f32_16x16x32_f16 v[106:109], v[242:245], v[198:201], v[106:109]
	v_mfma_f32_16x16x32_f16 v[102:105], v[242:245], v[202:205], v[102:105]
	ds_read_b128 v[242:245], v60 offset:56704
	s_nop 0
	s_nop 0
	s_waitcnt lgkmcnt(7)
	v_mfma_f32_16x16x32_f16 v[114:117], v[238:241], v[198:201], v[114:117]
	v_mfma_f32_16x16x32_f16 v[110:113], v[238:241], v[202:205], v[110:113]
	ds_read_b128 v[238:241], v60 offset:61056
	s_nop 0
	s_nop 0
	s_waitcnt lgkmcnt(7)
	v_mfma_f32_16x16x32_f16 v[48:51], v[246:249], v[198:201], v[48:51]
	ds_read_b128 v[198:201], v60 offset:35008
	v_mfma_f32_16x16x32_f16 v[52:55], v[246:249], v[202:205], v[52:55]
	ds_read_b128 v[202:205], v60 offset:61120
	ds_read_b128 v[246:249], v60 offset:39360
	ds_read_b128 v[118:121], v56 offset:128
	ds_read_b128 v[122:125], v56 offset:4480
	s_nop 0
	s_nop 0
	s_waitcnt lgkmcnt(1)
	v_mfma_f32_16x16x32_f16 v[66:69], v[210:213], v[118:121], v[66:69]
	s_waitcnt lgkmcnt(0)
	v_mfma_f32_16x16x32_f16 v[62:65], v[210:213], v[122:125], v[62:65]
	ds_read_b128 v[210:213], v60 offset:43712
	s_nop 0
	s_nop 0
	v_mfma_f32_16x16x32_f16 v[74:77], v[222:225], v[118:121], v[74:77]
	v_mfma_f32_16x16x32_f16 v[70:73], v[222:225], v[122:125], v[70:73]
	ds_read_b128 v[222:225], v60 offset:48064
	s_nop 0
	s_nop 0
	v_mfma_f32_16x16x32_f16 v[148:151], v[226:229], v[118:121], v[82:85]
	v_mfma_f32_16x16x32_f16 v[126:129], v[226:229], v[122:125], v[78:81]
	ds_read_b128 v[226:229], v60 offset:52416
	s_nop 2
	s_nop 0
	s_nop 0
	v_mfma_f32_16x16x32_f16 v[152:155], v[230:233], v[118:121], v[90:93]
	v_mfma_f32_16x16x32_f16 v[84:87], v[230:233], v[122:125], v[86:89]
	ds_read_b128 v[230:233], v60 offset:56768
	s_nop 0
	s_nop 0
	v_mfma_f32_16x16x32_f16 v[156:159], v[234:237], v[118:121], v[98:101]
	v_mfma_f32_16x16x32_f16 v[174:177], v[234:237], v[122:125], v[94:97]
	s_nop 0
	s_nop 0
	v_mfma_f32_16x16x32_f16 v[178:181], v[242:245], v[118:121], v[106:109]
	v_mfma_f32_16x16x32_f16 v[182:185], v[242:245], v[122:125], v[102:105]
	s_nop 0
	s_nop 0
	v_mfma_f32_16x16x32_f16 v[186:189], v[238:241], v[118:121], v[114:117]
	v_mfma_f32_16x16x32_f16 v[190:193], v[238:241], v[122:125], v[110:113]
	ds_read_b128 v[78:81], v60 offset:65408
	s_nop 0
	s_waitcnt lgkmcnt(0)
	v_mfma_f32_16x16x32_f16 v[116:119], v[78:81], v[118:121], v[48:51]
	v_mfma_f32_16x16x32_f16 v[52:55], v[78:81], v[122:125], v[52:55]
	ds_read_b128 v[120:123], v56 offset:192
	ds_read_b128 v[194:197], v56 offset:4544
	s_nop 0
	s_nop 0
	s_nop 0
	s_waitcnt lgkmcnt(1)
	v_mfma_f32_16x16x32_f16 v[92:95], v[198:201], v[120:123], v[66:69]
	s_waitcnt lgkmcnt(0)
	v_mfma_f32_16x16x32_f16 v[80:83], v[198:201], v[194:197], v[62:65]
	s_nop 0
	s_nop 0
	v_mfma_f32_16x16x32_f16 v[112:115], v[246:249], v[120:123], v[74:77]
	ds_read_b128 v[64:67], v60 offset:65472
	v_mfma_f32_16x16x32_f16 v[108:111], v[246:249], v[194:197], v[70:73]
	s_nop 0
	s_nop 0
	v_mfma_f32_16x16x32_f16 v[88:91], v[210:213], v[120:123], v[148:151]
	v_mfma_f32_16x16x32_f16 v[100:103], v[210:213], v[194:197], v[126:129]
	s_nop 0
	s_nop 0
	v_mfma_f32_16x16x32_f16 v[104:107], v[222:225], v[120:123], v[152:155]
	v_mfma_f32_16x16x32_f16 v[96:99], v[222:225], v[194:197], v[84:87]
	s_nop 0
	s_nop 0
	v_mfma_f32_16x16x32_f16 v[68:71], v[226:229], v[120:123], v[156:159]
	v_mfma_f32_16x16x32_f16 v[76:79], v[226:229], v[194:197], v[174:177]
	s_nop 0
	s_waitcnt lgkmcnt(0)
	v_mfma_f32_16x16x32_f16 v[60:63], v[64:67], v[120:123], v[116:119]
	v_mfma_f32_16x16x32_f16 v[52:55], v[64:67], v[194:197], v[52:55]
	v_lshlrev_b32_e32 v64, 2, v135
	v_add_u32_e32 v65, 0x11000, v64
	v_add_u32_e32 v64, 0x11200, v64
	s_nop 0
	v_mfma_f32_16x16x32_f16 v[84:87], v[230:233], v[120:123], v[178:181]
	ds_read_b32 v137, v65
	v_or_b32_e32 v116, 0x11200, v168
	ds_read_b128 v[124:127], v116
	v_mfma_f32_16x16x32_f16 v[72:75], v[230:233], v[194:197], v[182:185]
	v_or_b32_e32 v116, 0x11400, v168
	ds_read_b128 v[116:119], v116
	v_mfma_f32_16x16x32_f16 v[48:51], v[202:205], v[120:123], v[186:189]
	v_or_b32_e32 v120, 0x11600, v168
	ds_read_b128 v[120:123], v120
	ds_read_b32 v139, v64
	v_lshlrev_b32_e32 v64, 2, v133
	v_add_u32_e32 v65, 0x11000, v64
	v_add_u32_e32 v64, 0x11200, v64
	ds_read_b32 v141, v65
	ds_read_b32 v143, v64
	v_or_b32_e32 v64, 0x11000, v168
	ds_read_b128 v[64:67], v64
	v_mfma_f32_16x16x32_f16 v[56:59], v[202:205], v[194:197], v[190:193]
	s_nop 0
	s_waitcnt lgkmcnt(0)
	v_sub_f32_e32 v128, v137, v64
	v_sub_f32_e32 v64, v141, v64
	v_min_f32_e32 v64, 0, v64
	v_mul_f32_e32 v64, 0x3fb8aa3b, v64
	v_exp_f32_e32 v152, v64
	v_sub_f32_e32 v64, v143, v124
	v_min_f32_e32 v64, 0, v64
	v_mul_f32_e32 v64, 0x3fb8aa3b, v64
	v_exp_f32_e32 v156, v64
	v_sub_f32_e32 v64, v137, v65
	v_min_f32_e32 v64, 0, v64
	v_mul_f32_e32 v64, 0x3fb8aa3b, v64
	v_exp_f32_e32 v149, v64
	v_sub_f32_e32 v64, v139, v125
	v_min_f32_e32 v64, 0, v64
	v_mul_f32_e32 v64, 0x3fb8aa3b, v64
	v_exp_f32_e32 v167, v64
	v_sub_f32_e32 v64, v141, v65
	v_min_f32_e32 v64, 0, v64
	v_mul_f32_e32 v64, 0x3fb8aa3b, v64
	v_exp_f32_e32 v153, v64
	v_sub_f32_e32 v64, v143, v125
	v_min_f32_e32 v64, 0, v64
	v_mul_f32_e32 v64, 0x3fb8aa3b, v64
	v_exp_f32_e32 v157, v64
	v_sub_f32_e32 v64, v137, v66
	v_min_f32_e32 v64, 0, v64
	v_mul_f32_e32 v64, 0x3fb8aa3b, v64
	v_exp_f32_e32 v150, v64
	v_sub_f32_e32 v64, v139, v126
	v_min_f32_e32 v64, 0, v64
	v_mul_f32_e32 v64, 0x3fb8aa3b, v64
	v_exp_f32_e32 v154, v64
	v_sub_f32_e32 v64, v141, v66
	v_min_f32_e32 v64, 0, v64
	v_mul_f32_e32 v64, 0x3fb8aa3b, v64
	v_exp_f32_e32 v158, v64
	v_sub_f32_e32 v64, v143, v126
	v_min_f32_e32 v64, 0, v64
	v_mul_f32_e32 v64, 0x3fb8aa3b, v64
	v_exp_f32_e32 v160, v64
	v_sub_f32_e32 v64, v137, v67
	v_min_f32_e32 v64, 0, v64
	v_mul_f32_e32 v64, 0x3fb8aa3b, v64
	v_exp_f32_e32 v151, v64
	v_sub_f32_e32 v64, v139, v127
	v_min_f32_e32 v64, 0, v64
	v_mul_f32_e32 v64, 0x3fb8aa3b, v64
	v_exp_f32_e32 v155, v64
	v_sub_f32_e32 v64, v141, v67
	v_min_f32_e32 v64, 0, v64
	v_mul_f32_e32 v64, 0x3fb8aa3b, v64
	v_exp_f32_e32 v159, v64
	v_sub_f32_e32 v64, v143, v127
	v_min_f32_e32 v64, 0, v64
	v_mul_f32_e32 v64, 0x3fb8aa3b, v64
	v_exp_f32_e32 v161, v64
	v_or_b32_e32 v64, 0x11040, v168
	v_min_f32_e32 v128, 0, v128
	ds_read_b128 v[64:67], v64
	v_mul_f32_e32 v128, 0x3fb8aa3b, v128
	v_exp_f32_e32 v148, v128
	v_sub_f32_e32 v128, v139, v124
	v_or_b32_e32 v124, 0x11240, v168
	ds_read_b128 v[174:177], v124
	v_min_f32_e32 v128, 0, v128
	s_nop 0
	s_waitcnt lgkmcnt(1)
	v_sub_f32_e32 v145, v137, v64
	v_mul_f32_e32 v128, 0x3fb8aa3b, v128
	v_min_f32_e32 v145, 0, v145
	v_exp_f32_e32 v166, v128
	v_or_b32_e32 v128, 0x11640, v168
	v_mul_f32_e32 v145, 0x3fb8aa3b, v145
	ds_read_b128 v[128:131], v128
	v_exp_f32_e32 v178, v145
	s_nop 0
	s_waitcnt lgkmcnt(1)
	v_sub_f32_e32 v145, v139, v174
	v_min_f32_e32 v145, 0, v145
	v_mul_f32_e32 v145, 0x3fb8aa3b, v145
	v_exp_f32_e32 v180, v145
	v_sub_f32_e32 v145, v143, v174
	v_min_f32_e32 v145, 0, v145
	v_mul_f32_e32 v145, 0x3fb8aa3b, v145
	v_exp_f32_e32 v174, v145
	v_sub_f32_e32 v145, v137, v65
	v_min_f32_e32 v145, 0, v145
	v_mul_f32_e32 v145, 0x3fb8aa3b, v145
	v_exp_f32_e32 v179, v145
	v_sub_f32_e32 v145, v139, v175
	v_min_f32_e32 v145, 0, v145
	v_mul_f32_e32 v145, 0x3fb8aa3b, v145
	v_exp_f32_e32 v181, v145
	v_sub_f32_e32 v145, v143, v175
	v_min_f32_e32 v145, 0, v145
	v_mul_f32_e32 v145, 0x3fb8aa3b, v145
	v_exp_f32_e32 v175, v145
	v_sub_f32_e32 v145, v137, v66
	v_sub_f32_e32 v66, v141, v66
	v_min_f32_e32 v66, 0, v66
	v_mul_f32_e32 v66, 0x3fb8aa3b, v66
	v_exp_f32_e32 v186, v66
	v_sub_f32_e32 v66, v143, v176
	v_min_f32_e32 v145, 0, v145
	v_min_f32_e32 v66, 0, v66
	v_mul_f32_e32 v145, 0x3fb8aa3b, v145
	v_mul_f32_e32 v66, 0x3fb8aa3b, v66
	v_exp_f32_e32 v182, v145
	v_sub_f32_e32 v145, v139, v176
	v_exp_f32_e32 v176, v66
	v_sub_f32_e32 v66, v137, v67
	v_min_f32_e32 v66, 0, v66
	v_mul_f32_e32 v66, 0x3fb8aa3b, v66
	v_exp_f32_e32 v183, v66
	v_sub_f32_e32 v66, v139, v177
	v_min_f32_e32 v66, 0, v66
	v_mul_f32_e32 v66, 0x3fb8aa3b, v66
	v_exp_f32_e32 v185, v66
	v_sub_f32_e32 v66, v141, v67
	v_min_f32_e32 v66, 0, v66
	v_mul_f32_e32 v66, 0x3fb8aa3b, v66
	v_or_b32_e32 v124, 0x11440, v168
	v_sub_f32_e32 v64, v141, v64
	v_sub_f32_e32 v65, v141, v65
	v_min_f32_e32 v145, 0, v145
	v_exp_f32_e32 v187, v66
	v_sub_f32_e32 v66, v143, v177
	ds_read_b128 v[124:127], v124
	v_min_f32_e32 v64, 0, v64
	v_min_f32_e32 v65, 0, v65
	v_mul_f32_e32 v145, 0x3fb8aa3b, v145
	v_min_f32_e32 v66, 0, v66
	v_mul_f32_e32 v64, 0x3fb8aa3b, v64
	v_mul_f32_e32 v65, 0x3fb8aa3b, v65
	v_exp_f32_e32 v184, v145
	v_mul_f32_e32 v66, 0x3fb8aa3b, v66
	v_sub_u32_e32 v145, v147, v135
	v_exp_f32_e32 v64, v64
	v_exp_f32_e32 v65, v65
	v_exp_f32_e32 v177, v66
	v_add_u32_e32 v66, -1, v145
	v_cmp_lt_i32_e32 vcc, -1, v145
	v_cmp_lt_i32_e64 s[36:37], -2, v145
	v_lshrrev_b32_e32 v66, 31, v66
	v_lshrrev_b32_e32 v67, 31, v145
	v_cndmask_b32_e64 v189, 0, 1.0, s[36:37]
	v_cndmask_b32_e64 v188, 0, 1.0, vcc
	v_cvt_f32_ubyte0_e32 v67, v67
	v_cvt_f32_ubyte0_e32 v66, v66
	s_nop 0
	s_waitcnt lgkmcnt(1)
	v_pk_mul_f32 v[192:193], v[128:129], v[188:189]
	s_nop 0
	s_waitcnt lgkmcnt(0)
	v_pk_mul_f32 v[190:191], v[124:125], v[66:67]
	v_pk_mul_f32 v[174:175], v[192:193], v[174:175]
	v_cmp_lt_i32_e32 vcc, s0, v145
	v_pk_fma_f32 v[64:65], v[190:191], v[64:65], v[174:175]
	s_movk_i32 s0, 0xffee
	v_pk_mul_f32 v[108:109], v[108:109], v[64:65]
	v_pk_mul_f32 v[64:65], v[116:117], v[66:67]
	v_pk_mul_f32 v[66:67], v[120:121], v[188:189]
	v_cmp_lt_i32_e64 s[36:37], s0, v145
	v_pk_mul_f32 v[66:67], v[66:67], v[166:167]
	s_movk_i32 s0, 0xffed
	v_pk_fma_f32 v[64:65], v[64:65], v[148:149], v[66:67]
	v_add_u32_e32 v66, 15, v145
	v_pk_mul_f32 v[64:65], v[92:93], v[64:65]
	v_lshrrev_b32_e32 v66, 31, v66
	v_cvt_pk_f16_f32 v64, v64, v65
	v_add_u32_e32 v65, 16, v145
	v_lshrrev_b32_e32 v65, 31, v65
	v_cvt_f32_ubyte0_e32 v93, v65
	v_cvt_f32_ubyte0_e32 v92, v66
	v_cndmask_b32_e64 v149, 0, 1.0, s[36:37]
	v_cndmask_b32_e64 v148, 0, 1.0, vcc
	v_pk_mul_f32 v[66:67], v[124:125], v[92:93]
	v_pk_mul_f32 v[124:125], v[128:129], v[148:149]
	v_cmp_lt_i32_e32 vcc, s0, v145
	v_pk_mul_f32 v[124:125], v[124:125], v[180:181]
	s_movk_i32 s0, 0xffec
	v_pk_fma_f32 v[66:67], v[66:67], v[178:179], v[124:125]
	v_add_u32_e32 v65, 18, v145
	v_pk_mul_f32 v[66:67], v[112:113], v[66:67]
	v_cmp_lt_i32_e64 s[36:37], s0, v145
	v_cvt_pk_f16_f32 v66, v66, v67
	v_add_u32_e32 v67, 17, v145
	v_lshrrev_b32_e32 v67, 31, v67
	v_lshrrev_b32_e32 v65, 31, v65
	v_cndmask_b32_e64 v129, 0, 1.0, s[36:37]
	v_cndmask_b32_e64 v128, 0, 1.0, vcc
	v_cvt_f32_ubyte0_e32 v125, v65
	v_cvt_f32_ubyte0_e32 v124, v67
	v_pk_mul_f32 v[166:167], v[130:131], v[128:129]
	v_pk_mul_f32 v[112:113], v[126:127], v[124:125]
	v_pk_mul_f32 v[166:167], v[166:167], v[184:185]
	v_add_u32_e32 v65, -16, v145
	v_pk_fma_f32 v[112:113], v[112:113], v[182:183], v[166:167]
	v_lshrrev_b32_e32 v65, 31, v65
	v_pk_mul_f32 v[112:113], v[114:115], v[112:113]
	v_sub_u32_e32 v114, 15, v145
	v_cvt_pk_f16_f32 v67, v112, v113
	v_cvt_f32_ubyte0_e32 v113, v65
	v_sub_u32_e32 v65, 14, v145
	v_subrev_u32_e32 v112, 17, v145
	v_lshrrev_b32_e32 v114, 31, v114
	v_lshrrev_b32_e32 v65, 31, v65
	v_lshrrev_b32_e32 v112, 31, v112
	v_cvt_f32_ubyte0_e32 v115, v65
	v_cvt_f32_ubyte0_e32 v114, v114
	v_cvt_f32_ubyte0_e32 v112, v112
	v_pk_mul_f32 v[114:115], v[120:121], v[114:115]
	v_pk_mul_f32 v[112:113], v[116:117], v[112:113]
	v_pk_mul_f32 v[114:115], v[114:115], v[156:157]
	v_add_u32_e32 v65, -14, v145
	v_pk_fma_f32 v[112:113], v[112:113], v[152:153], v[114:115]
	v_lshrrev_b32_e32 v65, 31, v65
	v_pk_mul_f32 v[80:81], v[80:81], v[112:113]
	v_cvt_f32_ubyte0_e32 v113, v65
	v_cvt_pk_f16_f32 v80, v80, v81
	v_add_u32_e32 v81, -15, v145
	v_lshrrev_b32_e32 v81, 31, v81
	v_cvt_f32_ubyte0_e32 v112, v81
	v_sub_u32_e32 v65, 12, v145
	v_sub_u32_e32 v81, 13, v145
	v_lshrrev_b32_e32 v81, 31, v81
	v_lshrrev_b32_e32 v65, 31, v65
	v_cvt_f32_ubyte0_e32 v115, v65
	v_cvt_f32_ubyte0_e32 v114, v81
	v_pk_mul_f32 v[114:115], v[122:123], v[114:115]
	v_pk_mul_f32 v[112:113], v[118:119], v[112:113]
	v_pk_mul_f32 v[114:115], v[114:115], v[160:161]
	v_add_u32_e32 v65, 2, v145
	v_pk_fma_f32 v[112:113], v[112:113], v[158:159], v[114:115]
	v_cmp_lt_i32_e32 vcc, -3, v145
	v_pk_mul_f32 v[82:83], v[82:83], v[112:113]
	v_cmp_lt_i32_e64 s[36:37], -4, v145
	v_cvt_pk_f16_f32 v81, v82, v83
	v_add_u32_e32 v83, 1, v145
	v_lshrrev_b32_e32 v83, 31, v83
	v_lshrrev_b32_e32 v65, 31, v65
	v_cndmask_b32_e64 v113, 0, 1.0, s[36:37]
	v_cndmask_b32_e64 v112, 0, 1.0, vcc
	v_cvt_pk_f16_f32 v82, v108, v109
	v_cvt_f32_ubyte0_e32 v109, v65
	v_cvt_f32_ubyte0_e32 v108, v83
	v_pk_mul_f32 v[116:117], v[130:131], v[112:113]
	v_pk_mul_f32 v[112:113], v[122:123], v[112:113]
	v_pk_mul_f32 v[114:115], v[126:127], v[108:109]
	v_pk_mul_f32 v[116:117], v[116:117], v[176:177]
	v_pk_mul_f32 v[108:109], v[118:119], v[108:109]
	v_pk_mul_f32 v[112:113], v[112:113], v[154:155]
	v_pk_fma_f32 v[114:115], v[114:115], v[186:187], v[116:117]
	v_pk_fma_f32 v[108:109], v[108:109], v[150:151], v[112:113]
	v_pk_mul_f32 v[110:111], v[110:111], v[114:115]
	v_pk_mul_f32 v[94:95], v[94:95], v[108:109]
	v_cvt_pk_f16_f32 v83, v110, v111
	v_cvt_pk_f16_f32 v65, v94, v95
	v_or_b32_e32 v94, 0x11080, v168
	v_or_b32_e32 v95, 0x11280, v168
	ds_read_b128 v[116:119], v94
	ds_read_b128 v[120:123], v95
	v_or_b32_e32 v94, 0x11480, v168
	v_or_b32_e32 v95, 0x11680, v168
	ds_read_b128 v[112:115], v94
	ds_read_b128 v[108:111], v95
	s_waitcnt lgkmcnt(3)
	v_sub_f32_e32 v94, v137, v116
	v_min_f32_e32 v94, 0, v94
	v_mul_f32_e32 v94, 0x3fb8aa3b, v94
	v_exp_f32_e32 v150, v94
	s_waitcnt lgkmcnt(2)
	v_sub_f32_e32 v94, v139, v120
	v_min_f32_e32 v94, 0, v94
	v_mul_f32_e32 v94, 0x3fb8aa3b, v94
	v_exp_f32_e32 v160, v94
	v_sub_f32_e32 v94, v141, v116
	v_min_f32_e32 v94, 0, v94
	v_mul_f32_e32 v94, 0x3fb8aa3b, v94
	v_exp_f32_e32 v166, v94
	v_sub_f32_e32 v94, v143, v120
	v_min_f32_e32 v94, 0, v94
	v_mul_f32_e32 v94, 0x3fb8aa3b, v94
	v_exp_f32_e32 v174, v94
	v_sub_f32_e32 v94, v137, v117
	v_min_f32_e32 v94, 0, v94
	v_mul_f32_e32 v94, 0x3fb8aa3b, v94
	v_exp_f32_e32 v151, v94
	v_sub_f32_e32 v94, v139, v121
	v_min_f32_e32 v94, 0, v94
	v_mul_f32_e32 v94, 0x3fb8aa3b, v94
	v_exp_f32_e32 v161, v94
	v_sub_f32_e32 v94, v141, v117
	v_min_f32_e32 v94, 0, v94
	v_mul_f32_e32 v94, 0x3fb8aa3b, v94
	v_exp_f32_e32 v167, v94
	v_sub_f32_e32 v94, v143, v121
	v_min_f32_e32 v94, 0, v94
	v_mul_f32_e32 v94, 0x3fb8aa3b, v94
	v_exp_f32_e32 v175, v94
	v_sub_f32_e32 v94, v137, v118
	v_min_f32_e32 v94, 0, v94
	v_mul_f32_e32 v94, 0x3fb8aa3b, v94
	v_exp_f32_e32 v126, v94
	v_sub_f32_e32 v94, v139, v122
	v_min_f32_e32 v94, 0, v94
	v_mul_f32_e32 v94, 0x3fb8aa3b, v94
	v_exp_f32_e32 v130, v94
	v_sub_f32_e32 v94, v141, v118
	v_min_f32_e32 v94, 0, v94
	v_mul_f32_e32 v94, 0x3fb8aa3b, v94
	v_exp_f32_e32 v176, v94
	v_sub_f32_e32 v94, v143, v122
	v_min_f32_e32 v94, 0, v94
	v_mul_f32_e32 v94, 0x3fb8aa3b, v94
	v_exp_f32_e32 v178, v94
	v_sub_f32_e32 v94, v137, v119
	v_min_f32_e32 v94, 0, v94
	v_mul_f32_e32 v94, 0x3fb8aa3b, v94
	v_exp_f32_e32 v127, v94
	v_sub_f32_e32 v94, v139, v123
	v_min_f32_e32 v94, 0, v94
	v_mul_f32_e32 v94, 0x3fb8aa3b, v94
	v_exp_f32_e32 v131, v94
	v_sub_f32_e32 v94, v141, v119
	v_min_f32_e32 v94, 0, v94
	v_mul_f32_e32 v94, 0x3fb8aa3b, v94
	v_exp_f32_e32 v177, v94
	v_sub_f32_e32 v94, v143, v123
	v_min_f32_e32 v94, 0, v94
	v_mul_f32_e32 v94, 0x3fb8aa3b, v94
	v_or_b32_e32 v147, 48, v147
	v_exp_f32_e32 v179, v94
	v_lshlrev_b32_e32 v94, 2, v147
	v_or_b32_e32 v95, 0x11000, v94
	v_or_b32_e32 v120, 0x11200, v94
	ds_read_b128 v[116:119], v95
	ds_read_b128 v[120:123], v120
	v_or_b32_e32 v95, 0x11400, v94
	v_or_b32_e32 v94, 0x11600, v94
	ds_read_b128 v[152:155], v95
	ds_read_b128 v[156:159], v94
	s_waitcnt lgkmcnt(3)
	v_sub_f32_e32 v94, v137, v116
	s_waitcnt lgkmcnt(2)
	v_sub_f32_e32 v95, v139, v120
	v_min_f32_e32 v95, 0, v95
	v_mul_f32_e32 v95, 0x3fb8aa3b, v95
	v_exp_f32_e32 v180, v95
	v_sub_f32_e32 v95, v141, v116
	v_sub_f32_e32 v116, v139, v121
	v_min_f32_e32 v116, 0, v116
	v_mul_f32_e32 v116, 0x3fb8aa3b, v116
	v_exp_f32_e32 v181, v116
	v_sub_f32_e32 v116, v141, v117
	v_min_f32_e32 v116, 0, v116
	v_mul_f32_e32 v116, 0x3fb8aa3b, v116
	v_exp_f32_e32 v183, v116
	v_sub_f32_e32 v116, v143, v121
	v_min_f32_e32 v116, 0, v116
	v_mul_f32_e32 v116, 0x3fb8aa3b, v116
	v_exp_f32_e32 v185, v116
	v_sub_f32_e32 v116, v137, v118
	v_min_f32_e32 v116, 0, v116
	v_mul_f32_e32 v116, 0x3fb8aa3b, v116
	v_exp_f32_e32 v186, v116
	v_sub_f32_e32 v116, v139, v122
	v_min_f32_e32 v116, 0, v116
	v_mul_f32_e32 v116, 0x3fb8aa3b, v116
	v_exp_f32_e32 v188, v116
	v_sub_f32_e32 v116, v141, v118
	v_min_f32_e32 v116, 0, v116
	v_mul_f32_e32 v116, 0x3fb8aa3b, v116
	v_exp_f32_e32 v190, v116
	v_sub_f32_e32 v116, v143, v122
	v_min_f32_e32 v116, 0, v116
	v_mul_f32_e32 v116, 0x3fb8aa3b, v116
	v_exp_f32_e32 v192, v116
	v_sub_f32_e32 v116, v137, v119
	v_min_f32_e32 v116, 0, v116
	v_mul_f32_e32 v116, 0x3fb8aa3b, v116
	v_exp_f32_e32 v187, v116
	v_sub_f32_e32 v116, v139, v123
	v_min_f32_e32 v116, 0, v116
	v_min_f32_e32 v95, 0, v95
	v_mul_f32_e32 v116, 0x3fb8aa3b, v116
	v_mul_f32_e32 v95, 0x3fb8aa3b, v95
	v_exp_f32_e32 v189, v116
	v_sub_f32_e32 v116, v141, v119
	v_exp_f32_e32 v182, v95
	v_sub_f32_e32 v95, v143, v120
	v_min_f32_e32 v116, 0, v116
	v_min_f32_e32 v95, 0, v95
	v_mul_f32_e32 v116, 0x3fb8aa3b, v116
	v_mul_f32_e32 v95, 0x3fb8aa3b, v95
	v_exp_f32_e32 v191, v116
	v_sub_f32_e32 v116, v143, v123
	v_exp_f32_e32 v184, v95
	v_sub_f32_e32 v95, v137, v117
	v_min_f32_e32 v116, 0, v116
	v_min_f32_e32 v94, 0, v94
	v_min_f32_e32 v95, 0, v95
	v_mul_f32_e32 v116, 0x3fb8aa3b, v116
	s_movk_i32 s0, 0xffce
	v_mul_f32_e32 v94, 0x3fb8aa3b, v94
	v_mul_f32_e32 v95, 0x3fb8aa3b, v95
	v_exp_f32_e32 v193, v116
	v_add_u32_e32 v116, 48, v145
	v_add_u32_e32 v117, 47, v145
	v_cmp_lt_i32_e32 vcc, s0, v145
	s_movk_i32 s0, 0xffcf
	v_exp_f32_e32 v94, v94
	v_exp_f32_e32 v95, v95
	v_lshrrev_b32_e32 v118, 31, v117
	v_lshrrev_b32_e32 v116, 31, v116
	v_cndmask_b32_e64 v119, 0, 1.0, vcc
	v_cmp_lt_i32_e32 vcc, s0, v145
	v_cvt_f32_ubyte0_e32 v117, v116
	v_cvt_f32_ubyte0_e32 v116, v118
	v_cndmask_b32_e64 v118, 0, 1.0, vcc
	s_waitcnt lgkmcnt(0)
	v_pk_mul_f32 v[122:123], v[156:157], v[118:119]
	v_pk_mul_f32 v[120:121], v[152:153], v[116:117]
	v_pk_mul_f32 v[122:123], v[122:123], v[180:181]
	s_movk_i32 s0, 0xffcc
	v_pk_fma_f32 v[94:95], v[120:121], v[94:95], v[122:123]
	v_cmp_lt_i32_e32 vcc, s0, v145
	v_pk_mul_f32 v[94:95], v[104:105], v[94:95]
	s_movk_i32 s0, 0xffcd
	v_cvt_pk_f16_f32 v94, v94, v95
	v_add_u32_e32 v95, 50, v145
	v_add_u32_e32 v104, 49, v145
	v_cndmask_b32_e64 v123, 0, 1.0, vcc
	v_cmp_lt_i32_e32 vcc, s0, v145
	v_lshrrev_b32_e32 v104, 31, v104
	v_lshrrev_b32_e32 v95, 31, v95
	v_cndmask_b32_e64 v122, 0, 1.0, vcc
	v_cvt_f32_ubyte0_e32 v121, v95
	v_cvt_f32_ubyte0_e32 v120, v104
	v_pk_mul_f32 v[180:181], v[158:159], v[122:123]
	v_pk_mul_f32 v[104:105], v[154:155], v[120:121]
	v_pk_mul_f32 v[180:181], v[180:181], v[188:189]
	v_pk_mul_f32 v[92:93], v[112:113], v[92:93]
	v_pk_fma_f32 v[104:105], v[104:105], v[186:187], v[180:181]
	s_movk_i32 s0, 0xffde
	v_pk_mul_f32 v[104:105], v[106:107], v[104:105]
	v_cmp_lt_i32_e32 vcc, s0, v145
	v_cvt_pk_f16_f32 v95, v104, v105
	v_pk_mul_f32 v[104:105], v[108:109], v[148:149]
	s_movk_i32 s0, 0xffdf
	v_pk_mul_f32 v[104:105], v[104:105], v[174:175]
	s_nop 0
	v_pk_fma_f32 v[92:93], v[92:93], v[166:167], v[104:105]
	v_pk_mul_f32 v[104:105], v[110:111], v[128:129]
	v_pk_mul_f32 v[92:93], v[100:101], v[92:93]
	v_pk_mul_f32 v[104:105], v[104:105], v[178:179]
	v_cvt_pk_f16_f32 v100, v92, v93
	v_pk_mul_f32 v[92:93], v[114:115], v[124:125]
	s_nop 0
	v_pk_fma_f32 v[92:93], v[92:93], v[176:177], v[104:105]
	s_nop 0
	v_pk_mul_f32 v[92:93], v[102:103], v[92:93]
	v_cndmask_b32_e64 v103, 0, 1.0, vcc
	v_cvt_pk_f16_f32 v101, v92, v93
	v_add_u32_e32 v92, 32, v145
	v_add_u32_e32 v93, 31, v145
	v_lshrrev_b32_e32 v102, 31, v93
	v_lshrrev_b32_e32 v92, 31, v92
	v_cmp_lt_i32_e32 vcc, s0, v145
	v_cvt_f32_ubyte0_e32 v93, v92
	v_cvt_f32_ubyte0_e32 v92, v102
	v_cndmask_b32_e64 v102, 0, 1.0, vcc
	v_pk_mul_f32 v[106:107], v[156:157], v[102:103]
	v_pk_mul_f32 v[102:103], v[108:109], v[102:103]
	v_pk_mul_f32 v[104:105], v[152:153], v[92:93]
	v_pk_mul_f32 v[106:107], v[106:107], v[184:185]
	v_pk_mul_f32 v[92:93], v[112:113], v[92:93]
	v_pk_mul_f32 v[102:103], v[102:103], v[160:161]
	v_pk_fma_f32 v[104:105], v[104:105], v[182:183], v[106:107]
	v_pk_fma_f32 v[92:93], v[92:93], v[150:151], v[102:103]
	s_movk_i32 s0, 0xffdc
	v_pk_mul_f32 v[96:97], v[96:97], v[104:105]
	v_pk_mul_f32 v[88:89], v[88:89], v[92:93]
	v_cmp_lt_i32_e32 vcc, s0, v145
	s_movk_i32 s0, 0xffdd
	v_cvt_pk_f16_f32 v92, v88, v89
	v_cvt_pk_f16_f32 v102, v96, v97
	v_add_u32_e32 v88, 34, v145
	v_add_u32_e32 v89, 33, v145
	v_cndmask_b32_e64 v97, 0, 1.0, vcc
	v_cmp_lt_i32_e32 vcc, s0, v145
	v_lshrrev_b32_e32 v93, 31, v89
	v_lshrrev_b32_e32 v88, 31, v88
	v_cndmask_b32_e64 v96, 0, 1.0, vcc
	v_cvt_f32_ubyte0_e32 v89, v88
	v_cvt_f32_ubyte0_e32 v88, v93
	v_pk_mul_f32 v[106:107], v[158:159], v[96:97]
	v_pk_mul_f32 v[96:97], v[110:111], v[96:97]
	v_pk_mul_f32 v[104:105], v[154:155], v[88:89]
	v_pk_mul_f32 v[106:107], v[106:107], v[192:193]
	v_pk_mul_f32 v[88:89], v[114:115], v[88:89]
	v_pk_mul_f32 v[96:97], v[96:97], v[130:131]
	v_pk_fma_f32 v[104:105], v[104:105], v[190:191], v[106:107]
	v_pk_fma_f32 v[88:89], v[88:89], v[126:127], v[96:97]
	v_pk_mul_f32 v[98:99], v[98:99], v[104:105]
	v_pk_mul_f32 v[88:89], v[90:91], v[88:89]
	v_cvt_pk_f16_f32 v103, v98, v99
	v_cvt_pk_f16_f32 v93, v88, v89
	v_or_b32_e32 v88, 0x11100, v168
	v_or_b32_e32 v96, 0x11300, v168
	ds_read_b128 v[88:91], v88
	ds_read_b128 v[108:111], v96
	v_or_b32_e32 v96, 0x11500, v168
	v_or_b32_e32 v97, 0x11700, v168
	ds_read_b128 v[104:107], v96
	ds_read_b128 v[96:99], v97
	s_waitcnt lgkmcnt(3)
	v_sub_f32_e32 v112, v137, v88
	v_sub_f32_e32 v88, v141, v88
	v_min_f32_e32 v88, 0, v88
	v_mul_f32_e32 v88, 0x3fb8aa3b, v88
	v_exp_f32_e32 v152, v88
	s_waitcnt lgkmcnt(2)
	v_sub_f32_e32 v88, v143, v108
	v_min_f32_e32 v88, 0, v88
	v_mul_f32_e32 v88, 0x3fb8aa3b, v88
	v_exp_f32_e32 v154, v88
	v_sub_f32_e32 v88, v137, v89
	v_min_f32_e32 v88, 0, v88
	v_mul_f32_e32 v88, 0x3fb8aa3b, v88
	v_exp_f32_e32 v125, v88
	v_sub_f32_e32 v88, v139, v109
	v_min_f32_e32 v88, 0, v88
	v_mul_f32_e32 v88, 0x3fb8aa3b, v88
	v_exp_f32_e32 v131, v88
	v_sub_f32_e32 v88, v141, v89
	v_min_f32_e32 v88, 0, v88
	v_mul_f32_e32 v88, 0x3fb8aa3b, v88
	v_exp_f32_e32 v153, v88
	v_sub_f32_e32 v88, v143, v109
	v_min_f32_e32 v112, 0, v112
	v_min_f32_e32 v88, 0, v88
	v_mul_f32_e32 v112, 0x3fb8aa3b, v112
	v_mul_f32_e32 v88, 0x3fb8aa3b, v88
	v_exp_f32_e32 v124, v112
	v_sub_f32_e32 v112, v139, v108
	v_exp_f32_e32 v155, v88
	v_sub_f32_e32 v88, v137, v90
	v_min_f32_e32 v112, 0, v112
	v_min_f32_e32 v88, 0, v88
	v_mul_f32_e32 v112, 0x3fb8aa3b, v112
	v_mul_f32_e32 v88, 0x3fb8aa3b, v88
	v_exp_f32_e32 v130, v112
	v_exp_f32_e32 v112, v88
	v_sub_f32_e32 v88, v139, v110
	v_min_f32_e32 v88, 0, v88
	v_mul_f32_e32 v88, 0x3fb8aa3b, v88
	v_exp_f32_e32 v114, v88
	v_sub_f32_e32 v88, v141, v90
	v_min_f32_e32 v88, 0, v88
	v_mul_f32_e32 v88, 0x3fb8aa3b, v88
	v_exp_f32_e32 v156, v88
	v_sub_f32_e32 v88, v143, v110
	v_min_f32_e32 v88, 0, v88
	v_mul_f32_e32 v88, 0x3fb8aa3b, v88
	v_exp_f32_e32 v158, v88
	v_sub_f32_e32 v88, v137, v91
	v_min_f32_e32 v88, 0, v88
	v_mul_f32_e32 v88, 0x3fb8aa3b, v88
	v_exp_f32_e32 v113, v88
	v_sub_f32_e32 v88, v139, v111
	v_min_f32_e32 v88, 0, v88
	v_mul_f32_e32 v88, 0x3fb8aa3b, v88
	v_exp_f32_e32 v115, v88
	v_sub_f32_e32 v88, v141, v91
	v_min_f32_e32 v88, 0, v88
	v_mul_f32_e32 v88, 0x3fb8aa3b, v88
	v_exp_f32_e32 v157, v88
	v_sub_f32_e32 v88, v143, v111
	v_min_f32_e32 v88, 0, v88
	v_mul_f32_e32 v88, 0x3fb8aa3b, v88
	v_exp_f32_e32 v159, v88
	v_or_b32_e32 v88, 0x11140, v168
	v_or_b32_e32 v108, 0x11340, v168
	ds_read_b128 v[88:91], v88
	ds_read_b128 v[108:111], v108
	v_or_b32_e32 v126, 0x11540, v168
	v_or_b32_e32 v148, 0x11740, v168
	ds_read_b128 v[126:129], v126
	ds_read_b128 v[148:151], v148
	s_waitcnt lgkmcnt(3)
	v_sub_f32_e32 v160, v137, v88
	v_sub_f32_e32 v88, v141, v88
	v_min_f32_e32 v88, 0, v88
	v_mul_f32_e32 v88, 0x3fb8aa3b, v88
	v_exp_f32_e32 v174, v88
	s_waitcnt lgkmcnt(2)
	v_sub_f32_e32 v88, v143, v108
	v_min_f32_e32 v88, 0, v88
	v_mul_f32_e32 v88, 0x3fb8aa3b, v88
	v_sub_f32_e32 v161, v139, v108
	v_exp_f32_e32 v176, v88
	v_sub_f32_e32 v88, v137, v89
	v_min_f32_e32 v161, 0, v161
	v_min_f32_e32 v88, 0, v88
	v_mul_f32_e32 v161, 0x3fb8aa3b, v161
	v_mul_f32_e32 v88, 0x3fb8aa3b, v88
	v_exp_f32_e32 v166, v161
	v_exp_f32_e32 v161, v88
	v_sub_f32_e32 v88, v139, v109
	v_min_f32_e32 v88, 0, v88
	v_mul_f32_e32 v88, 0x3fb8aa3b, v88
	v_exp_f32_e32 v167, v88
	v_sub_f32_e32 v88, v141, v89
	v_min_f32_e32 v88, 0, v88
	v_mul_f32_e32 v88, 0x3fb8aa3b, v88
	v_exp_f32_e32 v175, v88
	v_sub_f32_e32 v88, v143, v109
	v_min_f32_e32 v88, 0, v88
	v_mul_f32_e32 v88, 0x3fb8aa3b, v88
	v_exp_f32_e32 v177, v88
	v_sub_f32_e32 v88, v137, v90
	v_min_f32_e32 v88, 0, v88
	v_mul_f32_e32 v88, 0x3fb8aa3b, v88
	v_exp_f32_e32 v178, v88
	v_sub_f32_e32 v88, v139, v110
	v_min_f32_e32 v88, 0, v88
	v_mul_f32_e32 v88, 0x3fb8aa3b, v88
	v_exp_f32_e32 v180, v88
	v_sub_f32_e32 v88, v141, v90
	v_min_f32_e32 v88, 0, v88
	v_mul_f32_e32 v88, 0x3fb8aa3b, v88
	v_exp_f32_e32 v182, v88
	v_sub_f32_e32 v88, v143, v110
	v_min_f32_e32 v88, 0, v88
	v_mul_f32_e32 v88, 0x3fb8aa3b, v88
	v_exp_f32_e32 v184, v88
	v_sub_f32_e32 v88, v137, v91
	v_min_f32_e32 v88, 0, v88
	v_mul_f32_e32 v88, 0x3fb8aa3b, v88
	v_exp_f32_e32 v179, v88
	v_sub_f32_e32 v88, v139, v111
	v_min_f32_e32 v88, 0, v88
	v_mul_f32_e32 v88, 0x3fb8aa3b, v88
	v_exp_f32_e32 v181, v88
	v_sub_f32_e32 v88, v141, v91
	v_min_f32_e32 v88, 0, v88
	v_mul_f32_e32 v88, 0x3fb8aa3b, v88
	v_exp_f32_e32 v183, v88
	v_sub_f32_e32 v88, v143, v111
	v_min_f32_e32 v160, 0, v160
	v_min_f32_e32 v88, 0, v88
	s_movk_i32 s0, 0xffae
	v_mul_f32_e32 v160, 0x3fb8aa3b, v160
	v_mul_f32_e32 v88, 0x3fb8aa3b, v88
	v_cmp_lt_i32_e32 vcc, s0, v145
	s_movk_i32 s0, 0xffaf
	v_exp_f32_e32 v160, v160
	v_exp_f32_e32 v185, v88
	v_add_u32_e32 v88, 0x50, v145
	v_add_u32_e32 v89, 0x4f, v145
	v_cndmask_b32_e64 v109, 0, 1.0, vcc
	v_cmp_lt_i32_e32 vcc, s0, v145
	v_lshrrev_b32_e32 v89, 31, v89
	v_lshrrev_b32_e32 v88, 31, v88
	v_cndmask_b32_e64 v108, 0, 1.0, vcc
	v_cvt_f32_ubyte0_e32 v91, v88
	v_cvt_f32_ubyte0_e32 v90, v89
	s_waitcnt lgkmcnt(0)
	v_pk_mul_f32 v[110:111], v[148:149], v[108:109]
	v_pk_mul_f32 v[88:89], v[126:127], v[90:91]
	v_pk_mul_f32 v[110:111], v[110:111], v[166:167]
	s_movk_i32 s0, 0xffac
	v_pk_fma_f32 v[88:89], v[88:89], v[160:161], v[110:111]
	v_cmp_lt_i32_e32 vcc, s0, v145
	v_pk_mul_f32 v[84:85], v[84:85], v[88:89]
	s_movk_i32 s0, 0xffad
	v_cvt_pk_f16_f32 v88, v84, v85
	v_add_u32_e32 v84, 0x52, v145
	v_add_u32_e32 v85, 0x51, v145
	v_cndmask_b32_e64 v111, 0, 1.0, vcc
	v_cmp_lt_i32_e32 vcc, s0, v145
	v_lshrrev_b32_e32 v89, 31, v85
	v_lshrrev_b32_e32 v84, 31, v84
	v_cndmask_b32_e64 v110, 0, 1.0, vcc
	v_cvt_f32_ubyte0_e32 v85, v84
	v_cvt_f32_ubyte0_e32 v84, v89
	v_pk_mul_f32 v[166:167], v[150:151], v[110:111]
	v_pk_mul_f32 v[160:161], v[128:129], v[84:85]
	v_pk_mul_f32 v[166:167], v[166:167], v[180:181]
	s_movk_i32 s0, 0xffbe
	v_pk_fma_f32 v[160:161], v[160:161], v[178:179], v[166:167]
	v_cmp_lt_i32_e32 vcc, s0, v145
	v_pk_mul_f32 v[86:87], v[86:87], v[160:161]
	s_movk_i32 s0, 0xffbf
	v_cvt_pk_f16_f32 v89, v86, v87
	v_pk_mul_f32 v[86:87], v[104:105], v[116:117]
	v_pk_mul_f32 v[116:117], v[96:97], v[118:119]
	s_nop 0
	v_pk_mul_f32 v[116:117], v[116:117], v[154:155]
	s_nop 0
	v_pk_fma_f32 v[86:87], v[86:87], v[152:153], v[116:117]
	v_pk_mul_f32 v[116:117], v[98:99], v[122:123]
	v_pk_mul_f32 v[76:77], v[76:77], v[86:87]
	v_pk_mul_f32 v[86:87], v[106:107], v[120:121]
	v_pk_mul_f32 v[116:117], v[116:117], v[158:159]
	v_cvt_pk_f16_f32 v76, v76, v77
	v_pk_fma_f32 v[86:87], v[86:87], v[156:157], v[116:117]
	s_nop 0
	v_pk_mul_f32 v[78:79], v[78:79], v[86:87]
	v_cndmask_b32_e64 v87, 0, 1.0, vcc
	v_cvt_pk_f16_f32 v77, v78, v79
	v_add_u32_e32 v78, 64, v145
	v_add_u32_e32 v79, 63, v145
	v_lshrrev_b32_e32 v86, 31, v79
	v_lshrrev_b32_e32 v78, 31, v78
	v_cmp_lt_i32_e32 vcc, s0, v145
	v_cvt_f32_ubyte0_e32 v79, v78
	v_cvt_f32_ubyte0_e32 v78, v86
	v_cndmask_b32_e64 v86, 0, 1.0, vcc
	v_pk_mul_f32 v[118:119], v[148:149], v[86:87]
	v_pk_mul_f32 v[86:87], v[96:97], v[86:87]
	v_pk_mul_f32 v[116:117], v[126:127], v[78:79]
	v_pk_mul_f32 v[78:79], v[104:105], v[78:79]
	v_pk_mul_f32 v[86:87], v[86:87], v[130:131]
	v_pk_mul_f32 v[118:119], v[118:119], v[176:177]
	v_pk_fma_f32 v[78:79], v[78:79], v[124:125], v[86:87]
	v_pk_fma_f32 v[116:117], v[116:117], v[174:175], v[118:119]
	v_pk_mul_f32 v[68:69], v[68:69], v[78:79]
	s_movk_i32 s0, 0xffbc
	v_pk_mul_f32 v[72:73], v[72:73], v[116:117]
	v_cvt_pk_f16_f32 v86, v68, v69
	v_add_u32_e32 v68, 0x42, v145
	v_add_u32_e32 v69, 0x41, v145
	v_cmp_lt_i32_e32 vcc, s0, v145
	s_movk_i32 s0, 0xffbd
	v_cvt_pk_f16_f32 v78, v72, v73
	v_lshrrev_b32_e32 v72, 31, v69
	v_lshrrev_b32_e32 v68, 31, v68
	v_cndmask_b32_e64 v73, 0, 1.0, vcc
	v_cmp_lt_i32_e32 vcc, s0, v145
	v_cvt_f32_ubyte0_e32 v69, v68
	v_cvt_f32_ubyte0_e32 v68, v72
	v_cndmask_b32_e64 v72, 0, 1.0, vcc
	v_pk_mul_f32 v[104:105], v[150:151], v[72:73]
	v_pk_mul_f32 v[72:73], v[98:99], v[72:73]
	v_pk_mul_f32 v[96:97], v[128:129], v[68:69]
	v_pk_mul_f32 v[104:105], v[104:105], v[184:185]
	v_pk_mul_f32 v[68:69], v[106:107], v[68:69]
	v_pk_mul_f32 v[72:73], v[72:73], v[114:115]
	v_pk_fma_f32 v[96:97], v[96:97], v[182:183], v[104:105]
	v_pk_fma_f32 v[68:69], v[68:69], v[112:113], v[72:73]
	v_pk_mul_f32 v[74:75], v[74:75], v[96:97]
	v_pk_mul_f32 v[68:69], v[70:71], v[68:69]
	v_cvt_pk_f16_f32 v79, v74, v75
	v_cvt_pk_f16_f32 v87, v68, v69
	v_or_b32_e32 v68, 0x11180, v168
	v_or_b32_e32 v69, 0x11380, v168
	ds_read_b128 v[112:115], v68
	ds_read_b128 v[116:119], v69
	v_or_b32_e32 v68, 0x11580, v168
	v_or_b32_e32 v69, 0x11780, v168
	ds_read_b128 v[72:75], v68
	ds_read_b128 v[68:71], v69
	s_waitcnt lgkmcnt(3)
	v_sub_f32_e32 v96, v137, v112
	v_min_f32_e32 v96, 0, v96
	v_mul_f32_e32 v96, 0x3fb8aa3b, v96
	v_exp_f32_e32 v98, v96
	s_waitcnt lgkmcnt(2)
	v_sub_f32_e32 v96, v139, v116
	v_min_f32_e32 v96, 0, v96
	v_sub_f32_e32 v97, v143, v116
	v_sub_f32_e32 v105, v139, v118
	v_mul_f32_e32 v96, 0x3fb8aa3b, v96
	v_min_f32_e32 v97, 0, v97
	v_min_f32_e32 v105, 0, v105
	v_exp_f32_e32 v128, v96
	v_sub_f32_e32 v96, v141, v112
	v_mul_f32_e32 v97, 0x3fb8aa3b, v97
	v_mul_f32_e32 v105, 0x3fb8aa3b, v105
	v_sub_f32_e32 v112, v141, v115
	v_exp_f32_e32 v130, v97
	v_sub_f32_e32 v97, v137, v113
	v_exp_f32_e32 v106, v105
	v_sub_f32_e32 v105, v141, v114
	v_min_f32_e32 v112, 0, v112
	v_min_f32_e32 v97, 0, v97
	v_min_f32_e32 v105, 0, v105
	v_mul_f32_e32 v112, 0x3fb8aa3b, v112
	v_mul_f32_e32 v97, 0x3fb8aa3b, v97
	v_mul_f32_e32 v105, 0x3fb8aa3b, v105
	v_exp_f32_e32 v149, v112
	v_sub_f32_e32 v112, v143, v119
	v_exp_f32_e32 v99, v97
	v_sub_f32_e32 v97, v139, v117
	v_sub_f32_e32 v104, v143, v117
	v_exp_f32_e32 v148, v105
	v_sub_f32_e32 v105, v143, v118
	v_min_f32_e32 v112, 0, v112
	v_min_f32_e32 v97, 0, v97
	v_min_f32_e32 v104, 0, v104
	v_min_f32_e32 v105, 0, v105
	v_mul_f32_e32 v112, 0x3fb8aa3b, v112
	v_mul_f32_e32 v97, 0x3fb8aa3b, v97
	v_mul_f32_e32 v104, 0x3fb8aa3b, v104
	v_mul_f32_e32 v105, 0x3fb8aa3b, v105
	v_exp_f32_e32 v151, v112
	v_or_b32_e32 v112, 0x111c0, v168
	v_or_b32_e32 v116, 0x113c0, v168
	v_exp_f32_e32 v129, v97
	v_sub_f32_e32 v97, v141, v113
	v_exp_f32_e32 v131, v104
	v_sub_f32_e32 v104, v137, v114
	v_exp_f32_e32 v150, v105
	v_sub_f32_e32 v105, v137, v115
	v_sub_f32_e32 v107, v139, v119
	ds_read_b128 v[112:115], v112
	ds_read_b128 v[116:119], v116
	v_or_b32_e32 v120, 0x115c0, v168
	v_or_b32_e32 v124, 0x117c0, v168
	ds_read_b128 v[120:123], v120
	ds_read_b128 v[124:127], v124
	s_waitcnt lgkmcnt(3)
	v_sub_f32_e32 v152, v137, v112
	s_waitcnt lgkmcnt(2)
	v_sub_f32_e32 v153, v139, v116
	v_min_f32_e32 v153, 0, v153
	v_mul_f32_e32 v153, 0x3fb8aa3b, v153
	v_exp_f32_e32 v154, v153
	v_sub_f32_e32 v153, v137, v113
	v_sub_f32_e32 v156, v137, v114
	v_sub_f32_e32 v157, v139, v118
	v_sub_f32_e32 v137, v137, v115
	v_min_f32_e32 v157, 0, v157
	v_min_f32_e32 v137, 0, v137
	v_sub_f32_e32 v155, v139, v117
	v_mul_f32_e32 v157, 0x3fb8aa3b, v157
	v_mul_f32_e32 v137, 0x3fb8aa3b, v137
	v_min_f32_e32 v155, 0, v155
	v_exp_f32_e32 v158, v157
	v_exp_f32_e32 v157, v137
	v_sub_f32_e32 v137, v139, v119
	v_min_f32_e32 v152, 0, v152
	v_min_f32_e32 v153, 0, v153
	v_mul_f32_e32 v155, 0x3fb8aa3b, v155
	v_min_f32_e32 v137, 0, v137
	s_movk_i32 s0, 0xff8e
	v_mul_f32_e32 v152, 0x3fb8aa3b, v152
	v_mul_f32_e32 v153, 0x3fb8aa3b, v153
	v_exp_f32_e32 v155, v155
	v_mul_f32_e32 v137, 0x3fb8aa3b, v137
	v_cmp_lt_i32_e32 vcc, s0, v145
	s_movk_i32 s0, 0xff8f
	v_exp_f32_e32 v152, v152
	v_exp_f32_e32 v153, v153
	v_exp_f32_e32 v159, v137
	v_add_u32_e32 v137, 0x70, v145
	v_add_u32_e32 v139, 0x6f, v145
	v_cndmask_b32_e64 v167, 0, 1.0, vcc
	v_cmp_lt_i32_e32 vcc, s0, v145
	v_lshrrev_b32_e32 v139, 31, v139
	v_lshrrev_b32_e32 v137, 31, v137
	v_cndmask_b32_e64 v166, 0, 1.0, vcc
	v_cvt_f32_ubyte0_e32 v161, v137
	v_cvt_f32_ubyte0_e32 v160, v139
	s_waitcnt lgkmcnt(0)
	v_pk_mul_f32 v[166:167], v[124:125], v[166:167]
	v_pk_mul_f32 v[160:161], v[120:121], v[160:161]
	v_pk_mul_f32 v[154:155], v[166:167], v[154:155]
	v_min_f32_e32 v156, 0, v156
	v_pk_fma_f32 v[152:153], v[160:161], v[152:153], v[154:155]
	s_movk_i32 s0, 0xff8c
	v_mul_f32_e32 v156, 0x3fb8aa3b, v156
	v_pk_mul_f32 v[60:61], v[60:61], v[152:153]
	v_cmp_lt_i32_e32 vcc, s0, v145
	s_movk_i32 s0, 0xff8d
	v_exp_f32_e32 v156, v156
	v_cvt_pk_f16_f32 v60, v60, v61
	v_add_u32_e32 v61, 0x72, v145
	v_add_u32_e32 v137, 0x71, v145
	v_cndmask_b32_e64 v155, 0, 1.0, vcc
	v_cmp_lt_i32_e32 vcc, s0, v145
	v_lshrrev_b32_e32 v137, 31, v137
	v_lshrrev_b32_e32 v61, 31, v61
	v_cndmask_b32_e64 v154, 0, 1.0, vcc
	v_min_f32_e32 v96, 0, v96
	v_min_f32_e32 v97, 0, v97
	v_cvt_f32_ubyte0_e32 v153, v61
	v_cvt_f32_ubyte0_e32 v152, v137
	v_pk_mul_f32 v[154:155], v[126:127], v[154:155]
	v_mul_f32_e32 v96, 0x3fb8aa3b, v96
	v_mul_f32_e32 v97, 0x3fb8aa3b, v97
	v_pk_mul_f32 v[152:153], v[122:123], v[152:153]
	v_pk_mul_f32 v[154:155], v[154:155], v[158:159]
	v_exp_f32_e32 v96, v96
	v_exp_f32_e32 v97, v97
	v_pk_fma_f32 v[152:153], v[152:153], v[156:157], v[154:155]
	v_sub_f32_e32 v116, v143, v116
	v_pk_mul_f32 v[62:63], v[62:63], v[152:153]
	v_sub_f32_e32 v117, v143, v117
	v_cvt_pk_f16_f32 v61, v62, v63
	v_pk_mul_f32 v[62:63], v[72:73], v[90:91]
	v_pk_mul_f32 v[90:91], v[68:69], v[108:109]
	v_sub_f32_e32 v112, v141, v112
	v_pk_mul_f32 v[90:91], v[90:91], v[130:131]
	v_min_f32_e32 v116, 0, v116
	v_pk_fma_f32 v[62:63], v[62:63], v[96:97], v[90:91]
	v_sub_f32_e32 v113, v141, v113
	v_pk_mul_f32 v[56:57], v[56:57], v[62:63]
	v_pk_mul_f32 v[62:63], v[70:71], v[110:111]
	v_cvt_pk_f16_f32 v96, v56, v57
	v_pk_mul_f32 v[56:57], v[74:75], v[84:85]
	v_pk_mul_f32 v[62:63], v[62:63], v[150:151]
	v_min_f32_e32 v117, 0, v117
	v_pk_fma_f32 v[56:57], v[56:57], v[148:149], v[62:63]
	s_movk_i32 s0, 0xff9e
	v_pk_mul_f32 v[56:57], v[58:59], v[56:57]
	v_min_f32_e32 v112, 0, v112
	v_mul_f32_e32 v116, 0x3fb8aa3b, v116
	v_min_f32_e32 v113, 0, v113
	v_mul_f32_e32 v117, 0x3fb8aa3b, v117
	v_cvt_pk_f16_f32 v97, v56, v57
	v_add_u32_e32 v56, 0x60, v145
	v_add_u32_e32 v57, 0x5f, v145
	v_cmp_lt_i32_e32 vcc, s0, v145
	s_movk_i32 s0, 0xff9f
	v_mul_f32_e32 v112, 0x3fb8aa3b, v112
	v_exp_f32_e32 v116, v116
	v_mul_f32_e32 v113, 0x3fb8aa3b, v113
	v_exp_f32_e32 v117, v117
	v_lshrrev_b32_e32 v58, 31, v57
	v_lshrrev_b32_e32 v56, 31, v56
	v_cndmask_b32_e64 v59, 0, 1.0, vcc
	v_cmp_lt_i32_e32 vcc, s0, v145
	v_exp_f32_e32 v112, v112
	v_exp_f32_e32 v113, v113
	v_cvt_f32_ubyte0_e32 v57, v56
	v_cvt_f32_ubyte0_e32 v56, v58
	v_cndmask_b32_e64 v58, 0, 1.0, vcc
	v_pk_mul_f32 v[84:85], v[124:125], v[58:59]
	v_pk_mul_f32 v[58:59], v[68:69], v[58:59]
	v_sub_f32_e32 v118, v143, v118
	v_sub_f32_e32 v119, v143, v119
	v_pk_mul_f32 v[62:63], v[120:121], v[56:57]
	v_pk_mul_f32 v[56:57], v[72:73], v[56:57]
	v_pk_mul_f32 v[58:59], v[58:59], v[128:129]
	v_min_f32_e32 v107, 0, v107
	v_sub_f32_e32 v114, v141, v114
	v_min_f32_e32 v118, 0, v118
	v_sub_f32_e32 v115, v141, v115
	v_min_f32_e32 v119, 0, v119
	v_pk_mul_f32 v[84:85], v[84:85], v[116:117]
	v_pk_fma_f32 v[56:57], v[56:57], v[98:99], v[58:59]
	v_min_f32_e32 v104, 0, v104
	v_min_f32_e32 v105, 0, v105
	v_mul_f32_e32 v107, 0x3fb8aa3b, v107
	v_min_f32_e32 v114, 0, v114
	v_mul_f32_e32 v118, 0x3fb8aa3b, v118
	v_min_f32_e32 v115, 0, v115
	v_mul_f32_e32 v119, 0x3fb8aa3b, v119
	v_pk_fma_f32 v[62:63], v[62:63], v[112:113], v[84:85]
	v_pk_mul_f32 v[48:49], v[48:49], v[56:57]
	s_movk_i32 s0, 0xff9c
	v_mul_f32_e32 v104, 0x3fb8aa3b, v104
	v_mul_f32_e32 v105, 0x3fb8aa3b, v105
	v_exp_f32_e32 v107, v107
	v_mul_f32_e32 v114, 0x3fb8aa3b, v114
	v_exp_f32_e32 v118, v118
	v_mul_f32_e32 v115, 0x3fb8aa3b, v115
	v_exp_f32_e32 v119, v119
	v_pk_mul_f32 v[52:53], v[52:53], v[62:63]
	v_cvt_pk_f16_f32 v58, v48, v49
	v_add_u32_e32 v48, 0x62, v145
	v_add_u32_e32 v49, 0x61, v145
	v_cmp_lt_i32_e32 vcc, s0, v145
	s_movk_i32 s0, 0xff9d
	v_exp_f32_e32 v104, v104
	v_exp_f32_e32 v105, v105
	v_exp_f32_e32 v114, v114
	v_exp_f32_e32 v115, v115
	v_cvt_pk_f16_f32 v98, v52, v53
	v_lshrrev_b32_e32 v52, 31, v49
	v_lshrrev_b32_e32 v48, 31, v48
	v_cndmask_b32_e64 v53, 0, 1.0, vcc
	v_cmp_lt_i32_e32 vcc, s0, v145
	v_cvt_f32_ubyte0_e32 v49, v48
	v_cvt_f32_ubyte0_e32 v48, v52
	v_cndmask_b32_e64 v52, 0, 1.0, vcc
	v_pk_mul_f32 v[62:63], v[126:127], v[52:53]
	v_pk_mul_f32 v[52:53], v[70:71], v[52:53]
	v_pk_mul_f32 v[56:57], v[122:123], v[48:49]
	v_pk_mul_f32 v[62:63], v[62:63], v[118:119]
	v_pk_mul_f32 v[48:49], v[74:75], v[48:49]
	v_pk_mul_f32 v[52:53], v[52:53], v[106:107]
	v_pk_fma_f32 v[56:57], v[56:57], v[114:115], v[62:63]
	v_pk_fma_f32 v[48:49], v[48:49], v[104:105], v[52:53]
	v_pk_mul_f32 v[54:55], v[54:55], v[56:57]
	v_pk_mul_f32 v[48:49], v[50:51], v[48:49]
	v_cvt_pk_f16_f32 v99, v54, v55
	v_cvt_pk_f16_f32 v59, v48, v49
	s_barrier
	s_waitcnt vmcnt(11)
	ds_write_b128 v132, v[0:3]
	s_waitcnt vmcnt(10)
	ds_write_b128 v134, v[4:7]
	s_waitcnt vmcnt(9)
	ds_write_b128 v136, v[8:11]
	s_waitcnt vmcnt(8)
	ds_write_b128 v138, v[12:15]
	s_waitcnt vmcnt(7)
	ds_write_b128 v132, v[16:19] offset:17408
	s_waitcnt vmcnt(6)
	ds_write_b128 v134, v[20:23] offset:17408
	s_waitcnt vmcnt(5)
	ds_write_b128 v136, v[24:27] offset:17408
	s_waitcnt vmcnt(4)
	ds_write_b128 v138, v[28:31] offset:17408
	s_waitcnt vmcnt(3)
	ds_write_b128 v140, v[32:35] offset:17408
	s_waitcnt vmcnt(2)
	ds_write_b128 v142, v[36:39] offset:17408
	s_waitcnt vmcnt(1)
	ds_write_b128 v144, v[40:43] offset:17408
	s_waitcnt vmcnt(0)
	ds_write_b128 v146, v[44:47] offset:17408
	v_lshlrev_b32_e32 v16, 3, v164
	v_mad_u32_u24 v17, v162, s12, v16
	s_waitcnt lgkmcnt(0)
	s_barrier
	ds_read2_b64 v[198:201], v17 offset1:4
	s_nop 0
	v_add_u32_e32 v42, 0x1000, v17
	ds_read2_b64 v[202:205], v42 offset0:32 offset1:36
	v_add_u32_e32 v43, 0x2000, v17
	ds_read2_b64 v[210:213], v43 offset0:64 offset1:68
	v_add_u32_e32 v44, 0x3000, v17
	ds_read2_b64 v[222:225], v44 offset0:96 offset1:100
	s_nop 0
	s_nop 0
	s_nop 0
	s_waitcnt lgkmcnt(4)
	s_waitcnt lgkmcnt(3)
	v_mfma_f32_16x16x32_f16 v[4:7], v[198:201], v[64:67], 0
	v_mfma_f32_16x16x32_f16 v[0:3], v[198:201], v[80:83], 0
	s_nop 0
	s_waitcnt lgkmcnt(2)
	v_mfma_f32_16x16x32_f16 v[12:15], v[202:205], v[64:67], 0
	v_mfma_f32_16x16x32_f16 v[8:11], v[202:205], v[80:83], 0
	s_nop 0
	s_waitcnt lgkmcnt(1)
	v_mfma_f32_16x16x32_f16 v[22:25], v[210:213], v[64:67], 0
	v_mfma_f32_16x16x32_f16 v[18:21], v[210:213], v[80:83], 0
	s_nop 0
	s_waitcnt lgkmcnt(0)
	v_mfma_f32_16x16x32_f16 v[30:33], v[222:225], v[64:67], 0
	v_mfma_f32_16x16x32_f16 v[26:29], v[222:225], v[80:83], 0
	ds_read2_b64 v[198:201], v17 offset0:8 offset1:12
	ds_read2_b64 v[202:205], v42 offset0:40 offset1:44
	ds_read2_b64 v[210:213], v43 offset0:72 offset1:76
	s_nop 0
	s_waitcnt lgkmcnt(3)
	s_waitcnt lgkmcnt(2)
	v_mfma_f32_16x16x32_f16 v[4:7], v[198:201], v[92:95], v[4:7]
	v_mfma_f32_16x16x32_f16 v[0:3], v[198:201], v[100:103], v[0:3]
	s_nop 0
	s_nop 0
	s_waitcnt lgkmcnt(1)
	v_mfma_f32_16x16x32_f16 v[12:15], v[202:205], v[92:95], v[12:15]
	v_mfma_f32_16x16x32_f16 v[8:11], v[202:205], v[100:103], v[8:11]
	s_nop 0
	s_nop 0
	s_waitcnt lgkmcnt(0)
	v_mfma_f32_16x16x32_f16 v[22:25], v[210:213], v[92:95], v[22:25]
	v_mfma_f32_16x16x32_f16 v[18:21], v[210:213], v[100:103], v[18:21]
	ds_read2_b64 v[34:37], v44 offset0:104 offset1:108
	s_nop 0
	s_waitcnt lgkmcnt(0)
	v_mfma_f32_16x16x32_f16 v[30:33], v[34:37], v[92:95], v[30:33]
	v_mfma_f32_16x16x32_f16 v[26:29], v[34:37], v[100:103], v[26:29]
	ds_read2_b64 v[198:201], v17 offset0:16 offset1:20
	ds_read2_b64 v[202:205], v43 offset0:80 offset1:84
	s_nop 0
	s_waitcnt lgkmcnt(2)
	s_waitcnt lgkmcnt(1)
	v_mfma_f32_16x16x32_f16 v[4:7], v[198:201], v[86:89], v[4:7]
	v_mfma_f32_16x16x32_f16 v[0:3], v[198:201], v[76:79], v[0:3]
	ds_read2_b64 v[34:37], v42 offset0:48 offset1:52
	s_nop 0
	s_waitcnt lgkmcnt(0)
	v_mfma_f32_16x16x32_f16 v[38:41], v[34:37], v[86:89], v[12:15]
	s_nop 2
	s_nop 0
	s_nop 0
	v_mfma_f32_16x16x32_f16 v[22:25], v[202:205], v[86:89], v[22:25]
	v_mfma_f32_16x16x32_f16 v[18:21], v[202:205], v[76:79], v[18:21]
	ds_read2_b64 v[12:15], v44 offset0:112 offset1:116
	v_mfma_f32_16x16x32_f16 v[8:11], v[34:37], v[76:79], v[8:11]
	s_nop 0
	s_waitcnt lgkmcnt(0)
	v_mfma_f32_16x16x32_f16 v[30:33], v[12:15], v[86:89], v[30:33]
	v_mfma_f32_16x16x32_f16 v[26:29], v[12:15], v[76:79], v[26:29]
	ds_read2_b64 v[198:201], v17 offset0:24 offset1:28
	ds_read2_b64 v[202:205], v42 offset0:56 offset1:60
	ds_read2_b64 v[210:213], v43 offset0:88 offset1:92
	ds_read2_b64 v[222:225], v44 offset0:120 offset1:124
	s_nop 0
	s_waitcnt lgkmcnt(4)
	s_waitcnt lgkmcnt(3)
	v_mfma_f32_16x16x32_f16 v[34:37], v[198:201], v[58:61], v[4:7]
	v_mfma_f32_16x16x32_f16 v[12:15], v[198:201], v[96:99], v[0:3]
	s_nop 2
	s_nop 0
	s_nop 0
	s_waitcnt lgkmcnt(2)
	v_mfma_f32_16x16x32_f16 v[38:41], v[202:205], v[58:61], v[38:41]
	v_mfma_f32_16x16x32_f16 v[8:11], v[202:205], v[96:99], v[8:11]
	s_nop 0
	s_nop 0
	s_waitcnt lgkmcnt(1)
	v_mfma_f32_16x16x32_f16 v[22:25], v[210:213], v[58:61], v[22:25]
	v_mfma_f32_16x16x32_f16 v[4:7], v[210:213], v[96:99], v[18:21]
	s_nop 0
	s_nop 0
	s_waitcnt lgkmcnt(0)
	v_mfma_f32_16x16x32_f16 v[30:33], v[222:225], v[58:61], v[30:33]
	v_mfma_f32_16x16x32_f16 v[0:3], v[222:225], v[96:99], v[26:29]
	v_readlane_b32 s0, v255, 48
	s_or_b32 s4, s9, s0
	s_ashr_i32 s5, s4, 31
	v_readlane_b32 s44, v253, 32
	s_lshl_b64 s[4:5], s[4:5], 2
	v_readlane_b32 s54, v253, 42
	v_readlane_b32 s55, v253, 43
	s_add_u32 s4, s54, s4
	s_addc_u32 s5, s55, s5
	global_load_dword v18, v169, s[4:5]
	s_lshl_b32 s0, s9, 8
	v_readlane_b32 s4, v253, 58
	v_readlane_b32 s5, v253, 59
	s_add_u32 s4, s4, s0
	v_add_u32_e32 v26, s8, v135
	s_addc_u32 s5, s5, 0
	v_lshlrev_b32_e32 v19, 1, v135
	v_ashrrev_i32_e32 v27, 31, v26
	s_movk_i32 s0, 0x440
	v_lshl_add_u64 v[20:21], s[4:5], 0, v[168:169]
	v_lshlrev_b64 v[26:27], 11, v[26:27]
	v_mad_u32_u24 v17, v164, s0, v19
	v_lshl_add_u64 v[42:43], v[20:21], 0, v[26:27]
	ds_read_u16 v26, v17
	ds_read_u16 v27, v17 offset:272
	ds_read_u16 v28, v17 offset:544
	ds_read_u16 v29, v17 offset:816
	s_mov_b32 s0, 0
	s_waitcnt lgkmcnt(3)
	v_cvt_f32_f16_e32 v26, v26
	s_waitcnt lgkmcnt(2)
	v_cvt_f32_f16_e32 v27, v27
	s_waitcnt lgkmcnt(1)
	v_cvt_f32_f16_e32 v28, v28
	s_waitcnt lgkmcnt(0)
	v_cvt_f32_f16_e32 v29, v29
	s_mov_b64 s[4:5], -1
	s_mov_b32 s9, 0x11a00
	v_readlane_b32 s45, v253, 33
	v_readlane_b32 s46, v253, 34
	v_readlane_b32 s47, v253, 35
	v_readlane_b32 s48, v253, 36
	v_readlane_b32 s49, v253, 37
	v_readlane_b32 s50, v253, 38
	v_readlane_b32 s51, v253, 39
	v_readlane_b32 s52, v253, 40
	v_readlane_b32 s53, v253, 41
	v_readlane_b32 s56, v253, 44
	v_readlane_b32 s57, v253, 45
	v_readlane_b32 s58, v253, 46
	v_readlane_b32 s59, v253, 47
	s_waitcnt vmcnt(0)
	v_pk_fma_f32 v[26:27], v[18:19], v[26:27], v[34:35] op_sel_hi:[0,1,1]
	v_pk_fma_f32 v[28:29], v[18:19], v[28:29], v[36:37] op_sel_hi:[0,1,1]
	v_mad_u32_u24 v19, v147, s12, v19
	global_store_dwordx4 v[42:43], v[26:29], off
	v_add_u32_e32 v34, 0xffffde00, v19
	ds_read_u16 v26, v34
	ds_read_u16 v27, v17 offset:4624
	ds_read_u16 v28, v17 offset:4896
	ds_read_u16 v29, v17 offset:5168
	s_waitcnt lgkmcnt(3)
	v_cvt_f32_f16_e32 v26, v26
	s_waitcnt lgkmcnt(2)
	v_cvt_f32_f16_e32 v27, v27
	s_waitcnt lgkmcnt(1)
	v_cvt_f32_f16_e32 v28, v28
	s_waitcnt lgkmcnt(0)
	v_cvt_f32_f16_e32 v29, v29
	v_pk_fma_f32 v[26:27], v[18:19], v[26:27], v[38:39] op_sel_hi:[0,1,1]
	v_pk_fma_f32 v[28:29], v[18:19], v[28:29], v[40:41] op_sel_hi:[0,1,1]
	global_store_dwordx4 v[42:43], v[26:29], off offset:64
	ds_read_u16 v26, v34 offset:4352
	ds_read_u16 v27, v17 offset:8976
	ds_read_u16 v28, v17 offset:9248
	ds_read_u16 v29, v17 offset:9520
	s_waitcnt lgkmcnt(3)
	v_cvt_f32_f16_e32 v26, v26
	s_waitcnt lgkmcnt(2)
	v_cvt_f32_f16_e32 v27, v27
	v_pk_fma_f32 v[22:23], v[18:19], v[26:27], v[22:23] op_sel_hi:[0,1,1]
	s_waitcnt lgkmcnt(0)
	v_cvt_f32_f16_e32 v27, v29
	v_cvt_f32_f16_e32 v26, v28
	v_pk_fma_f32 v[24:25], v[18:19], v[26:27], v[24:25] op_sel_hi:[0,1,1]
	global_store_dwordx4 v[42:43], v[22:25], off offset:128
	ds_read_u16 v22, v19
	ds_read_u16 v23, v17 offset:13328
	ds_read_u16 v24, v17 offset:13600
	ds_read_u16 v25, v17 offset:13872
	s_waitcnt lgkmcnt(3)
	v_cvt_f32_f16_e32 v22, v22
	s_waitcnt lgkmcnt(2)
	v_cvt_f32_f16_e32 v23, v23
	s_waitcnt lgkmcnt(1)
	v_cvt_f32_f16_e32 v24, v24
	s_waitcnt lgkmcnt(0)
	v_cvt_f32_f16_e32 v25, v25
	v_pk_fma_f32 v[22:23], v[18:19], v[22:23], v[30:31] op_sel_hi:[0,1,1]
	v_pk_fma_f32 v[24:25], v[18:19], v[24:25], v[32:33] op_sel_hi:[0,1,1]
	global_store_dwordx4 v[42:43], v[22:25], off offset:192
	s_nop 1
	v_add_u32_e32 v22, s8, v133
	v_ashrrev_i32_e32 v23, 31, v22
	v_lshlrev_b64 v[22:23], 11, v[22:23]
	v_lshl_add_u64 v[20:21], v[20:21], 0, v[22:23]
	ds_read_u16 v22, v17 offset:32
	ds_read_u16 v23, v17 offset:304
	ds_read_u16 v24, v17 offset:576
	ds_read_u16 v25, v17 offset:848
	s_waitcnt lgkmcnt(3)
	v_cvt_f32_f16_e32 v22, v22
	s_waitcnt lgkmcnt(2)
	v_cvt_f32_f16_e32 v23, v23
	v_pk_fma_f32 v[12:13], v[18:19], v[22:23], v[12:13] op_sel_hi:[0,1,1]
	s_waitcnt lgkmcnt(0)
	v_cvt_f32_f16_e32 v23, v25
	v_cvt_f32_f16_e32 v22, v24
	v_pk_fma_f32 v[14:15], v[18:19], v[22:23], v[14:15] op_sel_hi:[0,1,1]
	global_store_dwordx4 v[20:21], v[12:15], off
	ds_read_u16 v12, v34 offset:32
	ds_read_u16 v13, v17 offset:4656
	ds_read_u16 v14, v17 offset:4928
	ds_read_u16 v15, v17 offset:5200
	s_waitcnt lgkmcnt(3)
	v_cvt_f32_f16_e32 v12, v12
	s_waitcnt lgkmcnt(2)
	v_cvt_f32_f16_e32 v13, v13
	v_pk_fma_f32 v[8:9], v[18:19], v[12:13], v[8:9] op_sel_hi:[0,1,1]
	s_waitcnt lgkmcnt(0)
	v_cvt_f32_f16_e32 v13, v15
	v_cvt_f32_f16_e32 v12, v14
	v_pk_fma_f32 v[10:11], v[18:19], v[12:13], v[10:11] op_sel_hi:[0,1,1]
	global_store_dwordx4 v[20:21], v[8:11], off offset:64
	ds_read_u16 v8, v34 offset:4384
	ds_read_u16 v9, v17 offset:9008
	ds_read_u16 v10, v17 offset:9280
	ds_read_u16 v11, v17 offset:9552
	s_waitcnt lgkmcnt(3)
	v_cvt_f32_f16_e32 v8, v8
	s_waitcnt lgkmcnt(2)
	v_cvt_f32_f16_e32 v9, v9
	v_pk_fma_f32 v[4:5], v[18:19], v[8:9], v[4:5] op_sel_hi:[0,1,1]
	s_waitcnt lgkmcnt(0)
	v_cvt_f32_f16_e32 v9, v11
	v_cvt_f32_f16_e32 v8, v10
	v_pk_fma_f32 v[6:7], v[18:19], v[8:9], v[6:7] op_sel_hi:[0,1,1]
	global_store_dwordx4 v[20:21], v[4:7], off offset:128
	ds_read_u16 v4, v19 offset:32
	ds_read_u16 v5, v17 offset:13360
	ds_read_u16 v6, v17 offset:13632
	ds_read_u16 v7, v17 offset:13904
	v_mov_b32_e32 v17, v169
	s_waitcnt lgkmcnt(3)
	v_cvt_f32_f16_e32 v4, v4
	s_waitcnt lgkmcnt(2)
	v_cvt_f32_f16_e32 v5, v5
	v_pk_fma_f32 v[0:1], v[18:19], v[4:5], v[0:1] op_sel_hi:[0,1,1]
	s_waitcnt lgkmcnt(0)
	v_cvt_f32_f16_e32 v5, v7
	v_cvt_f32_f16_e32 v4, v6
	v_lshlrev_b32_e32 v6, 4, v163
	v_pk_fma_f32 v[2:3], v[18:19], v[4:5], v[2:3] op_sel_hi:[0,1,1]
	global_store_dwordx4 v[20:21], v[0:3], off offset:192
	s_nop 1
	v_lshlrev_b32_e32 v0, 7, v162
	v_lshl_or_b32 v0, v163, 11, v0
	v_ashrrev_i32_e32 v1, 31, v0
	v_lshl_add_u64 v[0:1], v[0:1], 1, s[30:31]
	v_lshl_add_u64 v[0:1], v[0:1], 0, v[16:17]
.LBB0_160:
	v_cndmask_b32_e64 v2, 0, 1, s[4:5]
	v_mov_b32_e32 v7, v162
	v_cmp_ne_u32_e32 vcc, 1, v2
	s_and_b64 s[4:5], s[4:5], exec
	v_add_u32_e32 v2, v7, v6
	v_mad_u64_u32 v[4:5], s[6:7], v2, s12, v[168:169]
	ds_read_b128 v[8:11], v4
	s_cselect_b32 s8, 0x11800, s9
	v_lshl_or_b32 v5, v16, 2, s8
	ds_read_b128 v[12:15], v5
	ds_read_b128 v[18:21], v5 offset:16
	s_or_b32 s0, s0, s38
	s_waitcnt lgkmcnt(3)
	s_waitcnt lgkmcnt(2)
	v_cvt_f32_f16_e32 v2, v8
	v_cvt_f32_f16_sdwa v3, v8 dst_sel:DWORD dst_unused:UNUSED_PAD src0_sel:WORD_1
	s_lshl_b64 s[4:5], s[0:1], 14
	s_mov_b32 s0, 1
	s_and_b64 vcc, exec, vcc
	s_nop 0
	s_waitcnt lgkmcnt(1)
	v_pk_mul_f32 v[2:3], v[12:13], v[2:3]
	s_nop 0
	v_cvt_pk_f16_f32 v8, v2, v3
	v_cvt_f32_f16_e32 v2, v10
	v_cvt_f32_f16_sdwa v3, v10 dst_sel:DWORD dst_unused:UNUSED_PAD src0_sel:WORD_1
	s_nop 0
	s_waitcnt lgkmcnt(0)
	v_pk_mul_f32 v[2:3], v[18:19], v[2:3]
	s_nop 0
	v_cvt_pk_f16_f32 v10, v2, v3
	v_cvt_f32_f16_e32 v2, v9
	v_cvt_f32_f16_sdwa v3, v9 dst_sel:DWORD dst_unused:UNUSED_PAD src0_sel:WORD_1
	v_pk_mul_f32 v[2:3], v[14:15], v[2:3]
	s_nop 0
	v_cvt_pk_f16_f32 v9, v2, v3
	v_cvt_f32_f16_e32 v2, v11
	v_cvt_f32_f16_sdwa v3, v11 dst_sel:DWORD dst_unused:UNUSED_PAD src0_sel:WORD_1
	v_pk_mul_f32 v[2:3], v[20:21], v[2:3]
	s_nop 0
	v_cvt_pk_f16_f32 v11, v2, v3
	v_mad_u64_u32 v[2:3], s[6:7], v7, s12, v[168:169]
	ds_read_b128 v[198:201], v2 offset:17408
	ds_read_b128 v[202:205], v2 offset:21760
	ds_read_b128 v[210:213], v2 offset:26112
	ds_read_b128 v[222:225], v2 offset:30464
	ds_read_b128 v[226:229], v2 offset:34816
	ds_read_b128 v[230:233], v2 offset:39168
	ds_read_b128 v[234:237], v2 offset:43520
	ds_read_b128 v[238:241], v2 offset:47872
	ds_read_b128 v[242:245], v2 offset:17472
	ds_read_b128 v[246:249], v2 offset:21824
	s_nop 0
	s_nop 0
	s_nop 0
	s_nop 0
	s_nop 0
	s_nop 0
	s_nop 0
	s_nop 0
	s_nop 0
	s_waitcnt lgkmcnt(9)
	v_mfma_f32_16x16x32_f16 v[12:15], v[198:201], v[8:11], 0
	ds_read_b128 v[198:201], v2 offset:26176
	s_nop 0
	s_waitcnt lgkmcnt(9)
	v_mfma_f32_16x16x32_f16 v[18:21], v[202:205], v[8:11], 0
	ds_read_b128 v[202:205], v2 offset:30528
	s_nop 0
	s_waitcnt lgkmcnt(9)
	v_mfma_f32_16x16x32_f16 v[22:25], v[210:213], v[8:11], 0
	ds_read_b128 v[210:213], v2 offset:34880
	s_nop 0
	s_waitcnt lgkmcnt(9)
	v_mfma_f32_16x16x32_f16 v[26:29], v[222:225], v[8:11], 0
	ds_read_b128 v[222:225], v2 offset:39232
	s_nop 0
	s_waitcnt lgkmcnt(9)
	v_mfma_f32_16x16x32_f16 v[30:33], v[226:229], v[8:11], 0
	ds_read_b128 v[226:229], v2 offset:43584
	s_nop 0
	s_waitcnt lgkmcnt(9)
	v_mfma_f32_16x16x32_f16 v[34:37], v[230:233], v[8:11], 0
	ds_read_b128 v[230:233], v2 offset:47936
	s_nop 0
	s_waitcnt lgkmcnt(9)
	v_mfma_f32_16x16x32_f16 v[38:41], v[234:237], v[8:11], 0
	ds_read_b128 v[234:237], v2 offset:17536
	s_nop 0
	s_waitcnt lgkmcnt(9)
	v_mfma_f32_16x16x32_f16 v[8:11], v[238:241], v[8:11], 0
	ds_read_b128 v[238:241], v2 offset:21888
	ds_read_b128 v[42:45], v4 offset:64
	ds_read_b128 v[46:49], v5 offset:128
	ds_read_b128 v[50:53], v5 offset:144
	s_nop 0
	s_waitcnt lgkmcnt(2)
	v_cvt_f32_f16_e32 v54, v42
	v_cvt_f32_f16_sdwa v55, v42 dst_sel:DWORD dst_unused:UNUSED_PAD src0_sel:WORD_1
	s_nop 0
	s_waitcnt lgkmcnt(1)
	v_pk_mul_f32 v[46:47], v[46:47], v[54:55]
	s_nop 0
	v_cvt_pk_f16_f32 v42, v46, v47
	v_cvt_f32_f16_e32 v46, v44
	v_cvt_f32_f16_sdwa v47, v44 dst_sel:DWORD dst_unused:UNUSED_PAD src0_sel:WORD_1
	s_nop 0
	s_waitcnt lgkmcnt(0)
	v_pk_mul_f32 v[46:47], v[50:51], v[46:47]
	s_nop 0
	v_cvt_pk_f16_f32 v44, v46, v47
	v_cvt_f32_f16_e32 v46, v43
	v_cvt_f32_f16_sdwa v47, v43 dst_sel:DWORD dst_unused:UNUSED_PAD src0_sel:WORD_1
	v_pk_mul_f32 v[46:47], v[48:49], v[46:47]
	s_nop 0
	v_cvt_pk_f16_f32 v43, v46, v47
	v_cvt_f32_f16_e32 v46, v45
	v_cvt_f32_f16_sdwa v47, v45 dst_sel:DWORD dst_unused:UNUSED_PAD src0_sel:WORD_1
	v_pk_mul_f32 v[46:47], v[52:53], v[46:47]
	s_nop 0
	v_cvt_pk_f16_f32 v45, v46, v47
	s_nop 0
	s_nop 0
	v_mfma_f32_16x16x32_f16 v[12:15], v[242:245], v[42:45], v[12:15]
	ds_read_b128 v[242:245], v2 offset:26240
	s_nop 0
	s_nop 0
	v_mfma_f32_16x16x32_f16 v[18:21], v[246:249], v[42:45], v[18:21]
	ds_read_b128 v[246:249], v2 offset:30592
	s_nop 0
	s_nop 0
	v_mfma_f32_16x16x32_f16 v[22:25], v[198:201], v[42:45], v[22:25]
	ds_read_b128 v[198:201], v2 offset:34944
	s_nop 0
	s_nop 0
	v_mfma_f32_16x16x32_f16 v[26:29], v[202:205], v[42:45], v[26:29]
	ds_read_b128 v[202:205], v2 offset:39296
	s_nop 0
	s_nop 0
	v_mfma_f32_16x16x32_f16 v[30:33], v[210:213], v[42:45], v[30:33]
	ds_read_b128 v[210:213], v2 offset:43648
	s_nop 0
	s_nop 0
	v_mfma_f32_16x16x32_f16 v[34:37], v[222:225], v[42:45], v[34:37]
	ds_read_b128 v[222:225], v2 offset:48000
	s_nop 0
	s_nop 0
	v_mfma_f32_16x16x32_f16 v[38:41], v[226:229], v[42:45], v[38:41]
	ds_read_b128 v[226:229], v2 offset:17600
	s_nop 0
	s_nop 0
	v_mfma_f32_16x16x32_f16 v[8:11], v[230:233], v[42:45], v[8:11]
	ds_read_b128 v[230:233], v2 offset:21952
	ds_read_b128 v[42:45], v4 offset:128
	ds_read_b128 v[46:49], v5 offset:256
	ds_read_b128 v[50:53], v5 offset:272
	s_nop 0
	s_waitcnt lgkmcnt(2)
	v_cvt_f32_f16_e32 v54, v42
	v_cvt_f32_f16_sdwa v55, v42 dst_sel:DWORD dst_unused:UNUSED_PAD src0_sel:WORD_1
	s_nop 0
	s_waitcnt lgkmcnt(1)
	v_pk_mul_f32 v[46:47], v[46:47], v[54:55]
	s_nop 0
	v_cvt_pk_f16_f32 v42, v46, v47
	v_cvt_f32_f16_e32 v46, v44
	v_cvt_f32_f16_sdwa v47, v44 dst_sel:DWORD dst_unused:UNUSED_PAD src0_sel:WORD_1
	s_nop 0
	s_waitcnt lgkmcnt(0)
	v_pk_mul_f32 v[46:47], v[50:51], v[46:47]
	s_nop 0
	v_cvt_pk_f16_f32 v44, v46, v47
	v_cvt_f32_f16_e32 v46, v43
	v_cvt_f32_f16_sdwa v47, v43 dst_sel:DWORD dst_unused:UNUSED_PAD src0_sel:WORD_1
	v_pk_mul_f32 v[46:47], v[48:49], v[46:47]
	s_nop 0
	v_cvt_pk_f16_f32 v43, v46, v47
	v_cvt_f32_f16_e32 v46, v45
	v_cvt_f32_f16_sdwa v47, v45 dst_sel:DWORD dst_unused:UNUSED_PAD src0_sel:WORD_1
	v_pk_mul_f32 v[46:47], v[52:53], v[46:47]
	s_nop 0
	v_cvt_pk_f16_f32 v45, v46, v47
	s_nop 0
	s_nop 0
	v_mfma_f32_16x16x32_f16 v[12:15], v[234:237], v[42:45], v[12:15]
	ds_read_b128 v[234:237], v2 offset:26304
	s_nop 0
	s_nop 0
	v_mfma_f32_16x16x32_f16 v[18:21], v[238:241], v[42:45], v[18:21]
	ds_read_b128 v[238:241], v2 offset:30656
	s_nop 0
	s_nop 0
	v_mfma_f32_16x16x32_f16 v[22:25], v[242:245], v[42:45], v[22:25]
	ds_read_b128 v[242:245], v2 offset:35008
	s_nop 0
	s_nop 0
	v_mfma_f32_16x16x32_f16 v[26:29], v[246:249], v[42:45], v[26:29]
	ds_read_b128 v[246:249], v2 offset:39360
	s_nop 0
	s_nop 0
	v_mfma_f32_16x16x32_f16 v[30:33], v[198:201], v[42:45], v[30:33]
	ds_read_b128 v[198:201], v2 offset:48064
	s_nop 0
	s_nop 0
	v_mfma_f32_16x16x32_f16 v[34:37], v[202:205], v[42:45], v[34:37]
	s_nop 0
	s_nop 0
	v_mfma_f32_16x16x32_f16 v[38:41], v[210:213], v[42:45], v[38:41]
	s_nop 0
	s_nop 0
	v_mfma_f32_16x16x32_f16 v[8:11], v[222:225], v[42:45], v[8:11]
	ds_read_b128 v[42:45], v4 offset:192
	ds_read_b128 v[46:49], v5 offset:384
	ds_read_b128 v[50:53], v5 offset:400
	s_nop 0
	s_waitcnt lgkmcnt(2)
	v_cvt_f32_f16_e32 v4, v42
	v_cvt_f32_f16_sdwa v5, v42 dst_sel:DWORD dst_unused:UNUSED_PAD src0_sel:WORD_1
	s_nop 0
	s_waitcnt lgkmcnt(1)
	v_pk_mul_f32 v[4:5], v[46:47], v[4:5]
	s_nop 0
	v_cvt_pk_f16_f32 v42, v4, v5
	v_cvt_f32_f16_e32 v4, v44
	v_cvt_f32_f16_sdwa v5, v44 dst_sel:DWORD dst_unused:UNUSED_PAD src0_sel:WORD_1
	s_nop 0
	s_waitcnt lgkmcnt(0)
	v_pk_mul_f32 v[4:5], v[50:51], v[4:5]
	s_nop 0
	v_cvt_pk_f16_f32 v44, v4, v5
	v_cvt_f32_f16_e32 v4, v43
	v_cvt_f32_f16_sdwa v5, v43 dst_sel:DWORD dst_unused:UNUSED_PAD src0_sel:WORD_1
	v_pk_mul_f32 v[4:5], v[48:49], v[4:5]
	s_nop 0
	v_cvt_pk_f16_f32 v43, v4, v5
	v_cvt_f32_f16_e32 v4, v45
	v_cvt_f32_f16_sdwa v5, v45 dst_sel:DWORD dst_unused:UNUSED_PAD src0_sel:WORD_1
	v_pk_mul_f32 v[4:5], v[52:53], v[4:5]
	s_nop 0
	v_cvt_pk_f16_f32 v45, v4, v5
	s_nop 0
	s_nop 0
	v_mfma_f32_16x16x32_f16 v[12:15], v[226:229], v[42:45], v[12:15]
	s_nop 0
	s_nop 0
	v_mfma_f32_16x16x32_f16 v[18:21], v[230:233], v[42:45], v[18:21]
	s_nop 0
	s_nop 0
	v_mfma_f32_16x16x32_f16 v[22:25], v[234:237], v[42:45], v[22:25]
	s_nop 0
	s_nop 0
	v_mfma_f32_16x16x32_f16 v[26:29], v[238:241], v[42:45], v[26:29]
	s_nop 0
	s_nop 0
	v_mfma_f32_16x16x32_f16 v[30:33], v[242:245], v[42:45], v[30:33]
	s_nop 0
	s_nop 0
	v_mfma_f32_16x16x32_f16 v[34:37], v[246:249], v[42:45], v[34:37]
	ds_read_b128 v[46:49], v2 offset:43712
	s_nop 0
	s_nop 0
	v_mfma_f32_16x16x32_f16 v[2:5], v[198:201], v[42:45], v[8:11]
	s_nop 2
	v_cvt_pk_f16_f32 v9, v14, v15
	v_cvt_pk_f16_f32 v8, v12, v13
	v_lshl_add_u64 v[10:11], v[0:1], 0, s[4:5]
	global_store_dwordx2 v[10:11], v[8:9], off
	v_cvt_pk_f16_f32 v9, v20, v21
	v_cvt_pk_f16_f32 v8, v18, v19
	s_waitcnt lgkmcnt(0)
	v_mfma_f32_16x16x32_f16 v[38:41], v[46:49], v[42:45], v[38:41]
	global_store_dwordx2 v[10:11], v[8:9], off offset:32
	v_cvt_pk_f16_f32 v9, v24, v25
	v_cvt_pk_f16_f32 v8, v22, v23
	global_store_dwordx2 v[10:11], v[8:9], off offset:64
	v_cvt_pk_f16_f32 v9, v28, v29
	v_cvt_pk_f16_f32 v8, v26, v27
	global_store_dwordx2 v[10:11], v[8:9], off offset:96
	v_cvt_pk_f16_f32 v9, v32, v33
	v_cvt_pk_f16_f32 v8, v30, v31
	global_store_dwordx2 v[10:11], v[8:9], off offset:128
	v_cvt_pk_f16_f32 v9, v36, v37
	v_cvt_pk_f16_f32 v8, v34, v35
	global_store_dwordx2 v[10:11], v[8:9], off offset:160
	v_cvt_pk_f16_f32 v9, v40, v41
	v_cvt_pk_f16_f32 v8, v38, v39
	v_cvt_pk_f16_f32 v5, v4, v5
	v_cvt_pk_f16_f32 v4, v2, v3
	s_mov_b64 s[4:5], 0
	global_store_dwordx2 v[10:11], v[8:9], off offset:192
	global_store_dwordx2 v[10:11], v[4:5], off offset:224
	s_cbranch_vccz .LBB0_160

.LBB0_165:
	s_or_b64 exec, exec, s[6:7]
	s_movk_i32 s12, 0x110
	v_mad_u64_u32 v[132:133], s[6:7], v82, s12, v[168:169]
	v_mad_u64_u32 v[134:135], s[6:7], v84, s12, v[168:169]
	v_mad_u64_u32 v[136:137], s[6:7], v86, s12, v[168:169]
	v_mad_u64_u32 v[138:139], s[6:7], v88, s12, v[168:169]
	v_mad_u64_u32 v[140:141], s[6:7], v90, s12, v[168:169]
	v_mad_u64_u32 v[142:143], s[6:7], v92, s12, v[168:169]
	v_mad_u64_u32 v[144:145], s[6:7], v94, s12, v[168:169]
	v_mad_u64_u32 v[146:147], s[6:7], v96, s12, v[168:169]
	s_mov_b32 s5, s1
	s_lshl_b64 s[6:7], s[4:5], 10
	v_readlane_b32 s0, v254, 18
	s_add_u32 s0, s0, s6
	v_readlane_b32 s6, v254, 19
	s_addc_u32 s6, s6, s7
	s_lshl_b32 s7, s9, 17
	s_add_u32 s0, s0, s7
	s_addc_u32 s7, s6, 0
	s_lshl_b32 s10, s10, 1
	s_add_u32 s6, s0, s10
	s_addc_u32 s7, s7, 0
	s_lshl_b64 s[4:5], s[4:5], 9
	v_readlane_b32 s0, v254, 20
	s_add_u32 s0, s0, s4
	v_readlane_b32 s4, v254, 21
	s_addc_u32 s4, s4, s5
	s_lshl_b32 s5, s11, 11
	s_add_u32 s0, s0, s5
	s_addc_u32 s5, s4, 0
	s_add_u32 s4, s0, s10
	v_bfe_u32 v164, v80, 4, 2
	s_addc_u32 s5, s5, 0
	v_and_b32_e32 v162, 15, v80
	s_waitcnt vmcnt(15)
	ds_write_b128 v132, v[0:3]
	s_waitcnt vmcnt(14)
	ds_write_b128 v132, v[4:7] offset:34816
	s_waitcnt vmcnt(13)
	ds_write_b128 v134, v[8:11]
	s_waitcnt vmcnt(12)
	ds_write_b128 v134, v[12:15] offset:34816
	s_waitcnt vmcnt(11)
	ds_write_b128 v136, v[16:19]
	s_waitcnt vmcnt(10)
	ds_write_b128 v136, v[20:23] offset:34816
	s_waitcnt vmcnt(9)
	ds_write_b128 v138, v[24:27]
	s_waitcnt vmcnt(8)
	ds_write_b128 v138, v[28:31] offset:34816
	s_waitcnt vmcnt(7)
	ds_write_b128 v140, v[32:35]
	s_waitcnt vmcnt(6)
	ds_write_b128 v140, v[36:39] offset:34816
	s_waitcnt vmcnt(5)
	ds_write_b128 v142, v[40:43]
	s_waitcnt vmcnt(4)
	ds_write_b128 v142, v[44:47] offset:34816
	v_lshl_add_u64 v[12:13], s[6:7], 0, v[168:169]
	v_lshlrev_b64 v[16:17], 1, v[64:65]
	v_lshlrev_b64 v[20:21], 1, v[70:71]
	v_lshlrev_b64 v[24:25], 1, v[74:75]
	v_lshlrev_b64 v[28:29], 1, v[78:79]
	v_lshl_add_u64 v[44:45], s[4:5], 0, v[168:169]
	v_lshlrev_b32_e32 v168, 4, v164
	s_waitcnt vmcnt(3)
	ds_write_b128 v144, v[48:51]
	s_waitcnt vmcnt(2)
	ds_write_b128 v144, v[52:55] offset:34816
	s_waitcnt vmcnt(1)
	ds_write_b128 v146, v[56:59]
	s_waitcnt vmcnt(0)
	ds_write_b128 v146, v[60:63] offset:34816
	v_lshl_add_u64 v[0:1], v[12:13], 0, v[16:17]
	v_lshl_add_u64 v[4:5], v[12:13], 0, v[20:21]
	v_lshl_add_u64 v[8:9], v[12:13], 0, v[24:25]
	v_lshl_add_u64 v[12:13], v[12:13], 0, v[28:29]
	v_lshl_add_u64 v[16:17], v[44:45], 0, v[16:17]
	v_lshl_add_u64 v[20:21], v[44:45], 0, v[20:21]
	v_lshl_add_u64 v[24:25], v[44:45], 0, v[24:25]
	v_lshl_add_u64 v[28:29], v[44:45], 0, v[28:29]
	v_lshl_add_u64 v[32:33], v[66:67], 1, v[44:45]
	v_lshl_add_u64 v[36:37], v[68:69], 1, v[44:45]
	v_lshl_add_u64 v[40:41], v[72:73], 1, v[44:45]
	v_lshl_add_u64 v[44:45], v[76:77], 1, v[44:45]
	v_mad_u32_u24 v60, v162, s12, v168
	v_ashrrev_i32_e32 v163, 6, v80
	global_load_dwordx4 v[0:3], v[0:1], off
	v_lshl_or_b32 v135, v163, 5, v162
	global_load_dwordx4 v[4:7], v[4:5], off
	v_mad_u64_u32 v[56:57], s[4:5], v135, s12, v[168:169]
	global_load_dwordx4 v[8:11], v[8:9], off
	v_or_b32_e32 v133, 16, v135
	global_load_dwordx4 v[12:15], v[12:13], off
	v_lshlrev_b32_e32 v147, 2, v164
	global_load_dwordx4 v[16:19], v[16:17], off
	s_movk_i32 s0, 0xffef
	global_load_dwordx4 v[20:23], v[20:21], off
	s_nop 0
	global_load_dwordx4 v[24:27], v[24:25], off
	s_nop 0
	global_load_dwordx4 v[28:31], v[28:29], off
	s_nop 0
	global_load_dwordx4 v[32:35], v[32:33], off
	s_nop 0
	global_load_dwordx4 v[36:39], v[36:37], off
	s_nop 0
	global_load_dwordx4 v[40:43], v[40:41], off
	s_nop 0
	global_load_dwordx4 v[44:47], v[44:45], off
	s_waitcnt lgkmcnt(0)
	s_barrier
	ds_read_b128 v[198:201], v60 offset:34816
	ds_read_b128 v[202:205], v60 offset:39168
	ds_read_b128 v[210:213], v60 offset:43520
	ds_read_b128 v[222:225], v60 offset:47872
	ds_read_b128 v[226:229], v60 offset:52224
	ds_read_b128 v[230:233], v60 offset:56576
	ds_read_b128 v[234:237], v60 offset:60928
	ds_read_b128 v[238:241], v60 offset:65280
	ds_read_b128 v[242:245], v56
	ds_read_b128 v[246:249], v56 offset:4352
	s_nop 0
	s_nop 0
	s_nop 0
	s_nop 0
	s_nop 0
	s_nop 0
	s_nop 0
	s_nop 0
	s_nop 0
	s_nop 0
	s_waitcnt lgkmcnt(10)
	s_waitcnt lgkmcnt(1)
	v_mfma_f32_16x16x32_f16 v[66:69], v[198:201], v[242:245], 0
	s_nop 0
	s_waitcnt lgkmcnt(0)
	v_mfma_f32_16x16x32_f16 v[62:65], v[198:201], v[246:249], 0
	ds_read_b128 v[198:201], v56 offset:64
	v_mfma_f32_16x16x32_f16 v[74:77], v[202:205], v[242:245], 0
	v_mfma_f32_16x16x32_f16 v[70:73], v[202:205], v[246:249], 0
	ds_read_b128 v[202:205], v56 offset:4416
	v_mfma_f32_16x16x32_f16 v[82:85], v[210:213], v[242:245], 0
	v_mfma_f32_16x16x32_f16 v[78:81], v[210:213], v[246:249], 0
	ds_read_b128 v[210:213], v60 offset:34880
	v_mfma_f32_16x16x32_f16 v[90:93], v[222:225], v[242:245], 0
	v_mfma_f32_16x16x32_f16 v[86:89], v[222:225], v[246:249], 0
	ds_read_b128 v[222:225], v60 offset:39232
	v_mfma_f32_16x16x32_f16 v[98:101], v[226:229], v[242:245], 0
	v_mfma_f32_16x16x32_f16 v[94:97], v[226:229], v[246:249], 0
	ds_read_b128 v[226:229], v60 offset:43584
	v_mfma_f32_16x16x32_f16 v[106:109], v[230:233], v[242:245], 0
	v_mfma_f32_16x16x32_f16 v[102:105], v[230:233], v[246:249], 0
	ds_read_b128 v[230:233], v60 offset:47936
	v_mfma_f32_16x16x32_f16 v[114:117], v[234:237], v[242:245], 0
	v_mfma_f32_16x16x32_f16 v[110:113], v[234:237], v[246:249], 0
	ds_read_b128 v[234:237], v60 offset:52288
	v_mfma_f32_16x16x32_f16 v[48:51], v[238:241], v[242:245], 0
	ds_read_b128 v[242:245], v60 offset:56640
	v_mfma_f32_16x16x32_f16 v[52:55], v[238:241], v[246:249], 0
	ds_read_b128 v[238:241], v60 offset:60992
	ds_read_b128 v[246:249], v60 offset:65344
	s_nop 0
	s_nop 0
	s_nop 0
	s_nop 0
	s_waitcnt lgkmcnt(7)
	v_mfma_f32_16x16x32_f16 v[66:69], v[210:213], v[198:201], v[66:69]
	v_mfma_f32_16x16x32_f16 v[62:65], v[210:213], v[202:205], v[62:65]
	ds_read_b128 v[210:213], v60 offset:34944
	s_nop 0
	s_nop 0
	s_waitcnt lgkmcnt(7)
	v_mfma_f32_16x16x32_f16 v[74:77], v[222:225], v[198:201], v[74:77]
	v_mfma_f32_16x16x32_f16 v[70:73], v[222:225], v[202:205], v[70:73]
	ds_read_b128 v[222:225], v60 offset:39296
	s_nop 0
	s_nop 0
	s_waitcnt lgkmcnt(7)
	v_mfma_f32_16x16x32_f16 v[82:85], v[226:229], v[198:201], v[82:85]
	v_mfma_f32_16x16x32_f16 v[78:81], v[226:229], v[202:205], v[78:81]
	ds_read_b128 v[226:229], v60 offset:43648
	s_nop 0
	s_nop 0
	s_waitcnt lgkmcnt(7)
	v_mfma_f32_16x16x32_f16 v[90:93], v[230:233], v[198:201], v[90:93]
	v_mfma_f32_16x16x32_f16 v[86:89], v[230:233], v[202:205], v[86:89]
	ds_read_b128 v[230:233], v60 offset:48000
	s_nop 0
	s_nop 0
	s_waitcnt lgkmcnt(7)
	v_mfma_f32_16x16x32_f16 v[98:101], v[234:237], v[198:201], v[98:101]
	v_mfma_f32_16x16x32_f16 v[94:97], v[234:237], v[202:205], v[94:97]
	ds_read_b128 v[234:237], v60 offset:52352
	s_nop 0
	s_nop 0
	s_waitcnt lgkmcnt(7)
	v_mfma_f32_16x16x32_f16 v[106:109], v[242:245], v[198:201], v[106:109]
	v_mfma_f32_16x16x32_f16 v[102:105], v[242:245], v[202:205], v[102:105]
	ds_read_b128 v[242:245], v60 offset:56704
	s_nop 0
	s_nop 0
	s_waitcnt lgkmcnt(7)
	v_mfma_f32_16x16x32_f16 v[114:117], v[238:241], v[198:201], v[114:117]
	v_mfma_f32_16x16x32_f16 v[110:113], v[238:241], v[202:205], v[110:113]
	ds_read_b128 v[238:241], v60 offset:61056
	s_nop 0
	s_nop 0
	s_waitcnt lgkmcnt(7)
	v_mfma_f32_16x16x32_f16 v[48:51], v[246:249], v[198:201], v[48:51]
	ds_read_b128 v[198:201], v60 offset:35008
	v_mfma_f32_16x16x32_f16 v[52:55], v[246:249], v[202:205], v[52:55]
	ds_read_b128 v[202:205], v60 offset:61120
	ds_read_b128 v[246:249], v60 offset:39360
	ds_read_b128 v[118:121], v56 offset:128
	ds_read_b128 v[122:125], v56 offset:4480
	s_nop 0
	s_nop 0
	s_waitcnt lgkmcnt(1)
	v_mfma_f32_16x16x32_f16 v[66:69], v[210:213], v[118:121], v[66:69]
	s_waitcnt lgkmcnt(0)
	v_mfma_f32_16x16x32_f16 v[62:65], v[210:213], v[122:125], v[62:65]
	ds_read_b128 v[210:213], v60 offset:43712
	s_nop 0
	s_nop 0
	v_mfma_f32_16x16x32_f16 v[74:77], v[222:225], v[118:121], v[74:77]
	v_mfma_f32_16x16x32_f16 v[70:73], v[222:225], v[122:125], v[70:73]
	ds_read_b128 v[222:225], v60 offset:48064
	s_nop 0
	s_nop 0
	v_mfma_f32_16x16x32_f16 v[148:151], v[226:229], v[118:121], v[82:85]
	v_mfma_f32_16x16x32_f16 v[126:129], v[226:229], v[122:125], v[78:81]
	ds_read_b128 v[226:229], v60 offset:52416
	s_nop 2
	s_nop 0
	s_nop 0
	v_mfma_f32_16x16x32_f16 v[152:155], v[230:233], v[118:121], v[90:93]
	v_mfma_f32_16x16x32_f16 v[84:87], v[230:233], v[122:125], v[86:89]
	ds_read_b128 v[230:233], v60 offset:56768
	s_nop 0
	s_nop 0
	v_mfma_f32_16x16x32_f16 v[156:159], v[234:237], v[118:121], v[98:101]
	v_mfma_f32_16x16x32_f16 v[174:177], v[234:237], v[122:125], v[94:97]
	s_nop 0
	s_nop 0
	v_mfma_f32_16x16x32_f16 v[178:181], v[242:245], v[118:121], v[106:109]
	v_mfma_f32_16x16x32_f16 v[182:185], v[242:245], v[122:125], v[102:105]
	s_nop 0
	s_nop 0
	v_mfma_f32_16x16x32_f16 v[186:189], v[238:241], v[118:121], v[114:117]
	v_mfma_f32_16x16x32_f16 v[190:193], v[238:241], v[122:125], v[110:113]
	ds_read_b128 v[78:81], v60 offset:65408
	s_nop 0
	s_waitcnt lgkmcnt(0)
	v_mfma_f32_16x16x32_f16 v[116:119], v[78:81], v[118:121], v[48:51]
	v_mfma_f32_16x16x32_f16 v[52:55], v[78:81], v[122:125], v[52:55]
	ds_read_b128 v[120:123], v56 offset:192
	ds_read_b128 v[194:197], v56 offset:4544
	s_nop 0
	s_nop 0
	s_nop 0
	s_waitcnt lgkmcnt(1)
	v_mfma_f32_16x16x32_f16 v[92:95], v[198:201], v[120:123], v[66:69]
	s_waitcnt lgkmcnt(0)
	v_mfma_f32_16x16x32_f16 v[80:83], v[198:201], v[194:197], v[62:65]
	s_nop 0
	s_nop 0
	v_mfma_f32_16x16x32_f16 v[112:115], v[246:249], v[120:123], v[74:77]
	ds_read_b128 v[64:67], v60 offset:65472
	v_mfma_f32_16x16x32_f16 v[108:111], v[246:249], v[194:197], v[70:73]
	s_nop 0
	s_nop 0
	v_mfma_f32_16x16x32_f16 v[88:91], v[210:213], v[120:123], v[148:151]
	v_mfma_f32_16x16x32_f16 v[100:103], v[210:213], v[194:197], v[126:129]
	s_nop 0
	s_nop 0
	v_mfma_f32_16x16x32_f16 v[104:107], v[222:225], v[120:123], v[152:155]
	v_mfma_f32_16x16x32_f16 v[96:99], v[222:225], v[194:197], v[84:87]
	s_nop 0
	s_nop 0
	v_mfma_f32_16x16x32_f16 v[68:71], v[226:229], v[120:123], v[156:159]
	v_mfma_f32_16x16x32_f16 v[76:79], v[226:229], v[194:197], v[174:177]
	s_nop 0
	s_waitcnt lgkmcnt(0)
	v_mfma_f32_16x16x32_f16 v[60:63], v[64:67], v[120:123], v[116:119]
	v_mfma_f32_16x16x32_f16 v[52:55], v[64:67], v[194:197], v[52:55]
	v_lshlrev_b32_e32 v64, 2, v135
	v_add_u32_e32 v65, 0x11000, v64
	v_add_u32_e32 v64, 0x11200, v64
	s_nop 0
	v_mfma_f32_16x16x32_f16 v[84:87], v[230:233], v[120:123], v[178:181]
	ds_read_b32 v137, v65
	v_or_b32_e32 v116, 0x11200, v168
	ds_read_b128 v[124:127], v116
	v_mfma_f32_16x16x32_f16 v[72:75], v[230:233], v[194:197], v[182:185]
	v_or_b32_e32 v116, 0x11400, v168
	ds_read_b128 v[116:119], v116
	v_mfma_f32_16x16x32_f16 v[48:51], v[202:205], v[120:123], v[186:189]
	v_or_b32_e32 v120, 0x11600, v168
	ds_read_b128 v[120:123], v120
	ds_read_b32 v139, v64
	v_lshlrev_b32_e32 v64, 2, v133
	v_add_u32_e32 v65, 0x11000, v64
	v_add_u32_e32 v64, 0x11200, v64
	ds_read_b32 v141, v65
	ds_read_b32 v143, v64
	v_or_b32_e32 v64, 0x11000, v168
	ds_read_b128 v[64:67], v64
	v_mfma_f32_16x16x32_f16 v[56:59], v[202:205], v[194:197], v[190:193]
	s_nop 0
	s_waitcnt lgkmcnt(0)
	v_sub_f32_e32 v128, v137, v64
	v_sub_f32_e32 v64, v141, v64
	v_min_f32_e32 v64, 0, v64
	v_mul_f32_e32 v64, 0x3fb8aa3b, v64
	v_exp_f32_e32 v152, v64
	v_sub_f32_e32 v64, v143, v124
	v_min_f32_e32 v64, 0, v64
	v_mul_f32_e32 v64, 0x3fb8aa3b, v64
	v_exp_f32_e32 v156, v64
	v_sub_f32_e32 v64, v137, v65
	v_min_f32_e32 v64, 0, v64
	v_mul_f32_e32 v64, 0x3fb8aa3b, v64
	v_exp_f32_e32 v149, v64
	v_sub_f32_e32 v64, v139, v125
	v_min_f32_e32 v64, 0, v64
	v_mul_f32_e32 v64, 0x3fb8aa3b, v64
	v_exp_f32_e32 v167, v64
	v_sub_f32_e32 v64, v141, v65
	v_min_f32_e32 v64, 0, v64
	v_mul_f32_e32 v64, 0x3fb8aa3b, v64
	v_exp_f32_e32 v153, v64
	v_sub_f32_e32 v64, v143, v125
	v_min_f32_e32 v64, 0, v64
	v_mul_f32_e32 v64, 0x3fb8aa3b, v64
	v_exp_f32_e32 v157, v64
	v_sub_f32_e32 v64, v137, v66
	v_min_f32_e32 v64, 0, v64
	v_mul_f32_e32 v64, 0x3fb8aa3b, v64
	v_exp_f32_e32 v150, v64
	v_sub_f32_e32 v64, v139, v126
	v_min_f32_e32 v64, 0, v64
	v_mul_f32_e32 v64, 0x3fb8aa3b, v64
	v_exp_f32_e32 v154, v64
	v_sub_f32_e32 v64, v141, v66
	v_min_f32_e32 v64, 0, v64
	v_mul_f32_e32 v64, 0x3fb8aa3b, v64
	v_exp_f32_e32 v158, v64
	v_sub_f32_e32 v64, v143, v126
	v_min_f32_e32 v64, 0, v64
	v_mul_f32_e32 v64, 0x3fb8aa3b, v64
	v_exp_f32_e32 v160, v64
	v_sub_f32_e32 v64, v137, v67
	v_min_f32_e32 v64, 0, v64
	v_mul_f32_e32 v64, 0x3fb8aa3b, v64
	v_exp_f32_e32 v151, v64
	v_sub_f32_e32 v64, v139, v127
	v_min_f32_e32 v64, 0, v64
	v_mul_f32_e32 v64, 0x3fb8aa3b, v64
	v_exp_f32_e32 v155, v64
	v_sub_f32_e32 v64, v141, v67
	v_min_f32_e32 v64, 0, v64
	v_mul_f32_e32 v64, 0x3fb8aa3b, v64
	v_exp_f32_e32 v159, v64
	v_sub_f32_e32 v64, v143, v127
	v_min_f32_e32 v64, 0, v64
	v_mul_f32_e32 v64, 0x3fb8aa3b, v64
	v_exp_f32_e32 v161, v64
	v_or_b32_e32 v64, 0x11040, v168
	v_min_f32_e32 v128, 0, v128
	ds_read_b128 v[64:67], v64
	v_mul_f32_e32 v128, 0x3fb8aa3b, v128
	v_exp_f32_e32 v148, v128
	v_sub_f32_e32 v128, v139, v124
	v_or_b32_e32 v124, 0x11240, v168
	ds_read_b128 v[174:177], v124
	v_min_f32_e32 v128, 0, v128
	s_nop 0
	s_waitcnt lgkmcnt(1)
	v_sub_f32_e32 v145, v137, v64
	v_mul_f32_e32 v128, 0x3fb8aa3b, v128
	v_min_f32_e32 v145, 0, v145
	v_exp_f32_e32 v166, v128
	v_or_b32_e32 v128, 0x11640, v168
	v_mul_f32_e32 v145, 0x3fb8aa3b, v145
	ds_read_b128 v[128:131], v128
	v_exp_f32_e32 v178, v145
	s_nop 0
	s_waitcnt lgkmcnt(1)
	v_sub_f32_e32 v145, v139, v174
	v_min_f32_e32 v145, 0, v145
	v_mul_f32_e32 v145, 0x3fb8aa3b, v145
	v_exp_f32_e32 v180, v145
	v_sub_f32_e32 v145, v143, v174
	v_min_f32_e32 v145, 0, v145
	v_mul_f32_e32 v145, 0x3fb8aa3b, v145
	v_exp_f32_e32 v174, v145
	v_sub_f32_e32 v145, v137, v65
	v_min_f32_e32 v145, 0, v145
	v_mul_f32_e32 v145, 0x3fb8aa3b, v145
	v_exp_f32_e32 v179, v145
	v_sub_f32_e32 v145, v139, v175
	v_min_f32_e32 v145, 0, v145
	v_mul_f32_e32 v145, 0x3fb8aa3b, v145
	v_exp_f32_e32 v181, v145
	v_sub_f32_e32 v145, v143, v175
	v_min_f32_e32 v145, 0, v145
	v_mul_f32_e32 v145, 0x3fb8aa3b, v145
	v_exp_f32_e32 v175, v145
	v_sub_f32_e32 v145, v137, v66
	v_sub_f32_e32 v66, v141, v66
	v_min_f32_e32 v66, 0, v66
	v_mul_f32_e32 v66, 0x3fb8aa3b, v66
	v_exp_f32_e32 v186, v66
	v_sub_f32_e32 v66, v143, v176
	v_min_f32_e32 v145, 0, v145
	v_min_f32_e32 v66, 0, v66
	v_mul_f32_e32 v145, 0x3fb8aa3b, v145
	v_mul_f32_e32 v66, 0x3fb8aa3b, v66
	v_exp_f32_e32 v182, v145
	v_sub_f32_e32 v145, v139, v176
	v_exp_f32_e32 v176, v66
	v_sub_f32_e32 v66, v137, v67
	v_min_f32_e32 v66, 0, v66
	v_mul_f32_e32 v66, 0x3fb8aa3b, v66
	v_exp_f32_e32 v183, v66
	v_sub_f32_e32 v66, v139, v177
	v_min_f32_e32 v66, 0, v66
	v_mul_f32_e32 v66, 0x3fb8aa3b, v66
	v_exp_f32_e32 v185, v66
	v_sub_f32_e32 v66, v141, v67
	v_min_f32_e32 v66, 0, v66
	v_mul_f32_e32 v66, 0x3fb8aa3b, v66
	v_or_b32_e32 v124, 0x11440, v168
	v_sub_f32_e32 v64, v141, v64
	v_sub_f32_e32 v65, v141, v65
	v_min_f32_e32 v145, 0, v145
	v_exp_f32_e32 v187, v66
	v_sub_f32_e32 v66, v143, v177
	ds_read_b128 v[124:127], v124
	v_min_f32_e32 v64, 0, v64
	v_min_f32_e32 v65, 0, v65
	v_mul_f32_e32 v145, 0x3fb8aa3b, v145
	v_min_f32_e32 v66, 0, v66
	v_mul_f32_e32 v64, 0x3fb8aa3b, v64
	v_mul_f32_e32 v65, 0x3fb8aa3b, v65
	v_exp_f32_e32 v184, v145
	v_mul_f32_e32 v66, 0x3fb8aa3b, v66
	v_sub_u32_e32 v145, v147, v135
	v_exp_f32_e32 v64, v64
	v_exp_f32_e32 v65, v65
	v_exp_f32_e32 v177, v66
	v_add_u32_e32 v66, -1, v145
	v_cmp_lt_i32_e32 vcc, -1, v145
	v_cmp_lt_i32_e64 s[36:37], -2, v145
	v_lshrrev_b32_e32 v66, 31, v66
	v_lshrrev_b32_e32 v67, 31, v145
	v_cndmask_b32_e64 v189, 0, 1.0, s[36:37]
	v_cndmask_b32_e64 v188, 0, 1.0, vcc
	v_cvt_f32_ubyte0_e32 v67, v67
	v_cvt_f32_ubyte0_e32 v66, v66
	s_nop 0
	s_waitcnt lgkmcnt(1)
	v_pk_mul_f32 v[192:193], v[128:129], v[188:189]
	s_nop 0
	s_waitcnt lgkmcnt(0)
	v_pk_mul_f32 v[190:191], v[124:125], v[66:67]
	v_pk_mul_f32 v[174:175], v[192:193], v[174:175]
	v_cmp_lt_i32_e32 vcc, s0, v145
	v_pk_fma_f32 v[64:65], v[190:191], v[64:65], v[174:175]
	s_movk_i32 s0, 0xffee
	v_pk_mul_f32 v[108:109], v[108:109], v[64:65]
	v_pk_mul_f32 v[64:65], v[116:117], v[66:67]
	v_pk_mul_f32 v[66:67], v[120:121], v[188:189]
	v_cmp_lt_i32_e64 s[36:37], s0, v145
	v_pk_mul_f32 v[66:67], v[66:67], v[166:167]
	s_movk_i32 s0, 0xffed
	v_pk_fma_f32 v[64:65], v[64:65], v[148:149], v[66:67]
	v_add_u32_e32 v66, 15, v145
	v_pk_mul_f32 v[64:65], v[92:93], v[64:65]
	v_lshrrev_b32_e32 v66, 31, v66
	v_cvt_pk_f16_f32 v64, v64, v65
	v_add_u32_e32 v65, 16, v145
	v_lshrrev_b32_e32 v65, 31, v65
	v_cvt_f32_ubyte0_e32 v93, v65
	v_cvt_f32_ubyte0_e32 v92, v66
	v_cndmask_b32_e64 v149, 0, 1.0, s[36:37]
	v_cndmask_b32_e64 v148, 0, 1.0, vcc
	v_pk_mul_f32 v[66:67], v[124:125], v[92:93]
	v_pk_mul_f32 v[124:125], v[128:129], v[148:149]
	v_cmp_lt_i32_e32 vcc, s0, v145
	v_pk_mul_f32 v[124:125], v[124:125], v[180:181]
	s_movk_i32 s0, 0xffec
	v_pk_fma_f32 v[66:67], v[66:67], v[178:179], v[124:125]
	v_add_u32_e32 v65, 18, v145
	v_pk_mul_f32 v[66:67], v[112:113], v[66:67]
	v_cmp_lt_i32_e64 s[36:37], s0, v145
	v_cvt_pk_f16_f32 v66, v66, v67
	v_add_u32_e32 v67, 17, v145
	v_lshrrev_b32_e32 v67, 31, v67
	v_lshrrev_b32_e32 v65, 31, v65
	v_cndmask_b32_e64 v129, 0, 1.0, s[36:37]
	v_cndmask_b32_e64 v128, 0, 1.0, vcc
	v_cvt_f32_ubyte0_e32 v125, v65
	v_cvt_f32_ubyte0_e32 v124, v67
	v_pk_mul_f32 v[166:167], v[130:131], v[128:129]
	v_pk_mul_f32 v[112:113], v[126:127], v[124:125]
	v_pk_mul_f32 v[166:167], v[166:167], v[184:185]
	v_add_u32_e32 v65, -16, v145
	v_pk_fma_f32 v[112:113], v[112:113], v[182:183], v[166:167]
	v_lshrrev_b32_e32 v65, 31, v65
	v_pk_mul_f32 v[112:113], v[114:115], v[112:113]
	v_sub_u32_e32 v114, 15, v145
	v_cvt_pk_f16_f32 v67, v112, v113
	v_cvt_f32_ubyte0_e32 v113, v65
	v_sub_u32_e32 v65, 14, v145
	v_subrev_u32_e32 v112, 17, v145
	v_lshrrev_b32_e32 v114, 31, v114
	v_lshrrev_b32_e32 v65, 31, v65
	v_lshrrev_b32_e32 v112, 31, v112
	v_cvt_f32_ubyte0_e32 v115, v65
	v_cvt_f32_ubyte0_e32 v114, v114
	v_cvt_f32_ubyte0_e32 v112, v112
	v_pk_mul_f32 v[114:115], v[120:121], v[114:115]
	v_pk_mul_f32 v[112:113], v[116:117], v[112:113]
	v_pk_mul_f32 v[114:115], v[114:115], v[156:157]
	v_add_u32_e32 v65, -14, v145
	v_pk_fma_f32 v[112:113], v[112:113], v[152:153], v[114:115]
	v_lshrrev_b32_e32 v65, 31, v65
	v_pk_mul_f32 v[80:81], v[80:81], v[112:113]
	v_cvt_f32_ubyte0_e32 v113, v65
	v_cvt_pk_f16_f32 v80, v80, v81
	v_add_u32_e32 v81, -15, v145
	v_lshrrev_b32_e32 v81, 31, v81
	v_cvt_f32_ubyte0_e32 v112, v81
	v_sub_u32_e32 v65, 12, v145
	v_sub_u32_e32 v81, 13, v145
	v_lshrrev_b32_e32 v81, 31, v81
	v_lshrrev_b32_e32 v65, 31, v65
	v_cvt_f32_ubyte0_e32 v115, v65
	v_cvt_f32_ubyte0_e32 v114, v81
	v_pk_mul_f32 v[114:115], v[122:123], v[114:115]
	v_pk_mul_f32 v[112:113], v[118:119], v[112:113]
	v_pk_mul_f32 v[114:115], v[114:115], v[160:161]
	v_add_u32_e32 v65, 2, v145
	v_pk_fma_f32 v[112:113], v[112:113], v[158:159], v[114:115]
	v_cmp_lt_i32_e32 vcc, -3, v145
	v_pk_mul_f32 v[82:83], v[82:83], v[112:113]
	v_cmp_lt_i32_e64 s[36:37], -4, v145
	v_cvt_pk_f16_f32 v81, v82, v83
	v_add_u32_e32 v83, 1, v145
	v_lshrrev_b32_e32 v83, 31, v83
	v_lshrrev_b32_e32 v65, 31, v65
	v_cndmask_b32_e64 v113, 0, 1.0, s[36:37]
	v_cndmask_b32_e64 v112, 0, 1.0, vcc
	v_cvt_pk_f16_f32 v82, v108, v109
	v_cvt_f32_ubyte0_e32 v109, v65
	v_cvt_f32_ubyte0_e32 v108, v83
	v_pk_mul_f32 v[116:117], v[130:131], v[112:113]
	v_pk_mul_f32 v[112:113], v[122:123], v[112:113]
	v_pk_mul_f32 v[114:115], v[126:127], v[108:109]
	v_pk_mul_f32 v[116:117], v[116:117], v[176:177]
	v_pk_mul_f32 v[108:109], v[118:119], v[108:109]
	v_pk_mul_f32 v[112:113], v[112:113], v[154:155]
	v_pk_fma_f32 v[114:115], v[114:115], v[186:187], v[116:117]
	v_pk_fma_f32 v[108:109], v[108:109], v[150:151], v[112:113]
	v_pk_mul_f32 v[110:111], v[110:111], v[114:115]
	v_pk_mul_f32 v[94:95], v[94:95], v[108:109]
	v_cvt_pk_f16_f32 v83, v110, v111
	v_cvt_pk_f16_f32 v65, v94, v95
	v_or_b32_e32 v94, 0x11080, v168
	v_or_b32_e32 v95, 0x11280, v168
	ds_read_b128 v[116:119], v94
	ds_read_b128 v[120:123], v95
	v_or_b32_e32 v94, 0x11480, v168
	v_or_b32_e32 v95, 0x11680, v168
	ds_read_b128 v[112:115], v94
	ds_read_b128 v[108:111], v95
	s_waitcnt lgkmcnt(3)
	v_sub_f32_e32 v94, v137, v116
	v_min_f32_e32 v94, 0, v94
	v_mul_f32_e32 v94, 0x3fb8aa3b, v94
	v_exp_f32_e32 v150, v94
	s_waitcnt lgkmcnt(2)
	v_sub_f32_e32 v94, v139, v120
	v_min_f32_e32 v94, 0, v94
	v_mul_f32_e32 v94, 0x3fb8aa3b, v94
	v_exp_f32_e32 v160, v94
	v_sub_f32_e32 v94, v141, v116
	v_min_f32_e32 v94, 0, v94
	v_mul_f32_e32 v94, 0x3fb8aa3b, v94
	v_exp_f32_e32 v166, v94
	v_sub_f32_e32 v94, v143, v120
	v_min_f32_e32 v94, 0, v94
	v_mul_f32_e32 v94, 0x3fb8aa3b, v94
	v_exp_f32_e32 v174, v94
	v_sub_f32_e32 v94, v137, v117
	v_min_f32_e32 v94, 0, v94
	v_mul_f32_e32 v94, 0x3fb8aa3b, v94
	v_exp_f32_e32 v151, v94
	v_sub_f32_e32 v94, v139, v121
	v_min_f32_e32 v94, 0, v94
	v_mul_f32_e32 v94, 0x3fb8aa3b, v94
	v_exp_f32_e32 v161, v94
	v_sub_f32_e32 v94, v141, v117
	v_min_f32_e32 v94, 0, v94
	v_mul_f32_e32 v94, 0x3fb8aa3b, v94
	v_exp_f32_e32 v167, v94
	v_sub_f32_e32 v94, v143, v121
	v_min_f32_e32 v94, 0, v94
	v_mul_f32_e32 v94, 0x3fb8aa3b, v94
	v_exp_f32_e32 v175, v94
	v_sub_f32_e32 v94, v137, v118
	v_min_f32_e32 v94, 0, v94
	v_mul_f32_e32 v94, 0x3fb8aa3b, v94
	v_exp_f32_e32 v126, v94
	v_sub_f32_e32 v94, v139, v122
	v_min_f32_e32 v94, 0, v94
	v_mul_f32_e32 v94, 0x3fb8aa3b, v94
	v_exp_f32_e32 v130, v94
	v_sub_f32_e32 v94, v141, v118
	v_min_f32_e32 v94, 0, v94
	v_mul_f32_e32 v94, 0x3fb8aa3b, v94
	v_exp_f32_e32 v176, v94
	v_sub_f32_e32 v94, v143, v122
	v_min_f32_e32 v94, 0, v94
	v_mul_f32_e32 v94, 0x3fb8aa3b, v94
	v_exp_f32_e32 v178, v94
	v_sub_f32_e32 v94, v137, v119
	v_min_f32_e32 v94, 0, v94
	v_mul_f32_e32 v94, 0x3fb8aa3b, v94
	v_exp_f32_e32 v127, v94
	v_sub_f32_e32 v94, v139, v123
	v_min_f32_e32 v94, 0, v94
	v_mul_f32_e32 v94, 0x3fb8aa3b, v94
	v_exp_f32_e32 v131, v94
	v_sub_f32_e32 v94, v141, v119
	v_min_f32_e32 v94, 0, v94
	v_mul_f32_e32 v94, 0x3fb8aa3b, v94
	v_exp_f32_e32 v177, v94
	v_sub_f32_e32 v94, v143, v123
	v_min_f32_e32 v94, 0, v94
	v_mul_f32_e32 v94, 0x3fb8aa3b, v94
	v_or_b32_e32 v147, 48, v147
	v_exp_f32_e32 v179, v94
	v_lshlrev_b32_e32 v94, 2, v147
	v_or_b32_e32 v95, 0x11000, v94
	v_or_b32_e32 v120, 0x11200, v94
	ds_read_b128 v[116:119], v95
	ds_read_b128 v[120:123], v120
	v_or_b32_e32 v95, 0x11400, v94
	v_or_b32_e32 v94, 0x11600, v94
	ds_read_b128 v[152:155], v95
	ds_read_b128 v[156:159], v94
	s_waitcnt lgkmcnt(3)
	v_sub_f32_e32 v94, v137, v116
	s_waitcnt lgkmcnt(2)
	v_sub_f32_e32 v95, v139, v120
	v_min_f32_e32 v95, 0, v95
	v_mul_f32_e32 v95, 0x3fb8aa3b, v95
	v_exp_f32_e32 v180, v95
	v_sub_f32_e32 v95, v141, v116
	v_sub_f32_e32 v116, v139, v121
	v_min_f32_e32 v116, 0, v116
	v_mul_f32_e32 v116, 0x3fb8aa3b, v116
	v_exp_f32_e32 v181, v116
	v_sub_f32_e32 v116, v141, v117
	v_min_f32_e32 v116, 0, v116
	v_mul_f32_e32 v116, 0x3fb8aa3b, v116
	v_exp_f32_e32 v183, v116
	v_sub_f32_e32 v116, v143, v121
	v_min_f32_e32 v116, 0, v116
	v_mul_f32_e32 v116, 0x3fb8aa3b, v116
	v_exp_f32_e32 v185, v116
	v_sub_f32_e32 v116, v137, v118
	v_min_f32_e32 v116, 0, v116
	v_mul_f32_e32 v116, 0x3fb8aa3b, v116
	v_exp_f32_e32 v186, v116
	v_sub_f32_e32 v116, v139, v122
	v_min_f32_e32 v116, 0, v116
	v_mul_f32_e32 v116, 0x3fb8aa3b, v116
	v_exp_f32_e32 v188, v116
	v_sub_f32_e32 v116, v141, v118
	v_min_f32_e32 v116, 0, v116
	v_mul_f32_e32 v116, 0x3fb8aa3b, v116
	v_exp_f32_e32 v190, v116
	v_sub_f32_e32 v116, v143, v122
	v_min_f32_e32 v116, 0, v116
	v_mul_f32_e32 v116, 0x3fb8aa3b, v116
	v_exp_f32_e32 v192, v116
	v_sub_f32_e32 v116, v137, v119
	v_min_f32_e32 v116, 0, v116
	v_mul_f32_e32 v116, 0x3fb8aa3b, v116
	v_exp_f32_e32 v187, v116
	v_sub_f32_e32 v116, v139, v123
	v_min_f32_e32 v116, 0, v116
	v_min_f32_e32 v95, 0, v95
	v_mul_f32_e32 v116, 0x3fb8aa3b, v116
	v_mul_f32_e32 v95, 0x3fb8aa3b, v95
	v_exp_f32_e32 v189, v116
	v_sub_f32_e32 v116, v141, v119
	v_exp_f32_e32 v182, v95
	v_sub_f32_e32 v95, v143, v120
	v_min_f32_e32 v116, 0, v116
	v_min_f32_e32 v95, 0, v95
	v_mul_f32_e32 v116, 0x3fb8aa3b, v116
	v_mul_f32_e32 v95, 0x3fb8aa3b, v95
	v_exp_f32_e32 v191, v116
	v_sub_f32_e32 v116, v143, v123
	v_exp_f32_e32 v184, v95
	v_sub_f32_e32 v95, v137, v117
	v_min_f32_e32 v116, 0, v116
	v_min_f32_e32 v94, 0, v94
	v_min_f32_e32 v95, 0, v95
	v_mul_f32_e32 v116, 0x3fb8aa3b, v116
	s_movk_i32 s0, 0xffce
	v_mul_f32_e32 v94, 0x3fb8aa3b, v94
	v_mul_f32_e32 v95, 0x3fb8aa3b, v95
	v_exp_f32_e32 v193, v116
	v_add_u32_e32 v116, 48, v145
	v_add_u32_e32 v117, 47, v145
	v_cmp_lt_i32_e32 vcc, s0, v145
	s_movk_i32 s0, 0xffcf
	v_exp_f32_e32 v94, v94
	v_exp_f32_e32 v95, v95
	v_lshrrev_b32_e32 v118, 31, v117
	v_lshrrev_b32_e32 v116, 31, v116
	v_cndmask_b32_e64 v119, 0, 1.0, vcc
	v_cmp_lt_i32_e32 vcc, s0, v145
	v_cvt_f32_ubyte0_e32 v117, v116
	v_cvt_f32_ubyte0_e32 v116, v118
	v_cndmask_b32_e64 v118, 0, 1.0, vcc
	s_waitcnt lgkmcnt(0)
	v_pk_mul_f32 v[122:123], v[156:157], v[118:119]
	v_pk_mul_f32 v[120:121], v[152:153], v[116:117]
	v_pk_mul_f32 v[122:123], v[122:123], v[180:181]
	s_movk_i32 s0, 0xffcc
	v_pk_fma_f32 v[94:95], v[120:121], v[94:95], v[122:123]
	v_cmp_lt_i32_e32 vcc, s0, v145
	v_pk_mul_f32 v[94:95], v[104:105], v[94:95]
	s_movk_i32 s0, 0xffcd
	v_cvt_pk_f16_f32 v94, v94, v95
	v_add_u32_e32 v95, 50, v145
	v_add_u32_e32 v104, 49, v145
	v_cndmask_b32_e64 v123, 0, 1.0, vcc
	v_cmp_lt_i32_e32 vcc, s0, v145
	v_lshrrev_b32_e32 v104, 31, v104
	v_lshrrev_b32_e32 v95, 31, v95
	v_cndmask_b32_e64 v122, 0, 1.0, vcc
	v_cvt_f32_ubyte0_e32 v121, v95
	v_cvt_f32_ubyte0_e32 v120, v104
	v_pk_mul_f32 v[180:181], v[158:159], v[122:123]
	v_pk_mul_f32 v[104:105], v[154:155], v[120:121]
	v_pk_mul_f32 v[180:181], v[180:181], v[188:189]
	v_pk_mul_f32 v[92:93], v[112:113], v[92:93]
	v_pk_fma_f32 v[104:105], v[104:105], v[186:187], v[180:181]
	s_movk_i32 s0, 0xffde
	v_pk_mul_f32 v[104:105], v[106:107], v[104:105]
	v_cmp_lt_i32_e32 vcc, s0, v145
	v_cvt_pk_f16_f32 v95, v104, v105
	v_pk_mul_f32 v[104:105], v[108:109], v[148:149]
	s_movk_i32 s0, 0xffdf
	v_pk_mul_f32 v[104:105], v[104:105], v[174:175]
	s_nop 0
	v_pk_fma_f32 v[92:93], v[92:93], v[166:167], v[104:105]
	v_pk_mul_f32 v[104:105], v[110:111], v[128:129]
	v_pk_mul_f32 v[92:93], v[100:101], v[92:93]
	v_pk_mul_f32 v[104:105], v[104:105], v[178:179]
	v_cvt_pk_f16_f32 v100, v92, v93
	v_pk_mul_f32 v[92:93], v[114:115], v[124:125]
	s_nop 0
	v_pk_fma_f32 v[92:93], v[92:93], v[176:177], v[104:105]
	s_nop 0
	v_pk_mul_f32 v[92:93], v[102:103], v[92:93]
	v_cndmask_b32_e64 v103, 0, 1.0, vcc
	v_cvt_pk_f16_f32 v101, v92, v93
	v_add_u32_e32 v92, 32, v145
	v_add_u32_e32 v93, 31, v145
	v_lshrrev_b32_e32 v102, 31, v93
	v_lshrrev_b32_e32 v92, 31, v92
	v_cmp_lt_i32_e32 vcc, s0, v145
	v_cvt_f32_ubyte0_e32 v93, v92
	v_cvt_f32_ubyte0_e32 v92, v102
	v_cndmask_b32_e64 v102, 0, 1.0, vcc
	v_pk_mul_f32 v[106:107], v[156:157], v[102:103]
	v_pk_mul_f32 v[102:103], v[108:109], v[102:103]
	v_pk_mul_f32 v[104:105], v[152:153], v[92:93]
	v_pk_mul_f32 v[106:107], v[106:107], v[184:185]
	v_pk_mul_f32 v[92:93], v[112:113], v[92:93]
	v_pk_mul_f32 v[102:103], v[102:103], v[160:161]
	v_pk_fma_f32 v[104:105], v[104:105], v[182:183], v[106:107]
	v_pk_fma_f32 v[92:93], v[92:93], v[150:151], v[102:103]
	s_movk_i32 s0, 0xffdc
	v_pk_mul_f32 v[96:97], v[96:97], v[104:105]
	v_pk_mul_f32 v[88:89], v[88:89], v[92:93]
	v_cmp_lt_i32_e32 vcc, s0, v145
	s_movk_i32 s0, 0xffdd
	v_cvt_pk_f16_f32 v92, v88, v89
	v_cvt_pk_f16_f32 v102, v96, v97
	v_add_u32_e32 v88, 34, v145
	v_add_u32_e32 v89, 33, v145
	v_cndmask_b32_e64 v97, 0, 1.0, vcc
	v_cmp_lt_i32_e32 vcc, s0, v145
	v_lshrrev_b32_e32 v93, 31, v89
	v_lshrrev_b32_e32 v88, 31, v88
	v_cndmask_b32_e64 v96, 0, 1.0, vcc
	v_cvt_f32_ubyte0_e32 v89, v88
	v_cvt_f32_ubyte0_e32 v88, v93
	v_pk_mul_f32 v[106:107], v[158:159], v[96:97]
	v_pk_mul_f32 v[96:97], v[110:111], v[96:97]
	v_pk_mul_f32 v[104:105], v[154:155], v[88:89]
	v_pk_mul_f32 v[106:107], v[106:107], v[192:193]
	v_pk_mul_f32 v[88:89], v[114:115], v[88:89]
	v_pk_mul_f32 v[96:97], v[96:97], v[130:131]
	v_pk_fma_f32 v[104:105], v[104:105], v[190:191], v[106:107]
	v_pk_fma_f32 v[88:89], v[88:89], v[126:127], v[96:97]
	v_pk_mul_f32 v[98:99], v[98:99], v[104:105]
	v_pk_mul_f32 v[88:89], v[90:91], v[88:89]
	v_cvt_pk_f16_f32 v103, v98, v99
	v_cvt_pk_f16_f32 v93, v88, v89
	v_or_b32_e32 v88, 0x11100, v168
	v_or_b32_e32 v96, 0x11300, v168
	ds_read_b128 v[88:91], v88
	ds_read_b128 v[108:111], v96
	v_or_b32_e32 v96, 0x11500, v168
	v_or_b32_e32 v97, 0x11700, v168
	ds_read_b128 v[104:107], v96
	ds_read_b128 v[96:99], v97
	s_waitcnt lgkmcnt(3)
	v_sub_f32_e32 v112, v137, v88
	v_sub_f32_e32 v88, v141, v88
	v_min_f32_e32 v88, 0, v88
	v_mul_f32_e32 v88, 0x3fb8aa3b, v88
	v_exp_f32_e32 v152, v88
	s_waitcnt lgkmcnt(2)
	v_sub_f32_e32 v88, v143, v108
	v_min_f32_e32 v88, 0, v88
	v_mul_f32_e32 v88, 0x3fb8aa3b, v88
	v_exp_f32_e32 v154, v88
	v_sub_f32_e32 v88, v137, v89
	v_min_f32_e32 v88, 0, v88
	v_mul_f32_e32 v88, 0x3fb8aa3b, v88
	v_exp_f32_e32 v125, v88
	v_sub_f32_e32 v88, v139, v109
	v_min_f32_e32 v88, 0, v88
	v_mul_f32_e32 v88, 0x3fb8aa3b, v88
	v_exp_f32_e32 v131, v88
	v_sub_f32_e32 v88, v141, v89
	v_min_f32_e32 v88, 0, v88
	v_mul_f32_e32 v88, 0x3fb8aa3b, v88
	v_exp_f32_e32 v153, v88
	v_sub_f32_e32 v88, v143, v109
	v_min_f32_e32 v112, 0, v112
	v_min_f32_e32 v88, 0, v88
	v_mul_f32_e32 v112, 0x3fb8aa3b, v112
	v_mul_f32_e32 v88, 0x3fb8aa3b, v88
	v_exp_f32_e32 v124, v112
	v_sub_f32_e32 v112, v139, v108
	v_exp_f32_e32 v155, v88
	v_sub_f32_e32 v88, v137, v90
	v_min_f32_e32 v112, 0, v112
	v_min_f32_e32 v88, 0, v88
	v_mul_f32_e32 v112, 0x3fb8aa3b, v112
	v_mul_f32_e32 v88, 0x3fb8aa3b, v88
	v_exp_f32_e32 v130, v112
	v_exp_f32_e32 v112, v88
	v_sub_f32_e32 v88, v139, v110
	v_min_f32_e32 v88, 0, v88
	v_mul_f32_e32 v88, 0x3fb8aa3b, v88
	v_exp_f32_e32 v114, v88
	v_sub_f32_e32 v88, v141, v90
	v_min_f32_e32 v88, 0, v88
	v_mul_f32_e32 v88, 0x3fb8aa3b, v88
	v_exp_f32_e32 v156, v88
	v_sub_f32_e32 v88, v143, v110
	v_min_f32_e32 v88, 0, v88
	v_mul_f32_e32 v88, 0x3fb8aa3b, v88
	v_exp_f32_e32 v158, v88
	v_sub_f32_e32 v88, v137, v91
	v_min_f32_e32 v88, 0, v88
	v_mul_f32_e32 v88, 0x3fb8aa3b, v88
	v_exp_f32_e32 v113, v88
	v_sub_f32_e32 v88, v139, v111
	v_min_f32_e32 v88, 0, v88
	v_mul_f32_e32 v88, 0x3fb8aa3b, v88
	v_exp_f32_e32 v115, v88
	v_sub_f32_e32 v88, v141, v91
	v_min_f32_e32 v88, 0, v88
	v_mul_f32_e32 v88, 0x3fb8aa3b, v88
	v_exp_f32_e32 v157, v88
	v_sub_f32_e32 v88, v143, v111
	v_min_f32_e32 v88, 0, v88
	v_mul_f32_e32 v88, 0x3fb8aa3b, v88
	v_exp_f32_e32 v159, v88
	v_or_b32_e32 v88, 0x11140, v168
	v_or_b32_e32 v108, 0x11340, v168
	ds_read_b128 v[88:91], v88
	ds_read_b128 v[108:111], v108
	v_or_b32_e32 v126, 0x11540, v168
	v_or_b32_e32 v148, 0x11740, v168
	ds_read_b128 v[126:129], v126
	ds_read_b128 v[148:151], v148
	s_waitcnt lgkmcnt(3)
	v_sub_f32_e32 v160, v137, v88
	v_sub_f32_e32 v88, v141, v88
	v_min_f32_e32 v88, 0, v88
	v_mul_f32_e32 v88, 0x3fb8aa3b, v88
	v_exp_f32_e32 v174, v88
	s_waitcnt lgkmcnt(2)
	v_sub_f32_e32 v88, v143, v108
	v_min_f32_e32 v88, 0, v88
	v_mul_f32_e32 v88, 0x3fb8aa3b, v88
	v_sub_f32_e32 v161, v139, v108
	v_exp_f32_e32 v176, v88
	v_sub_f32_e32 v88, v137, v89
	v_min_f32_e32 v161, 0, v161
	v_min_f32_e32 v88, 0, v88
	v_mul_f32_e32 v161, 0x3fb8aa3b, v161
	v_mul_f32_e32 v88, 0x3fb8aa3b, v88
	v_exp_f32_e32 v166, v161
	v_exp_f32_e32 v161, v88
	v_sub_f32_e32 v88, v139, v109
	v_min_f32_e32 v88, 0, v88
	v_mul_f32_e32 v88, 0x3fb8aa3b, v88
	v_exp_f32_e32 v167, v88
	v_sub_f32_e32 v88, v141, v89
	v_min_f32_e32 v88, 0, v88
	v_mul_f32_e32 v88, 0x3fb8aa3b, v88
	v_exp_f32_e32 v175, v88
	v_sub_f32_e32 v88, v143, v109
	v_min_f32_e32 v88, 0, v88
	v_mul_f32_e32 v88, 0x3fb8aa3b, v88
	v_exp_f32_e32 v177, v88
	v_sub_f32_e32 v88, v137, v90
	v_min_f32_e32 v88, 0, v88
	v_mul_f32_e32 v88, 0x3fb8aa3b, v88
	v_exp_f32_e32 v178, v88
	v_sub_f32_e32 v88, v139, v110
	v_min_f32_e32 v88, 0, v88
	v_mul_f32_e32 v88, 0x3fb8aa3b, v88
	v_exp_f32_e32 v180, v88
	v_sub_f32_e32 v88, v141, v90
	v_min_f32_e32 v88, 0, v88
	v_mul_f32_e32 v88, 0x3fb8aa3b, v88
	v_exp_f32_e32 v182, v88
	v_sub_f32_e32 v88, v143, v110
	v_min_f32_e32 v88, 0, v88
	v_mul_f32_e32 v88, 0x3fb8aa3b, v88
	v_exp_f32_e32 v184, v88
	v_sub_f32_e32 v88, v137, v91
	v_min_f32_e32 v88, 0, v88
	v_mul_f32_e32 v88, 0x3fb8aa3b, v88
	v_exp_f32_e32 v179, v88
	v_sub_f32_e32 v88, v139, v111
	v_min_f32_e32 v88, 0, v88
	v_mul_f32_e32 v88, 0x3fb8aa3b, v88
	v_exp_f32_e32 v181, v88
	v_sub_f32_e32 v88, v141, v91
	v_min_f32_e32 v88, 0, v88
	v_mul_f32_e32 v88, 0x3fb8aa3b, v88
	v_exp_f32_e32 v183, v88
	v_sub_f32_e32 v88, v143, v111
	v_min_f32_e32 v160, 0, v160
	v_min_f32_e32 v88, 0, v88
	s_movk_i32 s0, 0xffae
	v_mul_f32_e32 v160, 0x3fb8aa3b, v160
	v_mul_f32_e32 v88, 0x3fb8aa3b, v88
	v_cmp_lt_i32_e32 vcc, s0, v145
	s_movk_i32 s0, 0xffaf
	v_exp_f32_e32 v160, v160
	v_exp_f32_e32 v185, v88
	v_add_u32_e32 v88, 0x50, v145
	v_add_u32_e32 v89, 0x4f, v145
	v_cndmask_b32_e64 v109, 0, 1.0, vcc
	v_cmp_lt_i32_e32 vcc, s0, v145
	v_lshrrev_b32_e32 v89, 31, v89
	v_lshrrev_b32_e32 v88, 31, v88
	v_cndmask_b32_e64 v108, 0, 1.0, vcc
	v_cvt_f32_ubyte0_e32 v91, v88
	v_cvt_f32_ubyte0_e32 v90, v89
	s_waitcnt lgkmcnt(0)
	v_pk_mul_f32 v[110:111], v[148:149], v[108:109]
	v_pk_mul_f32 v[88:89], v[126:127], v[90:91]
	v_pk_mul_f32 v[110:111], v[110:111], v[166:167]
	s_movk_i32 s0, 0xffac
	v_pk_fma_f32 v[88:89], v[88:89], v[160:161], v[110:111]
	v_cmp_lt_i32_e32 vcc, s0, v145
	v_pk_mul_f32 v[84:85], v[84:85], v[88:89]
	s_movk_i32 s0, 0xffad
	v_cvt_pk_f16_f32 v88, v84, v85
	v_add_u32_e32 v84, 0x52, v145
	v_add_u32_e32 v85, 0x51, v145
	v_cndmask_b32_e64 v111, 0, 1.0, vcc
	v_cmp_lt_i32_e32 vcc, s0, v145
	v_lshrrev_b32_e32 v89, 31, v85
	v_lshrrev_b32_e32 v84, 31, v84
	v_cndmask_b32_e64 v110, 0, 1.0, vcc
	v_cvt_f32_ubyte0_e32 v85, v84
	v_cvt_f32_ubyte0_e32 v84, v89
	v_pk_mul_f32 v[166:167], v[150:151], v[110:111]
	v_pk_mul_f32 v[160:161], v[128:129], v[84:85]
	v_pk_mul_f32 v[166:167], v[166:167], v[180:181]
	s_movk_i32 s0, 0xffbe
	v_pk_fma_f32 v[160:161], v[160:161], v[178:179], v[166:167]
	v_cmp_lt_i32_e32 vcc, s0, v145
	v_pk_mul_f32 v[86:87], v[86:87], v[160:161]
	s_movk_i32 s0, 0xffbf
	v_cvt_pk_f16_f32 v89, v86, v87
	v_pk_mul_f32 v[86:87], v[104:105], v[116:117]
	v_pk_mul_f32 v[116:117], v[96:97], v[118:119]
	s_nop 0
	v_pk_mul_f32 v[116:117], v[116:117], v[154:155]
	s_nop 0
	v_pk_fma_f32 v[86:87], v[86:87], v[152:153], v[116:117]
	v_pk_mul_f32 v[116:117], v[98:99], v[122:123]
	v_pk_mul_f32 v[76:77], v[76:77], v[86:87]
	v_pk_mul_f32 v[86:87], v[106:107], v[120:121]
	v_pk_mul_f32 v[116:117], v[116:117], v[158:159]
	v_cvt_pk_f16_f32 v76, v76, v77
	v_pk_fma_f32 v[86:87], v[86:87], v[156:157], v[116:117]
	s_nop 0
	v_pk_mul_f32 v[78:79], v[78:79], v[86:87]
	v_cndmask_b32_e64 v87, 0, 1.0, vcc
	v_cvt_pk_f16_f32 v77, v78, v79
	v_add_u32_e32 v78, 64, v145
	v_add_u32_e32 v79, 63, v145
	v_lshrrev_b32_e32 v86, 31, v79
	v_lshrrev_b32_e32 v78, 31, v78
	v_cmp_lt_i32_e32 vcc, s0, v145
	v_cvt_f32_ubyte0_e32 v79, v78
	v_cvt_f32_ubyte0_e32 v78, v86
	v_cndmask_b32_e64 v86, 0, 1.0, vcc
	v_pk_mul_f32 v[118:119], v[148:149], v[86:87]
	v_pk_mul_f32 v[86:87], v[96:97], v[86:87]
	v_pk_mul_f32 v[116:117], v[126:127], v[78:79]
	v_pk_mul_f32 v[78:79], v[104:105], v[78:79]
	v_pk_mul_f32 v[86:87], v[86:87], v[130:131]
	v_pk_mul_f32 v[118:119], v[118:119], v[176:177]
	v_pk_fma_f32 v[78:79], v[78:79], v[124:125], v[86:87]
	v_pk_fma_f32 v[116:117], v[116:117], v[174:175], v[118:119]
	v_pk_mul_f32 v[68:69], v[68:69], v[78:79]
	s_movk_i32 s0, 0xffbc
	v_pk_mul_f32 v[72:73], v[72:73], v[116:117]
	v_cvt_pk_f16_f32 v86, v68, v69
	v_add_u32_e32 v68, 0x42, v145
	v_add_u32_e32 v69, 0x41, v145
	v_cmp_lt_i32_e32 vcc, s0, v145
	s_movk_i32 s0, 0xffbd
	v_cvt_pk_f16_f32 v78, v72, v73
	v_lshrrev_b32_e32 v72, 31, v69
	v_lshrrev_b32_e32 v68, 31, v68
	v_cndmask_b32_e64 v73, 0, 1.0, vcc
	v_cmp_lt_i32_e32 vcc, s0, v145
	v_cvt_f32_ubyte0_e32 v69, v68
	v_cvt_f32_ubyte0_e32 v68, v72
	v_cndmask_b32_e64 v72, 0, 1.0, vcc
	v_pk_mul_f32 v[104:105], v[150:151], v[72:73]
	v_pk_mul_f32 v[72:73], v[98:99], v[72:73]
	v_pk_mul_f32 v[96:97], v[128:129], v[68:69]
	v_pk_mul_f32 v[104:105], v[104:105], v[184:185]
	v_pk_mul_f32 v[68:69], v[106:107], v[68:69]
	v_pk_mul_f32 v[72:73], v[72:73], v[114:115]
	v_pk_fma_f32 v[96:97], v[96:97], v[182:183], v[104:105]
	v_pk_fma_f32 v[68:69], v[68:69], v[112:113], v[72:73]
	v_pk_mul_f32 v[74:75], v[74:75], v[96:97]
	v_pk_mul_f32 v[68:69], v[70:71], v[68:69]
	v_cvt_pk_f16_f32 v79, v74, v75
	v_cvt_pk_f16_f32 v87, v68, v69
	v_or_b32_e32 v68, 0x11180, v168
	v_or_b32_e32 v69, 0x11380, v168
	ds_read_b128 v[112:115], v68
	ds_read_b128 v[116:119], v69
	v_or_b32_e32 v68, 0x11580, v168
	v_or_b32_e32 v69, 0x11780, v168
	ds_read_b128 v[72:75], v68
	ds_read_b128 v[68:71], v69
	s_waitcnt lgkmcnt(3)
	v_sub_f32_e32 v96, v137, v112
	v_min_f32_e32 v96, 0, v96
	v_mul_f32_e32 v96, 0x3fb8aa3b, v96
	v_exp_f32_e32 v98, v96
	s_waitcnt lgkmcnt(2)
	v_sub_f32_e32 v96, v139, v116
	v_min_f32_e32 v96, 0, v96
	v_sub_f32_e32 v97, v143, v116
	v_sub_f32_e32 v105, v139, v118
	v_mul_f32_e32 v96, 0x3fb8aa3b, v96
	v_min_f32_e32 v97, 0, v97
	v_min_f32_e32 v105, 0, v105
	v_exp_f32_e32 v128, v96
	v_sub_f32_e32 v96, v141, v112
	v_mul_f32_e32 v97, 0x3fb8aa3b, v97
	v_mul_f32_e32 v105, 0x3fb8aa3b, v105
	v_sub_f32_e32 v112, v141, v115
	v_exp_f32_e32 v130, v97
	v_sub_f32_e32 v97, v137, v113
	v_exp_f32_e32 v106, v105
	v_sub_f32_e32 v105, v141, v114
	v_min_f32_e32 v112, 0, v112
	v_min_f32_e32 v97, 0, v97
	v_min_f32_e32 v105, 0, v105
	v_mul_f32_e32 v112, 0x3fb8aa3b, v112
	v_mul_f32_e32 v97, 0x3fb8aa3b, v97
	v_mul_f32_e32 v105, 0x3fb8aa3b, v105
	v_exp_f32_e32 v149, v112
	v_sub_f32_e32 v112, v143, v119
	v_exp_f32_e32 v99, v97
	v_sub_f32_e32 v97, v139, v117
	v_sub_f32_e32 v104, v143, v117
	v_exp_f32_e32 v148, v105
	v_sub_f32_e32 v105, v143, v118
	v_min_f32_e32 v112, 0, v112
	v_min_f32_e32 v97, 0, v97
	v_min_f32_e32 v104, 0, v104
	v_min_f32_e32 v105, 0, v105
	v_mul_f32_e32 v112, 0x3fb8aa3b, v112
	v_mul_f32_e32 v97, 0x3fb8aa3b, v97
	v_mul_f32_e32 v104, 0x3fb8aa3b, v104
	v_mul_f32_e32 v105, 0x3fb8aa3b, v105
	v_exp_f32_e32 v151, v112
	v_or_b32_e32 v112, 0x111c0, v168
	v_or_b32_e32 v116, 0x113c0, v168
	v_exp_f32_e32 v129, v97
	v_sub_f32_e32 v97, v141, v113
	v_exp_f32_e32 v131, v104
	v_sub_f32_e32 v104, v137, v114
	v_exp_f32_e32 v150, v105
	v_sub_f32_e32 v105, v137, v115
	v_sub_f32_e32 v107, v139, v119
	ds_read_b128 v[112:115], v112
	ds_read_b128 v[116:119], v116
	v_or_b32_e32 v120, 0x115c0, v168
	v_or_b32_e32 v124, 0x117c0, v168
	ds_read_b128 v[120:123], v120
	ds_read_b128 v[124:127], v124
	s_waitcnt lgkmcnt(3)
	v_sub_f32_e32 v152, v137, v112
	s_waitcnt lgkmcnt(2)
	v_sub_f32_e32 v153, v139, v116
	v_min_f32_e32 v153, 0, v153
	v_mul_f32_e32 v153, 0x3fb8aa3b, v153
	v_exp_f32_e32 v154, v153
	v_sub_f32_e32 v153, v137, v113
	v_sub_f32_e32 v156, v137, v114
	v_sub_f32_e32 v157, v139, v118
	v_sub_f32_e32 v137, v137, v115
	v_min_f32_e32 v157, 0, v157
	v_min_f32_e32 v137, 0, v137
	v_sub_f32_e32 v155, v139, v117
	v_mul_f32_e32 v157, 0x3fb8aa3b, v157
	v_mul_f32_e32 v137, 0x3fb8aa3b, v137
	v_min_f32_e32 v155, 0, v155
	v_exp_f32_e32 v158, v157
	v_exp_f32_e32 v157, v137
	v_sub_f32_e32 v137, v139, v119
	v_min_f32_e32 v152, 0, v152
	v_min_f32_e32 v153, 0, v153
	v_mul_f32_e32 v155, 0x3fb8aa3b, v155
	v_min_f32_e32 v137, 0, v137
	s_movk_i32 s0, 0xff8e
	v_mul_f32_e32 v152, 0x3fb8aa3b, v152
	v_mul_f32_e32 v153, 0x3fb8aa3b, v153
	v_exp_f32_e32 v155, v155
	v_mul_f32_e32 v137, 0x3fb8aa3b, v137
	v_cmp_lt_i32_e32 vcc, s0, v145
	s_movk_i32 s0, 0xff8f
	v_exp_f32_e32 v152, v152
	v_exp_f32_e32 v153, v153
	v_exp_f32_e32 v159, v137
	v_add_u32_e32 v137, 0x70, v145
	v_add_u32_e32 v139, 0x6f, v145
	v_cndmask_b32_e64 v167, 0, 1.0, vcc
	v_cmp_lt_i32_e32 vcc, s0, v145
	v_lshrrev_b32_e32 v139, 31, v139
	v_lshrrev_b32_e32 v137, 31, v137
	v_cndmask_b32_e64 v166, 0, 1.0, vcc
	v_cvt_f32_ubyte0_e32 v161, v137
	v_cvt_f32_ubyte0_e32 v160, v139
	s_waitcnt lgkmcnt(0)
	v_pk_mul_f32 v[166:167], v[124:125], v[166:167]
	v_pk_mul_f32 v[160:161], v[120:121], v[160:161]
	v_pk_mul_f32 v[154:155], v[166:167], v[154:155]
	v_min_f32_e32 v156, 0, v156
	v_pk_fma_f32 v[152:153], v[160:161], v[152:153], v[154:155]
	s_movk_i32 s0, 0xff8c
	v_mul_f32_e32 v156, 0x3fb8aa3b, v156
	v_pk_mul_f32 v[60:61], v[60:61], v[152:153]
	v_cmp_lt_i32_e32 vcc, s0, v145
	s_movk_i32 s0, 0xff8d
	v_exp_f32_e32 v156, v156
	v_cvt_pk_f16_f32 v60, v60, v61
	v_add_u32_e32 v61, 0x72, v145
	v_add_u32_e32 v137, 0x71, v145
	v_cndmask_b32_e64 v155, 0, 1.0, vcc
	v_cmp_lt_i32_e32 vcc, s0, v145
	v_lshrrev_b32_e32 v137, 31, v137
	v_lshrrev_b32_e32 v61, 31, v61
	v_cndmask_b32_e64 v154, 0, 1.0, vcc
	v_min_f32_e32 v96, 0, v96
	v_min_f32_e32 v97, 0, v97
	v_cvt_f32_ubyte0_e32 v153, v61
	v_cvt_f32_ubyte0_e32 v152, v137
	v_pk_mul_f32 v[154:155], v[126:127], v[154:155]
	v_mul_f32_e32 v96, 0x3fb8aa3b, v96
	v_mul_f32_e32 v97, 0x3fb8aa3b, v97
	v_pk_mul_f32 v[152:153], v[122:123], v[152:153]
	v_pk_mul_f32 v[154:155], v[154:155], v[158:159]
	v_exp_f32_e32 v96, v96
	v_exp_f32_e32 v97, v97
	v_pk_fma_f32 v[152:153], v[152:153], v[156:157], v[154:155]
	v_sub_f32_e32 v116, v143, v116
	v_pk_mul_f32 v[62:63], v[62:63], v[152:153]
	v_sub_f32_e32 v117, v143, v117
	v_cvt_pk_f16_f32 v61, v62, v63
	v_pk_mul_f32 v[62:63], v[72:73], v[90:91]
	v_pk_mul_f32 v[90:91], v[68:69], v[108:109]
	v_sub_f32_e32 v112, v141, v112
	v_pk_mul_f32 v[90:91], v[90:91], v[130:131]
	v_min_f32_e32 v116, 0, v116
	v_pk_fma_f32 v[62:63], v[62:63], v[96:97], v[90:91]
	v_sub_f32_e32 v113, v141, v113
	v_pk_mul_f32 v[56:57], v[56:57], v[62:63]
	v_pk_mul_f32 v[62:63], v[70:71], v[110:111]
	v_cvt_pk_f16_f32 v96, v56, v57
	v_pk_mul_f32 v[56:57], v[74:75], v[84:85]
	v_pk_mul_f32 v[62:63], v[62:63], v[150:151]
	v_min_f32_e32 v117, 0, v117
	v_pk_fma_f32 v[56:57], v[56:57], v[148:149], v[62:63]
	s_movk_i32 s0, 0xff9e
	v_pk_mul_f32 v[56:57], v[58:59], v[56:57]
	v_min_f32_e32 v112, 0, v112
	v_mul_f32_e32 v116, 0x3fb8aa3b, v116
	v_min_f32_e32 v113, 0, v113
	v_mul_f32_e32 v117, 0x3fb8aa3b, v117
	v_cvt_pk_f16_f32 v97, v56, v57
	v_add_u32_e32 v56, 0x60, v145
	v_add_u32_e32 v57, 0x5f, v145
	v_cmp_lt_i32_e32 vcc, s0, v145
	s_movk_i32 s0, 0xff9f
	v_mul_f32_e32 v112, 0x3fb8aa3b, v112
	v_exp_f32_e32 v116, v116
	v_mul_f32_e32 v113, 0x3fb8aa3b, v113
	v_exp_f32_e32 v117, v117
	v_lshrrev_b32_e32 v58, 31, v57
	v_lshrrev_b32_e32 v56, 31, v56
	v_cndmask_b32_e64 v59, 0, 1.0, vcc
	v_cmp_lt_i32_e32 vcc, s0, v145
	v_exp_f32_e32 v112, v112
	v_exp_f32_e32 v113, v113
	v_cvt_f32_ubyte0_e32 v57, v56
	v_cvt_f32_ubyte0_e32 v56, v58
	v_cndmask_b32_e64 v58, 0, 1.0, vcc
	v_pk_mul_f32 v[84:85], v[124:125], v[58:59]
	v_pk_mul_f32 v[58:59], v[68:69], v[58:59]
	v_sub_f32_e32 v118, v143, v118
	v_sub_f32_e32 v119, v143, v119
	v_pk_mul_f32 v[62:63], v[120:121], v[56:57]
	v_pk_mul_f32 v[56:57], v[72:73], v[56:57]
	v_pk_mul_f32 v[58:59], v[58:59], v[128:129]
	v_min_f32_e32 v107, 0, v107
	v_sub_f32_e32 v114, v141, v114
	v_min_f32_e32 v118, 0, v118
	v_sub_f32_e32 v115, v141, v115
	v_min_f32_e32 v119, 0, v119
	v_pk_mul_f32 v[84:85], v[84:85], v[116:117]
	v_pk_fma_f32 v[56:57], v[56:57], v[98:99], v[58:59]
	v_min_f32_e32 v104, 0, v104
	v_min_f32_e32 v105, 0, v105
	v_mul_f32_e32 v107, 0x3fb8aa3b, v107
	v_min_f32_e32 v114, 0, v114
	v_mul_f32_e32 v118, 0x3fb8aa3b, v118
	v_min_f32_e32 v115, 0, v115
	v_mul_f32_e32 v119, 0x3fb8aa3b, v119
	v_pk_fma_f32 v[62:63], v[62:63], v[112:113], v[84:85]
	v_pk_mul_f32 v[48:49], v[48:49], v[56:57]
	s_movk_i32 s0, 0xff9c
	v_mul_f32_e32 v104, 0x3fb8aa3b, v104
	v_mul_f32_e32 v105, 0x3fb8aa3b, v105
	v_exp_f32_e32 v107, v107
	v_mul_f32_e32 v114, 0x3fb8aa3b, v114
	v_exp_f32_e32 v118, v118
	v_mul_f32_e32 v115, 0x3fb8aa3b, v115
	v_exp_f32_e32 v119, v119
	v_pk_mul_f32 v[52:53], v[52:53], v[62:63]
	v_cvt_pk_f16_f32 v58, v48, v49
	v_add_u32_e32 v48, 0x62, v145
	v_add_u32_e32 v49, 0x61, v145
	v_cmp_lt_i32_e32 vcc, s0, v145
	s_movk_i32 s0, 0xff9d
	v_exp_f32_e32 v104, v104
	v_exp_f32_e32 v105, v105
	v_exp_f32_e32 v114, v114
	v_exp_f32_e32 v115, v115
	v_cvt_pk_f16_f32 v98, v52, v53
	v_lshrrev_b32_e32 v52, 31, v49
	v_lshrrev_b32_e32 v48, 31, v48
	v_cndmask_b32_e64 v53, 0, 1.0, vcc
	v_cmp_lt_i32_e32 vcc, s0, v145
	v_cvt_f32_ubyte0_e32 v49, v48
	v_cvt_f32_ubyte0_e32 v48, v52
	v_cndmask_b32_e64 v52, 0, 1.0, vcc
	v_pk_mul_f32 v[62:63], v[126:127], v[52:53]
	v_pk_mul_f32 v[52:53], v[70:71], v[52:53]
	v_pk_mul_f32 v[56:57], v[122:123], v[48:49]
	v_pk_mul_f32 v[62:63], v[62:63], v[118:119]
	v_pk_mul_f32 v[48:49], v[74:75], v[48:49]
	v_pk_mul_f32 v[52:53], v[52:53], v[106:107]
	v_pk_fma_f32 v[56:57], v[56:57], v[114:115], v[62:63]
	v_pk_fma_f32 v[48:49], v[48:49], v[104:105], v[52:53]
	v_pk_mul_f32 v[54:55], v[54:55], v[56:57]
	v_pk_mul_f32 v[48:49], v[50:51], v[48:49]
	v_cvt_pk_f16_f32 v99, v54, v55
	v_cvt_pk_f16_f32 v59, v48, v49
	s_barrier
	s_waitcnt vmcnt(11)
	ds_write_b128 v132, v[0:3]
	s_waitcnt vmcnt(10)
	ds_write_b128 v134, v[4:7]
	s_waitcnt vmcnt(9)
	ds_write_b128 v136, v[8:11]
	s_waitcnt vmcnt(8)
	ds_write_b128 v138, v[12:15]
	s_waitcnt vmcnt(7)
	ds_write_b128 v132, v[16:19] offset:17408
	s_waitcnt vmcnt(6)
	ds_write_b128 v134, v[20:23] offset:17408
	s_waitcnt vmcnt(5)
	ds_write_b128 v136, v[24:27] offset:17408
	s_waitcnt vmcnt(4)
	ds_write_b128 v138, v[28:31] offset:17408
	s_waitcnt vmcnt(3)
	ds_write_b128 v140, v[32:35] offset:17408
	s_waitcnt vmcnt(2)
	ds_write_b128 v142, v[36:39] offset:17408
	s_waitcnt vmcnt(1)
	ds_write_b128 v144, v[40:43] offset:17408
	s_waitcnt vmcnt(0)
	ds_write_b128 v146, v[44:47] offset:17408
	v_lshlrev_b32_e32 v16, 3, v164
	v_mad_u32_u24 v17, v162, s12, v16
	s_waitcnt lgkmcnt(0)
	s_barrier
	ds_read2_b64 v[198:201], v17 offset1:4
	s_nop 0
	v_add_u32_e32 v42, 0x1000, v17
	ds_read2_b64 v[202:205], v42 offset0:32 offset1:36
	v_add_u32_e32 v43, 0x2000, v17
	ds_read2_b64 v[210:213], v43 offset0:64 offset1:68
	v_add_u32_e32 v44, 0x3000, v17
	ds_read2_b64 v[222:225], v44 offset0:96 offset1:100
	s_nop 0
	s_nop 0
	s_nop 0
	s_waitcnt lgkmcnt(4)
	s_waitcnt lgkmcnt(3)
	v_mfma_f32_16x16x32_f16 v[4:7], v[198:201], v[64:67], 0
	v_mfma_f32_16x16x32_f16 v[0:3], v[198:201], v[80:83], 0
	s_nop 0
	s_waitcnt lgkmcnt(2)
	v_mfma_f32_16x16x32_f16 v[12:15], v[202:205], v[64:67], 0
	v_mfma_f32_16x16x32_f16 v[8:11], v[202:205], v[80:83], 0
	s_nop 0
	s_waitcnt lgkmcnt(1)
	v_mfma_f32_16x16x32_f16 v[22:25], v[210:213], v[64:67], 0
	v_mfma_f32_16x16x32_f16 v[18:21], v[210:213], v[80:83], 0
	s_nop 0
	s_waitcnt lgkmcnt(0)
	v_mfma_f32_16x16x32_f16 v[30:33], v[222:225], v[64:67], 0
	v_mfma_f32_16x16x32_f16 v[26:29], v[222:225], v[80:83], 0
	ds_read2_b64 v[198:201], v17 offset0:8 offset1:12
	ds_read2_b64 v[202:205], v42 offset0:40 offset1:44
	ds_read2_b64 v[210:213], v43 offset0:72 offset1:76
	s_nop 0
	s_waitcnt lgkmcnt(3)
	s_waitcnt lgkmcnt(2)
	v_mfma_f32_16x16x32_f16 v[4:7], v[198:201], v[92:95], v[4:7]
	v_mfma_f32_16x16x32_f16 v[0:3], v[198:201], v[100:103], v[0:3]
	s_nop 0
	s_nop 0
	s_waitcnt lgkmcnt(1)
	v_mfma_f32_16x16x32_f16 v[12:15], v[202:205], v[92:95], v[12:15]
	v_mfma_f32_16x16x32_f16 v[8:11], v[202:205], v[100:103], v[8:11]
	s_nop 0
	s_nop 0
	s_waitcnt lgkmcnt(0)
	v_mfma_f32_16x16x32_f16 v[22:25], v[210:213], v[92:95], v[22:25]
	v_mfma_f32_16x16x32_f16 v[18:21], v[210:213], v[100:103], v[18:21]
	ds_read2_b64 v[34:37], v44 offset0:104 offset1:108
	s_nop 0
	s_waitcnt lgkmcnt(0)
	v_mfma_f32_16x16x32_f16 v[30:33], v[34:37], v[92:95], v[30:33]
	v_mfma_f32_16x16x32_f16 v[26:29], v[34:37], v[100:103], v[26:29]
	ds_read2_b64 v[198:201], v17 offset0:16 offset1:20
	ds_read2_b64 v[202:205], v43 offset0:80 offset1:84
	s_nop 0
	s_waitcnt lgkmcnt(2)
	s_waitcnt lgkmcnt(1)
	v_mfma_f32_16x16x32_f16 v[4:7], v[198:201], v[86:89], v[4:7]
	v_mfma_f32_16x16x32_f16 v[0:3], v[198:201], v[76:79], v[0:3]
	ds_read2_b64 v[34:37], v42 offset0:48 offset1:52
	s_nop 0
	s_waitcnt lgkmcnt(0)
	v_mfma_f32_16x16x32_f16 v[38:41], v[34:37], v[86:89], v[12:15]
	s_nop 2
	s_nop 0
	s_nop 0
	v_mfma_f32_16x16x32_f16 v[22:25], v[202:205], v[86:89], v[22:25]
	v_mfma_f32_16x16x32_f16 v[18:21], v[202:205], v[76:79], v[18:21]
	ds_read2_b64 v[12:15], v44 offset0:112 offset1:116
	v_mfma_f32_16x16x32_f16 v[8:11], v[34:37], v[76:79], v[8:11]
	s_nop 0
	s_waitcnt lgkmcnt(0)
	v_mfma_f32_16x16x32_f16 v[30:33], v[12:15], v[86:89], v[30:33]
	v_mfma_f32_16x16x32_f16 v[26:29], v[12:15], v[76:79], v[26:29]
	ds_read2_b64 v[198:201], v17 offset0:24 offset1:28
	ds_read2_b64 v[202:205], v42 offset0:56 offset1:60
	ds_read2_b64 v[210:213], v43 offset0:88 offset1:92
	ds_read2_b64 v[222:225], v44 offset0:120 offset1:124
	s_nop 0
	s_waitcnt lgkmcnt(4)
	s_waitcnt lgkmcnt(3)
	v_mfma_f32_16x16x32_f16 v[34:37], v[198:201], v[58:61], v[4:7]
	v_mfma_f32_16x16x32_f16 v[12:15], v[198:201], v[96:99], v[0:3]
	s_nop 2
	s_nop 0
	s_nop 0
	s_waitcnt lgkmcnt(2)
	v_mfma_f32_16x16x32_f16 v[38:41], v[202:205], v[58:61], v[38:41]
	v_mfma_f32_16x16x32_f16 v[8:11], v[202:205], v[96:99], v[8:11]
	s_nop 0
	s_nop 0
	s_waitcnt lgkmcnt(1)
	v_mfma_f32_16x16x32_f16 v[22:25], v[210:213], v[58:61], v[22:25]
	v_mfma_f32_16x16x32_f16 v[4:7], v[210:213], v[96:99], v[18:21]
	s_nop 0
	s_nop 0
	s_waitcnt lgkmcnt(0)
	v_mfma_f32_16x16x32_f16 v[30:33], v[222:225], v[58:61], v[30:33]
	v_mfma_f32_16x16x32_f16 v[0:3], v[222:225], v[96:99], v[26:29]
	v_readlane_b32 s0, v255, 48
	s_or_b32 s4, s9, s0
	s_ashr_i32 s5, s4, 31
	v_readlane_b32 s44, v253, 32
	s_lshl_b64 s[4:5], s[4:5], 2
	v_readlane_b32 s54, v253, 42
	v_readlane_b32 s55, v253, 43
	s_add_u32 s4, s54, s4
	s_addc_u32 s5, s55, s5
	global_load_dword v18, v169, s[4:5]
	s_lshl_b32 s0, s9, 8
	v_readlane_b32 s4, v253, 58
	v_readlane_b32 s5, v253, 59
	s_add_u32 s4, s4, s0
	v_add_u32_e32 v26, s8, v135
	s_addc_u32 s5, s5, 0
	v_lshlrev_b32_e32 v19, 1, v135
	v_ashrrev_i32_e32 v27, 31, v26
	s_movk_i32 s0, 0x440
	v_lshl_add_u64 v[20:21], s[4:5], 0, v[168:169]
	v_lshlrev_b64 v[26:27], 11, v[26:27]
	v_mad_u32_u24 v17, v164, s0, v19
	v_lshl_add_u64 v[42:43], v[20:21], 0, v[26:27]
	ds_read_u16 v26, v17
	ds_read_u16 v27, v17 offset:272
	ds_read_u16 v28, v17 offset:544
	ds_read_u16 v29, v17 offset:816
	s_mov_b32 s0, 0
	s_waitcnt lgkmcnt(3)
	v_cvt_f32_f16_e32 v26, v26
	s_waitcnt lgkmcnt(2)
	v_cvt_f32_f16_e32 v27, v27
	s_waitcnt lgkmcnt(1)
	v_cvt_f32_f16_e32 v28, v28
	s_waitcnt lgkmcnt(0)
	v_cvt_f32_f16_e32 v29, v29
	s_mov_b64 s[4:5], -1
	s_mov_b32 s9, 0x11a00
	v_readlane_b32 s45, v253, 33
	v_readlane_b32 s46, v253, 34
	v_readlane_b32 s47, v253, 35
	v_readlane_b32 s48, v253, 36
	v_readlane_b32 s49, v253, 37
	v_readlane_b32 s50, v253, 38
	v_readlane_b32 s51, v253, 39
	v_readlane_b32 s52, v253, 40
	v_readlane_b32 s53, v253, 41
	v_readlane_b32 s56, v253, 44
	v_readlane_b32 s57, v253, 45
	v_readlane_b32 s58, v253, 46
	v_readlane_b32 s59, v253, 47
	s_waitcnt vmcnt(0)
	v_pk_fma_f32 v[26:27], v[18:19], v[26:27], v[34:35] op_sel_hi:[0,1,1]
	v_pk_fma_f32 v[28:29], v[18:19], v[28:29], v[36:37] op_sel_hi:[0,1,1]
	v_mad_u32_u24 v19, v147, s12, v19
	global_store_dwordx4 v[42:43], v[26:29], off
	v_add_u32_e32 v34, 0xffffde00, v19
	ds_read_u16 v26, v34
	ds_read_u16 v27, v17 offset:4624
	ds_read_u16 v28, v17 offset:4896
	ds_read_u16 v29, v17 offset:5168
	s_waitcnt lgkmcnt(3)
	v_cvt_f32_f16_e32 v26, v26
	s_waitcnt lgkmcnt(2)
	v_cvt_f32_f16_e32 v27, v27
	s_waitcnt lgkmcnt(1)
	v_cvt_f32_f16_e32 v28, v28
	s_waitcnt lgkmcnt(0)
	v_cvt_f32_f16_e32 v29, v29
	v_pk_fma_f32 v[26:27], v[18:19], v[26:27], v[38:39] op_sel_hi:[0,1,1]
	v_pk_fma_f32 v[28:29], v[18:19], v[28:29], v[40:41] op_sel_hi:[0,1,1]
	global_store_dwordx4 v[42:43], v[26:29], off offset:64
	ds_read_u16 v26, v34 offset:4352
	ds_read_u16 v27, v17 offset:8976
	ds_read_u16 v28, v17 offset:9248
	ds_read_u16 v29, v17 offset:9520
	s_waitcnt lgkmcnt(3)
	v_cvt_f32_f16_e32 v26, v26
	s_waitcnt lgkmcnt(2)
	v_cvt_f32_f16_e32 v27, v27
	v_pk_fma_f32 v[22:23], v[18:19], v[26:27], v[22:23] op_sel_hi:[0,1,1]
	s_waitcnt lgkmcnt(0)
	v_cvt_f32_f16_e32 v27, v29
	v_cvt_f32_f16_e32 v26, v28
	v_pk_fma_f32 v[24:25], v[18:19], v[26:27], v[24:25] op_sel_hi:[0,1,1]
	global_store_dwordx4 v[42:43], v[22:25], off offset:128
	ds_read_u16 v22, v19
	ds_read_u16 v23, v17 offset:13328
	ds_read_u16 v24, v17 offset:13600
	ds_read_u16 v25, v17 offset:13872
	s_waitcnt lgkmcnt(3)
	v_cvt_f32_f16_e32 v22, v22
	s_waitcnt lgkmcnt(2)
	v_cvt_f32_f16_e32 v23, v23
	s_waitcnt lgkmcnt(1)
	v_cvt_f32_f16_e32 v24, v24
	s_waitcnt lgkmcnt(0)
	v_cvt_f32_f16_e32 v25, v25
	v_pk_fma_f32 v[22:23], v[18:19], v[22:23], v[30:31] op_sel_hi:[0,1,1]
	v_pk_fma_f32 v[24:25], v[18:19], v[24:25], v[32:33] op_sel_hi:[0,1,1]
	global_store_dwordx4 v[42:43], v[22:25], off offset:192
	s_nop 1
	v_add_u32_e32 v22, s8, v133
	v_ashrrev_i32_e32 v23, 31, v22
	v_lshlrev_b64 v[22:23], 11, v[22:23]
	v_lshl_add_u64 v[20:21], v[20:21], 0, v[22:23]
	ds_read_u16 v22, v17 offset:32
	ds_read_u16 v23, v17 offset:304
	ds_read_u16 v24, v17 offset:576
	ds_read_u16 v25, v17 offset:848
	s_waitcnt lgkmcnt(3)
	v_cvt_f32_f16_e32 v22, v22
	s_waitcnt lgkmcnt(2)
	v_cvt_f32_f16_e32 v23, v23
	v_pk_fma_f32 v[12:13], v[18:19], v[22:23], v[12:13] op_sel_hi:[0,1,1]
	s_waitcnt lgkmcnt(0)
	v_cvt_f32_f16_e32 v23, v25
	v_cvt_f32_f16_e32 v22, v24
	v_pk_fma_f32 v[14:15], v[18:19], v[22:23], v[14:15] op_sel_hi:[0,1,1]
	global_store_dwordx4 v[20:21], v[12:15], off
	ds_read_u16 v12, v34 offset:32
	ds_read_u16 v13, v17 offset:4656
	ds_read_u16 v14, v17 offset:4928
	ds_read_u16 v15, v17 offset:5200
	s_waitcnt lgkmcnt(3)
	v_cvt_f32_f16_e32 v12, v12
	s_waitcnt lgkmcnt(2)
	v_cvt_f32_f16_e32 v13, v13
	v_pk_fma_f32 v[8:9], v[18:19], v[12:13], v[8:9] op_sel_hi:[0,1,1]
	s_waitcnt lgkmcnt(0)
	v_cvt_f32_f16_e32 v13, v15
	v_cvt_f32_f16_e32 v12, v14
	v_pk_fma_f32 v[10:11], v[18:19], v[12:13], v[10:11] op_sel_hi:[0,1,1]
	global_store_dwordx4 v[20:21], v[8:11], off offset:64
	ds_read_u16 v8, v34 offset:4384
	ds_read_u16 v9, v17 offset:9008
	ds_read_u16 v10, v17 offset:9280
	ds_read_u16 v11, v17 offset:9552
	s_waitcnt lgkmcnt(3)
	v_cvt_f32_f16_e32 v8, v8
	s_waitcnt lgkmcnt(2)
	v_cvt_f32_f16_e32 v9, v9
	v_pk_fma_f32 v[4:5], v[18:19], v[8:9], v[4:5] op_sel_hi:[0,1,1]
	s_waitcnt lgkmcnt(0)
	v_cvt_f32_f16_e32 v9, v11
	v_cvt_f32_f16_e32 v8, v10
	v_pk_fma_f32 v[6:7], v[18:19], v[8:9], v[6:7] op_sel_hi:[0,1,1]
	global_store_dwordx4 v[20:21], v[4:7], off offset:128
	ds_read_u16 v4, v19 offset:32
	ds_read_u16 v5, v17 offset:13360
	ds_read_u16 v6, v17 offset:13632
	ds_read_u16 v7, v17 offset:13904
	v_mov_b32_e32 v17, v169
	s_waitcnt lgkmcnt(3)
	v_cvt_f32_f16_e32 v4, v4
	s_waitcnt lgkmcnt(2)
	v_cvt_f32_f16_e32 v5, v5
	v_pk_fma_f32 v[0:1], v[18:19], v[4:5], v[0:1] op_sel_hi:[0,1,1]
	s_waitcnt lgkmcnt(0)
	v_cvt_f32_f16_e32 v5, v7
	v_cvt_f32_f16_e32 v4, v6
	v_lshlrev_b32_e32 v6, 4, v163
	v_pk_fma_f32 v[2:3], v[18:19], v[4:5], v[2:3] op_sel_hi:[0,1,1]
	global_store_dwordx4 v[20:21], v[0:3], off offset:192
	s_nop 1
	v_lshlrev_b32_e32 v0, 7, v162
	v_lshl_or_b32 v0, v163, 11, v0
	v_ashrrev_i32_e32 v1, 31, v0
	v_lshl_add_u64 v[0:1], v[0:1], 1, s[30:31]
	v_lshl_add_u64 v[0:1], v[0:1], 0, v[16:17]
